# per-phase barrier sink depth k=2,3,2,3 (deeper sink where the partner's load segment is short), rest as v66
# speedup vs baseline: 1.0006x; 1.0006x over previous
; #define PG8_STAGE(bufoff, gbase, voff) do { _Pragma("unroll") for (int _i = 0; _i < 2; ++_i) \
;         __builtin_amdgcn_global_load_lds((const unsigned*)((const char*)(gbase) + (voff)[_i]), (LAS unsigned*)(lds + (bufoff) + ldsw + _i * 8192), 16, 0, 0); } while (0)
; #define PG8_LDA(dst, b, h) do { _Pragma("unroll") for (int m = 0; m < 4; ++m) _Pragma("unroll") for (int k = 0; k < 2; ++k) dst[m][k] = *(const LAS bf16x8*)(lds + PG8_SA(b, h) + aoff + m * 2048 + k * 1024); } while (0)
; #define PG8_LDB(dst, b, h) do { _Pragma("unroll") for (int n = 0; n < 2; ++n) _Pragma("unroll") for (int k = 0; k < 2; ++k) dst[n][k] = *(const LAS bf16x8*)(lds + PG8_SB(b, h) + boff + n * 2048 + k * 1024); } while (0)
; #define PG8_WAIT_V(n) asm volatile("s_waitcnt vmcnt(" #n ")" ::: "memory")
; #define PG8_WAIT_L(n) asm volatile("s_waitcnt lgkmcnt(" #n ")" ::: "memory")
; #define PG8_BAR __builtin_amdgcn_s_barrier()
; #define PG8_SCHED __builtin_amdgcn_sched_barrier(0)
; #define PG8_BAR __builtin_amdgcn_s_barrier()
; template <class Epi>
; DI void gemm_phase(LAS unsigned char* lds, const Gemm g, const StaticOrder S, const Epi E) {
;     ...
;             PG8_LDB(B0, 0, 0); PG8_SCHED; PG8_LDA(At, 0, 0); PG8_STAGE(PG8_SA(1, 1), a1 + hstep, voffA);
;             PG8_WAIT_L(8); PG8_BAR; PG8_WAIT_L(0); PG8_MMA(0, 0, At, B0); PG8_BAR; PG8_SCHED;
;             PG8_LDB(B1, 0, 1); PG8_STAGE(PG8_SB(0, 0), b2, voffB);
;             PG8_BAR; PG8_WAIT_L(0); PG8_MMA(0, 1, At, B1); PG8_BAR;
;             PG8_LDA(At, 0, 1); PG8_STAGE(PG8_SA(0, 0), a2, voffA);
;             PG8_BAR; PG8_WAIT_L(0); PG8_MMA(1, 0, At, B0); PG8_BAR; PG8_SCHED;
;             PG8_STAGE(PG8_SB(0, 1), b2 + hstep, voffB);
;             PG8_WAIT_V(6); PG8_BAR; PG8_MMA(1, 1, At, B1); PG8_BAR;
;             PG8_LDB(B0, 1, 0); PG8_SCHED; PG8_LDA(At, 1, 0); PG8_STAGE(PG8_SA(0, 1), a2 + hstep, voffA);
;             PG8_WAIT_L(8); PG8_BAR; PG8_WAIT_L(0); PG8_MMA(0, 0, At, B0); PG8_BAR; PG8_SCHED;
;             PG8_LDB(B1, 1, 1); PG8_STAGE(PG8_SB(1, 0), b3, voffB);
;             PG8_BAR; PG8_WAIT_L(0); PG8_MMA(0, 1, At, B1); PG8_BAR;
;             PG8_LDA(At, 1, 1); PG8_STAGE(PG8_SA(1, 0), a3, voffA);
;             PG8_BAR; PG8_WAIT_L(0); PG8_MMA(1, 0, At, B0); PG8_BAR; PG8_SCHED;
;             PG8_STAGE(PG8_SB(1, 1), b3 + hstep, voffB);
;             PG8_WAIT_V(6); PG8_BAR; PG8_MMA(1, 1, At, B1); PG8_BAR;
.LBB0_107:
	ds_read_b128 v[152:155], v149
	ds_read_b128 v[156:159], v149 offset:1024
	ds_read_b128 v[160:163], v149 offset:2048
	ds_read_b128 v[164:167], v149 offset:3072
	s_add_u32 s14, s76, 0xfffc0080
	s_addc_u32 s15, s77, -1
	s_cmp_eq_u32 s97, 12
	s_cselect_b32 s81, s11, s15
	s_cselect_b32 s80, s93, s14
	s_cselect_b32 s79, s9, s96
	s_cselect_b32 s78, s94, s95
	v_lshl_add_u64 v[144:145], s[76:77], 0, v[136:137]
	s_add_i32 m0, s29, 0xc000
	ds_read_b128 v[168:171], v150
	ds_read_b128 v[176:179], v150 offset:2048
	ds_read_b128 v[184:187], v150 offset:4096
	ds_read_b128 v[192:195], v150 offset:6144
	global_load_lds_dwordx4 v[144:145], off
	v_lshl_add_u64 v[144:145], s[76:77], 0, v[138:139]
	s_add_i32 m0, s29, 0xe000
	s_nop 0
	global_load_lds_dwordx4 v[144:145], off
	s_waitcnt lgkmcnt(4)
	s_setprio 1
	s_barrier
	ds_read_b128 v[172:175], v150 offset:1024
	ds_read_b128 v[180:183], v150 offset:3072
	ds_read_b128 v[188:191], v150 offset:5120
	ds_read_b128 v[196:199], v150 offset:7168
	s_waitcnt lgkmcnt(4)
	v_mfma_f32_16x16x32_bf16 v[124:127], v[152:155], v[168:171], v[124:127]
	v_mfma_f32_16x16x32_bf16 v[116:119], v[160:163], v[168:171], v[116:119]
	v_mfma_f32_16x16x32_bf16 v[108:111], v[152:155], v[176:179], v[108:111]
	v_mfma_f32_16x16x32_bf16 v[100:103], v[160:163], v[176:179], v[100:103]
	v_mfma_f32_16x16x32_bf16 v[92:95], v[152:155], v[184:187], v[92:95]
	v_mfma_f32_16x16x32_bf16 v[84:87], v[160:163], v[184:187], v[84:87]
	v_mfma_f32_16x16x32_bf16 v[76:79], v[152:155], v[192:195], v[76:79]
	v_mfma_f32_16x16x32_bf16 v[68:71], v[160:163], v[192:195], v[68:71]
	s_waitcnt lgkmcnt(3)
	v_mfma_f32_16x16x32_bf16 v[124:127], v[156:159], v[172:175], v[124:127]
	v_mfma_f32_16x16x32_bf16 v[116:119], v[164:167], v[172:175], v[116:119]
	s_waitcnt lgkmcnt(2)
	v_mfma_f32_16x16x32_bf16 v[108:111], v[156:159], v[180:183], v[108:111]
	v_mfma_f32_16x16x32_bf16 v[100:103], v[164:167], v[180:183], v[100:103]
	s_waitcnt lgkmcnt(1)
	v_mfma_f32_16x16x32_bf16 v[92:95], v[156:159], v[188:191], v[92:95]
	v_mfma_f32_16x16x32_bf16 v[84:87], v[164:167], v[188:191], v[84:87]
	s_waitcnt lgkmcnt(0)
	s_setprio 2
	s_barrier
	v_mfma_f32_16x16x32_bf16 v[76:79], v[156:159], v[196:199], v[76:79]
	v_mfma_f32_16x16x32_bf16 v[68:71], v[164:167], v[196:199], v[68:71]
	s_setprio 0
	s_add_i32 s14, s89, s7
	v_lshl_add_u64 v[144:145], s[78:79], 0, v[132:133]
	s_mov_b32 m0, s14
	ds_read_b128 v[200:203], v151
	ds_read_b128 v[204:207], v151 offset:1024
	ds_read_b128 v[208:211], v151 offset:2048
	ds_read_b128 v[212:215], v151 offset:3072
	global_load_lds_dwordx4 v[144:145], off
	v_lshl_add_u64 v[216:217], s[78:79], 0, v[128:129]
	s_add_i32 m0, s14, 0x2000
	s_nop 0
	global_load_lds_dwordx4 v[216:217], off
	s_setprio 1
	s_barrier
	s_waitcnt lgkmcnt(0)
	v_mfma_f32_16x16x32_bf16 v[120:123], v[200:203], v[168:171], v[120:123]
	v_mfma_f32_16x16x32_bf16 v[112:115], v[208:211], v[168:171], v[112:115]
	v_mfma_f32_16x16x32_bf16 v[104:107], v[200:203], v[176:179], v[104:107]
	v_mfma_f32_16x16x32_bf16 v[96:99], v[208:211], v[176:179], v[96:99]
	v_mfma_f32_16x16x32_bf16 v[88:91], v[200:203], v[184:187], v[88:91]
	v_mfma_f32_16x16x32_bf16 v[80:83], v[208:211], v[184:187], v[80:83]
	v_mfma_f32_16x16x32_bf16 v[72:75], v[200:203], v[192:195], v[72:75]
	v_mfma_f32_16x16x32_bf16 v[64:67], v[208:211], v[192:195], v[64:67]
	v_mfma_f32_16x16x32_bf16 v[120:123], v[204:207], v[172:175], v[120:123]
	v_mfma_f32_16x16x32_bf16 v[112:115], v[212:215], v[172:175], v[112:115]
	v_mfma_f32_16x16x32_bf16 v[104:107], v[204:207], v[180:183], v[104:107]
	v_mfma_f32_16x16x32_bf16 v[96:99], v[212:215], v[180:183], v[96:99]
	v_mfma_f32_16x16x32_bf16 v[88:91], v[204:207], v[188:191], v[88:91]
	s_setprio 2
	s_barrier
	v_mfma_f32_16x16x32_bf16 v[80:83], v[212:215], v[188:191], v[80:83]
	v_mfma_f32_16x16x32_bf16 v[72:75], v[204:207], v[196:199], v[72:75]
	v_mfma_f32_16x16x32_bf16 v[64:67], v[212:215], v[196:199], v[64:67]
	s_setprio 0
	s_mov_b32 m0, s29
	v_lshl_add_u64 v[218:219], s[80:81], 0, v[134:135]
	ds_read_b128 v[168:171], v150 offset:16384
	ds_read_b128 v[176:179], v150 offset:18432
	ds_read_b128 v[184:187], v150 offset:20480
	ds_read_b128 v[192:195], v150 offset:22528
	global_load_lds_dwordx4 v[218:219], off
	v_lshl_add_u64 v[220:221], s[80:81], 0, v[130:131]
	s_mov_b32 m0, s59
	s_nop 0
	global_load_lds_dwordx4 v[220:221], off
	s_setprio 1
	s_barrier
	ds_read_b128 v[172:175], v150 offset:17408
	ds_read_b128 v[180:183], v150 offset:19456
	ds_read_b128 v[188:191], v150 offset:21504
	ds_read_b128 v[196:199], v150 offset:23552
	s_waitcnt lgkmcnt(4)
	v_mfma_f32_16x16x32_bf16 v[60:63], v[152:155], v[168:171], v[60:63]
	v_mfma_f32_16x16x32_bf16 v[52:55], v[160:163], v[168:171], v[52:55]
	v_mfma_f32_16x16x32_bf16 v[44:47], v[152:155], v[176:179], v[44:47]
	v_mfma_f32_16x16x32_bf16 v[36:39], v[160:163], v[176:179], v[36:39]
	v_mfma_f32_16x16x32_bf16 v[28:31], v[152:155], v[184:187], v[28:31]
	v_mfma_f32_16x16x32_bf16 v[20:23], v[160:163], v[184:187], v[20:23]
	v_mfma_f32_16x16x32_bf16 v[12:15], v[152:155], v[192:195], v[12:15]
	v_mfma_f32_16x16x32_bf16 v[4:7], v[160:163], v[192:195], v[4:7]
	s_waitcnt lgkmcnt(3)
	v_mfma_f32_16x16x32_bf16 v[60:63], v[156:159], v[172:175], v[60:63]
	v_mfma_f32_16x16x32_bf16 v[52:55], v[164:167], v[172:175], v[52:55]
	s_waitcnt lgkmcnt(2)
	v_mfma_f32_16x16x32_bf16 v[44:47], v[156:159], v[180:183], v[44:47]
	v_mfma_f32_16x16x32_bf16 v[36:39], v[164:167], v[180:183], v[36:39]
	s_waitcnt lgkmcnt(1)
	v_mfma_f32_16x16x32_bf16 v[28:31], v[156:159], v[188:191], v[28:31]
	v_mfma_f32_16x16x32_bf16 v[20:23], v[164:167], v[188:191], v[20:23]
	s_waitcnt lgkmcnt(0)
	s_setprio 2
	s_barrier
; #define PG8_STAGE(bufoff, gbase, voff) do { _Pragma("unroll") for (int _i = 0; _i < 2; ++_i) \
;         __builtin_amdgcn_global_load_lds((const unsigned*)((const char*)(gbase) + (voff)[_i]), (LAS unsigned*)(lds + (bufoff) + ldsw + _i * 8192), 16, 0, 0); } while (0)
; #define PG8_LDA(dst, b, h) do { _Pragma("unroll") for (int m = 0; m < 4; ++m) _Pragma("unroll") for (int k = 0; k < 2; ++k) dst[m][k] = *(const LAS bf16x8*)(lds + PG8_SA(b, h) + aoff + m * 2048 + k * 1024); } while (0)
; #define PG8_LDB(dst, b, h) do { _Pragma("unroll") for (int n = 0; n < 2; ++n) _Pragma("unroll") for (int k = 0; k < 2; ++k) dst[n][k] = *(const LAS bf16x8*)(lds + PG8_SB(b, h) + boff + n * 2048 + k * 1024); } while (0)
; #define PG8_WAIT_V(n) asm volatile("s_waitcnt vmcnt(" #n ")" ::: "memory")
; #define PG8_WAIT_L(n) asm volatile("s_waitcnt lgkmcnt(" #n ")" ::: "memory")
; #define PG8_BAR __builtin_amdgcn_s_barrier()
; #define PG8_SCHED __builtin_amdgcn_sched_barrier(0)
; #define PG8_BAR __builtin_amdgcn_s_barrier()
; template <class Epi>
; DI void gemm_phase(LAS unsigned char* lds, const Gemm g, const StaticOrder S, const Epi E) {
;     ...
;             PG8_LDB(B0, 0, 0); PG8_SCHED; PG8_LDA(At, 0, 0); PG8_STAGE(PG8_SA(1, 1), a1 + hstep, voffA);
;             PG8_WAIT_L(8); PG8_BAR; PG8_WAIT_L(0); PG8_MMA(0, 0, At, B0); PG8_BAR; PG8_SCHED;
;             PG8_LDB(B1, 0, 1); PG8_STAGE(PG8_SB(0, 0), b2, voffB);
;             PG8_BAR; PG8_WAIT_L(0); PG8_MMA(0, 1, At, B1); PG8_BAR;
;             PG8_LDA(At, 0, 1); PG8_STAGE(PG8_SA(0, 0), a2, voffA);
;             PG8_BAR; PG8_WAIT_L(0); PG8_MMA(1, 0, At, B0); PG8_BAR; PG8_SCHED;
;             PG8_STAGE(PG8_SB(0, 1), b2 + hstep, voffB);
;             PG8_WAIT_V(6); PG8_BAR; PG8_MMA(1, 1, At, B1); PG8_BAR;
;             PG8_LDB(B0, 1, 0); PG8_SCHED; PG8_LDA(At, 1, 0); PG8_STAGE(PG8_SA(0, 1), a2 + hstep, voffA);
;             PG8_WAIT_L(8); PG8_BAR; PG8_WAIT_L(0); PG8_MMA(0, 0, At, B0); PG8_BAR; PG8_SCHED;
;             PG8_LDB(B1, 1, 1); PG8_STAGE(PG8_SB(1, 0), b3, voffB);
;             PG8_BAR; PG8_WAIT_L(0); PG8_MMA(0, 1, At, B1); PG8_BAR;
;             PG8_LDA(At, 1, 1); PG8_STAGE(PG8_SA(1, 0), a3, voffA);
;             PG8_BAR; PG8_WAIT_L(0); PG8_MMA(1, 0, At, B0); PG8_BAR; PG8_SCHED;
;             PG8_STAGE(PG8_SB(1, 1), b3 + hstep, voffB);
;             PG8_WAIT_V(6); PG8_BAR; PG8_MMA(1, 1, At, B1); PG8_BAR;
	v_mfma_f32_16x16x32_bf16 v[12:15], v[156:159], v[196:199], v[12:15]
	v_mfma_f32_16x16x32_bf16 v[4:7], v[164:167], v[196:199], v[4:7]
	s_setprio 0
	s_add_u32 s14, s78, 0x40000
	s_addc_u32 s15, s79, 0
	s_add_i32 s35, s90, s7
	v_lshl_add_u64 v[152:153], s[14:15], 0, v[132:133]
	s_mov_b32 m0, s35
	s_nop 0
	global_load_lds_dwordx4 v[152:153], off
	v_lshl_add_u64 v[152:153], s[14:15], 0, v[128:129]
	s_add_i32 m0, s35, 0x2000
	s_nop 0
	global_load_lds_dwordx4 v[152:153], off
	s_waitcnt vmcnt(6)
	s_setprio 1
	s_barrier
	v_mfma_f32_16x16x32_bf16 v[56:59], v[200:203], v[168:171], v[56:59]
	v_mfma_f32_16x16x32_bf16 v[48:51], v[208:211], v[168:171], v[48:51]
	v_mfma_f32_16x16x32_bf16 v[40:43], v[200:203], v[176:179], v[40:43]
	v_mfma_f32_16x16x32_bf16 v[32:35], v[208:211], v[176:179], v[32:35]
	v_mfma_f32_16x16x32_bf16 v[24:27], v[200:203], v[184:187], v[24:27]
	v_mfma_f32_16x16x32_bf16 v[16:19], v[208:211], v[184:187], v[16:19]
	v_mfma_f32_16x16x32_bf16 v[8:11], v[200:203], v[192:195], v[8:11]
	v_mfma_f32_16x16x32_bf16 v[0:3], v[208:211], v[192:195], v[0:3]
	v_mfma_f32_16x16x32_bf16 v[56:59], v[204:207], v[172:175], v[56:59]
	v_mfma_f32_16x16x32_bf16 v[48:51], v[212:215], v[172:175], v[48:51]
	v_mfma_f32_16x16x32_bf16 v[40:43], v[204:207], v[180:183], v[40:43]
	v_mfma_f32_16x16x32_bf16 v[32:35], v[212:215], v[180:183], v[32:35]
	v_mfma_f32_16x16x32_bf16 v[24:27], v[204:207], v[188:191], v[24:27]
	s_setprio 2
	s_barrier
	v_mfma_f32_16x16x32_bf16 v[16:19], v[212:215], v[188:191], v[16:19]
	v_mfma_f32_16x16x32_bf16 v[8:11], v[204:207], v[196:199], v[8:11]
	v_mfma_f32_16x16x32_bf16 v[0:3], v[212:215], v[196:199], v[0:3]
	s_setprio 0
	s_add_i32 s35, 0, 0x18000
	v_add_u32_e32 v164, s35, v147
	ds_read_b128 v[152:155], v164
	ds_read_b128 v[156:159], v164 offset:1024
	ds_read_b128 v[160:163], v164 offset:2048
	ds_read_b128 v[164:167], v164 offset:3072
	s_add_u32 s14, s80, 0x40000
	s_addc_u32 s15, s81, 0
	s_mov_b32 m0, s82
	v_lshl_add_u64 v[200:201], s[14:15], 0, v[134:135]
	ds_read_b128 v[168:171], v150 offset:32768
	ds_read_b128 v[176:179], v150 offset:34816
	ds_read_b128 v[184:187], v150 offset:36864
	ds_read_b128 v[192:195], v150 offset:38912
	global_load_lds_dwordx4 v[200:201], off
	v_lshl_add_u64 v[200:201], s[14:15], 0, v[130:131]
	s_mov_b32 m0, s83
	s_nop 0
	global_load_lds_dwordx4 v[200:201], off
	s_waitcnt lgkmcnt(4)
	s_setprio 1
	s_barrier
	ds_read_b128 v[172:175], v150 offset:33792
	ds_read_b128 v[180:183], v150 offset:35840
	ds_read_b128 v[188:191], v150 offset:37888
	ds_read_b128 v[196:199], v150 offset:39936
	s_waitcnt lgkmcnt(4)
	v_mfma_f32_16x16x32_bf16 v[124:127], v[152:155], v[168:171], v[124:127]
	v_mfma_f32_16x16x32_bf16 v[116:119], v[160:163], v[168:171], v[116:119]
	v_mfma_f32_16x16x32_bf16 v[108:111], v[152:155], v[176:179], v[108:111]
	v_mfma_f32_16x16x32_bf16 v[100:103], v[160:163], v[176:179], v[100:103]
	v_mfma_f32_16x16x32_bf16 v[92:95], v[152:155], v[184:187], v[92:95]
	v_mfma_f32_16x16x32_bf16 v[84:87], v[160:163], v[184:187], v[84:87]
	v_mfma_f32_16x16x32_bf16 v[76:79], v[152:155], v[192:195], v[76:79]
	v_mfma_f32_16x16x32_bf16 v[68:71], v[160:163], v[192:195], v[68:71]
	s_waitcnt lgkmcnt(3)
	v_mfma_f32_16x16x32_bf16 v[124:127], v[156:159], v[172:175], v[124:127]
	v_mfma_f32_16x16x32_bf16 v[116:119], v[164:167], v[172:175], v[116:119]
	s_waitcnt lgkmcnt(2)
	v_mfma_f32_16x16x32_bf16 v[108:111], v[156:159], v[180:183], v[108:111]
	v_mfma_f32_16x16x32_bf16 v[100:103], v[164:167], v[180:183], v[100:103]
	s_waitcnt lgkmcnt(1)
	v_mfma_f32_16x16x32_bf16 v[92:95], v[156:159], v[188:191], v[92:95]
	v_mfma_f32_16x16x32_bf16 v[84:87], v[164:167], v[188:191], v[84:87]
	s_waitcnt lgkmcnt(0)
	s_setprio 2
	s_barrier
	v_mfma_f32_16x16x32_bf16 v[76:79], v[156:159], v[196:199], v[76:79]
	v_mfma_f32_16x16x32_bf16 v[68:71], v[164:167], v[196:199], v[68:71]
	s_setprio 0
	s_add_i32 s80, 0, 0x1c000
	s_add_i32 s14, s35, s7
	v_add_u32_e32 v212, s80, v147
	v_lshl_add_u64 v[144:145], v[144:145], 0, s[4:5]
	s_mov_b32 m0, s14
	ds_read_b128 v[200:203], v212
	ds_read_b128 v[204:207], v212 offset:1024
	ds_read_b128 v[208:211], v212 offset:2048
	ds_read_b128 v[212:215], v212 offset:3072
	global_load_lds_dwordx4 v[144:145], off
	v_lshl_add_u64 v[144:145], v[216:217], 0, s[4:5]
	s_add_i32 m0, s14, 0x2000
	s_nop 0
	global_load_lds_dwordx4 v[144:145], off
	s_setprio 1
	s_barrier
	s_waitcnt lgkmcnt(0)
	v_mfma_f32_16x16x32_bf16 v[120:123], v[200:203], v[168:171], v[120:123]
	v_mfma_f32_16x16x32_bf16 v[112:115], v[208:211], v[168:171], v[112:115]
	v_mfma_f32_16x16x32_bf16 v[104:107], v[200:203], v[176:179], v[104:107]
	v_mfma_f32_16x16x32_bf16 v[96:99], v[208:211], v[176:179], v[96:99]
	v_mfma_f32_16x16x32_bf16 v[88:91], v[200:203], v[184:187], v[88:91]
	v_mfma_f32_16x16x32_bf16 v[80:83], v[208:211], v[184:187], v[80:83]
	v_mfma_f32_16x16x32_bf16 v[72:75], v[200:203], v[192:195], v[72:75]
	v_mfma_f32_16x16x32_bf16 v[64:67], v[208:211], v[192:195], v[64:67]
	v_mfma_f32_16x16x32_bf16 v[120:123], v[204:207], v[172:175], v[120:123]
	v_mfma_f32_16x16x32_bf16 v[112:115], v[212:215], v[172:175], v[112:115]
	v_mfma_f32_16x16x32_bf16 v[104:107], v[204:207], v[180:183], v[104:107]
	v_mfma_f32_16x16x32_bf16 v[96:99], v[212:215], v[180:183], v[96:99]
	v_mfma_f32_16x16x32_bf16 v[88:91], v[204:207], v[188:191], v[88:91]
	s_setprio 2
	s_barrier
	v_mfma_f32_16x16x32_bf16 v[80:83], v[212:215], v[188:191], v[80:83]
	v_mfma_f32_16x16x32_bf16 v[72:75], v[204:207], v[196:199], v[72:75]
	v_mfma_f32_16x16x32_bf16 v[64:67], v[212:215], v[196:199], v[64:67]
	s_setprio 0
	s_mov_b32 m0, s85
	v_lshl_add_u64 v[144:145], v[218:219], 0, s[4:5]
	ds_read_b128 v[168:171], v150 offset:49152
	ds_read_b128 v[176:179], v150 offset:51200
	ds_read_b128 v[184:187], v150 offset:53248
	ds_read_b128 v[192:195], v150 offset:55296
	global_load_lds_dwordx4 v[144:145], off
	v_lshl_add_u64 v[144:145], v[220:221], 0, s[4:5]
	s_mov_b32 m0, s86
	s_nop 0
	global_load_lds_dwordx4 v[144:145], off
	s_setprio 1
	s_barrier
; template <class Epi>
; DI void gemm_phase(LAS unsigned char* lds, const Gemm g, const StaticOrder S, const Epi E) {
;     ...
;             PG8_LDB(B0, 0, 0); PG8_SCHED; PG8_LDA(At, 0, 0); PG8_STAGE(PG8_SA(1, 1), a1 + hstep, voffA);
;             PG8_WAIT_L(8); PG8_BAR; PG8_WAIT_L(0); PG8_MMA(0, 0, At, B0); PG8_BAR; PG8_SCHED;
;             PG8_LDB(B1, 0, 1); PG8_STAGE(PG8_SB(0, 0), b2, voffB);
;             PG8_BAR; PG8_WAIT_L(0); PG8_MMA(0, 1, At, B1); PG8_BAR;
;             PG8_LDA(At, 0, 1); PG8_STAGE(PG8_SA(0, 0), a2, voffA);
;             PG8_BAR; PG8_WAIT_L(0); PG8_MMA(1, 0, At, B0); PG8_BAR; PG8_SCHED;
;             PG8_STAGE(PG8_SB(0, 1), b2 + hstep, voffB);
;             PG8_WAIT_V(6); PG8_BAR; PG8_MMA(1, 1, At, B1); PG8_BAR;
;             PG8_LDB(B0, 1, 0); PG8_SCHED; PG8_LDA(At, 1, 0); PG8_STAGE(PG8_SA(0, 1), a2 + hstep, voffA);
;             PG8_WAIT_L(8); PG8_BAR; PG8_WAIT_L(0); PG8_MMA(0, 0, At, B0); PG8_BAR; PG8_SCHED;
;             PG8_LDB(B1, 1, 1); PG8_STAGE(PG8_SB(1, 0), b3, voffB);
;             PG8_BAR; PG8_WAIT_L(0); PG8_MMA(0, 1, At, B1); PG8_BAR;
;             PG8_LDA(At, 1, 1); PG8_STAGE(PG8_SA(1, 0), a3, voffA);
;             PG8_BAR; PG8_WAIT_L(0); PG8_MMA(1, 0, At, B0); PG8_BAR; PG8_SCHED;
;             PG8_STAGE(PG8_SB(1, 1), b3 + hstep, voffB);
;             PG8_WAIT_V(6); PG8_BAR; PG8_MMA(1, 1, At, B1); PG8_BAR;
;     DI void operator()(AccRef acc, const Unit& u, int wr, int wc, int fr, int fq) const {
;         const int row0 = u.pm * 256 + wr * 64 + fr, col = u.pn * 128 + wc * 32 + 8 * fq;
;         RowScales rsc; if (RS) rsc = load_rowscales(ss, row0);
; #pragma unroll
;         for (int ai = 0; ai < 2; ++ai)
; #pragma unroll
;             for (int m = 0; m < 4; ++m) {
;                 const int row = row0 + ai * 128 + m * 16;
;                 const float r = RS ? rsc.r[ai][m] : 1.0f;
;                 const f32x4 a0 = acc[ai][0][m][0] * r, a1 = acc[ai][0][m][1] * r, b0 = acc[ai][1][m][0] * r, b1 = acc[ai][1][m][1] * r;
;                 u32x4 w;
;                 w.x = pk_bf16(fast_silu(a0[0]) * b0[0], fast_silu(a0[1]) * b0[1]); w.y = pk_bf16(fast_silu(a0[2]) * b0[2], fast_silu(a0[3]) * b0[3]);
;                 w.z = pk_bf16(fast_silu(a1[0]) * b1[0], fast_silu(a1[1]) * b1[1]); w.w = pk_bf16(fast_silu(a1[2]) * b1[2], fast_silu(a1[3]) * b1[3]);
;                 *(u32x4*)(G + (size_t)row * DFF + col) = w;
;             }
	ds_read_b128 v[172:175], v150 offset:50176
	ds_read_b128 v[180:183], v150 offset:52224
	ds_read_b128 v[188:191], v150 offset:54272
	ds_read_b128 v[196:199], v150 offset:56320
	s_waitcnt lgkmcnt(4)
	v_mfma_f32_16x16x32_bf16 v[60:63], v[152:155], v[168:171], v[60:63]
	v_mfma_f32_16x16x32_bf16 v[52:55], v[160:163], v[168:171], v[52:55]
	v_mfma_f32_16x16x32_bf16 v[44:47], v[152:155], v[176:179], v[44:47]
	v_mfma_f32_16x16x32_bf16 v[36:39], v[160:163], v[176:179], v[36:39]
	v_mfma_f32_16x16x32_bf16 v[28:31], v[152:155], v[184:187], v[28:31]
	v_mfma_f32_16x16x32_bf16 v[20:23], v[160:163], v[184:187], v[20:23]
	v_mfma_f32_16x16x32_bf16 v[12:15], v[152:155], v[192:195], v[12:15]
	v_mfma_f32_16x16x32_bf16 v[4:7], v[160:163], v[192:195], v[4:7]
	s_waitcnt lgkmcnt(3)
	v_mfma_f32_16x16x32_bf16 v[60:63], v[156:159], v[172:175], v[60:63]
	v_mfma_f32_16x16x32_bf16 v[52:55], v[164:167], v[172:175], v[52:55]
	s_waitcnt lgkmcnt(2)
	v_mfma_f32_16x16x32_bf16 v[44:47], v[156:159], v[180:183], v[44:47]
	v_mfma_f32_16x16x32_bf16 v[36:39], v[164:167], v[180:183], v[36:39]
	s_waitcnt lgkmcnt(1)
	v_mfma_f32_16x16x32_bf16 v[28:31], v[156:159], v[188:191], v[28:31]
	v_mfma_f32_16x16x32_bf16 v[20:23], v[164:167], v[188:191], v[20:23]
	s_waitcnt lgkmcnt(0)
	s_setprio 2
	s_barrier
	v_mfma_f32_16x16x32_bf16 v[12:15], v[156:159], v[196:199], v[12:15]
	v_mfma_f32_16x16x32_bf16 v[4:7], v[164:167], v[196:199], v[4:7]
	s_setprio 0
	s_add_u32 s14, s78, 0x40080
	s_addc_u32 s15, s79, 0
	s_add_i32 s35, s80, s7
	v_lshl_add_u64 v[144:145], s[14:15], 0, v[132:133]
	s_mov_b32 m0, s35
	s_nop 0
	global_load_lds_dwordx4 v[144:145], off
	v_lshl_add_u64 v[144:145], s[14:15], 0, v[128:129]
	s_add_i32 m0, s35, 0x2000
	s_nop 0
	global_load_lds_dwordx4 v[144:145], off
	s_waitcnt vmcnt(6)
	s_setprio 1
	s_barrier
	v_mfma_f32_16x16x32_bf16 v[56:59], v[200:203], v[168:171], v[56:59]
	v_mfma_f32_16x16x32_bf16 v[48:51], v[208:211], v[168:171], v[48:51]
	v_mfma_f32_16x16x32_bf16 v[40:43], v[200:203], v[176:179], v[40:43]
	v_mfma_f32_16x16x32_bf16 v[32:35], v[208:211], v[176:179], v[32:35]
	v_mfma_f32_16x16x32_bf16 v[24:27], v[200:203], v[184:187], v[24:27]
	v_mfma_f32_16x16x32_bf16 v[16:19], v[208:211], v[184:187], v[16:19]
	v_mfma_f32_16x16x32_bf16 v[8:11], v[200:203], v[192:195], v[8:11]
	v_mfma_f32_16x16x32_bf16 v[0:3], v[208:211], v[192:195], v[0:3]
	v_mfma_f32_16x16x32_bf16 v[56:59], v[204:207], v[172:175], v[56:59]
	v_mfma_f32_16x16x32_bf16 v[48:51], v[212:215], v[172:175], v[48:51]
	v_mfma_f32_16x16x32_bf16 v[40:43], v[204:207], v[180:183], v[40:43]
	v_mfma_f32_16x16x32_bf16 v[32:35], v[212:215], v[180:183], v[32:35]
	v_mfma_f32_16x16x32_bf16 v[24:27], v[204:207], v[188:191], v[24:27]
	s_setprio 2
	s_barrier
	v_mfma_f32_16x16x32_bf16 v[16:19], v[212:215], v[188:191], v[16:19]
	v_mfma_f32_16x16x32_bf16 v[8:11], v[204:207], v[196:199], v[8:11]
	v_mfma_f32_16x16x32_bf16 v[0:3], v[212:215], v[196:199], v[0:3]
	s_setprio 0
	s_add_i32 s97, s97, 2
	s_add_u32 s76, s76, 0x100
	s_addc_u32 s77, s77, 0
	s_add_u32 s95, s95, 0x100
	s_addc_u32 s96, s96, 0
	s_cmp_gt_u32 s97, 13
	s_cbranch_scc0 .LBB0_107
	v_mul_f32_e32 v153, 0xbfb8aa3b, v124
	v_exp_f32_e32 v153, v153
	v_mul_f32_e32 v154, 0xbfb8aa3b, v125
	v_exp_f32_e32 v155, v154
	v_lshl_or_b32 v144, s92, 7, v148
	v_add_f32_e32 v153, 1.0, v153
	v_rcp_f32_e32 v154, v153
	v_add_f32_e32 v153, 1.0, v155
	v_mul_f32_e32 v155, 0xbfb8aa3b, v126
	v_exp_f32_e32 v156, v155
	v_mul_f32_e32 v155, 0xbfb8aa3b, v127
	v_exp_f32_e32 v157, v155
	v_rcp_f32_e32 v155, v153
	v_add_f32_e32 v153, 1.0, v156
	v_rcp_f32_e32 v156, v153
	v_add_f32_e32 v153, 1.0, v157
	v_rcp_f32_e32 v157, v153
	v_pk_mul_f32 v[124:125], v[124:125], v[154:155]
	v_ashrrev_i32_e32 v145, 31, v144
	v_pk_mul_f32 v[120:121], v[124:125], v[120:121]
	v_pk_mul_f32 v[124:125], v[126:127], v[156:157]
	v_cvt_pk_bf16_f32 v120, v120, v121
	v_mul_f32_e32 v121, 0xbfb8aa3b, v116
	v_pk_mul_f32 v[122:123], v[124:125], v[122:123]
	v_exp_f32_e32 v124, v121
	v_mul_f32_e32 v121, 0xbfb8aa3b, v117
	v_exp_f32_e32 v125, v121
	v_cvt_pk_bf16_f32 v121, v122, v123
	v_add_f32_e32 v122, 1.0, v124
	v_mul_f32_e32 v124, 0xbfb8aa3b, v118
	v_add_f32_e32 v123, 1.0, v125
	v_mul_f32_e32 v125, 0xbfb8aa3b, v119
	v_exp_f32_e32 v124, v124
	v_exp_f32_e32 v125, v125
	v_rcp_f32_e32 v122, v122
	v_rcp_f32_e32 v123, v123
	v_add_f32_e32 v124, 1.0, v124
	v_add_f32_e32 v125, 1.0, v125
	v_rcp_f32_e32 v124, v124
	v_rcp_f32_e32 v125, v125
	v_pk_mul_f32 v[116:117], v[116:117], v[122:123]
	v_lshl_add_u32 v152, s28, 8, v146
	v_pk_mul_f32 v[112:113], v[116:117], v[112:113]
	v_lshl_add_u64 v[144:145], v[144:145], 1, s[54:55]
	v_cvt_pk_bf16_f32 v122, v112, v113
	v_pk_mul_f32 v[112:113], v[118:119], v[124:125]
	v_or_b32_e32 v116, 16, v152
	v_pk_mul_f32 v[112:113], v[112:113], v[114:115]
	v_mul_f32_e32 v114, 0xbfb8aa3b, v110
	v_cvt_pk_bf16_f32 v123, v112, v113
	v_mad_i64_i32 v[112:113], s[14:15], v152, s91, v[144:145]
	global_store_dwordx4 v[112:113], v[120:123], off
	v_mul_f32_e32 v112, 0xbfb8aa3b, v108
	v_mul_f32_e32 v113, 0xbfb8aa3b, v109
	v_exp_f32_e32 v112, v112
	v_exp_f32_e32 v113, v113
	v_mul_f32_e32 v115, 0xbfb8aa3b, v111
	v_exp_f32_e32 v114, v114
	v_exp_f32_e32 v115, v115
	v_add_f32_e32 v112, 1.0, v112
	v_add_f32_e32 v113, 1.0, v113
	v_rcp_f32_e32 v112, v112
	v_rcp_f32_e32 v113, v113
	v_add_f32_e32 v114, 1.0, v114
	v_add_f32_e32 v115, 1.0, v115
	v_rcp_f32_e32 v114, v114
	v_rcp_f32_e32 v115, v115
	v_pk_mul_f32 v[108:109], v[108:109], v[112:113]
	s_and_b64 vcc, exec, s[0:1]
	v_pk_mul_f32 v[104:105], v[108:109], v[104:105]
	v_pk_mul_f32 v[108:109], v[110:111], v[114:115]
	v_cvt_pk_bf16_f32 v104, v104, v105
	v_mul_f32_e32 v105, 0xbfb8aa3b, v100
; DI unsigned pk_bf16(float lo, float hi) { f32x2 v = {lo, hi}; return __builtin_bit_cast(unsigned, __builtin_convertvector(v, bf16v2)); }
; DI float fast_silu(float x) { return x * fast_sigmoid(x); }
;     DI void operator()(AccRef acc, const Unit& u, int wr, int wc, int fr, int fq) const {
;         const int row0 = u.pm * 256 + wr * 64 + fr, col = u.pn * 128 + wc * 32 + 8 * fq;
;         RowScales rsc; if (RS) rsc = load_rowscales(ss, row0);
; #pragma unroll
;         for (int ai = 0; ai < 2; ++ai)
; #pragma unroll
;             for (int m = 0; m < 4; ++m) {
;                 const int row = row0 + ai * 128 + m * 16;
;                 const float r = RS ? rsc.r[ai][m] : 1.0f;
;                 const f32x4 a0 = acc[ai][0][m][0] * r, a1 = acc[ai][0][m][1] * r, b0 = acc[ai][1][m][0] * r, b1 = acc[ai][1][m][1] * r;
;                 u32x4 w;
;                 w.x = pk_bf16(fast_silu(a0[0]) * b0[0], fast_silu(a0[1]) * b0[1]); w.y = pk_bf16(fast_silu(a0[2]) * b0[2], fast_silu(a0[3]) * b0[3]);
;                 w.z = pk_bf16(fast_silu(a1[0]) * b1[0], fast_silu(a1[1]) * b1[1]); w.w = pk_bf16(fast_silu(a1[2]) * b1[2], fast_silu(a1[3]) * b1[3]);
;                 *(u32x4*)(G + (size_t)row * DFF + col) = w;
;             }
	v_pk_mul_f32 v[106:107], v[108:109], v[106:107]
	v_exp_f32_e32 v108, v105
	v_mul_f32_e32 v105, 0xbfb8aa3b, v101
	v_exp_f32_e32 v109, v105
	v_cvt_pk_bf16_f32 v105, v106, v107
	v_add_f32_e32 v106, 1.0, v108
	v_mul_f32_e32 v108, 0xbfb8aa3b, v102
	v_add_f32_e32 v107, 1.0, v109
	v_mul_f32_e32 v109, 0xbfb8aa3b, v103
	v_exp_f32_e32 v108, v108
	v_exp_f32_e32 v109, v109
	v_rcp_f32_e32 v106, v106
	v_rcp_f32_e32 v107, v107
	v_add_f32_e32 v108, 1.0, v108
	v_add_f32_e32 v109, 1.0, v109
	v_rcp_f32_e32 v108, v108
	v_rcp_f32_e32 v109, v109
	v_pk_mul_f32 v[100:101], v[100:101], v[106:107]
	s_mov_b32 s92, s8
	v_pk_mul_f32 v[96:97], v[100:101], v[96:97]
	v_or_b32_e32 v100, 32, v152
	v_cvt_pk_bf16_f32 v106, v96, v97
	v_pk_mul_f32 v[96:97], v[102:103], v[108:109]
	s_mov_b32 s28, s10
	v_pk_mul_f32 v[96:97], v[96:97], v[98:99]
	v_mul_f32_e32 v98, 0xbfb8aa3b, v94
	v_cvt_pk_bf16_f32 v107, v96, v97
	v_mad_i64_i32 v[96:97], s[14:15], v116, s91, v[144:145]
	global_store_dwordx4 v[96:97], v[104:107], off
	v_mul_f32_e32 v96, 0xbfb8aa3b, v92
	v_mul_f32_e32 v97, 0xbfb8aa3b, v93
	v_exp_f32_e32 v96, v96
	v_exp_f32_e32 v97, v97
	v_mul_f32_e32 v99, 0xbfb8aa3b, v95
	v_exp_f32_e32 v98, v98
	v_exp_f32_e32 v99, v99
	v_add_f32_e32 v96, 1.0, v96
	v_add_f32_e32 v97, 1.0, v97
	v_rcp_f32_e32 v96, v96
	v_rcp_f32_e32 v97, v97
	v_add_f32_e32 v98, 1.0, v98
	v_add_f32_e32 v99, 1.0, v99
	v_rcp_f32_e32 v98, v98
	v_rcp_f32_e32 v99, v99
	v_pk_mul_f32 v[92:93], v[92:93], v[96:97]
	s_mov_b64 s[78:79], s[26:27]
	v_pk_mul_f32 v[88:89], v[92:93], v[88:89]
	v_pk_mul_f32 v[92:93], v[94:95], v[98:99]
	v_cvt_pk_bf16_f32 v88, v88, v89
	v_mul_f32_e32 v89, 0xbfb8aa3b, v84
	v_pk_mul_f32 v[90:91], v[92:93], v[90:91]
	v_exp_f32_e32 v92, v89
	v_mul_f32_e32 v89, 0xbfb8aa3b, v85
	v_exp_f32_e32 v93, v89
	v_cvt_pk_bf16_f32 v89, v90, v91
	v_add_f32_e32 v90, 1.0, v92
	v_mul_f32_e32 v92, 0xbfb8aa3b, v86
	v_add_f32_e32 v91, 1.0, v93
	v_mul_f32_e32 v93, 0xbfb8aa3b, v87
	v_exp_f32_e32 v92, v92
	v_exp_f32_e32 v93, v93
	v_rcp_f32_e32 v90, v90
	v_rcp_f32_e32 v91, v91
	v_add_f32_e32 v92, 1.0, v92
	v_add_f32_e32 v93, 1.0, v93
	v_rcp_f32_e32 v92, v92
	v_rcp_f32_e32 v93, v93
	v_pk_mul_f32 v[84:85], v[84:85], v[90:91]
	s_mov_b64 s[76:77], s[24:25]
	v_pk_mul_f32 v[80:81], v[84:85], v[80:81]
	v_or_b32_e32 v84, 48, v152
	v_cvt_pk_bf16_f32 v90, v80, v81
	v_pk_mul_f32 v[80:81], v[86:87], v[92:93]
	s_nop 0
	v_pk_mul_f32 v[80:81], v[80:81], v[82:83]
	v_mul_f32_e32 v82, 0xbfb8aa3b, v78
	v_cvt_pk_bf16_f32 v91, v80, v81
	v_mad_i64_i32 v[80:81], s[14:15], v100, s91, v[144:145]
	global_store_dwordx4 v[80:81], v[88:91], off
	v_mul_f32_e32 v80, 0xbfb8aa3b, v76
	v_mul_f32_e32 v81, 0xbfb8aa3b, v77
	v_exp_f32_e32 v80, v80
	v_exp_f32_e32 v81, v81
	v_mul_f32_e32 v83, 0xbfb8aa3b, v79
	v_exp_f32_e32 v82, v82
	v_exp_f32_e32 v83, v83
	v_add_f32_e32 v80, 1.0, v80
	v_add_f32_e32 v81, 1.0, v81
	v_rcp_f32_e32 v80, v80
	v_rcp_f32_e32 v81, v81
	v_add_f32_e32 v82, 1.0, v82
	v_add_f32_e32 v83, 1.0, v83
	v_rcp_f32_e32 v82, v82
	v_rcp_f32_e32 v83, v83
	v_pk_mul_f32 v[76:77], v[76:77], v[80:81]
	s_nop 0
	v_pk_mul_f32 v[72:73], v[76:77], v[72:73]
	v_pk_mul_f32 v[76:77], v[78:79], v[82:83]
	v_cvt_pk_bf16_f32 v72, v72, v73
	v_mul_f32_e32 v73, 0xbfb8aa3b, v68
	v_pk_mul_f32 v[74:75], v[76:77], v[74:75]
	v_exp_f32_e32 v76, v73
	v_mul_f32_e32 v73, 0xbfb8aa3b, v69
	v_exp_f32_e32 v77, v73
	v_cvt_pk_bf16_f32 v73, v74, v75
	v_add_f32_e32 v74, 1.0, v76
	v_mul_f32_e32 v76, 0xbfb8aa3b, v70
	v_add_f32_e32 v75, 1.0, v77
	v_mul_f32_e32 v77, 0xbfb8aa3b, v71
	v_exp_f32_e32 v76, v76
	v_exp_f32_e32 v77, v77
	v_rcp_f32_e32 v74, v74
	v_rcp_f32_e32 v75, v75
	v_add_f32_e32 v76, 1.0, v76
	v_add_f32_e32 v77, 1.0, v77
	v_rcp_f32_e32 v76, v76
	v_rcp_f32_e32 v77, v77
	v_pk_mul_f32 v[68:69], v[68:69], v[74:75]
	s_nop 0
	v_pk_mul_f32 v[64:65], v[68:69], v[64:65]
	v_add_u32_e32 v68, 0x80, v152
	v_cvt_pk_bf16_f32 v74, v64, v65
	v_pk_mul_f32 v[64:65], v[70:71], v[76:77]
	s_nop 0
	v_pk_mul_f32 v[64:65], v[64:65], v[66:67]
	v_mul_f32_e32 v66, 0xbfb8aa3b, v62
	v_cvt_pk_bf16_f32 v75, v64, v65
	v_mad_i64_i32 v[64:65], s[14:15], v84, s91, v[144:145]
	global_store_dwordx4 v[64:65], v[72:75], off
	v_mul_f32_e32 v64, 0xbfb8aa3b, v60
	v_mul_f32_e32 v65, 0xbfb8aa3b, v61
	v_exp_f32_e32 v64, v64
	v_exp_f32_e32 v65, v65
	v_mul_f32_e32 v67, 0xbfb8aa3b, v63
	v_exp_f32_e32 v66, v66
	v_exp_f32_e32 v67, v67
	v_add_f32_e32 v64, 1.0, v64
	v_add_f32_e32 v65, 1.0, v65
	v_rcp_f32_e32 v64, v64
	v_rcp_f32_e32 v65, v65
	v_add_f32_e32 v66, 1.0, v66
	v_add_f32_e32 v67, 1.0, v67
	v_rcp_f32_e32 v66, v66
	v_rcp_f32_e32 v67, v67
	v_pk_mul_f32 v[60:61], v[60:61], v[64:65]
	s_nop 0
	v_pk_mul_f32 v[56:57], v[60:61], v[56:57]
	v_pk_mul_f32 v[60:61], v[62:63], v[66:67]
	v_cvt_pk_bf16_f32 v56, v56, v57
	v_mul_f32_e32 v57, 0xbfb8aa3b, v52
	v_pk_mul_f32 v[58:59], v[60:61], v[58:59]
	v_exp_f32_e32 v60, v57
	v_mul_f32_e32 v57, 0xbfb8aa3b, v53
	v_exp_f32_e32 v61, v57
	v_cvt_pk_bf16_f32 v57, v58, v59
	v_add_f32_e32 v58, 1.0, v60
	v_mul_f32_e32 v60, 0xbfb8aa3b, v54
	v_add_f32_e32 v59, 1.0, v61
	v_mul_f32_e32 v61, 0xbfb8aa3b, v55
	v_exp_f32_e32 v60, v60
	v_exp_f32_e32 v61, v61
	v_rcp_f32_e32 v58, v58
	v_rcp_f32_e32 v59, v59
	v_add_f32_e32 v60, 1.0, v60
	v_add_f32_e32 v61, 1.0, v61
; DI unsigned pk_bf16(float lo, float hi) { f32x2 v = {lo, hi}; return __builtin_bit_cast(unsigned, __builtin_convertvector(v, bf16v2)); }
; DI float fast_silu(float x) { return x * fast_sigmoid(x); }
; #define PG8_WAIT_V(n) asm volatile("s_waitcnt vmcnt(" #n ")" ::: "memory")
; #define PG8_BAR __builtin_amdgcn_s_barrier()
; #define PG8_WAIT_V(n) asm volatile("s_waitcnt vmcnt(" #n ")" ::: "memory")
; #define PG8_BAR __builtin_amdgcn_s_barrier()
; template <class Epi>
; DI void gemm_phase(LAS unsigned char* lds, const Gemm g, const StaticOrder S, const Epi E) {
;     ...
;         if (!has_next) break;
; #pragma unroll
;         for (int a = 0; a < 2; ++a)
; #pragma unroll
;             for (int b = 0; b < 2; ++b)
; #pragma unroll
;                 for (int m = 0; m < 4; ++m)
; #pragma unroll
;                     for (int n = 0; n < 2; ++n) acc[a][b][m][n] = (f32x4){0.f, 0.f, 0.f, 0.f};
;         cur = nxt; cA = nA; cB = nB; ++ui;
;     }
;     PG8_WAIT_V(0);
;     if (wr == 0) PG8_BAR;
;     PG8_BAR;
;     DI void operator()(AccRef acc, const Unit& u, int wr, int wc, int fr, int fq) const {
;         const int row0 = u.pm * 256 + wr * 64 + fr, col = u.pn * 128 + wc * 32 + 8 * fq;
;         RowScales rsc; if (RS) rsc = load_rowscales(ss, row0);
; #pragma unroll
;         for (int ai = 0; ai < 2; ++ai)
; #pragma unroll
;             for (int m = 0; m < 4; ++m) {
;                 const int row = row0 + ai * 128 + m * 16;
;                 const float r = RS ? rsc.r[ai][m] : 1.0f;
;                 const f32x4 a0 = acc[ai][0][m][0] * r, a1 = acc[ai][0][m][1] * r, b0 = acc[ai][1][m][0] * r, b1 = acc[ai][1][m][1] * r;
;                 u32x4 w;
;                 w.x = pk_bf16(fast_silu(a0[0]) * b0[0], fast_silu(a0[1]) * b0[1]); w.y = pk_bf16(fast_silu(a0[2]) * b0[2], fast_silu(a0[3]) * b0[3]);
;                 w.z = pk_bf16(fast_silu(a1[0]) * b1[0], fast_silu(a1[1]) * b1[1]); w.w = pk_bf16(fast_silu(a1[2]) * b1[2], fast_silu(a1[3]) * b1[3]);
;                 *(u32x4*)(G + (size_t)row * DFF + col) = w;
;             }
	v_rcp_f32_e32 v60, v60
	v_rcp_f32_e32 v61, v61
	v_pk_mul_f32 v[52:53], v[52:53], v[58:59]
	s_nop 0
	v_pk_mul_f32 v[48:49], v[52:53], v[48:49]
	v_add_u32_e32 v52, 0x90, v152
	v_cvt_pk_bf16_f32 v58, v48, v49
	v_pk_mul_f32 v[48:49], v[54:55], v[60:61]
	s_nop 0
	v_pk_mul_f32 v[48:49], v[48:49], v[50:51]
	v_mul_f32_e32 v50, 0xbfb8aa3b, v46
	v_cvt_pk_bf16_f32 v59, v48, v49
	v_mad_i64_i32 v[48:49], s[14:15], v68, s91, v[144:145]
	global_store_dwordx4 v[48:49], v[56:59], off
	v_mul_f32_e32 v48, 0xbfb8aa3b, v44
	v_mul_f32_e32 v49, 0xbfb8aa3b, v45
	v_exp_f32_e32 v48, v48
	v_exp_f32_e32 v49, v49
	v_mul_f32_e32 v51, 0xbfb8aa3b, v47
	v_exp_f32_e32 v50, v50
	v_exp_f32_e32 v51, v51
	v_add_f32_e32 v48, 1.0, v48
	v_add_f32_e32 v49, 1.0, v49
	v_rcp_f32_e32 v48, v48
	v_rcp_f32_e32 v49, v49
	v_add_f32_e32 v50, 1.0, v50
	v_add_f32_e32 v51, 1.0, v51
	v_rcp_f32_e32 v50, v50
	v_rcp_f32_e32 v51, v51
	v_pk_mul_f32 v[44:45], v[44:45], v[48:49]
	s_nop 0
	v_pk_mul_f32 v[40:41], v[44:45], v[40:41]
	v_pk_mul_f32 v[44:45], v[46:47], v[50:51]
	v_cvt_pk_bf16_f32 v40, v40, v41
	v_mul_f32_e32 v41, 0xbfb8aa3b, v36
	v_pk_mul_f32 v[42:43], v[44:45], v[42:43]
	v_exp_f32_e32 v44, v41
	v_mul_f32_e32 v41, 0xbfb8aa3b, v37
	v_exp_f32_e32 v45, v41
	v_cvt_pk_bf16_f32 v41, v42, v43
	v_add_f32_e32 v42, 1.0, v44
	v_mul_f32_e32 v44, 0xbfb8aa3b, v38
	v_add_f32_e32 v43, 1.0, v45
	v_mul_f32_e32 v45, 0xbfb8aa3b, v39
	v_exp_f32_e32 v44, v44
	v_exp_f32_e32 v45, v45
	v_rcp_f32_e32 v42, v42
	v_rcp_f32_e32 v43, v43
	v_add_f32_e32 v44, 1.0, v44
	v_add_f32_e32 v45, 1.0, v45
	v_rcp_f32_e32 v44, v44
	v_rcp_f32_e32 v45, v45
	v_pk_mul_f32 v[36:37], v[36:37], v[42:43]
	s_nop 0
	v_pk_mul_f32 v[32:33], v[36:37], v[32:33]
	v_add_u32_e32 v36, 0xa0, v152
	v_cvt_pk_bf16_f32 v42, v32, v33
	v_pk_mul_f32 v[32:33], v[38:39], v[44:45]
	s_nop 0
	v_pk_mul_f32 v[32:33], v[32:33], v[34:35]
	v_mul_f32_e32 v34, 0xbfb8aa3b, v30
	v_cvt_pk_bf16_f32 v43, v32, v33
	v_mad_i64_i32 v[32:33], s[14:15], v52, s91, v[144:145]
	global_store_dwordx4 v[32:33], v[40:43], off
	v_mul_f32_e32 v32, 0xbfb8aa3b, v28
	v_mul_f32_e32 v33, 0xbfb8aa3b, v29
	v_exp_f32_e32 v32, v32
	v_exp_f32_e32 v33, v33
	v_mul_f32_e32 v35, 0xbfb8aa3b, v31
	v_exp_f32_e32 v34, v34
	v_exp_f32_e32 v35, v35
	v_add_f32_e32 v32, 1.0, v32
	v_add_f32_e32 v33, 1.0, v33
	v_rcp_f32_e32 v32, v32
	v_rcp_f32_e32 v33, v33
	v_add_f32_e32 v34, 1.0, v34
	v_add_f32_e32 v35, 1.0, v35
	v_rcp_f32_e32 v34, v34
	v_rcp_f32_e32 v35, v35
	v_pk_mul_f32 v[28:29], v[28:29], v[32:33]
	s_nop 0
	v_pk_mul_f32 v[24:25], v[28:29], v[24:25]
	v_pk_mul_f32 v[28:29], v[30:31], v[34:35]
	v_cvt_pk_bf16_f32 v24, v24, v25
	v_mul_f32_e32 v25, 0xbfb8aa3b, v20
	v_pk_mul_f32 v[26:27], v[28:29], v[26:27]
	v_exp_f32_e32 v28, v25
	v_mul_f32_e32 v25, 0xbfb8aa3b, v21
	v_exp_f32_e32 v29, v25
	v_cvt_pk_bf16_f32 v25, v26, v27
	v_add_f32_e32 v26, 1.0, v28
	v_mul_f32_e32 v28, 0xbfb8aa3b, v22
	v_add_f32_e32 v27, 1.0, v29
	v_mul_f32_e32 v29, 0xbfb8aa3b, v23
	v_exp_f32_e32 v28, v28
	v_exp_f32_e32 v29, v29
	v_rcp_f32_e32 v26, v26
	v_rcp_f32_e32 v27, v27
	v_add_f32_e32 v28, 1.0, v28
	v_add_f32_e32 v29, 1.0, v29
	v_rcp_f32_e32 v28, v28
	v_rcp_f32_e32 v29, v29
	v_pk_mul_f32 v[20:21], v[20:21], v[26:27]
	s_nop 0
	v_pk_mul_f32 v[16:17], v[20:21], v[16:17]
	v_add_u32_e32 v20, 0xb0, v152
	v_cvt_pk_bf16_f32 v26, v16, v17
	v_pk_mul_f32 v[16:17], v[22:23], v[28:29]
	s_nop 0
	v_pk_mul_f32 v[16:17], v[16:17], v[18:19]
	v_mul_f32_e32 v18, 0xbfb8aa3b, v14
	v_cvt_pk_bf16_f32 v27, v16, v17
	v_mad_i64_i32 v[16:17], s[14:15], v36, s91, v[144:145]
	global_store_dwordx4 v[16:17], v[24:27], off
	v_mul_f32_e32 v16, 0xbfb8aa3b, v12
	v_mul_f32_e32 v17, 0xbfb8aa3b, v13
	v_exp_f32_e32 v16, v16
	v_exp_f32_e32 v17, v17
	v_mul_f32_e32 v19, 0xbfb8aa3b, v15
	v_exp_f32_e32 v18, v18
	v_exp_f32_e32 v19, v19
	v_add_f32_e32 v16, 1.0, v16
	v_add_f32_e32 v17, 1.0, v17
	v_rcp_f32_e32 v16, v16
	v_rcp_f32_e32 v17, v17
	v_add_f32_e32 v18, 1.0, v18
	v_add_f32_e32 v19, 1.0, v19
	v_rcp_f32_e32 v18, v18
	v_rcp_f32_e32 v19, v19
	v_pk_mul_f32 v[12:13], v[12:13], v[16:17]
	s_nop 0
	v_pk_mul_f32 v[8:9], v[12:13], v[8:9]
	v_pk_mul_f32 v[12:13], v[14:15], v[18:19]
	v_cvt_pk_bf16_f32 v8, v8, v9
	v_mul_f32_e32 v9, 0xbfb8aa3b, v4
	v_pk_mul_f32 v[10:11], v[12:13], v[10:11]
	v_exp_f32_e32 v12, v9
	v_mul_f32_e32 v9, 0xbfb8aa3b, v5
	v_exp_f32_e32 v13, v9
	v_cvt_pk_bf16_f32 v9, v10, v11
	v_add_f32_e32 v10, 1.0, v12
	v_mul_f32_e32 v12, 0xbfb8aa3b, v6
	v_add_f32_e32 v11, 1.0, v13
	v_mul_f32_e32 v13, 0xbfb8aa3b, v7
	v_exp_f32_e32 v12, v12
	v_exp_f32_e32 v13, v13
	v_rcp_f32_e32 v10, v10
	v_rcp_f32_e32 v11, v11
	v_add_f32_e32 v12, 1.0, v12
	v_add_f32_e32 v13, 1.0, v13
	v_rcp_f32_e32 v12, v12
	v_rcp_f32_e32 v13, v13
	v_pk_mul_f32 v[4:5], v[4:5], v[10:11]
	s_nop 0
	v_pk_mul_f32 v[0:1], v[4:5], v[0:1]
	s_nop 0
	v_cvt_pk_bf16_f32 v10, v0, v1
	v_pk_mul_f32 v[0:1], v[6:7], v[12:13]
	s_nop 0
	v_pk_mul_f32 v[0:1], v[0:1], v[2:3]
	s_nop 0
	v_cvt_pk_bf16_f32 v11, v0, v1
	v_mad_i64_i32 v[0:1], s[14:15], v20, s91, v[144:145]
	global_store_dwordx4 v[0:1], v[8:11], off
	s_cbranch_vccz .LBB0_104
	s_waitcnt vmcnt(0)
	v_readlane_b32 s92, v243, 8
	s_cmpk_gt_u32 s6, 0xff
	v_readlane_b32 s93, v243, 9
	s_cbranch_scc1 .LBB0_111
	s_barrier

; #define PG8_STAGE(bufoff, gbase, voff) do { _Pragma("unroll") for (int _i = 0; _i < 2; ++_i) \
;         __builtin_amdgcn_global_load_lds((const unsigned*)((const char*)(gbase) + (voff)[_i]), (LAS unsigned*)(lds + (bufoff) + ldsw + _i * 8192), 16, 0, 0); } while (0)
; #define PG8_LDA(dst, b, h) do { _Pragma("unroll") for (int m = 0; m < 4; ++m) _Pragma("unroll") for (int k = 0; k < 2; ++k) dst[m][k] = *(const LAS bf16x8*)(lds + PG8_SA(b, h) + aoff + m * 2048 + k * 1024); } while (0)
; #define PG8_LDB(dst, b, h) do { _Pragma("unroll") for (int n = 0; n < 2; ++n) _Pragma("unroll") for (int k = 0; k < 2; ++k) dst[n][k] = *(const LAS bf16x8*)(lds + PG8_SB(b, h) + boff + n * 2048 + k * 1024); } while (0)
; #define PG8_WAIT_V(n) asm volatile("s_waitcnt vmcnt(" #n ")" ::: "memory")
; #define PG8_WAIT_L(n) asm volatile("s_waitcnt lgkmcnt(" #n ")" ::: "memory")
; #define PG8_BAR __builtin_amdgcn_s_barrier()
; #define PG8_SCHED __builtin_amdgcn_sched_barrier(0)
; #define PG8_BAR __builtin_amdgcn_s_barrier()
; template <class Epi>
; DI void gemm_phase(LAS unsigned char* lds, const Gemm g, const StaticOrder S, const Epi E) {
;     ...
;             PG8_LDB(B0, 0, 0); PG8_SCHED; PG8_LDA(At, 0, 0); PG8_STAGE(PG8_SA(1, 1), a1 + hstep, voffA);
;             PG8_WAIT_L(8); PG8_BAR; PG8_WAIT_L(0); PG8_MMA(0, 0, At, B0); PG8_BAR; PG8_SCHED;
;             PG8_LDB(B1, 0, 1); PG8_STAGE(PG8_SB(0, 0), b2, voffB);
;             PG8_BAR; PG8_WAIT_L(0); PG8_MMA(0, 1, At, B1); PG8_BAR;
;             PG8_LDA(At, 0, 1); PG8_STAGE(PG8_SA(0, 0), a2, voffA);
;             PG8_BAR; PG8_WAIT_L(0); PG8_MMA(1, 0, At, B0); PG8_BAR; PG8_SCHED;
;             PG8_STAGE(PG8_SB(0, 1), b2 + hstep, voffB);
;             PG8_WAIT_V(6); PG8_BAR; PG8_MMA(1, 1, At, B1); PG8_BAR;
;             PG8_LDB(B0, 1, 0); PG8_SCHED; PG8_LDA(At, 1, 0); PG8_STAGE(PG8_SA(0, 1), a2 + hstep, voffA);
;             PG8_WAIT_L(8); PG8_BAR; PG8_WAIT_L(0); PG8_MMA(0, 0, At, B0); PG8_BAR; PG8_SCHED;
;             PG8_LDB(B1, 1, 1); PG8_STAGE(PG8_SB(1, 0), b3, voffB);
;             PG8_BAR; PG8_WAIT_L(0); PG8_MMA(0, 1, At, B1); PG8_BAR;
;             PG8_LDA(At, 1, 1); PG8_STAGE(PG8_SA(1, 0), a3, voffA);
;             PG8_BAR; PG8_WAIT_L(0); PG8_MMA(1, 0, At, B0); PG8_BAR; PG8_SCHED;
;             PG8_STAGE(PG8_SB(1, 1), b3 + hstep, voffB);
;             PG8_WAIT_V(6); PG8_BAR; PG8_MMA(1, 1, At, B1); PG8_BAR;
.LBB0_186:
	ds_read_b128 v[128:131], v207
	ds_read_b128 v[132:135], v207 offset:1024
	ds_read_b128 v[136:139], v207 offset:2048
	ds_read_b128 v[140:143], v207 offset:3072
	s_add_u32 s76, s28, 0x100
	s_addc_u32 s77, s29, 0
	s_cmp_eq_u32 s97, 40
	s_cselect_b32 s81, s9, s77
	s_cselect_b32 s80, s8, s76
	s_cselect_b32 s79, s11, s7
	s_cselect_b32 s78, s10, s6
	v_lshl_add_u64 v[192:193], s[28:29], 0, v[184:185]
	s_add_i32 m0, s82, 0xc000
	ds_read_b128 v[144:147], v208
	ds_read_b128 v[152:155], v208 offset:2048
	ds_read_b128 v[160:163], v208 offset:4096
	ds_read_b128 v[168:171], v208 offset:6144
	global_load_lds_dwordx4 v[192:193], off
	v_lshl_add_u64 v[192:193], s[28:29], 0, v[186:187]
	s_add_i32 m0, s82, 0xe000
	s_nop 0
	global_load_lds_dwordx4 v[192:193], off
	s_waitcnt lgkmcnt(4)
	s_setprio 1
	s_barrier
	ds_read_b128 v[148:151], v208 offset:1024
	ds_read_b128 v[156:159], v208 offset:3072
	ds_read_b128 v[164:167], v208 offset:5120
	ds_read_b128 v[172:175], v208 offset:7168
	s_waitcnt lgkmcnt(4)
	v_mfma_f32_16x16x32_bf16 v[124:127], v[128:131], v[144:147], v[124:127]
	v_mfma_f32_16x16x32_bf16 v[120:123], v[136:139], v[144:147], v[120:123]
	v_mfma_f32_16x16x32_bf16 v[108:111], v[128:131], v[152:155], v[108:111]
	v_mfma_f32_16x16x32_bf16 v[104:107], v[136:139], v[152:155], v[104:107]
	v_mfma_f32_16x16x32_bf16 v[92:95], v[128:131], v[160:163], v[92:95]
	v_mfma_f32_16x16x32_bf16 v[88:91], v[136:139], v[160:163], v[88:91]
	v_mfma_f32_16x16x32_bf16 v[76:79], v[128:131], v[168:171], v[76:79]
	v_mfma_f32_16x16x32_bf16 v[72:75], v[136:139], v[168:171], v[72:75]
	s_waitcnt lgkmcnt(3)
	v_mfma_f32_16x16x32_bf16 v[124:127], v[132:135], v[148:151], v[124:127]
	v_mfma_f32_16x16x32_bf16 v[120:123], v[140:143], v[148:151], v[120:123]
	s_waitcnt lgkmcnt(2)
	v_mfma_f32_16x16x32_bf16 v[108:111], v[132:135], v[156:159], v[108:111]
	v_mfma_f32_16x16x32_bf16 v[104:107], v[140:143], v[156:159], v[104:107]
	s_waitcnt lgkmcnt(1)
	v_mfma_f32_16x16x32_bf16 v[92:95], v[132:135], v[164:167], v[92:95]
	v_mfma_f32_16x16x32_bf16 v[88:91], v[140:143], v[164:167], v[88:91]
	s_waitcnt lgkmcnt(0)
	s_setprio 2
	s_barrier
	v_mfma_f32_16x16x32_bf16 v[76:79], v[132:135], v[172:175], v[76:79]
	v_mfma_f32_16x16x32_bf16 v[72:75], v[140:143], v[172:175], v[72:75]
	s_setprio 0
	s_add_i32 s14, s91, s59
	v_lshl_add_u64 v[216:217], s[78:79], 0, v[178:179]
	s_mov_b32 m0, s14
	ds_read_b128 v[192:195], v209
	ds_read_b128 v[196:199], v209 offset:1024
	ds_read_b128 v[200:203], v209 offset:2048
	ds_read_b128 v[212:215], v209 offset:3072
	global_load_lds_dwordx4 v[216:217], off
	v_lshl_add_u64 v[218:219], s[78:79], 0, v[182:183]
	s_add_i32 m0, s14, 0x2000
	s_nop 0
	global_load_lds_dwordx4 v[218:219], off
	s_setprio 1
	s_barrier
	s_waitcnt lgkmcnt(0)
	v_mfma_f32_16x16x32_bf16 v[116:119], v[192:195], v[144:147], v[116:119]
	v_mfma_f32_16x16x32_bf16 v[112:115], v[200:203], v[144:147], v[112:115]
	v_mfma_f32_16x16x32_bf16 v[100:103], v[192:195], v[152:155], v[100:103]
	v_mfma_f32_16x16x32_bf16 v[96:99], v[200:203], v[152:155], v[96:99]
	v_mfma_f32_16x16x32_bf16 v[84:87], v[192:195], v[160:163], v[84:87]
	v_mfma_f32_16x16x32_bf16 v[80:83], v[200:203], v[160:163], v[80:83]
	v_mfma_f32_16x16x32_bf16 v[68:71], v[192:195], v[168:171], v[68:71]
	v_mfma_f32_16x16x32_bf16 v[64:67], v[200:203], v[168:171], v[64:67]
	v_mfma_f32_16x16x32_bf16 v[116:119], v[196:199], v[148:151], v[116:119]
	v_mfma_f32_16x16x32_bf16 v[112:115], v[212:215], v[148:151], v[112:115]
	v_mfma_f32_16x16x32_bf16 v[100:103], v[196:199], v[156:159], v[100:103]
	v_mfma_f32_16x16x32_bf16 v[96:99], v[212:215], v[156:159], v[96:99]
	v_mfma_f32_16x16x32_bf16 v[84:87], v[196:199], v[164:167], v[84:87]
	s_setprio 2
	s_barrier
	v_mfma_f32_16x16x32_bf16 v[80:83], v[212:215], v[164:167], v[80:83]
	v_mfma_f32_16x16x32_bf16 v[68:71], v[196:199], v[172:175], v[68:71]
	v_mfma_f32_16x16x32_bf16 v[64:67], v[212:215], v[172:175], v[64:67]
	s_setprio 0
	s_mov_b32 m0, s82
	v_lshl_add_u64 v[220:221], s[80:81], 0, v[176:177]
	ds_read_b128 v[144:147], v208 offset:16384
	ds_read_b128 v[152:155], v208 offset:18432
	ds_read_b128 v[160:163], v208 offset:20480
	ds_read_b128 v[168:171], v208 offset:22528
	global_load_lds_dwordx4 v[220:221], off
	v_lshl_add_u64 v[224:225], s[80:81], 0, v[180:181]
	s_mov_b32 m0, s83
	s_nop 0
	global_load_lds_dwordx4 v[224:225], off
	s_setprio 1
	s_barrier
	ds_read_b128 v[148:151], v208 offset:17408
	ds_read_b128 v[156:159], v208 offset:19456
	ds_read_b128 v[164:167], v208 offset:21504
	ds_read_b128 v[172:175], v208 offset:23552
	s_waitcnt lgkmcnt(4)
	v_mfma_f32_16x16x32_bf16 v[60:63], v[128:131], v[144:147], v[60:63]
	v_mfma_f32_16x16x32_bf16 v[56:59], v[136:139], v[144:147], v[56:59]
	v_mfma_f32_16x16x32_bf16 v[44:47], v[128:131], v[152:155], v[44:47]
	v_mfma_f32_16x16x32_bf16 v[40:43], v[136:139], v[152:155], v[40:43]
	v_mfma_f32_16x16x32_bf16 v[28:31], v[128:131], v[160:163], v[28:31]
	v_mfma_f32_16x16x32_bf16 v[24:27], v[136:139], v[160:163], v[24:27]
	v_mfma_f32_16x16x32_bf16 v[12:15], v[128:131], v[168:171], v[12:15]
	v_mfma_f32_16x16x32_bf16 v[8:11], v[136:139], v[168:171], v[8:11]
	s_waitcnt lgkmcnt(3)
	v_mfma_f32_16x16x32_bf16 v[60:63], v[132:135], v[148:151], v[60:63]
	v_mfma_f32_16x16x32_bf16 v[56:59], v[140:143], v[148:151], v[56:59]
	s_waitcnt lgkmcnt(2)
	v_mfma_f32_16x16x32_bf16 v[44:47], v[132:135], v[156:159], v[44:47]
	v_mfma_f32_16x16x32_bf16 v[40:43], v[140:143], v[156:159], v[40:43]
	s_waitcnt lgkmcnt(1)
	v_mfma_f32_16x16x32_bf16 v[28:31], v[132:135], v[164:167], v[28:31]
	v_mfma_f32_16x16x32_bf16 v[24:27], v[140:143], v[164:167], v[24:27]
	s_waitcnt lgkmcnt(0)
	s_setprio 2
	s_barrier
; #define PG8_STAGE(bufoff, gbase, voff) do { _Pragma("unroll") for (int _i = 0; _i < 2; ++_i) \
;         __builtin_amdgcn_global_load_lds((const unsigned*)((const char*)(gbase) + (voff)[_i]), (LAS unsigned*)(lds + (bufoff) + ldsw + _i * 8192), 16, 0, 0); } while (0)
; #define PG8_LDA(dst, b, h) do { _Pragma("unroll") for (int m = 0; m < 4; ++m) _Pragma("unroll") for (int k = 0; k < 2; ++k) dst[m][k] = *(const LAS bf16x8*)(lds + PG8_SA(b, h) + aoff + m * 2048 + k * 1024); } while (0)
; #define PG8_LDB(dst, b, h) do { _Pragma("unroll") for (int n = 0; n < 2; ++n) _Pragma("unroll") for (int k = 0; k < 2; ++k) dst[n][k] = *(const LAS bf16x8*)(lds + PG8_SB(b, h) + boff + n * 2048 + k * 1024); } while (0)
; #define PG8_WAIT_V(n) asm volatile("s_waitcnt vmcnt(" #n ")" ::: "memory")
; #define PG8_WAIT_L(n) asm volatile("s_waitcnt lgkmcnt(" #n ")" ::: "memory")
; #define PG8_BAR __builtin_amdgcn_s_barrier()
; #define PG8_SCHED __builtin_amdgcn_sched_barrier(0)
; #define PG8_BAR __builtin_amdgcn_s_barrier()
; template <class Epi>
; DI void gemm_phase(LAS unsigned char* lds, const Gemm g, const StaticOrder S, const Epi E) {
;     ...
;             PG8_LDB(B0, 0, 0); PG8_SCHED; PG8_LDA(At, 0, 0); PG8_STAGE(PG8_SA(1, 1), a1 + hstep, voffA);
;             PG8_WAIT_L(8); PG8_BAR; PG8_WAIT_L(0); PG8_MMA(0, 0, At, B0); PG8_BAR; PG8_SCHED;
;             PG8_LDB(B1, 0, 1); PG8_STAGE(PG8_SB(0, 0), b2, voffB);
;             PG8_BAR; PG8_WAIT_L(0); PG8_MMA(0, 1, At, B1); PG8_BAR;
;             PG8_LDA(At, 0, 1); PG8_STAGE(PG8_SA(0, 0), a2, voffA);
;             PG8_BAR; PG8_WAIT_L(0); PG8_MMA(1, 0, At, B0); PG8_BAR; PG8_SCHED;
;             PG8_STAGE(PG8_SB(0, 1), b2 + hstep, voffB);
;             PG8_WAIT_V(6); PG8_BAR; PG8_MMA(1, 1, At, B1); PG8_BAR;
;             PG8_LDB(B0, 1, 0); PG8_SCHED; PG8_LDA(At, 1, 0); PG8_STAGE(PG8_SA(0, 1), a2 + hstep, voffA);
;             PG8_WAIT_L(8); PG8_BAR; PG8_WAIT_L(0); PG8_MMA(0, 0, At, B0); PG8_BAR; PG8_SCHED;
;             PG8_LDB(B1, 1, 1); PG8_STAGE(PG8_SB(1, 0), b3, voffB);
;             PG8_BAR; PG8_WAIT_L(0); PG8_MMA(0, 1, At, B1); PG8_BAR;
;             PG8_LDA(At, 1, 1); PG8_STAGE(PG8_SA(1, 0), a3, voffA);
;             PG8_BAR; PG8_WAIT_L(0); PG8_MMA(1, 0, At, B0); PG8_BAR; PG8_SCHED;
;             PG8_STAGE(PG8_SB(1, 1), b3 + hstep, voffB);
;             PG8_WAIT_V(6); PG8_BAR; PG8_MMA(1, 1, At, B1); PG8_BAR;
	v_mfma_f32_16x16x32_bf16 v[12:15], v[132:135], v[172:175], v[12:15]
	v_mfma_f32_16x16x32_bf16 v[8:11], v[140:143], v[172:175], v[8:11]
	s_setprio 0
	s_add_u32 s14, s78, 0xb0000
	s_addc_u32 s15, s79, 0
	s_add_i32 s28, s92, s59
	v_lshl_add_u64 v[128:129], s[14:15], 0, v[178:179]
	s_mov_b32 m0, s28
	s_nop 0
	global_load_lds_dwordx4 v[128:129], off
	v_lshl_add_u64 v[128:129], s[14:15], 0, v[182:183]
	s_add_i32 m0, s28, 0x2000
	s_nop 0
	global_load_lds_dwordx4 v[128:129], off
	s_waitcnt vmcnt(6)
	s_setprio 1
	s_barrier
	v_mfma_f32_16x16x32_bf16 v[52:55], v[192:195], v[144:147], v[52:55]
	v_mfma_f32_16x16x32_bf16 v[48:51], v[200:203], v[144:147], v[48:51]
	v_mfma_f32_16x16x32_bf16 v[36:39], v[192:195], v[152:155], v[36:39]
	v_mfma_f32_16x16x32_bf16 v[32:35], v[200:203], v[152:155], v[32:35]
	v_mfma_f32_16x16x32_bf16 v[20:23], v[192:195], v[160:163], v[20:23]
	v_mfma_f32_16x16x32_bf16 v[16:19], v[200:203], v[160:163], v[16:19]
	v_mfma_f32_16x16x32_bf16 v[4:7], v[192:195], v[168:171], v[4:7]
	v_mfma_f32_16x16x32_bf16 v[0:3], v[200:203], v[168:171], v[0:3]
	v_mfma_f32_16x16x32_bf16 v[52:55], v[196:199], v[148:151], v[52:55]
	v_mfma_f32_16x16x32_bf16 v[48:51], v[212:215], v[148:151], v[48:51]
	v_mfma_f32_16x16x32_bf16 v[36:39], v[196:199], v[156:159], v[36:39]
	v_mfma_f32_16x16x32_bf16 v[32:35], v[212:215], v[156:159], v[32:35]
	v_mfma_f32_16x16x32_bf16 v[20:23], v[196:199], v[164:167], v[20:23]
	s_setprio 2
	s_barrier
	v_mfma_f32_16x16x32_bf16 v[16:19], v[212:215], v[164:167], v[16:19]
	v_mfma_f32_16x16x32_bf16 v[4:7], v[196:199], v[172:175], v[4:7]
	v_mfma_f32_16x16x32_bf16 v[0:3], v[212:215], v[172:175], v[0:3]
	s_setprio 0
	s_add_i32 s28, 0, 0x18000
	v_add_u32_e32 v140, s28, v205
	ds_read_b128 v[128:131], v140
	ds_read_b128 v[132:135], v140 offset:1024
	ds_read_b128 v[136:139], v140 offset:2048
	ds_read_b128 v[140:143], v140 offset:3072
	s_add_u32 s14, s80, 0xb0000
	s_addc_u32 s15, s81, 0
	s_mov_b32 m0, s84
	v_lshl_add_u64 v[192:193], s[14:15], 0, v[176:177]
	ds_read_b128 v[144:147], v208 offset:32768
	ds_read_b128 v[152:155], v208 offset:34816
	ds_read_b128 v[160:163], v208 offset:36864
	ds_read_b128 v[168:171], v208 offset:38912
	global_load_lds_dwordx4 v[192:193], off
	v_lshl_add_u64 v[192:193], s[14:15], 0, v[180:181]
	s_mov_b32 m0, s85
	s_nop 0
	global_load_lds_dwordx4 v[192:193], off
	s_waitcnt lgkmcnt(4)
	s_setprio 1
	s_barrier
	ds_read_b128 v[148:151], v208 offset:33792
	ds_read_b128 v[156:159], v208 offset:35840
	ds_read_b128 v[164:167], v208 offset:37888
	ds_read_b128 v[172:175], v208 offset:39936
	s_waitcnt lgkmcnt(4)
	v_mfma_f32_16x16x32_bf16 v[124:127], v[128:131], v[144:147], v[124:127]
	v_mfma_f32_16x16x32_bf16 v[120:123], v[136:139], v[144:147], v[120:123]
	v_mfma_f32_16x16x32_bf16 v[108:111], v[128:131], v[152:155], v[108:111]
	v_mfma_f32_16x16x32_bf16 v[104:107], v[136:139], v[152:155], v[104:107]
	v_mfma_f32_16x16x32_bf16 v[92:95], v[128:131], v[160:163], v[92:95]
	v_mfma_f32_16x16x32_bf16 v[88:91], v[136:139], v[160:163], v[88:91]
	v_mfma_f32_16x16x32_bf16 v[76:79], v[128:131], v[168:171], v[76:79]
	v_mfma_f32_16x16x32_bf16 v[72:75], v[136:139], v[168:171], v[72:75]
	s_waitcnt lgkmcnt(3)
	v_mfma_f32_16x16x32_bf16 v[124:127], v[132:135], v[148:151], v[124:127]
	v_mfma_f32_16x16x32_bf16 v[120:123], v[140:143], v[148:151], v[120:123]
	s_waitcnt lgkmcnt(2)
	v_mfma_f32_16x16x32_bf16 v[108:111], v[132:135], v[156:159], v[108:111]
	v_mfma_f32_16x16x32_bf16 v[104:107], v[140:143], v[156:159], v[104:107]
	s_waitcnt lgkmcnt(1)
	v_mfma_f32_16x16x32_bf16 v[92:95], v[132:135], v[164:167], v[92:95]
	v_mfma_f32_16x16x32_bf16 v[88:91], v[140:143], v[164:167], v[88:91]
	s_waitcnt lgkmcnt(0)
	s_setprio 2
	s_barrier
	v_mfma_f32_16x16x32_bf16 v[76:79], v[132:135], v[172:175], v[76:79]
	v_mfma_f32_16x16x32_bf16 v[72:75], v[140:143], v[172:175], v[72:75]
	s_setprio 0
	s_add_i32 s29, 0, 0x1c000
	s_add_i32 s14, s28, s59
	v_add_u32_e32 v211, s29, v205
	v_lshl_add_u64 v[216:217], v[216:217], 0, s[24:25]
	s_mov_b32 m0, s14
	ds_read_b128 v[192:195], v211
	ds_read_b128 v[196:199], v211 offset:1024
	ds_read_b128 v[200:203], v211 offset:2048
	ds_read_b128 v[212:215], v211 offset:3072
	global_load_lds_dwordx4 v[216:217], off
	v_lshl_add_u64 v[216:217], v[218:219], 0, s[24:25]
	s_add_i32 m0, s14, 0x2000
	s_nop 0
	global_load_lds_dwordx4 v[216:217], off
	s_setprio 1
	s_barrier
	s_waitcnt lgkmcnt(0)
	v_mfma_f32_16x16x32_bf16 v[116:119], v[192:195], v[144:147], v[116:119]
	v_mfma_f32_16x16x32_bf16 v[112:115], v[200:203], v[144:147], v[112:115]
	v_mfma_f32_16x16x32_bf16 v[100:103], v[192:195], v[152:155], v[100:103]
	v_mfma_f32_16x16x32_bf16 v[96:99], v[200:203], v[152:155], v[96:99]
	v_mfma_f32_16x16x32_bf16 v[84:87], v[192:195], v[160:163], v[84:87]
	v_mfma_f32_16x16x32_bf16 v[80:83], v[200:203], v[160:163], v[80:83]
	v_mfma_f32_16x16x32_bf16 v[68:71], v[192:195], v[168:171], v[68:71]
	v_mfma_f32_16x16x32_bf16 v[64:67], v[200:203], v[168:171], v[64:67]
	v_mfma_f32_16x16x32_bf16 v[116:119], v[196:199], v[148:151], v[116:119]
	v_mfma_f32_16x16x32_bf16 v[112:115], v[212:215], v[148:151], v[112:115]
	v_mfma_f32_16x16x32_bf16 v[100:103], v[196:199], v[156:159], v[100:103]
	v_mfma_f32_16x16x32_bf16 v[96:99], v[212:215], v[156:159], v[96:99]
	v_mfma_f32_16x16x32_bf16 v[84:87], v[196:199], v[164:167], v[84:87]
	s_setprio 2
	s_barrier
	v_mfma_f32_16x16x32_bf16 v[80:83], v[212:215], v[164:167], v[80:83]
	v_mfma_f32_16x16x32_bf16 v[68:71], v[196:199], v[172:175], v[68:71]
	v_mfma_f32_16x16x32_bf16 v[64:67], v[212:215], v[172:175], v[64:67]
	s_setprio 0
	s_mov_b32 m0, s87
	v_lshl_add_u64 v[216:217], v[220:221], 0, s[24:25]
	ds_read_b128 v[144:147], v208 offset:49152
	ds_read_b128 v[152:155], v208 offset:51200
	ds_read_b128 v[160:163], v208 offset:53248
	ds_read_b128 v[168:171], v208 offset:55296
	global_load_lds_dwordx4 v[216:217], off
	v_lshl_add_u64 v[216:217], v[224:225], 0, s[24:25]
	s_mov_b32 m0, s88
	s_nop 0
	global_load_lds_dwordx4 v[216:217], off
	s_setprio 1
	s_barrier
; #define PG8_STAGE(bufoff, gbase, voff) do { _Pragma("unroll") for (int _i = 0; _i < 2; ++_i) \
;         __builtin_amdgcn_global_load_lds((const unsigned*)((const char*)(gbase) + (voff)[_i]), (LAS unsigned*)(lds + (bufoff) + ldsw + _i * 8192), 16, 0, 0); } while (0)
; #define PG8_LDA(dst, b, h) do { _Pragma("unroll") for (int m = 0; m < 4; ++m) _Pragma("unroll") for (int k = 0; k < 2; ++k) dst[m][k] = *(const LAS bf16x8*)(lds + PG8_SA(b, h) + aoff + m * 2048 + k * 1024); } while (0)
; #define PG8_LDB(dst, b, h) do { _Pragma("unroll") for (int n = 0; n < 2; ++n) _Pragma("unroll") for (int k = 0; k < 2; ++k) dst[n][k] = *(const LAS bf16x8*)(lds + PG8_SB(b, h) + boff + n * 2048 + k * 1024); } while (0)
; #define PG8_WAIT_V(n) asm volatile("s_waitcnt vmcnt(" #n ")" ::: "memory")
; #define PG8_WAIT_L(n) asm volatile("s_waitcnt lgkmcnt(" #n ")" ::: "memory")
; #define PG8_BAR __builtin_amdgcn_s_barrier()
; #define PG8_SCHED __builtin_amdgcn_sched_barrier(0)
; #define PG8_BAR __builtin_amdgcn_s_barrier()
; template <class Epi>
; DI void gemm_phase(LAS unsigned char* lds, const Gemm g, const StaticOrder S, const Epi E) {
;     ...
;             PG8_LDB(B0, 0, 0); PG8_SCHED; PG8_LDA(At, 0, 0); PG8_STAGE(PG8_SA(1, 1), a1 + hstep, voffA);
;             PG8_WAIT_L(8); PG8_BAR; PG8_WAIT_L(0); PG8_MMA(0, 0, At, B0); PG8_BAR; PG8_SCHED;
;             PG8_LDB(B1, 0, 1); PG8_STAGE(PG8_SB(0, 0), b2, voffB);
;             PG8_BAR; PG8_WAIT_L(0); PG8_MMA(0, 1, At, B1); PG8_BAR;
;             PG8_LDA(At, 0, 1); PG8_STAGE(PG8_SA(0, 0), a2, voffA);
;             PG8_BAR; PG8_WAIT_L(0); PG8_MMA(1, 0, At, B0); PG8_BAR; PG8_SCHED;
;             PG8_STAGE(PG8_SB(0, 1), b2 + hstep, voffB);
;             PG8_WAIT_V(6); PG8_BAR; PG8_MMA(1, 1, At, B1); PG8_BAR;
;             PG8_LDB(B0, 1, 0); PG8_SCHED; PG8_LDA(At, 1, 0); PG8_STAGE(PG8_SA(0, 1), a2 + hstep, voffA);
;             PG8_WAIT_L(8); PG8_BAR; PG8_WAIT_L(0); PG8_MMA(0, 0, At, B0); PG8_BAR; PG8_SCHED;
;             PG8_LDB(B1, 1, 1); PG8_STAGE(PG8_SB(1, 0), b3, voffB);
;             PG8_BAR; PG8_WAIT_L(0); PG8_MMA(0, 1, At, B1); PG8_BAR;
;             PG8_LDA(At, 1, 1); PG8_STAGE(PG8_SA(1, 0), a3, voffA);
;             PG8_BAR; PG8_WAIT_L(0); PG8_MMA(1, 0, At, B0); PG8_BAR; PG8_SCHED;
;             PG8_STAGE(PG8_SB(1, 1), b3 + hstep, voffB);
;             PG8_WAIT_V(6); PG8_BAR; PG8_MMA(1, 1, At, B1); PG8_BAR;
	ds_read_b128 v[148:151], v208 offset:50176
	ds_read_b128 v[156:159], v208 offset:52224
	ds_read_b128 v[164:167], v208 offset:54272
	ds_read_b128 v[172:175], v208 offset:56320
	s_waitcnt lgkmcnt(4)
	v_mfma_f32_16x16x32_bf16 v[60:63], v[128:131], v[144:147], v[60:63]
	v_mfma_f32_16x16x32_bf16 v[56:59], v[136:139], v[144:147], v[56:59]
	v_mfma_f32_16x16x32_bf16 v[44:47], v[128:131], v[152:155], v[44:47]
	v_mfma_f32_16x16x32_bf16 v[40:43], v[136:139], v[152:155], v[40:43]
	v_mfma_f32_16x16x32_bf16 v[28:31], v[128:131], v[160:163], v[28:31]
	v_mfma_f32_16x16x32_bf16 v[24:27], v[136:139], v[160:163], v[24:27]
	v_mfma_f32_16x16x32_bf16 v[12:15], v[128:131], v[168:171], v[12:15]
	v_mfma_f32_16x16x32_bf16 v[8:11], v[136:139], v[168:171], v[8:11]
	s_waitcnt lgkmcnt(3)
	v_mfma_f32_16x16x32_bf16 v[60:63], v[132:135], v[148:151], v[60:63]
	v_mfma_f32_16x16x32_bf16 v[56:59], v[140:143], v[148:151], v[56:59]
	s_waitcnt lgkmcnt(2)
	v_mfma_f32_16x16x32_bf16 v[44:47], v[132:135], v[156:159], v[44:47]
	v_mfma_f32_16x16x32_bf16 v[40:43], v[140:143], v[156:159], v[40:43]
	s_waitcnt lgkmcnt(1)
	v_mfma_f32_16x16x32_bf16 v[28:31], v[132:135], v[164:167], v[28:31]
	v_mfma_f32_16x16x32_bf16 v[24:27], v[140:143], v[164:167], v[24:27]
	s_waitcnt lgkmcnt(0)
	s_setprio 2
	s_barrier
	v_mfma_f32_16x16x32_bf16 v[12:15], v[132:135], v[172:175], v[12:15]
	v_mfma_f32_16x16x32_bf16 v[8:11], v[140:143], v[172:175], v[8:11]
	s_setprio 0
	s_add_u32 s14, s78, 0xb0080
	s_addc_u32 s15, s79, 0
	s_add_i32 s28, s29, s59
	v_lshl_add_u64 v[128:129], s[14:15], 0, v[178:179]
	s_mov_b32 m0, s28
	s_nop 0
	global_load_lds_dwordx4 v[128:129], off
	v_lshl_add_u64 v[128:129], s[14:15], 0, v[182:183]
	s_add_i32 m0, s28, 0x2000
	s_nop 0
	global_load_lds_dwordx4 v[128:129], off
	s_waitcnt vmcnt(6)
	s_setprio 1
	s_barrier
	v_mfma_f32_16x16x32_bf16 v[52:55], v[192:195], v[144:147], v[52:55]
	v_mfma_f32_16x16x32_bf16 v[48:51], v[200:203], v[144:147], v[48:51]
	v_mfma_f32_16x16x32_bf16 v[36:39], v[192:195], v[152:155], v[36:39]
	v_mfma_f32_16x16x32_bf16 v[32:35], v[200:203], v[152:155], v[32:35]
	v_mfma_f32_16x16x32_bf16 v[20:23], v[192:195], v[160:163], v[20:23]
	v_mfma_f32_16x16x32_bf16 v[16:19], v[200:203], v[160:163], v[16:19]
	v_mfma_f32_16x16x32_bf16 v[4:7], v[192:195], v[168:171], v[4:7]
	v_mfma_f32_16x16x32_bf16 v[0:3], v[200:203], v[168:171], v[0:3]
	v_mfma_f32_16x16x32_bf16 v[52:55], v[196:199], v[148:151], v[52:55]
	v_mfma_f32_16x16x32_bf16 v[48:51], v[212:215], v[148:151], v[48:51]
	v_mfma_f32_16x16x32_bf16 v[36:39], v[196:199], v[156:159], v[36:39]
	v_mfma_f32_16x16x32_bf16 v[32:35], v[212:215], v[156:159], v[32:35]
	v_mfma_f32_16x16x32_bf16 v[20:23], v[196:199], v[164:167], v[20:23]
	s_setprio 2
	s_barrier
	v_mfma_f32_16x16x32_bf16 v[16:19], v[212:215], v[164:167], v[16:19]
	v_mfma_f32_16x16x32_bf16 v[4:7], v[196:199], v[172:175], v[4:7]
	v_mfma_f32_16x16x32_bf16 v[0:3], v[212:215], v[172:175], v[0:3]
	s_setprio 0
	s_add_i32 s97, s97, 2
	s_add_u32 s6, s6, 0x100
	s_addc_u32 s7, s7, 0
	s_cmp_gt_u32 s97, 41
	s_mov_b64 s[28:29], s[76:77]
	s_cbranch_scc0 .LBB0_186
; DI unsigned pk_bf16(float lo, float hi) { f32x2 v = {lo, hi}; return __builtin_bit_cast(unsigned, __builtin_convertvector(v, bf16v2)); }
; DI f32x4 bf_lo4(u32x4 w) { f32x4 r; r[0] = bf_lo(w.x); r[1] = bf_hi(w.x); r[2] = bf_lo(w.y); r[3] = bf_hi(w.y); return r; }
; DI f32x4 bf_hi4(u32x4 w) { f32x4 r; r[0] = bf_lo(w.z); r[1] = bf_hi(w.z); r[2] = bf_lo(w.w); r[3] = bf_hi(w.w); return r; }
;     DI void operator()(AccRef acc, const Unit& u, int wr, int wc, int fr, int fq) const {
;         const float scale = HALFSTEP ? 0.5f : 1.0f;
;         const int row0 = u.pm * 256 + wr * 64 + fr, col0 = u.pn * 256 + wc * 32 + 8 * fq;
; #pragma unroll
;         for (int ai = 0; ai < 2; ++ai) {
;             f32x4 bv[4][2][2];
; #pragma unroll
;             for (int m = 0; m < 4; ++m)
; #pragma unroll
;                 for (int bj = 0; bj < 2; ++bj) {
;                     const size_t o = (size_t)(row0 + ai * 128 + m * 16) * DM + col0 + bj * 128;
;                     if (BASEF32) { bv[m][bj][0] = *(const f32x4*)(basef + o); bv[m][bj][1] = *(const f32x4*)(basef + o + 4); }
;                     else { const u32x4 h = *(const u32x4*)(xnb + o); bv[m][bj][0] = bf_lo4(h); bv[m][bj][1] = bf_hi4(h); }
;                 }
; #pragma unroll
;             for (int m = 0; m < 4; ++m) {
;                 const int row = row0 + ai * 128 + m * 16;
;                 float q = 0.f;
; #pragma unroll
;                 for (int bj = 0; bj < 2; ++bj) {
;                     const size_t o = (size_t)row * DM + col0 + bj * 128;
;                     const f32x4 r0 = bv[m][bj][0] + scale * acc[ai][bj][m][0], r1 = bv[m][bj][1] + scale * acc[ai][bj][m][1];
;                     u32x4 w; w.x = pk_bf16(r0[0], r0[1]); w.y = pk_bf16(r0[2], r0[3]); w.z = pk_bf16(r1[0], r1[1]); w.w = pk_bf16(r1[2], r1[3]);
;                     *(u32x4*)(xnb + o) = w;
;                     if (STATS) q += r0[0] * r0[0] + r0[1] * r0[1] + r0[2] * r0[2] + r0[3] * r0[3] + r1[0] * r1[0] + r1[1] * r1[1] + r1[2] * r1[2] + r1[3] * r1[3];
;                 }
;                 if (STATS) { q += __shfl_xor(q, 16); q += __shfl_xor(q, 32); if (fq == 0) atomicAdd(ss + row, q); }
;             }
;         }
	v_lshl_add_u32 v194, s96, 8, v204
	v_lshl_or_b32 v192, s95, 8, v206
	v_ashrrev_i32_e32 v193, 31, v192
	v_ashrrev_i32_e32 v195, 31, v194
	v_lshl_add_u64 v[196:197], v[192:193], 2, s[52:53]
	v_lshlrev_b64 v[128:129], 12, v[194:195]
	v_lshl_add_u64 v[128:129], v[196:197], 0, v[128:129]
	global_load_dwordx4 v[214:217], v[128:129], off
	global_load_dwordx4 v[218:221], v[128:129], off offset:16
	global_load_dwordx4 v[224:227], v[128:129], off offset:512
	global_load_dwordx4 v[228:231], v[128:129], off offset:528
	v_or_b32_e32 v202, 16, v194
	v_or_b32_e32 v200, 32, v194
	v_or_b32_e32 v198, 48, v194
	v_ashrrev_i32_e32 v203, 31, v202
	v_ashrrev_i32_e32 v201, 31, v200
	v_ashrrev_i32_e32 v199, 31, v198
	v_lshlrev_b64 v[128:129], 12, v[202:203]
	v_lshlrev_b64 v[130:131], 12, v[200:201]
	v_lshlrev_b64 v[132:133], 12, v[198:199]
	v_lshl_add_u64 v[128:129], v[196:197], 0, v[128:129]
	v_lshl_add_u64 v[130:131], v[196:197], 0, v[130:131]
	v_lshl_add_u64 v[132:133], v[196:197], 0, v[132:133]
	global_load_dwordx4 v[168:171], v[128:129], off offset:16
	global_load_dwordx4 v[172:175], v[128:129], off
	global_load_dwordx4 v[160:163], v[128:129], off offset:528
	global_load_dwordx4 v[164:167], v[128:129], off offset:512
	global_load_dwordx4 v[152:155], v[130:131], off offset:16
	global_load_dwordx4 v[156:159], v[130:131], off
	global_load_dwordx4 v[144:147], v[130:131], off offset:528
	global_load_dwordx4 v[148:151], v[130:131], off offset:512
	global_load_dwordx4 v[136:139], v[132:133], off offset:16
	global_load_dwordx4 v[140:143], v[132:133], off
	s_nop 0
	global_load_dwordx4 v[128:131], v[132:133], off offset:528
	s_nop 0
	global_load_dwordx4 v[132:135], v[132:133], off offset:512
	v_and_b32_e32 v212, 64, v210
	v_xor_b32_e32 v211, 16, v210
	v_add_u32_e32 v212, 64, v212
	v_xor_b32_e32 v213, 32, v210
	v_cmp_lt_i32_e32 vcc, v211, v212
	v_lshlrev_b64 v[232:233], 11, v[194:195]
	s_waitcnt vmcnt(0)
	v_pk_fma_f32 v[124:125], v[124:125], 0.5, v[214:215] op_sel_hi:[1,0,1]
	v_cndmask_b32_e32 v211, v210, v211, vcc
	v_cmp_lt_i32_e32 vcc, v213, v212
	v_pk_fma_f32 v[116:117], v[116:117], 0.5, v[224:225] op_sel_hi:[1,0,1]
	v_lshlrev_b32_e32 v212, 2, v211
	v_cndmask_b32_e32 v213, v210, v213, vcc
	v_lshlrev_b32_e32 v211, 2, v213
	v_pk_fma_f32 v[126:127], v[126:127], 0.5, v[216:217] op_sel_hi:[1,0,1]
	v_pk_fma_f32 v[216:217], v[112:113], 0.5, v[228:229] op_sel_hi:[1,0,1]
	v_cvt_pk_bf16_f32 v112, v124, v125
	v_mul_f32_e32 v125, v125, v125
	v_mul_f32_e32 v213, v117, v117
	v_pk_fma_f32 v[118:119], v[118:119], 0.5, v[226:227] op_sel_hi:[1,0,1]
	v_fmac_f32_e32 v125, v124, v124
	v_fmac_f32_e32 v213, v116, v116
	v_fmac_f32_e32 v125, v126, v126
	v_fmac_f32_e32 v213, v118, v118
	v_pk_fma_f32 v[120:121], v[120:121], 0.5, v[218:219] op_sel_hi:[1,0,1]
	v_fmac_f32_e32 v125, v127, v127
	v_fmac_f32_e32 v213, v119, v119
	v_fmac_f32_e32 v125, v120, v120
	v_fmac_f32_e32 v213, v216, v216
	v_pk_fma_f32 v[122:123], v[122:123], 0.5, v[220:221] op_sel_hi:[1,0,1]
	v_pk_fma_f32 v[214:215], v[114:115], 0.5, v[230:231] op_sel_hi:[1,0,1]
	v_fmac_f32_e32 v125, v121, v121
	v_fmac_f32_e32 v213, v217, v217
	v_fmac_f32_e32 v125, v122, v122
	v_fmac_f32_e32 v213, v214, v214
	v_fmac_f32_e32 v125, v123, v123
	v_fmac_f32_e32 v213, v215, v215
	v_cvt_pk_bf16_f32 v115, v122, v123
	v_add_f32_e32 v122, v125, v213
	ds_bpermute_b32 v123, v212, v122
	v_cvt_pk_bf16_f32 v114, v120, v121
	v_lshl_add_u64 v[120:121], s[56:57], 0, v[232:233]
	v_cvt_pk_bf16_f32 v113, v126, v127
	v_lshl_add_u64 v[120:121], v[192:193], 1, v[120:121]
	global_store_dwordx4 v[120:121], v[112:115], off
	s_waitcnt lgkmcnt(0)
	s_nop 0
	v_add_f32_e32 v112, v122, v123
	ds_bpermute_b32 v113, v211, v112
	v_cvt_pk_bf16_f32 v114, v116, v117
	v_cvt_pk_bf16_f32 v115, v118, v119
	v_cvt_pk_bf16_f32 v116, v216, v217
	v_cvt_pk_bf16_f32 v117, v214, v215
	global_store_dwordx4 v[120:121], v[114:117], off offset:256
	s_and_saveexec_b64 s[6:7], s[0:1]
	s_cbranch_execz .LBB0_189
	v_lshl_add_u64 v[114:115], v[194:195], 2, s[60:61]
	s_waitcnt lgkmcnt(0)
	v_add_f32_e32 v112, v112, v113
	global_atomic_add_f32 v[114:115], v112, off

; #define PG8_STAGE(bufoff, gbase, voff) do { _Pragma("unroll") for (int _i = 0; _i < 2; ++_i) \
;         __builtin_amdgcn_global_load_lds((const unsigned*)((const char*)(gbase) + (voff)[_i]), (LAS unsigned*)(lds + (bufoff) + ldsw + _i * 8192), 16, 0, 0); } while (0)
; #define PG8_LDA(dst, b, h) do { _Pragma("unroll") for (int m = 0; m < 4; ++m) _Pragma("unroll") for (int k = 0; k < 2; ++k) dst[m][k] = *(const LAS bf16x8*)(lds + PG8_SA(b, h) + aoff + m * 2048 + k * 1024); } while (0)
; #define PG8_LDB(dst, b, h) do { _Pragma("unroll") for (int n = 0; n < 2; ++n) _Pragma("unroll") for (int k = 0; k < 2; ++k) dst[n][k] = *(const LAS bf16x8*)(lds + PG8_SB(b, h) + boff + n * 2048 + k * 1024); } while (0)
; #define PG8_MMA(ai, bj, At, Bt) do { __builtin_amdgcn_s_setprio(1); _Pragma("unroll") for (int m = 0; m < 4; ++m) _Pragma("unroll") for (int n = 0; n < 2; ++n) _Pragma("unroll") for (int k = 0; k < 2; ++k) \
;         acc[ai][bj][m][n] = __builtin_amdgcn_mfma_f32_16x16x32_bf16(Bt[n][k], At[m][k], acc[ai][bj][m][n], 0, 0, 0); __builtin_amdgcn_s_setprio(0); } while (0)
; #define PG8_WAIT_V(n) asm volatile("s_waitcnt vmcnt(" #n ")" ::: "memory")
; #define PG8_WAIT_L(n) asm volatile("s_waitcnt lgkmcnt(" #n ")" ::: "memory")
; #define PG8_BAR __builtin_amdgcn_s_barrier()
; template <class Epi>
; DI void gemm_phase(LAS unsigned char* lds, const Gemm g, const StaticOrder S, const Epi E) {
;     ...
;         for (int t = 0; t < nt; t += 2) {
;             const bool last = (t == nt - 2);
;             const char* a1 = cA + (size_t)(t + 1) * kstep;
;             const char* a2 = last ? nA : cA + (size_t)(t + 2) * kstep; const char* b2 = last ? nB : cB + (size_t)(t + 2) * kstep;
;             const char* a3 = a2 + kstep; const char* b3 = b2 + kstep;
;             PG8_LDB(B0, 0, 0); PG8_SCHED; PG8_LDA(At, 0, 0); PG8_STAGE(PG8_SA(1, 1), a1 + hstep, voffA);
;             PG8_WAIT_L(8); PG8_BAR; PG8_WAIT_L(0); PG8_MMA(0, 0, At, B0); PG8_BAR; PG8_SCHED;
;             PG8_LDB(B1, 0, 1); PG8_STAGE(PG8_SB(0, 0), b2, voffB);
;             PG8_BAR; PG8_WAIT_L(0); PG8_MMA(0, 1, At, B1); PG8_BAR;
;             PG8_LDA(At, 0, 1); PG8_STAGE(PG8_SA(0, 0), a2, voffA);
;             PG8_BAR; PG8_WAIT_L(0); PG8_MMA(1, 0, At, B0); PG8_BAR; PG8_SCHED;
;             PG8_STAGE(PG8_SB(0, 1), b2 + hstep, voffB);
;             PG8_WAIT_V(6); PG8_BAR; PG8_MMA(1, 1, At, B1); PG8_BAR;
.LBB0_274:
	ds_read_b128 v[100:103], v227
	ds_read_b128 v[134:137], v227 offset:1024
	ds_read_b128 v[138:141], v227 offset:2048
	ds_read_b128 v[142:145], v227 offset:3072
	s_add_u32 s14, s8, 0xfffc0080
	s_addc_u32 s15, s9, -1
	s_cmp_eq_u32 s95, 12
	s_cselect_b32 s77, s1, s15
	s_cselect_b32 s76, s6, s14
	s_cselect_b32 s53, s7, s94
	s_cselect_b32 s52, s21, s23
	v_lshl_add_u64 v[104:105], s[8:9], 0, v[212:213]
	s_add_i32 m0, s78, 0xc000
	ds_read_b128 v[146:149], v228
	ds_read_b128 v[154:157], v228 offset:2048
	ds_read_b128 v[162:165], v228 offset:4096
	ds_read_b128 v[170:173], v228 offset:6144
	global_load_lds_dwordx4 v[104:105], off
	v_lshl_add_u64 v[104:105], s[8:9], 0, v[214:215]
	s_add_i32 m0, s78, 0xe000
	s_nop 0
	global_load_lds_dwordx4 v[104:105], off
	s_waitcnt lgkmcnt(4)
	s_setprio 1
	s_barrier
	ds_read_b128 v[150:153], v228 offset:1024
	ds_read_b128 v[158:161], v228 offset:3072
	ds_read_b128 v[166:169], v228 offset:5120
	ds_read_b128 v[174:177], v228 offset:7168
	s_waitcnt lgkmcnt(4)
	v_mfma_f32_16x16x32_bf16 v[130:133], v[100:103], v[146:149], v[130:133]
	v_mfma_f32_16x16x32_bf16 v[126:129], v[138:141], v[146:149], v[126:129]
	v_mfma_f32_16x16x32_bf16 v[114:117], v[100:103], v[154:157], v[114:117]
	v_mfma_f32_16x16x32_bf16 v[110:113], v[138:141], v[154:157], v[110:113]
	v_mfma_f32_16x16x32_bf16 v[92:95], v[100:103], v[162:165], v[92:95]
	v_mfma_f32_16x16x32_bf16 v[88:91], v[138:141], v[162:165], v[88:91]
	v_mfma_f32_16x16x32_bf16 v[76:79], v[100:103], v[170:173], v[76:79]
	v_mfma_f32_16x16x32_bf16 v[72:75], v[138:141], v[170:173], v[72:75]
	s_waitcnt lgkmcnt(3)
	v_mfma_f32_16x16x32_bf16 v[130:133], v[134:137], v[150:153], v[130:133]
	v_mfma_f32_16x16x32_bf16 v[126:129], v[142:145], v[150:153], v[126:129]
	s_waitcnt lgkmcnt(2)
	v_mfma_f32_16x16x32_bf16 v[114:117], v[134:137], v[158:161], v[114:117]
	v_mfma_f32_16x16x32_bf16 v[110:113], v[142:145], v[158:161], v[110:113]
	s_waitcnt lgkmcnt(1)
	v_mfma_f32_16x16x32_bf16 v[92:95], v[134:137], v[166:169], v[92:95]
	v_mfma_f32_16x16x32_bf16 v[88:91], v[142:145], v[166:169], v[88:91]
	s_waitcnt lgkmcnt(0)
	s_setprio 2
	s_barrier
	v_mfma_f32_16x16x32_bf16 v[76:79], v[134:137], v[174:177], v[76:79]
	v_mfma_f32_16x16x32_bf16 v[72:75], v[142:145], v[174:177], v[72:75]
	s_setprio 0
	s_add_i32 s14, s87, s59
	v_lshl_add_u64 v[194:195], s[52:53], 0, v[200:201]
	s_mov_b32 m0, s14
	ds_read_b128 v[178:181], v229
	ds_read_b128 v[182:185], v229 offset:1024
	ds_read_b128 v[186:189], v229 offset:2048
	ds_read_b128 v[190:193], v229 offset:3072
	global_load_lds_dwordx4 v[194:195], off
	v_lshl_add_u64 v[196:197], s[52:53], 0, v[204:205]
	s_add_i32 m0, s14, 0x2000
	s_nop 0
	global_load_lds_dwordx4 v[196:197], off
	s_setprio 1
	s_barrier
	s_waitcnt lgkmcnt(0)
	v_mfma_f32_16x16x32_bf16 v[122:125], v[178:181], v[146:149], v[122:125]
	v_mfma_f32_16x16x32_bf16 v[118:121], v[186:189], v[146:149], v[118:121]
	v_mfma_f32_16x16x32_bf16 v[104:107], v[178:181], v[154:157], v[106:109]
	v_mfma_f32_16x16x32_bf16 v[96:99], v[186:189], v[154:157], v[96:99]
	v_mfma_f32_16x16x32_bf16 v[84:87], v[178:181], v[162:165], v[84:87]
	v_mfma_f32_16x16x32_bf16 v[80:83], v[186:189], v[162:165], v[80:83]
	v_mfma_f32_16x16x32_bf16 v[68:71], v[178:181], v[170:173], v[68:71]
	v_mfma_f32_16x16x32_bf16 v[64:67], v[186:189], v[170:173], v[64:67]
	v_mfma_f32_16x16x32_bf16 v[122:125], v[182:185], v[150:153], v[122:125]
	v_mfma_f32_16x16x32_bf16 v[118:121], v[190:193], v[150:153], v[118:121]
	v_mfma_f32_16x16x32_bf16 v[104:107], v[182:185], v[158:161], v[104:107]
	v_mfma_f32_16x16x32_bf16 v[96:99], v[190:193], v[158:161], v[96:99]
	v_mfma_f32_16x16x32_bf16 v[84:87], v[182:185], v[166:169], v[84:87]
	s_setprio 2
	s_barrier
	v_mfma_f32_16x16x32_bf16 v[80:83], v[190:193], v[166:169], v[80:83]
	v_mfma_f32_16x16x32_bf16 v[68:71], v[182:185], v[174:177], v[68:71]
	v_mfma_f32_16x16x32_bf16 v[64:67], v[190:193], v[174:177], v[64:67]
	s_setprio 0
	s_mov_b32 m0, s78
	v_lshl_add_u64 v[220:221], s[76:77], 0, v[198:199]
	ds_read_b128 v[146:149], v228 offset:16384
	ds_read_b128 v[154:157], v228 offset:18432
	ds_read_b128 v[162:165], v228 offset:20480
	ds_read_b128 v[170:173], v228 offset:22528
	global_load_lds_dwordx4 v[220:221], off
	v_lshl_add_u64 v[232:233], s[76:77], 0, v[202:203]
	s_mov_b32 m0, s79
	s_nop 0
	global_load_lds_dwordx4 v[232:233], off
	s_setprio 1
	s_barrier
	ds_read_b128 v[150:153], v228 offset:17408
	ds_read_b128 v[158:161], v228 offset:19456
	ds_read_b128 v[166:169], v228 offset:21504
	ds_read_b128 v[174:177], v228 offset:23552
	s_waitcnt lgkmcnt(4)
	v_mfma_f32_16x16x32_bf16 v[60:63], v[100:103], v[146:149], v[60:63]
	v_mfma_f32_16x16x32_bf16 v[56:59], v[138:141], v[146:149], v[56:59]
	v_mfma_f32_16x16x32_bf16 v[44:47], v[100:103], v[154:157], v[44:47]
	v_mfma_f32_16x16x32_bf16 v[40:43], v[138:141], v[154:157], v[40:43]
	v_mfma_f32_16x16x32_bf16 v[28:31], v[100:103], v[162:165], v[28:31]
	v_mfma_f32_16x16x32_bf16 v[24:27], v[138:141], v[162:165], v[24:27]
	v_mfma_f32_16x16x32_bf16 v[12:15], v[100:103], v[170:173], v[12:15]
	v_mfma_f32_16x16x32_bf16 v[8:11], v[138:141], v[170:173], v[8:11]
	s_waitcnt lgkmcnt(3)
	v_mfma_f32_16x16x32_bf16 v[60:63], v[134:137], v[150:153], v[60:63]
	v_mfma_f32_16x16x32_bf16 v[56:59], v[142:145], v[150:153], v[56:59]
	s_waitcnt lgkmcnt(2)
	v_mfma_f32_16x16x32_bf16 v[44:47], v[134:137], v[158:161], v[44:47]
	v_mfma_f32_16x16x32_bf16 v[40:43], v[142:145], v[158:161], v[40:43]
	s_waitcnt lgkmcnt(1)
	v_mfma_f32_16x16x32_bf16 v[28:31], v[134:137], v[166:169], v[28:31]
	v_mfma_f32_16x16x32_bf16 v[24:27], v[142:145], v[166:169], v[24:27]
	s_waitcnt lgkmcnt(0)
	s_setprio 2
	s_barrier
; #define PG8_STAGE(bufoff, gbase, voff) do { _Pragma("unroll") for (int _i = 0; _i < 2; ++_i) \
;         __builtin_amdgcn_global_load_lds((const unsigned*)((const char*)(gbase) + (voff)[_i]), (LAS unsigned*)(lds + (bufoff) + ldsw + _i * 8192), 16, 0, 0); } while (0)
; #define PG8_LDA(dst, b, h) do { _Pragma("unroll") for (int m = 0; m < 4; ++m) _Pragma("unroll") for (int k = 0; k < 2; ++k) dst[m][k] = *(const LAS bf16x8*)(lds + PG8_SA(b, h) + aoff + m * 2048 + k * 1024); } while (0)
; #define PG8_LDB(dst, b, h) do { _Pragma("unroll") for (int n = 0; n < 2; ++n) _Pragma("unroll") for (int k = 0; k < 2; ++k) dst[n][k] = *(const LAS bf16x8*)(lds + PG8_SB(b, h) + boff + n * 2048 + k * 1024); } while (0)
; #define PG8_MMA(ai, bj, At, Bt) do { __builtin_amdgcn_s_setprio(1); _Pragma("unroll") for (int m = 0; m < 4; ++m) _Pragma("unroll") for (int n = 0; n < 2; ++n) _Pragma("unroll") for (int k = 0; k < 2; ++k) \
;         acc[ai][bj][m][n] = __builtin_amdgcn_mfma_f32_16x16x32_bf16(Bt[n][k], At[m][k], acc[ai][bj][m][n], 0, 0, 0); __builtin_amdgcn_s_setprio(0); } while (0)
; #define PG8_WAIT_V(n) asm volatile("s_waitcnt vmcnt(" #n ")" ::: "memory")
; #define PG8_WAIT_L(n) asm volatile("s_waitcnt lgkmcnt(" #n ")" ::: "memory")
; #define PG8_BAR __builtin_amdgcn_s_barrier()
; #define PG8_SCHED __builtin_amdgcn_sched_barrier(0)
; #define PG8_LDA(dst, b, h) do { _Pragma("unroll") for (int m = 0; m < 4; ++m) _Pragma("unroll") for (int k = 0; k < 2; ++k) dst[m][k] = *(const LAS bf16x8*)(lds + PG8_SA(b, h) + aoff + m * 2048 + k * 1024); } while (0)
; template <class Epi>
; DI void gemm_phase(LAS unsigned char* lds, const Gemm g, const StaticOrder S, const Epi E) {
;     ...
;             PG8_WAIT_V(6); PG8_BAR; PG8_MMA(1, 1, At, B1); PG8_BAR;
;             PG8_LDB(B0, 1, 0); PG8_SCHED; PG8_LDA(At, 1, 0); PG8_STAGE(PG8_SA(0, 1), a2 + hstep, voffA);
;             PG8_WAIT_L(8); PG8_BAR; PG8_WAIT_L(0); PG8_MMA(0, 0, At, B0); PG8_BAR; PG8_SCHED;
;             PG8_LDB(B1, 1, 1); PG8_STAGE(PG8_SB(1, 0), b3, voffB);
;             PG8_BAR; PG8_WAIT_L(0); PG8_MMA(0, 1, At, B1); PG8_BAR;
;             PG8_LDA(At, 1, 1); PG8_STAGE(PG8_SA(1, 0), a3, voffA);
;             PG8_BAR; PG8_WAIT_L(0); PG8_MMA(1, 0, At, B0); PG8_BAR; PG8_SCHED;
;             PG8_STAGE(PG8_SB(1, 1), b3 + hstep, voffB);
;             PG8_WAIT_V(6); PG8_BAR; PG8_MMA(1, 1, At, B1); PG8_BAR;
	v_mfma_f32_16x16x32_bf16 v[12:15], v[134:137], v[174:177], v[12:15]
	v_mfma_f32_16x16x32_bf16 v[8:11], v[142:145], v[174:177], v[8:11]
	s_setprio 0
	s_add_u32 s14, s52, 0x40000
	s_addc_u32 s15, s53, 0
	s_add_i32 s35, s90, s59
	v_lshl_add_u64 v[100:101], s[14:15], 0, v[200:201]
	s_mov_b32 m0, s35
	s_nop 0
	global_load_lds_dwordx4 v[100:101], off
	v_lshl_add_u64 v[100:101], s[14:15], 0, v[204:205]
	s_add_i32 m0, s35, 0x2000
	s_nop 0
	global_load_lds_dwordx4 v[100:101], off
	s_waitcnt vmcnt(6)
	s_setprio 1
	s_barrier
	v_mfma_f32_16x16x32_bf16 v[52:55], v[178:181], v[146:149], v[52:55]
	v_mfma_f32_16x16x32_bf16 v[48:51], v[186:189], v[146:149], v[48:51]
	v_mfma_f32_16x16x32_bf16 v[36:39], v[178:181], v[154:157], v[36:39]
	v_mfma_f32_16x16x32_bf16 v[32:35], v[186:189], v[154:157], v[32:35]
	v_mfma_f32_16x16x32_bf16 v[20:23], v[178:181], v[162:165], v[20:23]
	v_mfma_f32_16x16x32_bf16 v[16:19], v[186:189], v[162:165], v[16:19]
	v_mfma_f32_16x16x32_bf16 v[4:7], v[178:181], v[170:173], v[4:7]
	v_mfma_f32_16x16x32_bf16 v[0:3], v[186:189], v[170:173], v[0:3]
	v_mfma_f32_16x16x32_bf16 v[52:55], v[182:185], v[150:153], v[52:55]
	v_mfma_f32_16x16x32_bf16 v[48:51], v[190:193], v[150:153], v[48:51]
	v_mfma_f32_16x16x32_bf16 v[36:39], v[182:185], v[158:161], v[36:39]
	v_mfma_f32_16x16x32_bf16 v[32:35], v[190:193], v[158:161], v[32:35]
	v_mfma_f32_16x16x32_bf16 v[20:23], v[182:185], v[166:169], v[20:23]
	s_setprio 2
	s_barrier
	v_mfma_f32_16x16x32_bf16 v[16:19], v[190:193], v[166:169], v[16:19]
	v_mfma_f32_16x16x32_bf16 v[4:7], v[182:185], v[174:177], v[4:7]
	v_mfma_f32_16x16x32_bf16 v[0:3], v[190:193], v[174:177], v[0:3]
	s_setprio 0
	s_add_i32 s35, 0, 0x18000
	v_add_u32_e32 v108, s35, v225
	ds_read_b128 v[100:103], v108
	ds_read_b128 v[134:137], v108 offset:1024
	ds_read_b128 v[138:141], v108 offset:2048
	ds_read_b128 v[142:145], v108 offset:3072
	s_add_u32 s14, s76, 0x40000
	s_addc_u32 s15, s77, 0
	s_mov_b32 m0, s80
	v_lshl_add_u64 v[108:109], s[14:15], 0, v[198:199]
	ds_read_b128 v[146:149], v228 offset:32768
	ds_read_b128 v[154:157], v228 offset:34816
	ds_read_b128 v[162:165], v228 offset:36864
	ds_read_b128 v[170:173], v228 offset:38912
	global_load_lds_dwordx4 v[108:109], off
	v_lshl_add_u64 v[108:109], s[14:15], 0, v[202:203]
	s_mov_b32 m0, s81
	s_nop 0
	global_load_lds_dwordx4 v[108:109], off
	s_waitcnt lgkmcnt(4)
	s_setprio 1
	s_barrier
	ds_read_b128 v[150:153], v228 offset:33792
	ds_read_b128 v[158:161], v228 offset:35840
	ds_read_b128 v[166:169], v228 offset:37888
	ds_read_b128 v[174:177], v228 offset:39936
	s_waitcnt lgkmcnt(4)
	v_mfma_f32_16x16x32_bf16 v[130:133], v[100:103], v[146:149], v[130:133]
	v_mfma_f32_16x16x32_bf16 v[126:129], v[138:141], v[146:149], v[126:129]
	v_mfma_f32_16x16x32_bf16 v[114:117], v[100:103], v[154:157], v[114:117]
	v_mfma_f32_16x16x32_bf16 v[108:111], v[138:141], v[154:157], v[110:113]
	v_mfma_f32_16x16x32_bf16 v[92:95], v[100:103], v[162:165], v[92:95]
	v_mfma_f32_16x16x32_bf16 v[88:91], v[138:141], v[162:165], v[88:91]
	v_mfma_f32_16x16x32_bf16 v[76:79], v[100:103], v[170:173], v[76:79]
	v_mfma_f32_16x16x32_bf16 v[72:75], v[138:141], v[170:173], v[72:75]
	s_waitcnt lgkmcnt(3)
	v_mfma_f32_16x16x32_bf16 v[130:133], v[134:137], v[150:153], v[130:133]
	v_mfma_f32_16x16x32_bf16 v[126:129], v[142:145], v[150:153], v[126:129]
	s_waitcnt lgkmcnt(2)
	v_mfma_f32_16x16x32_bf16 v[114:117], v[134:137], v[158:161], v[114:117]
	v_mfma_f32_16x16x32_bf16 v[110:113], v[142:145], v[158:161], v[108:111]
	s_waitcnt lgkmcnt(1)
	v_mfma_f32_16x16x32_bf16 v[92:95], v[134:137], v[166:169], v[92:95]
	v_mfma_f32_16x16x32_bf16 v[88:91], v[142:145], v[166:169], v[88:91]
	s_waitcnt lgkmcnt(0)
	s_setprio 2
	s_barrier
	v_mfma_f32_16x16x32_bf16 v[76:79], v[134:137], v[174:177], v[76:79]
	v_mfma_f32_16x16x32_bf16 v[72:75], v[142:145], v[174:177], v[72:75]
	s_setprio 0
	s_add_i32 s76, 0, 0x1c000
	v_add_u32_e32 v108, s76, v225
	s_add_i32 s14, s35, s59
	ds_read_b128 v[178:181], v108
	ds_read_b128 v[182:185], v108 offset:1024
	ds_read_b128 v[186:189], v108 offset:2048
	ds_read_b128 v[190:193], v108 offset:3072
	v_lshl_add_u64 v[108:109], v[194:195], 0, s[18:19]
	s_mov_b32 m0, s14
	s_nop 0
	global_load_lds_dwordx4 v[108:109], off
	v_lshl_add_u64 v[108:109], v[196:197], 0, s[18:19]
	s_add_i32 m0, s14, 0x2000
	s_nop 0
	global_load_lds_dwordx4 v[108:109], off
	s_setprio 1
	s_barrier
	s_waitcnt lgkmcnt(0)
	v_mfma_f32_16x16x32_bf16 v[122:125], v[178:181], v[146:149], v[122:125]
	v_mfma_f32_16x16x32_bf16 v[118:121], v[186:189], v[146:149], v[118:121]
	v_mfma_f32_16x16x32_bf16 v[104:107], v[178:181], v[154:157], v[104:107]
	v_mfma_f32_16x16x32_bf16 v[96:99], v[186:189], v[154:157], v[96:99]
	v_mfma_f32_16x16x32_bf16 v[84:87], v[178:181], v[162:165], v[84:87]
	v_mfma_f32_16x16x32_bf16 v[80:83], v[186:189], v[162:165], v[80:83]
	v_mfma_f32_16x16x32_bf16 v[68:71], v[178:181], v[170:173], v[68:71]
	v_mfma_f32_16x16x32_bf16 v[64:67], v[186:189], v[170:173], v[64:67]
	v_mfma_f32_16x16x32_bf16 v[122:125], v[182:185], v[150:153], v[122:125]
	v_mfma_f32_16x16x32_bf16 v[118:121], v[190:193], v[150:153], v[118:121]
	v_mfma_f32_16x16x32_bf16 v[106:109], v[182:185], v[158:161], v[104:107]
	v_mfma_f32_16x16x32_bf16 v[96:99], v[190:193], v[158:161], v[96:99]
	v_mfma_f32_16x16x32_bf16 v[84:87], v[182:185], v[166:169], v[84:87]
	s_setprio 2
	s_barrier
; #define PG8_STAGE(bufoff, gbase, voff) do { _Pragma("unroll") for (int _i = 0; _i < 2; ++_i) \
;         __builtin_amdgcn_global_load_lds((const unsigned*)((const char*)(gbase) + (voff)[_i]), (LAS unsigned*)(lds + (bufoff) + ldsw + _i * 8192), 16, 0, 0); } while (0)
; #define PG8_LDA(dst, b, h) do { _Pragma("unroll") for (int m = 0; m < 4; ++m) _Pragma("unroll") for (int k = 0; k < 2; ++k) dst[m][k] = *(const LAS bf16x8*)(lds + PG8_SA(b, h) + aoff + m * 2048 + k * 1024); } while (0)
; #define PG8_LDB(dst, b, h) do { _Pragma("unroll") for (int n = 0; n < 2; ++n) _Pragma("unroll") for (int k = 0; k < 2; ++k) dst[n][k] = *(const LAS bf16x8*)(lds + PG8_SB(b, h) + boff + n * 2048 + k * 1024); } while (0)
; #define PG8_MMA(ai, bj, At, Bt) do { __builtin_amdgcn_s_setprio(1); _Pragma("unroll") for (int m = 0; m < 4; ++m) _Pragma("unroll") for (int n = 0; n < 2; ++n) _Pragma("unroll") for (int k = 0; k < 2; ++k) \
;         acc[ai][bj][m][n] = __builtin_amdgcn_mfma_f32_16x16x32_bf16(Bt[n][k], At[m][k], acc[ai][bj][m][n], 0, 0, 0); __builtin_amdgcn_s_setprio(0); } while (0)
; #define PG8_WAIT_V(n) asm volatile("s_waitcnt vmcnt(" #n ")" ::: "memory")
; #define PG8_WAIT_L(n) asm volatile("s_waitcnt lgkmcnt(" #n ")" ::: "memory")
; #define PG8_BAR __builtin_amdgcn_s_barrier()
; #define PG8_SCHED __builtin_amdgcn_sched_barrier(0)
; #define PG8_LDA(dst, b, h) do { _Pragma("unroll") for (int m = 0; m < 4; ++m) _Pragma("unroll") for (int k = 0; k < 2; ++k) dst[m][k] = *(const LAS bf16x8*)(lds + PG8_SA(b, h) + aoff + m * 2048 + k * 1024); } while (0)
; template <class Epi>
; DI void gemm_phase(LAS unsigned char* lds, const Gemm g, const StaticOrder S, const Epi E) {
;     ...
;             PG8_WAIT_V(6); PG8_BAR; PG8_MMA(1, 1, At, B1); PG8_BAR;
;             PG8_LDB(B0, 1, 0); PG8_SCHED; PG8_LDA(At, 1, 0); PG8_STAGE(PG8_SA(0, 1), a2 + hstep, voffA);
;             PG8_WAIT_L(8); PG8_BAR; PG8_WAIT_L(0); PG8_MMA(0, 0, At, B0); PG8_BAR; PG8_SCHED;
;             PG8_LDB(B1, 1, 1); PG8_STAGE(PG8_SB(1, 0), b3, voffB);
;             PG8_BAR; PG8_WAIT_L(0); PG8_MMA(0, 1, At, B1); PG8_BAR;
;             PG8_LDA(At, 1, 1); PG8_STAGE(PG8_SA(1, 0), a3, voffA);
;             PG8_BAR; PG8_WAIT_L(0); PG8_MMA(1, 0, At, B0); PG8_BAR; PG8_SCHED;
;             PG8_STAGE(PG8_SB(1, 1), b3 + hstep, voffB);
;             PG8_WAIT_V(6); PG8_BAR; PG8_MMA(1, 1, At, B1); PG8_BAR;
	v_mfma_f32_16x16x32_bf16 v[80:83], v[190:193], v[166:169], v[80:83]
	v_mfma_f32_16x16x32_bf16 v[68:71], v[182:185], v[174:177], v[68:71]
	v_mfma_f32_16x16x32_bf16 v[64:67], v[190:193], v[174:177], v[64:67]
	s_setprio 0
	s_mov_b32 m0, s83
	v_lshl_add_u64 v[104:105], v[220:221], 0, s[18:19]
	ds_read_b128 v[146:149], v228 offset:49152
	ds_read_b128 v[154:157], v228 offset:51200
	ds_read_b128 v[162:165], v228 offset:53248
	ds_read_b128 v[170:173], v228 offset:55296
	global_load_lds_dwordx4 v[104:105], off
	v_lshl_add_u64 v[104:105], v[232:233], 0, s[18:19]
	s_mov_b32 m0, s84
	s_nop 0
	global_load_lds_dwordx4 v[104:105], off
	s_setprio 1
	s_barrier
	ds_read_b128 v[150:153], v228 offset:50176
	ds_read_b128 v[158:161], v228 offset:52224
	ds_read_b128 v[166:169], v228 offset:54272
	ds_read_b128 v[174:177], v228 offset:56320
	s_waitcnt lgkmcnt(4)
	v_mfma_f32_16x16x32_bf16 v[60:63], v[100:103], v[146:149], v[60:63]
	v_mfma_f32_16x16x32_bf16 v[56:59], v[138:141], v[146:149], v[56:59]
	v_mfma_f32_16x16x32_bf16 v[44:47], v[100:103], v[154:157], v[44:47]
	v_mfma_f32_16x16x32_bf16 v[40:43], v[138:141], v[154:157], v[40:43]
	v_mfma_f32_16x16x32_bf16 v[28:31], v[100:103], v[162:165], v[28:31]
	v_mfma_f32_16x16x32_bf16 v[24:27], v[138:141], v[162:165], v[24:27]
	v_mfma_f32_16x16x32_bf16 v[12:15], v[100:103], v[170:173], v[12:15]
	v_mfma_f32_16x16x32_bf16 v[8:11], v[138:141], v[170:173], v[8:11]
	s_waitcnt lgkmcnt(3)
	v_mfma_f32_16x16x32_bf16 v[60:63], v[134:137], v[150:153], v[60:63]
	v_mfma_f32_16x16x32_bf16 v[56:59], v[142:145], v[150:153], v[56:59]
	s_waitcnt lgkmcnt(2)
	v_mfma_f32_16x16x32_bf16 v[44:47], v[134:137], v[158:161], v[44:47]
	v_mfma_f32_16x16x32_bf16 v[40:43], v[142:145], v[158:161], v[40:43]
	s_waitcnt lgkmcnt(1)
	v_mfma_f32_16x16x32_bf16 v[28:31], v[134:137], v[166:169], v[28:31]
	v_mfma_f32_16x16x32_bf16 v[24:27], v[142:145], v[166:169], v[24:27]
	s_waitcnt lgkmcnt(0)
	s_setprio 2
	s_barrier
	v_mfma_f32_16x16x32_bf16 v[12:15], v[134:137], v[174:177], v[12:15]
	v_mfma_f32_16x16x32_bf16 v[8:11], v[142:145], v[174:177], v[8:11]
	s_setprio 0
	s_add_u32 s14, s52, 0x40080
	s_addc_u32 s15, s53, 0
	s_add_i32 s35, s76, s59
	v_lshl_add_u64 v[100:101], s[14:15], 0, v[200:201]
	s_mov_b32 m0, s35
	s_nop 0
	global_load_lds_dwordx4 v[100:101], off
	v_lshl_add_u64 v[100:101], s[14:15], 0, v[204:205]
	s_add_i32 m0, s35, 0x2000
	s_nop 0
	global_load_lds_dwordx4 v[100:101], off
	s_waitcnt vmcnt(6)
	s_setprio 1
	s_barrier
	v_mfma_f32_16x16x32_bf16 v[52:55], v[178:181], v[146:149], v[52:55]
	v_mfma_f32_16x16x32_bf16 v[48:51], v[186:189], v[146:149], v[48:51]
	v_mfma_f32_16x16x32_bf16 v[36:39], v[178:181], v[154:157], v[36:39]
	v_mfma_f32_16x16x32_bf16 v[32:35], v[186:189], v[154:157], v[32:35]
	v_mfma_f32_16x16x32_bf16 v[20:23], v[178:181], v[162:165], v[20:23]
	v_mfma_f32_16x16x32_bf16 v[16:19], v[186:189], v[162:165], v[16:19]
	v_mfma_f32_16x16x32_bf16 v[4:7], v[178:181], v[170:173], v[4:7]
	v_mfma_f32_16x16x32_bf16 v[0:3], v[186:189], v[170:173], v[0:3]
	v_mfma_f32_16x16x32_bf16 v[52:55], v[182:185], v[150:153], v[52:55]
	v_mfma_f32_16x16x32_bf16 v[48:51], v[190:193], v[150:153], v[48:51]
	v_mfma_f32_16x16x32_bf16 v[36:39], v[182:185], v[158:161], v[36:39]
	v_mfma_f32_16x16x32_bf16 v[32:35], v[190:193], v[158:161], v[32:35]
	v_mfma_f32_16x16x32_bf16 v[20:23], v[182:185], v[166:169], v[20:23]
	s_setprio 2
	s_barrier
	v_mfma_f32_16x16x32_bf16 v[16:19], v[190:193], v[166:169], v[16:19]
	v_mfma_f32_16x16x32_bf16 v[4:7], v[182:185], v[174:177], v[4:7]
	v_mfma_f32_16x16x32_bf16 v[0:3], v[190:193], v[174:177], v[0:3]
	s_setprio 0
	s_add_i32 s95, s95, 2
	s_add_u32 s8, s8, 0x100
	s_addc_u32 s9, s9, 0
	s_add_u32 s23, s23, 0x100
	s_addc_u32 s94, s94, 0
	s_cmp_gt_u32 s95, 13
	s_cbranch_scc0 .LBB0_274
; DI RowScales load_rowscales(const float* ss, int row0) {
;     RowScales t;
; #pragma unroll
;     for (int ai = 0; ai < 2; ++ai)
; #pragma unroll
;         for (int m = 0; m < 4; ++m) t.r[ai][m] = ss[row0 + ai * 128 + m * 16];
;     DI void operator()(AccRef acc, const Unit& u, int wr, int wc, int fr, int fq) const {
;         const int X = u.pn >> 2, h = u.pn & 3, isk = wc >> 1, i0 = (wc & 1) * 32 + 8 * fq;
;         bf16_t* dst = (X ? qkoB : qkoA) + h * 256 + isk * 128 + i0;
;         const float qs0 = isk ? 1.0f : 0.08838834764831845f;
;         const int row0 = u.pm * 256 + wr * 64 + fr;
;         const RowScales rsc = load_rowscales(ss, row0);
; #pragma unroll
;         for (int ai = 0; ai < 2; ++ai) {
;             f32x4 cs[4][2], sn[4][2];
;             if (X == 0) {
; #pragma unroll
;                 for (int m = 0; m < 4; ++m) {
;                     const int pos = (row0 + ai * 128 + m * 16) & (SEQ - 1);
;                     cs[m][0] = *(const f32x4*)(cosT + pos * 64 + i0); cs[m][1] = *(const f32x4*)(cosT + pos * 64 + i0 + 4);
;                     sn[m][0] = *(const f32x4*)(sinT + pos * 64 + i0); sn[m][1] = *(const f32x4*)(sinT + pos * 64 + i0 + 4);
;                 }
;             } else {
; #pragma unroll
;                 for (int m = 0; m < 4; ++m) { cs[m][0] = cs[m][1] = (f32x4){1.f, 1.f, 1.f, 1.f}; sn[m][0] = sn[m][1] = (f32x4){0.f, 0.f, 0.f, 0.f}; }
;             }
	v_lshl_add_u32 v102, s0, 8, v224
	v_ashrrev_i32_e32 v103, 31, v102
	v_lshl_add_u64 v[134:135], v[102:103], 2, s[60:61]
	global_load_dword v237, v[134:135], off
	global_load_dword v236, v[134:135], off offset:64
	global_load_dword v105, v[134:135], off offset:128
	global_load_dword v101, v[134:135], off offset:192
	global_load_dword v231, v[134:135], off offset:512
	global_load_dword v232, v[134:135], off offset:576
	global_load_dword v233, v[134:135], off offset:640
	global_load_dword v234, v[134:135], off offset:704
	s_cmp_lt_u32 s93, 4
	s_cselect_b64 s[0:1], -1, 0
	s_cmp_gt_u32 s93, 3
	v_lshlrev_b32_e32 v235, 6, v102
	v_mov_b32_e32 v100, 1.0
	v_mov_b32_e32 v104, 0
	v_mov_b32_e32 v134, 0
	v_mov_b32_e32 v135, 0
	v_mov_b32_e32 v136, 0
	v_mov_b32_e32 v137, 0
	v_mov_b32_e32 v142, 0
	v_mov_b32_e32 v143, 0
	v_mov_b32_e32 v144, 0
	v_mov_b32_e32 v145, 0
	v_mov_b32_e32 v146, 0
	v_mov_b32_e32 v147, 0
	v_mov_b32_e32 v148, 0
	v_mov_b32_e32 v149, 0
	v_mov_b32_e32 v154, 0
	v_mov_b32_e32 v155, 0
	v_mov_b32_e32 v156, 0
	v_mov_b32_e32 v157, 0
	v_mov_b32_e32 v162, 0
	v_mov_b32_e32 v163, 0
	v_mov_b32_e32 v164, 0
	v_mov_b32_e32 v165, 0
	v_mov_b32_e32 v174, 0
	v_mov_b32_e32 v175, 0
	v_mov_b32_e32 v176, 0
	v_mov_b32_e32 v177, 0
	v_mov_b32_e32 v182, 0
	v_mov_b32_e32 v183, 0
	v_mov_b32_e32 v184, 0
	v_mov_b32_e32 v185, 0
	v_mov_b32_e32 v194, 0
	v_mov_b32_e32 v195, 0
	v_mov_b32_e32 v196, 0
	v_mov_b32_e32 v197, 0
	v_mov_b32_e32 v138, 1.0
	v_mov_b32_e32 v139, 1.0
	v_mov_b32_e32 v140, 1.0
	v_mov_b32_e32 v141, 1.0
	v_mov_b32_e32 v190, 1.0
	v_mov_b32_e32 v191, 1.0
	v_mov_b32_e32 v192, 1.0
	v_mov_b32_e32 v193, 1.0
	v_mov_b32_e32 v186, 1.0
	v_mov_b32_e32 v187, 1.0
	v_mov_b32_e32 v188, 1.0
	v_mov_b32_e32 v189, 1.0
	v_mov_b32_e32 v178, 1.0
	v_mov_b32_e32 v179, 1.0
	v_mov_b32_e32 v180, 1.0
	v_mov_b32_e32 v181, 1.0
	v_mov_b32_e32 v170, 1.0
	v_mov_b32_e32 v171, 1.0
	v_mov_b32_e32 v172, 1.0
	v_mov_b32_e32 v173, 1.0
	v_mov_b32_e32 v166, 1.0
	v_mov_b32_e32 v167, 1.0
	v_mov_b32_e32 v168, 1.0
	v_mov_b32_e32 v169, 1.0
	v_mov_b32_e32 v158, 1.0
	v_mov_b32_e32 v159, 1.0
	v_mov_b32_e32 v160, 1.0
	v_mov_b32_e32 v161, 1.0
	v_mov_b32_e32 v150, 1.0
	v_mov_b32_e32 v151, 1.0
	v_mov_b32_e32 v152, 1.0
	v_mov_b32_e32 v153, 1.0
	s_cbranch_scc1 .LBB0_277
	v_lshlrev_b32_e32 v134, 2, v235
	v_and_b32_e32 v134, 0x1fcf00, v134
	v_mov_b32_e32 v135, v207
	v_lshl_add_u64 v[136:137], v[208:209], 0, v[134:135]
	global_load_dwordx4 v[190:193], v[136:137], off
	global_load_dwordx4 v[186:189], v[136:137], off offset:16
	v_lshl_add_u64 v[136:137], v[210:211], 0, v[134:135]
	global_load_dwordx4 v[182:185], v[136:137], off offset:16
	global_load_dwordx4 v[194:197], v[136:137], off
	v_or_b32_e32 v136, 0x1000, v134
	v_mov_b32_e32 v137, v207
	v_lshl_add_u64 v[138:139], v[208:209], 0, v[136:137]
	v_lshl_add_u64 v[136:137], v[210:211], 0, v[136:137]
	global_load_dwordx4 v[178:181], v[138:139], off
	global_load_dwordx4 v[170:173], v[138:139], off offset:16
	global_load_dwordx4 v[162:165], v[136:137], off offset:16
	global_load_dwordx4 v[174:177], v[136:137], off
	v_or_b32_e32 v136, 0x2000, v134
	v_mov_b32_e32 v137, v207
	v_lshl_add_u64 v[138:139], v[208:209], 0, v[136:137]
	v_lshl_add_u64 v[136:137], v[210:211], 0, v[136:137]
	v_or_b32_e32 v134, 0x3000, v134
	global_load_dwordx4 v[166:169], v[138:139], off
	global_load_dwordx4 v[158:161], v[138:139], off offset:16
	global_load_dwordx4 v[146:149], v[136:137], off offset:16
	global_load_dwordx4 v[154:157], v[136:137], off
	v_lshl_add_u64 v[136:137], v[208:209], 0, v[134:135]
	v_lshl_add_u64 v[142:143], v[210:211], 0, v[134:135]
	global_load_dwordx4 v[138:141], v[136:137], off offset:16
	global_load_dwordx4 v[150:153], v[136:137], off
	s_nop 0
	global_load_dwordx4 v[134:137], v[142:143], off offset:16
	s_nop 0
	global_load_dwordx4 v[142:145], v[142:143], off

; #define PG8_STAGE(bufoff, gbase, voff) do { _Pragma("unroll") for (int _i = 0; _i < 2; ++_i) \
;         __builtin_amdgcn_global_load_lds((const unsigned*)((const char*)(gbase) + (voff)[_i]), (LAS unsigned*)(lds + (bufoff) + ldsw + _i * 8192), 16, 0, 0); } while (0)
; #define PG8_LDA(dst, b, h) do { _Pragma("unroll") for (int m = 0; m < 4; ++m) _Pragma("unroll") for (int k = 0; k < 2; ++k) dst[m][k] = *(const LAS bf16x8*)(lds + PG8_SA(b, h) + aoff + m * 2048 + k * 1024); } while (0)
; #define PG8_LDB(dst, b, h) do { _Pragma("unroll") for (int n = 0; n < 2; ++n) _Pragma("unroll") for (int k = 0; k < 2; ++k) dst[n][k] = *(const LAS bf16x8*)(lds + PG8_SB(b, h) + boff + n * 2048 + k * 1024); } while (0)
; #define PG8_MMA(ai, bj, At, Bt) do { __builtin_amdgcn_s_setprio(1); _Pragma("unroll") for (int m = 0; m < 4; ++m) _Pragma("unroll") for (int n = 0; n < 2; ++n) _Pragma("unroll") for (int k = 0; k < 2; ++k) \
;         acc[ai][bj][m][n] = __builtin_amdgcn_mfma_f32_16x16x32_bf16(Bt[n][k], At[m][k], acc[ai][bj][m][n], 0, 0, 0); __builtin_amdgcn_s_setprio(0); } while (0)
; #define PG8_WAIT_V(n) asm volatile("s_waitcnt vmcnt(" #n ")" ::: "memory")
; #define PG8_WAIT_L(n) asm volatile("s_waitcnt lgkmcnt(" #n ")" ::: "memory")
; #define PG8_BAR __builtin_amdgcn_s_barrier()
; template <class Epi>
; DI void gemm_phase(LAS unsigned char* lds, const Gemm g, const StaticOrder S, const Epi E) {
;     ...
;         for (int t = 0; t < nt; t += 2) {
;             const bool last = (t == nt - 2);
;             const char* a1 = cA + (size_t)(t + 1) * kstep;
;             const char* a2 = last ? nA : cA + (size_t)(t + 2) * kstep; const char* b2 = last ? nB : cB + (size_t)(t + 2) * kstep;
;             const char* a3 = a2 + kstep; const char* b3 = b2 + kstep;
;             PG8_LDB(B0, 0, 0); PG8_SCHED; PG8_LDA(At, 0, 0); PG8_STAGE(PG8_SA(1, 1), a1 + hstep, voffA);
;             PG8_WAIT_L(8); PG8_BAR; PG8_WAIT_L(0); PG8_MMA(0, 0, At, B0); PG8_BAR; PG8_SCHED;
;             PG8_LDB(B1, 0, 1); PG8_STAGE(PG8_SB(0, 0), b2, voffB);
;             PG8_BAR; PG8_WAIT_L(0); PG8_MMA(0, 1, At, B1); PG8_BAR;
;             PG8_LDA(At, 0, 1); PG8_STAGE(PG8_SA(0, 0), a2, voffA);
;             PG8_BAR; PG8_WAIT_L(0); PG8_MMA(1, 0, At, B0); PG8_BAR; PG8_SCHED;
;             PG8_STAGE(PG8_SB(0, 1), b2 + hstep, voffB);
;             PG8_WAIT_V(6); PG8_BAR; PG8_MMA(1, 1, At, B1); PG8_BAR;
.LBB0_298:
	ds_read_b128 v[128:131], v168
	ds_read_b128 v[132:135], v168 offset:1024
	ds_read_b128 v[154:157], v168 offset:2048
	ds_read_b128 v[158:161], v168 offset:3072
	s_add_u32 s5, s8, 0xfffc0080
	s_addc_u32 s14, s9, -1
	s_cmp_eq_u32 s4, 12
	s_cselect_b32 s81, s6, s14
	s_cselect_b32 s80, s7, s5
	s_cselect_b32 s79, s21, vcc_hi
	s_cselect_b32 s78, s23, vcc_lo
	v_lshl_add_u64 v[162:163], s[8:9], 0, v[146:147]
	s_add_i32 m0, s58, 0xc000
	ds_read_b128 v[172:175], v169
	ds_read_b128 v[180:183], v169 offset:2048
	ds_read_b128 v[188:191], v169 offset:4096
	ds_read_b128 v[196:199], v169 offset:6144
	global_load_lds_dwordx4 v[162:163], off
	v_lshl_add_u64 v[162:163], s[8:9], 0, v[148:149]
	s_add_i32 m0, s58, 0xe000
	s_nop 0
	global_load_lds_dwordx4 v[162:163], off
	s_waitcnt lgkmcnt(4)
	s_setprio 1
	s_barrier
	ds_read_b128 v[176:179], v169 offset:1024
	ds_read_b128 v[184:187], v169 offset:3072
	ds_read_b128 v[192:195], v169 offset:5120
	ds_read_b128 v[200:203], v169 offset:7168
	s_waitcnt lgkmcnt(4)
	v_mfma_f32_16x16x32_bf16 v[124:127], v[128:131], v[172:175], v[124:127]
	v_mfma_f32_16x16x32_bf16 v[120:123], v[154:157], v[172:175], v[120:123]
	v_mfma_f32_16x16x32_bf16 v[112:115], v[128:131], v[180:183], v[112:115]
	v_mfma_f32_16x16x32_bf16 v[104:107], v[154:157], v[180:183], v[104:107]
	v_mfma_f32_16x16x32_bf16 v[96:99], v[128:131], v[188:191], v[96:99]
	v_mfma_f32_16x16x32_bf16 v[88:91], v[154:157], v[188:191], v[88:91]
	v_mfma_f32_16x16x32_bf16 v[80:83], v[128:131], v[196:199], v[80:83]
	v_mfma_f32_16x16x32_bf16 v[72:75], v[154:157], v[196:199], v[72:75]
	s_waitcnt lgkmcnt(3)
	v_mfma_f32_16x16x32_bf16 v[124:127], v[132:135], v[176:179], v[124:127]
	v_mfma_f32_16x16x32_bf16 v[120:123], v[158:161], v[176:179], v[120:123]
	s_waitcnt lgkmcnt(2)
	v_mfma_f32_16x16x32_bf16 v[112:115], v[132:135], v[184:187], v[112:115]
	v_mfma_f32_16x16x32_bf16 v[104:107], v[158:161], v[184:187], v[104:107]
	s_waitcnt lgkmcnt(1)
	v_mfma_f32_16x16x32_bf16 v[96:99], v[132:135], v[192:195], v[96:99]
	v_mfma_f32_16x16x32_bf16 v[88:91], v[158:161], v[192:195], v[88:91]
	s_waitcnt lgkmcnt(0)
	s_setprio 2
	s_barrier
	v_mfma_f32_16x16x32_bf16 v[80:83], v[132:135], v[200:203], v[80:83]
	v_mfma_f32_16x16x32_bf16 v[72:75], v[158:161], v[200:203], v[72:75]
	s_setprio 0
	s_add_i32 s5, s94, s19
	v_lshl_add_u64 v[162:163], s[78:79], 0, v[138:139]
	s_mov_b32 m0, s5
	ds_read_b128 v[204:207], v170
	ds_read_b128 v[208:211], v170 offset:1024
	ds_read_b128 v[212:215], v170 offset:2048
	ds_read_b128 v[216:219], v170 offset:3072
	global_load_lds_dwordx4 v[162:163], off
	v_lshl_add_u64 v[220:221], s[78:79], 0, v[142:143]
	s_add_i32 m0, s5, 0x2000
	s_nop 0
	global_load_lds_dwordx4 v[220:221], off
	s_setprio 1
	s_barrier
	s_waitcnt lgkmcnt(0)
	v_mfma_f32_16x16x32_bf16 v[116:119], v[204:207], v[172:175], v[116:119]
	v_mfma_f32_16x16x32_bf16 v[108:111], v[212:215], v[172:175], v[108:111]
	v_mfma_f32_16x16x32_bf16 v[100:103], v[204:207], v[180:183], v[100:103]
	v_mfma_f32_16x16x32_bf16 v[92:95], v[212:215], v[180:183], v[92:95]
	v_mfma_f32_16x16x32_bf16 v[84:87], v[204:207], v[188:191], v[84:87]
	v_mfma_f32_16x16x32_bf16 v[76:79], v[212:215], v[188:191], v[76:79]
	v_mfma_f32_16x16x32_bf16 v[68:71], v[204:207], v[196:199], v[68:71]
	v_mfma_f32_16x16x32_bf16 v[64:67], v[212:215], v[196:199], v[64:67]
	v_mfma_f32_16x16x32_bf16 v[116:119], v[208:211], v[176:179], v[116:119]
	v_mfma_f32_16x16x32_bf16 v[108:111], v[216:219], v[176:179], v[108:111]
	v_mfma_f32_16x16x32_bf16 v[100:103], v[208:211], v[184:187], v[100:103]
	v_mfma_f32_16x16x32_bf16 v[92:95], v[216:219], v[184:187], v[92:95]
	v_mfma_f32_16x16x32_bf16 v[84:87], v[208:211], v[192:195], v[84:87]
	s_setprio 2
	s_barrier
	v_mfma_f32_16x16x32_bf16 v[76:79], v[216:219], v[192:195], v[76:79]
	v_mfma_f32_16x16x32_bf16 v[68:71], v[208:211], v[200:203], v[68:71]
	v_mfma_f32_16x16x32_bf16 v[64:67], v[216:219], v[200:203], v[64:67]
	s_setprio 0
	s_mov_b32 m0, s58
	v_lshl_add_u64 v[224:225], s[80:81], 0, v[136:137]
	ds_read_b128 v[172:175], v169 offset:16384
	ds_read_b128 v[180:183], v169 offset:18432
	ds_read_b128 v[188:191], v169 offset:20480
	ds_read_b128 v[196:199], v169 offset:22528
	global_load_lds_dwordx4 v[224:225], off
	v_lshl_add_u64 v[226:227], s[80:81], 0, v[140:141]
	s_mov_b32 m0, s59
	s_nop 0
	global_load_lds_dwordx4 v[226:227], off
	s_setprio 1
	s_barrier
	ds_read_b128 v[176:179], v169 offset:17408
	ds_read_b128 v[184:187], v169 offset:19456
	ds_read_b128 v[192:195], v169 offset:21504
	ds_read_b128 v[200:203], v169 offset:23552
	s_waitcnt lgkmcnt(4)
	v_mfma_f32_16x16x32_bf16 v[60:63], v[128:131], v[172:175], v[60:63]
	v_mfma_f32_16x16x32_bf16 v[56:59], v[154:157], v[172:175], v[56:59]
	v_mfma_f32_16x16x32_bf16 v[48:51], v[128:131], v[180:183], v[48:51]
	v_mfma_f32_16x16x32_bf16 v[40:43], v[154:157], v[180:183], v[40:43]
	v_mfma_f32_16x16x32_bf16 v[32:35], v[128:131], v[188:191], v[32:35]
	v_mfma_f32_16x16x32_bf16 v[24:27], v[154:157], v[188:191], v[24:27]
	v_mfma_f32_16x16x32_bf16 v[16:19], v[128:131], v[196:199], v[16:19]
	v_mfma_f32_16x16x32_bf16 v[8:11], v[154:157], v[196:199], v[8:11]
	s_waitcnt lgkmcnt(3)
	v_mfma_f32_16x16x32_bf16 v[60:63], v[132:135], v[176:179], v[60:63]
	v_mfma_f32_16x16x32_bf16 v[56:59], v[158:161], v[176:179], v[56:59]
	s_waitcnt lgkmcnt(2)
	v_mfma_f32_16x16x32_bf16 v[48:51], v[132:135], v[184:187], v[48:51]
	v_mfma_f32_16x16x32_bf16 v[40:43], v[158:161], v[184:187], v[40:43]
	s_waitcnt lgkmcnt(1)
	v_mfma_f32_16x16x32_bf16 v[32:35], v[132:135], v[192:195], v[32:35]
	v_mfma_f32_16x16x32_bf16 v[24:27], v[158:161], v[192:195], v[24:27]
	s_waitcnt lgkmcnt(0)
	s_setprio 2
	s_barrier
; #define PG8_STAGE(bufoff, gbase, voff) do { _Pragma("unroll") for (int _i = 0; _i < 2; ++_i) \
;         __builtin_amdgcn_global_load_lds((const unsigned*)((const char*)(gbase) + (voff)[_i]), (LAS unsigned*)(lds + (bufoff) + ldsw + _i * 8192), 16, 0, 0); } while (0)
; #define PG8_LDA(dst, b, h) do { _Pragma("unroll") for (int m = 0; m < 4; ++m) _Pragma("unroll") for (int k = 0; k < 2; ++k) dst[m][k] = *(const LAS bf16x8*)(lds + PG8_SA(b, h) + aoff + m * 2048 + k * 1024); } while (0)
; #define PG8_LDB(dst, b, h) do { _Pragma("unroll") for (int n = 0; n < 2; ++n) _Pragma("unroll") for (int k = 0; k < 2; ++k) dst[n][k] = *(const LAS bf16x8*)(lds + PG8_SB(b, h) + boff + n * 2048 + k * 1024); } while (0)
; #define PG8_MMA(ai, bj, At, Bt) do { __builtin_amdgcn_s_setprio(1); _Pragma("unroll") for (int m = 0; m < 4; ++m) _Pragma("unroll") for (int n = 0; n < 2; ++n) _Pragma("unroll") for (int k = 0; k < 2; ++k) \
;         acc[ai][bj][m][n] = __builtin_amdgcn_mfma_f32_16x16x32_bf16(Bt[n][k], At[m][k], acc[ai][bj][m][n], 0, 0, 0); __builtin_amdgcn_s_setprio(0); } while (0)
; #define PG8_WAIT_V(n) asm volatile("s_waitcnt vmcnt(" #n ")" ::: "memory")
; #define PG8_WAIT_L(n) asm volatile("s_waitcnt lgkmcnt(" #n ")" ::: "memory")
; #define PG8_BAR __builtin_amdgcn_s_barrier()
; #define PG8_SCHED __builtin_amdgcn_sched_barrier(0)
; #define PG8_LDA(dst, b, h) do { _Pragma("unroll") for (int m = 0; m < 4; ++m) _Pragma("unroll") for (int k = 0; k < 2; ++k) dst[m][k] = *(const LAS bf16x8*)(lds + PG8_SA(b, h) + aoff + m * 2048 + k * 1024); } while (0)
; template <class Epi>
; DI void gemm_phase(LAS unsigned char* lds, const Gemm g, const StaticOrder S, const Epi E) {
;     ...
;             PG8_WAIT_V(6); PG8_BAR; PG8_MMA(1, 1, At, B1); PG8_BAR;
;             PG8_LDB(B0, 1, 0); PG8_SCHED; PG8_LDA(At, 1, 0); PG8_STAGE(PG8_SA(0, 1), a2 + hstep, voffA);
;             PG8_WAIT_L(8); PG8_BAR; PG8_WAIT_L(0); PG8_MMA(0, 0, At, B0); PG8_BAR; PG8_SCHED;
;             PG8_LDB(B1, 1, 1); PG8_STAGE(PG8_SB(1, 0), b3, voffB);
;             PG8_BAR; PG8_WAIT_L(0); PG8_MMA(0, 1, At, B1); PG8_BAR;
;             PG8_LDA(At, 1, 1); PG8_STAGE(PG8_SA(1, 0), a3, voffA);
;             PG8_BAR; PG8_WAIT_L(0); PG8_MMA(1, 0, At, B0); PG8_BAR; PG8_SCHED;
;             PG8_STAGE(PG8_SB(1, 1), b3 + hstep, voffB);
;             PG8_WAIT_V(6); PG8_BAR; PG8_MMA(1, 1, At, B1); PG8_BAR;
	v_mfma_f32_16x16x32_bf16 v[16:19], v[132:135], v[200:203], v[16:19]
	v_mfma_f32_16x16x32_bf16 v[8:11], v[158:161], v[200:203], v[8:11]
	s_setprio 0
	s_add_u32 s14, s78, 0x40000
	s_addc_u32 s15, s79, 0
	s_add_i32 s5, s95, s19
	v_lshl_add_u64 v[128:129], s[14:15], 0, v[138:139]
	s_mov_b32 m0, s5
	s_nop 0
	global_load_lds_dwordx4 v[128:129], off
	v_lshl_add_u64 v[128:129], s[14:15], 0, v[142:143]
	s_add_i32 m0, s5, 0x2000
	s_nop 0
	global_load_lds_dwordx4 v[128:129], off
	s_waitcnt vmcnt(6)
	s_setprio 1
	s_barrier
	v_mfma_f32_16x16x32_bf16 v[52:55], v[204:207], v[172:175], v[52:55]
	v_mfma_f32_16x16x32_bf16 v[44:47], v[212:215], v[172:175], v[44:47]
	v_mfma_f32_16x16x32_bf16 v[36:39], v[204:207], v[180:183], v[36:39]
	v_mfma_f32_16x16x32_bf16 v[28:31], v[212:215], v[180:183], v[28:31]
	v_mfma_f32_16x16x32_bf16 v[20:23], v[204:207], v[188:191], v[20:23]
	v_mfma_f32_16x16x32_bf16 v[12:15], v[212:215], v[188:191], v[12:15]
	v_mfma_f32_16x16x32_bf16 v[4:7], v[204:207], v[196:199], v[4:7]
	v_mfma_f32_16x16x32_bf16 v[0:3], v[212:215], v[196:199], v[0:3]
	v_mfma_f32_16x16x32_bf16 v[52:55], v[208:211], v[176:179], v[52:55]
	v_mfma_f32_16x16x32_bf16 v[44:47], v[216:219], v[176:179], v[44:47]
	v_mfma_f32_16x16x32_bf16 v[36:39], v[208:211], v[184:187], v[36:39]
	v_mfma_f32_16x16x32_bf16 v[28:31], v[216:219], v[184:187], v[28:31]
	v_mfma_f32_16x16x32_bf16 v[20:23], v[208:211], v[192:195], v[20:23]
	s_setprio 2
	s_barrier
	v_mfma_f32_16x16x32_bf16 v[12:15], v[216:219], v[192:195], v[12:15]
	v_mfma_f32_16x16x32_bf16 v[4:7], v[208:211], v[200:203], v[4:7]
	v_mfma_f32_16x16x32_bf16 v[0:3], v[216:219], v[200:203], v[0:3]
	s_setprio 0
	s_add_i32 s5, 0, 0x18000
	v_add_u32_e32 v158, s5, v165
	ds_read_b128 v[128:131], v158
	ds_read_b128 v[132:135], v158 offset:1024
	ds_read_b128 v[154:157], v158 offset:2048
	ds_read_b128 v[158:161], v158 offset:3072
	s_add_u32 s14, s80, 0x40000
	s_addc_u32 s15, s81, 0
	s_mov_b32 m0, s77
	v_lshl_add_u64 v[204:205], s[14:15], 0, v[136:137]
	ds_read_b128 v[172:175], v169 offset:32768
	ds_read_b128 v[180:183], v169 offset:34816
	ds_read_b128 v[188:191], v169 offset:36864
	ds_read_b128 v[196:199], v169 offset:38912
	global_load_lds_dwordx4 v[204:205], off
	v_lshl_add_u64 v[204:205], s[14:15], 0, v[140:141]
	s_mov_b32 m0, s82
	s_nop 0
	global_load_lds_dwordx4 v[204:205], off
	s_waitcnt lgkmcnt(4)
	s_setprio 1
	s_barrier
	ds_read_b128 v[176:179], v169 offset:33792
	ds_read_b128 v[184:187], v169 offset:35840
	ds_read_b128 v[192:195], v169 offset:37888
	ds_read_b128 v[200:203], v169 offset:39936
	s_waitcnt lgkmcnt(4)
	v_mfma_f32_16x16x32_bf16 v[124:127], v[128:131], v[172:175], v[124:127]
	v_mfma_f32_16x16x32_bf16 v[120:123], v[154:157], v[172:175], v[120:123]
	v_mfma_f32_16x16x32_bf16 v[112:115], v[128:131], v[180:183], v[112:115]
	v_mfma_f32_16x16x32_bf16 v[104:107], v[154:157], v[180:183], v[104:107]
	v_mfma_f32_16x16x32_bf16 v[96:99], v[128:131], v[188:191], v[96:99]
	v_mfma_f32_16x16x32_bf16 v[88:91], v[154:157], v[188:191], v[88:91]
	v_mfma_f32_16x16x32_bf16 v[80:83], v[128:131], v[196:199], v[80:83]
	v_mfma_f32_16x16x32_bf16 v[72:75], v[154:157], v[196:199], v[72:75]
	s_waitcnt lgkmcnt(3)
	v_mfma_f32_16x16x32_bf16 v[124:127], v[132:135], v[176:179], v[124:127]
	v_mfma_f32_16x16x32_bf16 v[120:123], v[158:161], v[176:179], v[120:123]
	s_waitcnt lgkmcnt(2)
	v_mfma_f32_16x16x32_bf16 v[112:115], v[132:135], v[184:187], v[112:115]
	v_mfma_f32_16x16x32_bf16 v[104:107], v[158:161], v[184:187], v[104:107]
	s_waitcnt lgkmcnt(1)
	v_mfma_f32_16x16x32_bf16 v[96:99], v[132:135], v[192:195], v[96:99]
	v_mfma_f32_16x16x32_bf16 v[88:91], v[158:161], v[192:195], v[88:91]
	s_waitcnt lgkmcnt(0)
	s_setprio 2
	s_barrier
	v_mfma_f32_16x16x32_bf16 v[80:83], v[132:135], v[200:203], v[80:83]
	v_mfma_f32_16x16x32_bf16 v[72:75], v[158:161], v[200:203], v[72:75]
	s_setprio 0
	s_add_i32 s35, 0, 0x1c000
	s_add_i32 s5, s5, s19
	v_add_u32_e32 v171, s35, v165
	v_lshl_add_u64 v[162:163], v[162:163], 0, s[10:11]
	s_mov_b32 m0, s5
	ds_read_b128 v[204:207], v171
	ds_read_b128 v[208:211], v171 offset:1024
	ds_read_b128 v[212:215], v171 offset:2048
	ds_read_b128 v[216:219], v171 offset:3072
	global_load_lds_dwordx4 v[162:163], off
	v_lshl_add_u64 v[162:163], v[220:221], 0, s[10:11]
	s_add_i32 m0, s5, 0x2000
	s_nop 0
	global_load_lds_dwordx4 v[162:163], off
	s_setprio 1
	s_barrier
	s_waitcnt lgkmcnt(0)
	v_mfma_f32_16x16x32_bf16 v[116:119], v[204:207], v[172:175], v[116:119]
	v_mfma_f32_16x16x32_bf16 v[108:111], v[212:215], v[172:175], v[108:111]
	v_mfma_f32_16x16x32_bf16 v[100:103], v[204:207], v[180:183], v[100:103]
	v_mfma_f32_16x16x32_bf16 v[92:95], v[212:215], v[180:183], v[92:95]
	v_mfma_f32_16x16x32_bf16 v[84:87], v[204:207], v[188:191], v[84:87]
	v_mfma_f32_16x16x32_bf16 v[76:79], v[212:215], v[188:191], v[76:79]
	v_mfma_f32_16x16x32_bf16 v[68:71], v[204:207], v[196:199], v[68:71]
	v_mfma_f32_16x16x32_bf16 v[64:67], v[212:215], v[196:199], v[64:67]
	v_mfma_f32_16x16x32_bf16 v[116:119], v[208:211], v[176:179], v[116:119]
	v_mfma_f32_16x16x32_bf16 v[108:111], v[216:219], v[176:179], v[108:111]
	v_mfma_f32_16x16x32_bf16 v[100:103], v[208:211], v[184:187], v[100:103]
	v_mfma_f32_16x16x32_bf16 v[92:95], v[216:219], v[184:187], v[92:95]
	v_mfma_f32_16x16x32_bf16 v[84:87], v[208:211], v[192:195], v[84:87]
	s_setprio 2
	s_barrier
	v_mfma_f32_16x16x32_bf16 v[76:79], v[216:219], v[192:195], v[76:79]
	v_mfma_f32_16x16x32_bf16 v[68:71], v[208:211], v[200:203], v[68:71]
	v_mfma_f32_16x16x32_bf16 v[64:67], v[216:219], v[200:203], v[64:67]
	s_setprio 0
	s_mov_b32 m0, s86
	v_lshl_add_u64 v[162:163], v[224:225], 0, s[10:11]
	ds_read_b128 v[172:175], v169 offset:49152
	ds_read_b128 v[180:183], v169 offset:51200
	ds_read_b128 v[188:191], v169 offset:53248
	ds_read_b128 v[196:199], v169 offset:55296
	global_load_lds_dwordx4 v[162:163], off
	v_lshl_add_u64 v[162:163], v[226:227], 0, s[10:11]
	s_mov_b32 m0, s87
	s_nop 0
	global_load_lds_dwordx4 v[162:163], off
	s_setprio 1
	s_barrier
; #define PG8_STAGE(bufoff, gbase, voff) do { _Pragma("unroll") for (int _i = 0; _i < 2; ++_i) \
;         __builtin_amdgcn_global_load_lds((const unsigned*)((const char*)(gbase) + (voff)[_i]), (LAS unsigned*)(lds + (bufoff) + ldsw + _i * 8192), 16, 0, 0); } while (0)
; #define PG8_LDA(dst, b, h) do { _Pragma("unroll") for (int m = 0; m < 4; ++m) _Pragma("unroll") for (int k = 0; k < 2; ++k) dst[m][k] = *(const LAS bf16x8*)(lds + PG8_SA(b, h) + aoff + m * 2048 + k * 1024); } while (0)
; #define PG8_LDB(dst, b, h) do { _Pragma("unroll") for (int n = 0; n < 2; ++n) _Pragma("unroll") for (int k = 0; k < 2; ++k) dst[n][k] = *(const LAS bf16x8*)(lds + PG8_SB(b, h) + boff + n * 2048 + k * 1024); } while (0)
; #define PG8_WAIT_V(n) asm volatile("s_waitcnt vmcnt(" #n ")" ::: "memory")
; #define PG8_WAIT_L(n) asm volatile("s_waitcnt lgkmcnt(" #n ")" ::: "memory")
; #define PG8_BAR __builtin_amdgcn_s_barrier()
; #define PG8_SCHED __builtin_amdgcn_sched_barrier(0)
; #define PG8_BAR __builtin_amdgcn_s_barrier()
; template <class Epi>
; DI void gemm_phase(LAS unsigned char* lds, const Gemm g, const StaticOrder S, const Epi E) {
;     ...
;             PG8_WAIT_V(6); PG8_BAR; PG8_MMA(1, 1, At, B1); PG8_BAR;
;             PG8_LDB(B0, 1, 0); PG8_SCHED; PG8_LDA(At, 1, 0); PG8_STAGE(PG8_SA(0, 1), a2 + hstep, voffA);
;             PG8_WAIT_L(8); PG8_BAR; PG8_WAIT_L(0); PG8_MMA(0, 0, At, B0); PG8_BAR; PG8_SCHED;
;             PG8_LDB(B1, 1, 1); PG8_STAGE(PG8_SB(1, 0), b3, voffB);
;             PG8_BAR; PG8_WAIT_L(0); PG8_MMA(0, 1, At, B1); PG8_BAR;
;             PG8_LDA(At, 1, 1); PG8_STAGE(PG8_SA(1, 0), a3, voffA);
;             PG8_BAR; PG8_WAIT_L(0); PG8_MMA(1, 0, At, B0); PG8_BAR; PG8_SCHED;
;             PG8_STAGE(PG8_SB(1, 1), b3 + hstep, voffB);
;             PG8_WAIT_V(6); PG8_BAR; PG8_MMA(1, 1, At, B1); PG8_BAR;
;     DI void operator()(AccRef acc, const Unit& u, int wr, int wc, int fr, int fq) const {
;         f32x4 ts[2][2];
; #pragma unroll
;         for (int bj = 0; bj < 2; ++bj) { const int tok = u.pn * 256 + bj * 128 + wc * 32 + 8 * fq; ts[bj][0] = *(const f32x4*)(ss + tok); ts[bj][1] = *(const f32x4*)(ss + tok + 4); }
; #pragma unroll
;         for (int bj = 0; bj < 2; ++bj)
; #pragma unroll
;             for (int n = 0; n < 2; ++n)
; #pragma unroll
;                 for (int e = 0; e < 4; ++e) ts[bj][n][e] = rsqrtf(ts[bj][n][e] * (1.0f / 1024.0f) + 1e-6f);
	ds_read_b128 v[176:179], v169 offset:50176
	ds_read_b128 v[184:187], v169 offset:52224
	ds_read_b128 v[192:195], v169 offset:54272
	ds_read_b128 v[200:203], v169 offset:56320
	s_waitcnt lgkmcnt(4)
	v_mfma_f32_16x16x32_bf16 v[60:63], v[128:131], v[172:175], v[60:63]
	v_mfma_f32_16x16x32_bf16 v[56:59], v[154:157], v[172:175], v[56:59]
	v_mfma_f32_16x16x32_bf16 v[48:51], v[128:131], v[180:183], v[48:51]
	v_mfma_f32_16x16x32_bf16 v[40:43], v[154:157], v[180:183], v[40:43]
	v_mfma_f32_16x16x32_bf16 v[32:35], v[128:131], v[188:191], v[32:35]
	v_mfma_f32_16x16x32_bf16 v[24:27], v[154:157], v[188:191], v[24:27]
	v_mfma_f32_16x16x32_bf16 v[16:19], v[128:131], v[196:199], v[16:19]
	v_mfma_f32_16x16x32_bf16 v[8:11], v[154:157], v[196:199], v[8:11]
	s_waitcnt lgkmcnt(3)
	v_mfma_f32_16x16x32_bf16 v[60:63], v[132:135], v[176:179], v[60:63]
	v_mfma_f32_16x16x32_bf16 v[56:59], v[158:161], v[176:179], v[56:59]
	s_waitcnt lgkmcnt(2)
	v_mfma_f32_16x16x32_bf16 v[48:51], v[132:135], v[184:187], v[48:51]
	v_mfma_f32_16x16x32_bf16 v[40:43], v[158:161], v[184:187], v[40:43]
	s_waitcnt lgkmcnt(1)
	v_mfma_f32_16x16x32_bf16 v[32:35], v[132:135], v[192:195], v[32:35]
	v_mfma_f32_16x16x32_bf16 v[24:27], v[158:161], v[192:195], v[24:27]
	s_waitcnt lgkmcnt(0)
	s_setprio 2
	s_barrier
	v_mfma_f32_16x16x32_bf16 v[16:19], v[132:135], v[200:203], v[16:19]
	v_mfma_f32_16x16x32_bf16 v[8:11], v[158:161], v[200:203], v[8:11]
	s_setprio 0
	s_add_u32 s14, s78, 0x40080
	s_addc_u32 s15, s79, 0
	s_add_i32 s5, s35, s19
	v_lshl_add_u64 v[128:129], s[14:15], 0, v[138:139]
	s_mov_b32 m0, s5
	s_nop 0
	global_load_lds_dwordx4 v[128:129], off
	v_lshl_add_u64 v[128:129], s[14:15], 0, v[142:143]
	s_add_i32 m0, s5, 0x2000
	s_nop 0
	global_load_lds_dwordx4 v[128:129], off
	s_waitcnt vmcnt(6)
	s_setprio 1
	s_barrier
	v_mfma_f32_16x16x32_bf16 v[52:55], v[204:207], v[172:175], v[52:55]
	v_mfma_f32_16x16x32_bf16 v[44:47], v[212:215], v[172:175], v[44:47]
	v_mfma_f32_16x16x32_bf16 v[36:39], v[204:207], v[180:183], v[36:39]
	v_mfma_f32_16x16x32_bf16 v[28:31], v[212:215], v[180:183], v[28:31]
	v_mfma_f32_16x16x32_bf16 v[20:23], v[204:207], v[188:191], v[20:23]
	v_mfma_f32_16x16x32_bf16 v[12:15], v[212:215], v[188:191], v[12:15]
	v_mfma_f32_16x16x32_bf16 v[4:7], v[204:207], v[196:199], v[4:7]
	v_mfma_f32_16x16x32_bf16 v[0:3], v[212:215], v[196:199], v[0:3]
	v_mfma_f32_16x16x32_bf16 v[52:55], v[208:211], v[176:179], v[52:55]
	v_mfma_f32_16x16x32_bf16 v[44:47], v[216:219], v[176:179], v[44:47]
	v_mfma_f32_16x16x32_bf16 v[36:39], v[208:211], v[184:187], v[36:39]
	v_mfma_f32_16x16x32_bf16 v[28:31], v[216:219], v[184:187], v[28:31]
	v_mfma_f32_16x16x32_bf16 v[20:23], v[208:211], v[192:195], v[20:23]
	s_setprio 2
	s_barrier
	v_mfma_f32_16x16x32_bf16 v[12:15], v[216:219], v[192:195], v[12:15]
	v_mfma_f32_16x16x32_bf16 v[4:7], v[208:211], v[200:203], v[4:7]
	v_mfma_f32_16x16x32_bf16 v[0:3], v[216:219], v[200:203], v[0:3]
	s_setprio 0
	s_add_i32 s4, s4, 2
	s_add_u32 s8, s8, 0x100
	s_addc_u32 s9, s9, 0
	s_add_u32 vcc_lo, vcc_lo, 0x100
	s_addc_u32 vcc_hi, vcc_hi, 0
	s_cmp_gt_u32 s4, 13
	s_cbranch_scc0 .LBB0_298
	s_lshl_b32 s4, s97, 8
	v_or_b32_e32 v128, s4, v166
	v_ashrrev_i32_e32 v129, 31, v128
	v_lshl_add_u64 v[132:133], v[128:129], 2, s[60:61]
	global_load_dwordx4 v[158:161], v[132:133], off offset:16
	global_load_dwordx4 v[154:157], v[132:133], off
	global_load_dwordx4 v[128:131], v[132:133], off offset:528
	s_nop 0
	global_load_dwordx4 v[132:135], v[132:133], off offset:512
	s_mov_b32 s6, 0x358637bd
	v_mov_b64_e32 v[162:163], s[6:7]
	s_lshl_b32 s6, s76, 8
	s_add_i32 s6, s6, s84
	s_lshr_b32 s5, s97, 3
	s_and_b32 s7, s5, 0x1fffc
	s_bfe_u32 s5, s6, 0x20008
	s_or_b32 s4, s4, s85
	s_or_b32 s5, s5, s7
	s_cmpk_lt_u32 s6, 0x400
	s_mov_b32 s97, s20
	s_mov_b32 s76, s22
	s_mov_b64 s[78:79], s[28:29]
	s_waitcnt vmcnt(0)
	v_pk_fma_f32 v[158:159], v[158:159], s[16:17], v[162:163] op_sel_hi:[1,0,0]
	v_pk_fma_f32 v[154:155], v[154:155], s[16:17], v[162:163] op_sel_hi:[1,0,0]
	v_pk_fma_f32 v[156:157], v[156:157], s[16:17], v[162:163] op_sel_hi:[1,0,0]
	v_mul_f32_e32 v171, 0x4b800000, v154
	v_cmp_gt_f32_e64 s[8:9], s96, v154
	v_cmp_gt_f32_e32 vcc, s96, v155
	v_pk_fma_f32 v[160:161], v[160:161], s[16:17], v[162:163] op_sel_hi:[1,0,0]
	v_cndmask_b32_e64 v154, v154, v171, s[8:9]
	v_mul_f32_e32 v171, 0x4b800000, v155
	v_cndmask_b32_e32 v155, v155, v171, vcc
	v_rsq_f32_e32 v154, v154
	v_rsq_f32_e32 v155, v155
	v_mul_f32_e32 v171, 0x4b800000, v156
	v_pk_fma_f32 v[132:133], v[132:133], s[16:17], v[162:163] op_sel_hi:[1,0,0]
	v_pk_fma_f32 v[134:135], v[134:135], s[16:17], v[162:163] op_sel_hi:[1,0,0]
	v_pk_mul_f32 v[172:173], v[154:155], s[18:19] op_sel_hi:[1,0]
	v_pk_fma_f32 v[128:129], v[128:129], s[16:17], v[162:163] op_sel_hi:[1,0,0]
	v_cndmask_b32_e64 v154, v154, v172, s[8:9]
	v_cmp_gt_f32_e64 s[8:9], s96, v156
	v_cndmask_b32_e32 v155, v155, v173, vcc
	v_cmp_gt_f32_e32 vcc, s96, v157
	v_cndmask_b32_e64 v156, v156, v171, s[8:9]
	v_mul_f32_e32 v171, 0x4b800000, v157
	v_cndmask_b32_e32 v157, v157, v171, vcc
	v_rsq_f32_e32 v156, v156
	v_rsq_f32_e32 v157, v157
	v_mul_f32_e32 v171, 0x4b800000, v158
	v_pk_fma_f32 v[130:131], v[130:131], s[16:17], v[162:163] op_sel_hi:[1,0,0]
	v_pk_mul_f32 v[124:125], v[124:125], v[154:155]
	v_pk_mul_f32 v[172:173], v[156:157], s[18:19] op_sel_hi:[1,0]
	v_mul_f32_e32 v162, 0x4b800000, v130
	v_cndmask_b32_e64 v156, v156, v172, s[8:9]
	v_cmp_gt_f32_e64 s[8:9], s96, v158
	v_cndmask_b32_e32 v157, v157, v173, vcc
	v_cmp_gt_f32_e32 vcc, s96, v159
	v_cndmask_b32_e64 v158, v158, v171, s[8:9]
	v_mul_f32_e32 v171, 0x4b800000, v159
	v_cndmask_b32_e32 v159, v159, v171, vcc
	v_rsq_f32_e32 v158, v158
; DI unsigned pk_bf16(float lo, float hi) { f32x2 v = {lo, hi}; return __builtin_bit_cast(unsigned, __builtin_convertvector(v, bf16v2)); }
;     DI void operator()(AccRef acc, const Unit& u, int wr, int wc, int fr, int fq) const {
;         f32x4 ts[2][2];
; #pragma unroll
;         for (int bj = 0; bj < 2; ++bj) { const int tok = u.pn * 256 + bj * 128 + wc * 32 + 8 * fq; ts[bj][0] = *(const f32x4*)(ss + tok); ts[bj][1] = *(const f32x4*)(ss + tok + 4); }
; #pragma unroll
;         for (int bj = 0; bj < 2; ++bj)
; #pragma unroll
;             for (int n = 0; n < 2; ++n)
; #pragma unroll
;                 for (int e = 0; e < 4; ++e) ts[bj][n][e] = rsqrtf(ts[bj][n][e] * (1.0f / 1024.0f) + 1e-6f);
; #pragma unroll
;         for (int ai = 0; ai < 2; ++ai)
; #pragma unroll
;             for (int m = 0; m < 4; ++m) {
;                 const int R = u.pm * 256 + ai * 128 + wr * 64 + m * 16 + fr, X = R >> 10, hv = R & 1023;
; #pragma unroll
;                 for (int bj = 0; bj < 2; ++bj) {
;                     const int tok = u.pn * 256 + bj * 128 + wc * 32 + 8 * fq, b = tok >> 13, s = tok & (SEQ - 1);
;                     bf16_t* dst = (X ? vtB : vtA) + ((size_t)(((b * 4 + (hv >> 8)) * 128 + (s >> 6)) * 256 + (hv & 255))) * 64 + (s & 63);
;                     const f32x4 v0 = acc[ai][bj][m][0] * ts[bj][0], v1 = acc[ai][bj][m][1] * ts[bj][1];
;                     u32x4 w; w.x = pk_bf16(v0[0], v0[1]); w.y = pk_bf16(v0[2], v0[3]); w.z = pk_bf16(v1[0], v1[1]); w.w = pk_bf16(v1[2], v1[3]);
;                     *(u32x4*)dst = w;
	v_rsq_f32_e32 v159, v159
	v_mul_f32_e32 v171, 0x4b800000, v160
	v_pk_mul_f32 v[126:127], v[126:127], v[156:157]
	v_pk_mul_f32 v[112:113], v[112:113], v[154:155]
	v_pk_mul_f32 v[172:173], v[158:159], s[18:19] op_sel_hi:[1,0]
	v_pk_mul_f32 v[96:97], v[96:97], v[154:155]
	v_cndmask_b32_e64 v158, v158, v172, s[8:9]
	v_cmp_gt_f32_e64 s[8:9], s96, v160
	v_cndmask_b32_e32 v159, v159, v173, vcc
	v_cmp_gt_f32_e32 vcc, s96, v161
	v_cndmask_b32_e64 v160, v160, v171, s[8:9]
	v_mul_f32_e32 v171, 0x4b800000, v161
	v_cndmask_b32_e32 v161, v161, v171, vcc
	v_rsq_f32_e32 v160, v160
	v_rsq_f32_e32 v161, v161
	v_mul_f32_e32 v171, 0x4b800000, v132
	v_pk_mul_f32 v[80:81], v[80:81], v[154:155]
	v_pk_mul_f32 v[62:63], v[62:63], v[156:157]
	v_pk_mul_f32 v[172:173], v[160:161], s[18:19] op_sel_hi:[1,0]
	v_pk_mul_f32 v[60:61], v[60:61], v[154:155]
	v_cndmask_b32_e64 v160, v160, v172, s[8:9]
	v_cmp_gt_f32_e64 s[8:9], s96, v132
	v_cndmask_b32_e32 v161, v161, v173, vcc
	v_cmp_gt_f32_e32 vcc, s96, v133
	v_cndmask_b32_e64 v132, v132, v171, s[8:9]
	v_mul_f32_e32 v171, 0x4b800000, v133
	v_cndmask_b32_e32 v133, v133, v171, vcc
	v_rsq_f32_e32 v132, v132
	v_rsq_f32_e32 v133, v133
	v_mul_f32_e32 v171, 0x4b800000, v134
	v_pk_mul_f32 v[48:49], v[48:49], v[154:155]
	v_pk_mul_f32 v[32:33], v[32:33], v[154:155]
	v_pk_mul_f32 v[172:173], v[132:133], s[18:19] op_sel_hi:[1,0]
	v_pk_mul_f32 v[16:17], v[16:17], v[154:155]
	v_cndmask_b32_e64 v132, v132, v172, s[8:9]
	v_cmp_gt_f32_e64 s[8:9], s96, v134
	v_cndmask_b32_e32 v133, v133, v173, vcc
	v_cmp_gt_f32_e32 vcc, s96, v135
	v_cndmask_b32_e64 v134, v134, v171, s[8:9]
	v_mul_f32_e32 v171, 0x4b800000, v135
	v_cndmask_b32_e32 v135, v135, v171, vcc
	v_rsq_f32_e32 v134, v134
	v_rsq_f32_e32 v135, v135
	v_mul_f32_e32 v171, 0x4b800000, v128
	v_pk_mul_f32 v[116:117], v[116:117], v[132:133]
	v_pk_mul_f32 v[100:101], v[100:101], v[132:133]
	v_pk_mul_f32 v[172:173], v[134:135], s[18:19] op_sel_hi:[1,0]
	v_pk_mul_f32 v[84:85], v[84:85], v[132:133]
	v_cndmask_b32_e64 v134, v134, v172, s[8:9]
	v_cmp_gt_f32_e64 s[8:9], s96, v128
	v_cndmask_b32_e32 v135, v135, v173, vcc
	v_cmp_gt_f32_e32 vcc, s96, v129
	v_cndmask_b32_e64 v128, v128, v171, s[8:9]
	v_mul_f32_e32 v171, 0x4b800000, v129
	v_cndmask_b32_e32 v129, v129, v171, vcc
	v_rsq_f32_e32 v128, v128
	v_rsq_f32_e32 v129, v129
	v_lshl_or_b32 v171, s5, 15, v167
	v_pk_mul_f32 v[118:119], v[118:119], v[134:135]
	v_pk_mul_f32 v[102:103], v[102:103], v[134:135]
	v_pk_mul_f32 v[172:173], v[128:129], s[18:19] op_sel_hi:[1,0]
	v_pk_mul_f32 v[86:87], v[86:87], v[134:135]
	v_cndmask_b32_e64 v128, v128, v172, s[8:9]
	v_cmp_gt_f32_e64 s[8:9], s96, v130
	v_cndmask_b32_e32 v129, v129, v173, vcc
	v_cmp_gt_f32_e32 vcc, s96, v131
	v_cndmask_b32_e64 v130, v130, v162, s[8:9]
	v_mul_f32_e32 v162, 0x4b800000, v131
	v_cndmask_b32_e32 v131, v131, v162, vcc
	v_rsq_f32_e32 v130, v130
	v_rsq_f32_e32 v131, v131
	v_pk_mul_f32 v[172:173], v[122:123], v[160:161]
	v_pk_mul_f32 v[122:123], v[120:121], v[158:159]
	v_cvt_pk_bf16_f32 v120, v124, v125
	v_pk_mul_f32 v[162:163], v[130:131], s[18:19] op_sel_hi:[1,0]
	v_cvt_pk_bf16_f32 v121, v126, v127
	v_cndmask_b32_e64 v130, v130, v162, s[8:9]
	s_cselect_b32 s9, s53, s91
	s_cselect_b32 s8, s52, s90
	s_lshl_b32 s4, s4, 2
	s_and_b32 s4, s4, 0x7d00
	v_or_b32_e32 v162, s4, v171
	v_cndmask_b32_e32 v131, v131, v163, vcc
	v_ashrrev_i32_e32 v163, 31, v162
	v_lshlrev_b64 v[162:163], 7, v[162:163]
	v_lshl_add_u64 v[162:163], s[8:9], 0, v[162:163]
	v_lshl_add_u64 v[162:163], v[162:163], 0, v[144:145]
	v_cvt_pk_bf16_f32 v122, v122, v123
	v_cvt_pk_bf16_f32 v123, v172, v173
	s_or_b32 s5, s4, 0x200
	global_store_dwordx4 v[162:163], v[120:123], off
	s_addk_i32 s6, 0x80
	v_pk_mul_f32 v[70:71], v[70:71], v[134:135]
	v_or_b32_e32 v120, s5, v171
	v_ashrrev_i32_e32 v121, 31, v120
	v_lshlrev_b64 v[120:121], 7, v[120:121]
	v_lshl_add_u64 v[120:121], s[8:9], 0, v[120:121]
	v_pk_mul_f32 v[122:123], v[110:111], v[130:131]
	v_pk_mul_f32 v[110:111], v[108:109], v[128:129]
	v_lshl_add_u64 v[120:121], v[120:121], 0, v[144:145]
	v_cvt_pk_bf16_f32 v108, v116, v117
	v_cvt_pk_bf16_f32 v109, v118, v119
	v_cvt_pk_bf16_f32 v110, v110, v111
	v_cvt_pk_bf16_f32 v111, v122, v123
	v_or_b32_e32 v116, 16, v171
	global_store_dwordx4 v[120:121], v[108:111], off
	v_pk_mul_f32 v[68:69], v[68:69], v[132:133]
	v_pk_mul_f32 v[54:55], v[54:55], v[134:135]
	v_or_b32_e32 v108, s4, v116
	v_ashrrev_i32_e32 v109, 31, v108
	v_lshlrev_b64 v[108:109], 7, v[108:109]
	v_lshl_add_u64 v[108:109], s[8:9], 0, v[108:109]
	v_pk_mul_f32 v[110:111], v[114:115], v[156:157]
	v_pk_mul_f32 v[114:115], v[106:107], v[160:161]
	v_pk_mul_f32 v[106:107], v[104:105], v[158:159]
	v_lshl_add_u64 v[108:109], v[108:109], 0, v[144:145]
	v_cvt_pk_bf16_f32 v104, v112, v113
	v_cvt_pk_bf16_f32 v105, v110, v111
	v_cvt_pk_bf16_f32 v106, v106, v107
	v_cvt_pk_bf16_f32 v107, v114, v115
	global_store_dwordx4 v[108:109], v[104:107], off
	v_pk_mul_f32 v[52:53], v[52:53], v[132:133]
	v_pk_mul_f32 v[38:39], v[38:39], v[134:135]
	v_or_b32_e32 v104, s5, v116
	v_ashrrev_i32_e32 v105, 31, v104
	v_lshlrev_b64 v[104:105], 7, v[104:105]
	v_lshl_add_u64 v[104:105], s[8:9], 0, v[104:105]
	v_pk_mul_f32 v[106:107], v[94:95], v[130:131]
	v_pk_mul_f32 v[94:95], v[92:93], v[128:129]
	v_lshl_add_u64 v[104:105], v[104:105], 0, v[144:145]
	v_cvt_pk_bf16_f32 v92, v100, v101
	v_cvt_pk_bf16_f32 v93, v102, v103
	v_cvt_pk_bf16_f32 v94, v94, v95
	v_cvt_pk_bf16_f32 v95, v106, v107
	v_or_b32_e32 v100, 32, v171
	global_store_dwordx4 v[104:105], v[92:95], off
	v_pk_mul_f32 v[36:37], v[36:37], v[132:133]
	v_pk_mul_f32 v[22:23], v[22:23], v[134:135]
	v_or_b32_e32 v92, s4, v100
	v_ashrrev_i32_e32 v93, 31, v92
; DI unsigned pk_bf16(float lo, float hi) { f32x2 v = {lo, hi}; return __builtin_bit_cast(unsigned, __builtin_convertvector(v, bf16v2)); }
;     DI void operator()(AccRef acc, const Unit& u, int wr, int wc, int fr, int fq) const {
;     ...
;                 const int R = u.pm * 256 + ai * 128 + wr * 64 + m * 16 + fr, X = R >> 10, hv = R & 1023;
; #pragma unroll
;                 for (int bj = 0; bj < 2; ++bj) {
;                     const int tok = u.pn * 256 + bj * 128 + wc * 32 + 8 * fq, b = tok >> 13, s = tok & (SEQ - 1);
;                     bf16_t* dst = (X ? vtB : vtA) + ((size_t)(((b * 4 + (hv >> 8)) * 128 + (s >> 6)) * 256 + (hv & 255))) * 64 + (s & 63);
;                     const f32x4 v0 = acc[ai][bj][m][0] * ts[bj][0], v1 = acc[ai][bj][m][1] * ts[bj][1];
;                     u32x4 w; w.x = pk_bf16(v0[0], v0[1]); w.y = pk_bf16(v0[2], v0[3]); w.z = pk_bf16(v1[0], v1[1]); w.w = pk_bf16(v1[2], v1[3]);
;                     *(u32x4*)dst = w;
;                 }
;             }
	v_lshlrev_b64 v[92:93], 7, v[92:93]
	v_lshl_add_u64 v[92:93], s[8:9], 0, v[92:93]
	v_pk_mul_f32 v[94:95], v[98:99], v[156:157]
	v_pk_mul_f32 v[98:99], v[90:91], v[160:161]
	v_pk_mul_f32 v[90:91], v[88:89], v[158:159]
	v_lshl_add_u64 v[92:93], v[92:93], 0, v[144:145]
	v_cvt_pk_bf16_f32 v88, v96, v97
	v_cvt_pk_bf16_f32 v89, v94, v95
	v_cvt_pk_bf16_f32 v90, v90, v91
	v_cvt_pk_bf16_f32 v91, v98, v99
	global_store_dwordx4 v[92:93], v[88:91], off
	v_pk_mul_f32 v[20:21], v[20:21], v[132:133]
	v_pk_mul_f32 v[6:7], v[6:7], v[134:135]
	v_or_b32_e32 v88, s5, v100
	v_ashrrev_i32_e32 v89, 31, v88
	v_lshlrev_b64 v[88:89], 7, v[88:89]
	v_lshl_add_u64 v[88:89], s[8:9], 0, v[88:89]
	v_pk_mul_f32 v[90:91], v[78:79], v[130:131]
	v_pk_mul_f32 v[78:79], v[76:77], v[128:129]
	v_lshl_add_u64 v[88:89], v[88:89], 0, v[144:145]
	v_cvt_pk_bf16_f32 v76, v84, v85
	v_cvt_pk_bf16_f32 v77, v86, v87
	v_cvt_pk_bf16_f32 v78, v78, v79
	v_cvt_pk_bf16_f32 v79, v90, v91
	v_or_b32_e32 v84, 48, v171
	global_store_dwordx4 v[88:89], v[76:79], off
	v_pk_mul_f32 v[4:5], v[4:5], v[132:133]
	s_nop 0
	v_or_b32_e32 v76, s4, v84
	v_ashrrev_i32_e32 v77, 31, v76
	v_lshlrev_b64 v[76:77], 7, v[76:77]
	v_lshl_add_u64 v[76:77], s[8:9], 0, v[76:77]
	v_pk_mul_f32 v[78:79], v[82:83], v[156:157]
	v_pk_mul_f32 v[82:83], v[74:75], v[160:161]
	v_pk_mul_f32 v[74:75], v[72:73], v[158:159]
	v_lshl_add_u64 v[76:77], v[76:77], 0, v[144:145]
	v_cvt_pk_bf16_f32 v72, v80, v81
	v_cvt_pk_bf16_f32 v73, v78, v79
	v_cvt_pk_bf16_f32 v74, v74, v75
	v_cvt_pk_bf16_f32 v75, v82, v83
	global_store_dwordx4 v[76:77], v[72:75], off
	s_nop 1
	v_or_b32_e32 v72, s5, v84
	v_ashrrev_i32_e32 v73, 31, v72
	v_lshlrev_b64 v[72:73], 7, v[72:73]
	v_lshl_add_u64 v[72:73], s[8:9], 0, v[72:73]
	s_bfe_u32 s8, s6, 0x20008
	s_or_b32 s7, s8, s7
	s_lshl_b32 s7, s7, 15
	s_and_b32 s8, s6, 0xc0
	v_pk_mul_f32 v[74:75], v[66:67], v[130:131]
	v_pk_mul_f32 v[66:67], v[64:65], v[128:129]
	s_or_b32 s7, s7, s8
	v_lshl_add_u64 v[72:73], v[72:73], 0, v[144:145]
	v_cvt_pk_bf16_f32 v64, v68, v69
	v_cvt_pk_bf16_f32 v65, v70, v71
	v_cvt_pk_bf16_f32 v66, v66, v67
	v_cvt_pk_bf16_f32 v67, v74, v75
	v_or_b32_e32 v68, s7, v164
	global_store_dwordx4 v[72:73], v[64:67], off
	s_cmpk_lt_u32 s6, 0x400
	s_cselect_b32 s9, s53, s91
	v_or_b32_e32 v64, s4, v68
	v_ashrrev_i32_e32 v65, 31, v64
	s_cselect_b32 s8, s52, s90
	v_lshlrev_b64 v[64:65], 7, v[64:65]
	v_lshl_add_u64 v[64:65], s[8:9], 0, v[64:65]
	v_pk_mul_f32 v[66:67], v[58:59], v[160:161]
	v_pk_mul_f32 v[58:59], v[56:57], v[158:159]
	v_lshl_add_u64 v[64:65], v[64:65], 0, v[144:145]
	v_cvt_pk_bf16_f32 v56, v60, v61
	v_cvt_pk_bf16_f32 v57, v62, v63
	v_cvt_pk_bf16_f32 v58, v58, v59
	v_cvt_pk_bf16_f32 v59, v66, v67
	global_store_dwordx4 v[64:65], v[56:59], off
	s_and_b64 vcc, exec, s[0:1]
	s_nop 0
	v_or_b32_e32 v56, s5, v68
	v_ashrrev_i32_e32 v57, 31, v56
	v_lshlrev_b64 v[56:57], 7, v[56:57]
	v_lshl_add_u64 v[56:57], s[8:9], 0, v[56:57]
	v_pk_mul_f32 v[58:59], v[46:47], v[130:131]
	v_pk_mul_f32 v[46:47], v[44:45], v[128:129]
	v_lshl_add_u64 v[56:57], v[56:57], 0, v[144:145]
	v_cvt_pk_bf16_f32 v44, v52, v53
	v_cvt_pk_bf16_f32 v45, v54, v55
	v_cvt_pk_bf16_f32 v46, v46, v47
	v_cvt_pk_bf16_f32 v47, v58, v59
	v_or_b32_e32 v52, 16, v68
	global_store_dwordx4 v[56:57], v[44:47], off
	s_nop 1
	v_or_b32_e32 v44, s4, v52
	v_ashrrev_i32_e32 v45, 31, v44
	v_lshlrev_b64 v[44:45], 7, v[44:45]
	v_lshl_add_u64 v[44:45], s[8:9], 0, v[44:45]
	v_pk_mul_f32 v[46:47], v[50:51], v[156:157]
	v_pk_mul_f32 v[50:51], v[42:43], v[160:161]
	v_pk_mul_f32 v[42:43], v[40:41], v[158:159]
	v_lshl_add_u64 v[44:45], v[44:45], 0, v[144:145]
	v_cvt_pk_bf16_f32 v40, v48, v49
	v_cvt_pk_bf16_f32 v41, v46, v47
	v_cvt_pk_bf16_f32 v42, v42, v43
	v_cvt_pk_bf16_f32 v43, v50, v51
	global_store_dwordx4 v[44:45], v[40:43], off
	s_nop 1
	v_or_b32_e32 v40, s5, v52
	v_ashrrev_i32_e32 v41, 31, v40
	v_lshlrev_b64 v[40:41], 7, v[40:41]
	v_lshl_add_u64 v[40:41], s[8:9], 0, v[40:41]
	v_pk_mul_f32 v[42:43], v[30:31], v[130:131]
	v_pk_mul_f32 v[30:31], v[28:29], v[128:129]
	v_lshl_add_u64 v[40:41], v[40:41], 0, v[144:145]
	v_cvt_pk_bf16_f32 v28, v36, v37
	v_cvt_pk_bf16_f32 v29, v38, v39
	v_cvt_pk_bf16_f32 v30, v30, v31
	v_cvt_pk_bf16_f32 v31, v42, v43
	v_or_b32_e32 v36, 32, v68
	global_store_dwordx4 v[40:41], v[28:31], off
	s_nop 1
	v_or_b32_e32 v28, s4, v36
	v_ashrrev_i32_e32 v29, 31, v28
	v_lshlrev_b64 v[28:29], 7, v[28:29]
	v_lshl_add_u64 v[28:29], s[8:9], 0, v[28:29]
	v_pk_mul_f32 v[30:31], v[34:35], v[156:157]
	v_pk_mul_f32 v[34:35], v[26:27], v[160:161]
	v_pk_mul_f32 v[26:27], v[24:25], v[158:159]
	v_lshl_add_u64 v[28:29], v[28:29], 0, v[144:145]
	v_cvt_pk_bf16_f32 v24, v32, v33
	v_cvt_pk_bf16_f32 v25, v30, v31
	v_cvt_pk_bf16_f32 v26, v26, v27
	v_cvt_pk_bf16_f32 v27, v34, v35
	global_store_dwordx4 v[28:29], v[24:27], off
	s_nop 1
	v_or_b32_e32 v24, s5, v36
	v_ashrrev_i32_e32 v25, 31, v24
	v_lshlrev_b64 v[24:25], 7, v[24:25]
	v_lshl_add_u64 v[24:25], s[8:9], 0, v[24:25]
	v_pk_mul_f32 v[26:27], v[14:15], v[130:131]
	v_pk_mul_f32 v[14:15], v[12:13], v[128:129]
	v_lshl_add_u64 v[24:25], v[24:25], 0, v[144:145]
	v_cvt_pk_bf16_f32 v12, v20, v21
	v_cvt_pk_bf16_f32 v13, v22, v23
	v_cvt_pk_bf16_f32 v14, v14, v15
	v_cvt_pk_bf16_f32 v15, v26, v27
	v_or_b32_e32 v20, 48, v68
	global_store_dwordx4 v[24:25], v[12:15], off
	s_nop 1
	v_or_b32_e32 v12, s4, v20
	v_ashrrev_i32_e32 v13, 31, v12
	v_lshlrev_b64 v[12:13], 7, v[12:13]
	v_lshl_add_u64 v[12:13], s[8:9], 0, v[12:13]
	v_pk_mul_f32 v[14:15], v[18:19], v[156:157]
	v_pk_mul_f32 v[18:19], v[10:11], v[160:161]
	v_pk_mul_f32 v[10:11], v[8:9], v[158:159]
	v_lshl_add_u64 v[12:13], v[12:13], 0, v[144:145]
	v_cvt_pk_bf16_f32 v8, v16, v17
	v_cvt_pk_bf16_f32 v9, v14, v15
	v_cvt_pk_bf16_f32 v10, v10, v11
	v_cvt_pk_bf16_f32 v11, v18, v19
	global_store_dwordx4 v[12:13], v[8:11], off
	s_nop 1
	v_or_b32_e32 v8, s5, v20
	v_ashrrev_i32_e32 v9, 31, v8
	v_lshlrev_b64 v[8:9], 7, v[8:9]
	v_lshl_add_u64 v[8:9], s[8:9], 0, v[8:9]
	v_pk_mul_f32 v[10:11], v[2:3], v[130:131]
	v_pk_mul_f32 v[2:3], v[0:1], v[128:129]
	v_lshl_add_u64 v[8:9], v[8:9], 0, v[144:145]
	v_cvt_pk_bf16_f32 v0, v4, v5
	v_cvt_pk_bf16_f32 v1, v6, v7
	v_cvt_pk_bf16_f32 v2, v2, v3
	v_cvt_pk_bf16_f32 v3, v10, v11
	s_mov_b64 s[8:9], s[24:25]
	global_store_dwordx4 v[8:9], v[0:3], off
	s_cbranch_vccz .LBB0_291
	s_waitcnt vmcnt(0)
	s_cmpk_gt_u32 s17, 0xff
	s_cbranch_scc1 .LBB0_302
	s_barrier

; #define PG8_STAGE(bufoff, gbase, voff) do { _Pragma("unroll") for (int _i = 0; _i < 2; ++_i) \
;         __builtin_amdgcn_global_load_lds((const unsigned*)((const char*)(gbase) + (voff)[_i]), (LAS unsigned*)(lds + (bufoff) + ldsw + _i * 8192), 16, 0, 0); } while (0)
; #define PG8_LDA(dst, b, h) do { _Pragma("unroll") for (int m = 0; m < 4; ++m) _Pragma("unroll") for (int k = 0; k < 2; ++k) dst[m][k] = *(const LAS bf16x8*)(lds + PG8_SA(b, h) + aoff + m * 2048 + k * 1024); } while (0)
; #define PG8_LDB(dst, b, h) do { _Pragma("unroll") for (int n = 0; n < 2; ++n) _Pragma("unroll") for (int k = 0; k < 2; ++k) dst[n][k] = *(const LAS bf16x8*)(lds + PG8_SB(b, h) + boff + n * 2048 + k * 1024); } while (0)
; #define PG8_MMA(ai, bj, At, Bt) do { __builtin_amdgcn_s_setprio(1); _Pragma("unroll") for (int m = 0; m < 4; ++m) _Pragma("unroll") for (int n = 0; n < 2; ++n) _Pragma("unroll") for (int k = 0; k < 2; ++k) \
;         acc[ai][bj][m][n] = __builtin_amdgcn_mfma_f32_16x16x32_bf16(Bt[n][k], At[m][k], acc[ai][bj][m][n], 0, 0, 0); __builtin_amdgcn_s_setprio(0); } while (0)
; #define PG8_WAIT_V(n) asm volatile("s_waitcnt vmcnt(" #n ")" ::: "memory")
; #define PG8_WAIT_L(n) asm volatile("s_waitcnt lgkmcnt(" #n ")" ::: "memory")
; template <class Epi0, class Epi1>
; DI void gemm_phase_dual(LAS unsigned char* lds, const Gemm g, const Gemm g1, const StaticOrder S, const Epi0 E0, const Epi1 E1) {
;     ...
;         for (int t = 0; t < nt; t += 2) {
;             const bool last = (t == nt - 2);
;             const char* a1 = cA + (size_t)(t + 1) * kstep;
;             const char* a2 = last ? nA : cA + (size_t)(t + 2) * kstep; const char* b2 = last ? nB : cB + (size_t)(t + 2) * kstep;
;             const char* a3 = a2 + kstep; const char* b3 = b2 + kstep;
;             PG8_LDB(B0, 0, 0); PG8_SCHED; PG8_LDA(At, 0, 0); PG8_STAGE(PG8_SA(1, 1), a1 + hstep, voffA);
;             PG8_WAIT_L(8); PG8_BAR; PG8_WAIT_L(0); PG8_MMA(0, 0, At, B0); PG8_BAR; PG8_SCHED;
;             PG8_LDB(B1, 0, 1); PG8_STAGE(PG8_SB(0, 0), b2, voffB);
;             PG8_BAR; PG8_WAIT_L(0); PG8_MMA(0, 1, At, B1); PG8_BAR;
;             PG8_LDA(At, 0, 1); PG8_STAGE(PG8_SA(0, 0), a2, voffA);
;             PG8_BAR; PG8_WAIT_L(0); PG8_MMA(1, 0, At, B0); PG8_BAR; PG8_SCHED;
;             PG8_STAGE(PG8_SB(0, 1), b2 + hstep, voffB);
;             PG8_WAIT_V(6); PG8_BAR; PG8_MMA(1, 1, At, B1); PG8_BAR;
.LBB0_632:
	ds_read_b128 v[128:131], v181
	ds_read_b128 v[132:135], v181 offset:1024
	ds_read_b128 v[136:139], v181 offset:2048
	ds_read_b128 v[140:143], v181 offset:3072
	s_add_u32 s12, s10, 0xfffc0080
	s_addc_u32 s13, s11, -1
	s_cmp_eq_u32 s19, 12
	s_cselect_b32 s15, s1, s13
	s_cselect_b32 s14, s6, s12
	s_cselect_b32 s13, s7, s18
	s_cselect_b32 s12, s16, s17
	v_lshl_add_u64 v[190:191], s[10:11], 0, v[168:169]
	s_add_i32 m0, s49, 0xc000
	ds_read_b128 v[144:147], v183
	ds_read_b128 v[152:155], v183 offset:2048
	ds_read_b128 v[194:197], v183 offset:4096
	ds_read_b128 v[202:205], v183 offset:6144
	global_load_lds_dwordx4 v[190:191], off
	v_lshl_add_u64 v[190:191], s[10:11], 0, v[170:171]
	s_add_i32 m0, s49, 0xe000
	s_nop 0
	global_load_lds_dwordx4 v[190:191], off
	s_waitcnt lgkmcnt(4)
	s_setprio 1
	s_barrier
	ds_read_b128 v[148:151], v183 offset:1024
	ds_read_b128 v[184:187], v183 offset:3072
	ds_read_b128 v[198:201], v183 offset:5120
	ds_read_b128 v[206:209], v183 offset:7168
	s_waitcnt lgkmcnt(4)
	v_mfma_f32_16x16x32_bf16 v[124:127], v[128:131], v[144:147], v[124:127]
	v_mfma_f32_16x16x32_bf16 v[120:123], v[136:139], v[144:147], v[120:123]
	v_mfma_f32_16x16x32_bf16 v[108:111], v[128:131], v[152:155], v[108:111]
	v_mfma_f32_16x16x32_bf16 v[104:107], v[136:139], v[152:155], v[104:107]
	v_mfma_f32_16x16x32_bf16 v[92:95], v[128:131], v[194:197], v[92:95]
	v_mfma_f32_16x16x32_bf16 v[88:91], v[136:139], v[194:197], v[88:91]
	v_mfma_f32_16x16x32_bf16 v[76:79], v[128:131], v[202:205], v[76:79]
	v_mfma_f32_16x16x32_bf16 v[72:75], v[136:139], v[202:205], v[72:75]
	s_waitcnt lgkmcnt(3)
	v_mfma_f32_16x16x32_bf16 v[124:127], v[132:135], v[148:151], v[124:127]
	v_mfma_f32_16x16x32_bf16 v[120:123], v[140:143], v[148:151], v[120:123]
	s_waitcnt lgkmcnt(2)
	v_mfma_f32_16x16x32_bf16 v[108:111], v[132:135], v[184:187], v[108:111]
	v_mfma_f32_16x16x32_bf16 v[104:107], v[140:143], v[184:187], v[104:107]
	s_waitcnt lgkmcnt(1)
	v_mfma_f32_16x16x32_bf16 v[92:95], v[132:135], v[198:201], v[92:95]
	v_mfma_f32_16x16x32_bf16 v[88:91], v[140:143], v[198:201], v[88:91]
	s_waitcnt lgkmcnt(0)
	s_setprio 2
	s_barrier
	v_mfma_f32_16x16x32_bf16 v[76:79], v[132:135], v[206:209], v[76:79]
	v_mfma_f32_16x16x32_bf16 v[72:75], v[140:143], v[206:209], v[72:75]
	s_setprio 0
	s_add_i32 s41, s78, s48
	v_lshl_add_u64 v[190:191], s[12:13], 0, v[158:159]
	s_mov_b32 m0, s41
	ds_read_b128 v[210:213], v189
	ds_read_b128 v[214:217], v189 offset:1024
	ds_read_b128 v[218:221], v189 offset:2048
	ds_read_b128 v[224:227], v189 offset:3072
	global_load_lds_dwordx4 v[190:191], off
	v_lshl_add_u64 v[228:229], s[12:13], 0, v[162:163]
	s_add_i32 m0, s41, 0x2000
	s_nop 0
	global_load_lds_dwordx4 v[228:229], off
	s_setprio 1
	s_barrier
	s_waitcnt lgkmcnt(0)
	v_mfma_f32_16x16x32_bf16 v[116:119], v[210:213], v[144:147], v[116:119]
	v_mfma_f32_16x16x32_bf16 v[112:115], v[218:221], v[144:147], v[112:115]
	v_mfma_f32_16x16x32_bf16 v[100:103], v[210:213], v[152:155], v[100:103]
	v_mfma_f32_16x16x32_bf16 v[96:99], v[218:221], v[152:155], v[96:99]
	v_mfma_f32_16x16x32_bf16 v[84:87], v[210:213], v[194:197], v[84:87]
	v_mfma_f32_16x16x32_bf16 v[80:83], v[218:221], v[194:197], v[80:83]
	v_mfma_f32_16x16x32_bf16 v[68:71], v[210:213], v[202:205], v[68:71]
	v_mfma_f32_16x16x32_bf16 v[64:67], v[218:221], v[202:205], v[64:67]
	v_mfma_f32_16x16x32_bf16 v[116:119], v[214:217], v[148:151], v[116:119]
	v_mfma_f32_16x16x32_bf16 v[112:115], v[224:227], v[148:151], v[112:115]
	v_mfma_f32_16x16x32_bf16 v[100:103], v[214:217], v[184:187], v[100:103]
	v_mfma_f32_16x16x32_bf16 v[96:99], v[224:227], v[184:187], v[96:99]
	v_mfma_f32_16x16x32_bf16 v[84:87], v[214:217], v[198:201], v[84:87]
	s_setprio 2
	s_barrier
	v_mfma_f32_16x16x32_bf16 v[80:83], v[224:227], v[198:201], v[80:83]
	v_mfma_f32_16x16x32_bf16 v[68:71], v[214:217], v[206:209], v[68:71]
	v_mfma_f32_16x16x32_bf16 v[64:67], v[224:227], v[206:209], v[64:67]
	s_setprio 0
	s_mov_b32 m0, s49
	v_lshl_add_u64 v[230:231], s[14:15], 0, v[156:157]
	ds_read_b128 v[144:147], v183 offset:16384
	ds_read_b128 v[152:155], v183 offset:18432
	ds_read_b128 v[194:197], v183 offset:20480
	ds_read_b128 v[202:205], v183 offset:22528
	global_load_lds_dwordx4 v[230:231], off
	v_lshl_add_u64 v[232:233], s[14:15], 0, v[160:161]
	s_mov_b32 m0, s50
	s_nop 0
	global_load_lds_dwordx4 v[232:233], off
	s_setprio 1
	s_barrier
	ds_read_b128 v[148:151], v183 offset:17408
	ds_read_b128 v[184:187], v183 offset:19456
	ds_read_b128 v[198:201], v183 offset:21504
	ds_read_b128 v[206:209], v183 offset:23552
	s_waitcnt lgkmcnt(4)
	v_mfma_f32_16x16x32_bf16 v[60:63], v[128:131], v[144:147], v[60:63]
	v_mfma_f32_16x16x32_bf16 v[56:59], v[136:139], v[144:147], v[56:59]
	v_mfma_f32_16x16x32_bf16 v[44:47], v[128:131], v[152:155], v[44:47]
	v_mfma_f32_16x16x32_bf16 v[40:43], v[136:139], v[152:155], v[40:43]
	v_mfma_f32_16x16x32_bf16 v[28:31], v[128:131], v[194:197], v[28:31]
	v_mfma_f32_16x16x32_bf16 v[24:27], v[136:139], v[194:197], v[24:27]
	v_mfma_f32_16x16x32_bf16 v[12:15], v[128:131], v[202:205], v[12:15]
	v_mfma_f32_16x16x32_bf16 v[8:11], v[136:139], v[202:205], v[8:11]
	s_waitcnt lgkmcnt(3)
	v_mfma_f32_16x16x32_bf16 v[60:63], v[132:135], v[148:151], v[60:63]
	v_mfma_f32_16x16x32_bf16 v[56:59], v[140:143], v[148:151], v[56:59]
	s_waitcnt lgkmcnt(2)
	v_mfma_f32_16x16x32_bf16 v[44:47], v[132:135], v[184:187], v[44:47]
	v_mfma_f32_16x16x32_bf16 v[40:43], v[140:143], v[184:187], v[40:43]
	s_waitcnt lgkmcnt(1)
	v_mfma_f32_16x16x32_bf16 v[28:31], v[132:135], v[198:201], v[28:31]
	v_mfma_f32_16x16x32_bf16 v[24:27], v[140:143], v[198:201], v[24:27]
	s_waitcnt lgkmcnt(0)
	s_setprio 2
	s_barrier
; #define PG8_STAGE(bufoff, gbase, voff) do { _Pragma("unroll") for (int _i = 0; _i < 2; ++_i) \
;         __builtin_amdgcn_global_load_lds((const unsigned*)((const char*)(gbase) + (voff)[_i]), (LAS unsigned*)(lds + (bufoff) + ldsw + _i * 8192), 16, 0, 0); } while (0)
; #define PG8_LDA(dst, b, h) do { _Pragma("unroll") for (int m = 0; m < 4; ++m) _Pragma("unroll") for (int k = 0; k < 2; ++k) dst[m][k] = *(const LAS bf16x8*)(lds + PG8_SA(b, h) + aoff + m * 2048 + k * 1024); } while (0)
; #define PG8_LDB(dst, b, h) do { _Pragma("unroll") for (int n = 0; n < 2; ++n) _Pragma("unroll") for (int k = 0; k < 2; ++k) dst[n][k] = *(const LAS bf16x8*)(lds + PG8_SB(b, h) + boff + n * 2048 + k * 1024); } while (0)
; #define PG8_MMA(ai, bj, At, Bt) do { __builtin_amdgcn_s_setprio(1); _Pragma("unroll") for (int m = 0; m < 4; ++m) _Pragma("unroll") for (int n = 0; n < 2; ++n) _Pragma("unroll") for (int k = 0; k < 2; ++k) \
;         acc[ai][bj][m][n] = __builtin_amdgcn_mfma_f32_16x16x32_bf16(Bt[n][k], At[m][k], acc[ai][bj][m][n], 0, 0, 0); __builtin_amdgcn_s_setprio(0); } while (0)
; #define PG8_WAIT_V(n) asm volatile("s_waitcnt vmcnt(" #n ")" ::: "memory")
; #define PG8_WAIT_L(n) asm volatile("s_waitcnt lgkmcnt(" #n ")" ::: "memory")
; #define PG8_BAR __builtin_amdgcn_s_barrier()
; #define PG8_SCHED __builtin_amdgcn_sched_barrier(0)
; #define PG8_WAIT_V(n) asm volatile("s_waitcnt vmcnt(" #n ")" ::: "memory")
; #define PG8_WAIT_L(n) asm volatile("s_waitcnt lgkmcnt(" #n ")" ::: "memory")
; template <class Epi0, class Epi1>
; DI void gemm_phase_dual(LAS unsigned char* lds, const Gemm g, const Gemm g1, const StaticOrder S, const Epi0 E0, const Epi1 E1) {
;     ...
;             PG8_WAIT_V(6); PG8_BAR; PG8_MMA(1, 1, At, B1); PG8_BAR;
;             PG8_LDB(B0, 1, 0); PG8_SCHED; PG8_LDA(At, 1, 0); PG8_STAGE(PG8_SA(0, 1), a2 + hstep, voffA);
;             PG8_WAIT_L(8); PG8_BAR; PG8_WAIT_L(0); PG8_MMA(0, 0, At, B0); PG8_BAR; PG8_SCHED;
;             PG8_LDB(B1, 1, 1); PG8_STAGE(PG8_SB(1, 0), b3, voffB);
;             PG8_BAR; PG8_WAIT_L(0); PG8_MMA(0, 1, At, B1); PG8_BAR;
;             PG8_LDA(At, 1, 1); PG8_STAGE(PG8_SA(1, 0), a3, voffA);
;             PG8_BAR; PG8_WAIT_L(0); PG8_MMA(1, 0, At, B0); PG8_BAR; PG8_SCHED;
;             PG8_STAGE(PG8_SB(1, 1), b3 + hstep, voffB);
;             PG8_WAIT_V(6); PG8_BAR; PG8_MMA(1, 1, At, B1); PG8_BAR;
	v_mfma_f32_16x16x32_bf16 v[12:15], v[132:135], v[206:209], v[12:15]
	v_mfma_f32_16x16x32_bf16 v[8:11], v[140:143], v[206:209], v[8:11]
	s_setprio 0
	s_add_u32 s90, s12, 0x40000
	s_addc_u32 s91, s13, 0
	s_add_i32 s41, s79, s48
	v_lshl_add_u64 v[128:129], s[90:91], 0, v[158:159]
	s_mov_b32 m0, s41
	s_nop 0
	global_load_lds_dwordx4 v[128:129], off
	v_lshl_add_u64 v[128:129], s[90:91], 0, v[162:163]
	s_add_i32 m0, s41, 0x2000
	s_nop 0
	global_load_lds_dwordx4 v[128:129], off
	s_waitcnt vmcnt(6)
	s_setprio 1
	s_barrier
	v_mfma_f32_16x16x32_bf16 v[52:55], v[210:213], v[144:147], v[52:55]
	v_mfma_f32_16x16x32_bf16 v[48:51], v[218:221], v[144:147], v[48:51]
	v_mfma_f32_16x16x32_bf16 v[36:39], v[210:213], v[152:155], v[36:39]
	v_mfma_f32_16x16x32_bf16 v[32:35], v[218:221], v[152:155], v[32:35]
	v_mfma_f32_16x16x32_bf16 v[20:23], v[210:213], v[194:197], v[20:23]
	v_mfma_f32_16x16x32_bf16 v[16:19], v[218:221], v[194:197], v[16:19]
	v_mfma_f32_16x16x32_bf16 v[4:7], v[210:213], v[202:205], v[4:7]
	v_mfma_f32_16x16x32_bf16 v[0:3], v[218:221], v[202:205], v[0:3]
	v_mfma_f32_16x16x32_bf16 v[52:55], v[214:217], v[148:151], v[52:55]
	v_mfma_f32_16x16x32_bf16 v[48:51], v[224:227], v[148:151], v[48:51]
	v_mfma_f32_16x16x32_bf16 v[36:39], v[214:217], v[184:187], v[36:39]
	v_mfma_f32_16x16x32_bf16 v[32:35], v[224:227], v[184:187], v[32:35]
	v_mfma_f32_16x16x32_bf16 v[20:23], v[214:217], v[198:201], v[20:23]
	s_setprio 2
	s_barrier
	v_mfma_f32_16x16x32_bf16 v[16:19], v[224:227], v[198:201], v[16:19]
	v_mfma_f32_16x16x32_bf16 v[4:7], v[214:217], v[206:209], v[4:7]
	v_mfma_f32_16x16x32_bf16 v[0:3], v[224:227], v[206:209], v[0:3]
	s_setprio 0
	s_add_i32 s41, 0, 0x18000
	v_add_u32_e32 v140, s41, v179
	ds_read_b128 v[128:131], v140
	ds_read_b128 v[132:135], v140 offset:1024
	ds_read_b128 v[136:139], v140 offset:2048
	ds_read_b128 v[140:143], v140 offset:3072
	s_add_u32 s14, s14, 0x40000
	s_addc_u32 s15, s15, 0
	s_mov_b32 m0, s51
	v_lshl_add_u64 v[210:211], s[14:15], 0, v[156:157]
	ds_read_b128 v[144:147], v183 offset:32768
	ds_read_b128 v[152:155], v183 offset:34816
	ds_read_b128 v[194:197], v183 offset:36864
	ds_read_b128 v[202:205], v183 offset:38912
	global_load_lds_dwordx4 v[210:211], off
	v_lshl_add_u64 v[210:211], s[14:15], 0, v[160:161]
	s_mov_b32 m0, s58
	s_nop 0
	global_load_lds_dwordx4 v[210:211], off
	s_waitcnt lgkmcnt(4)
	s_setprio 1
	s_barrier
	ds_read_b128 v[148:151], v183 offset:33792
	ds_read_b128 v[184:187], v183 offset:35840
	ds_read_b128 v[198:201], v183 offset:37888
	ds_read_b128 v[206:209], v183 offset:39936
	s_waitcnt lgkmcnt(4)
	v_mfma_f32_16x16x32_bf16 v[124:127], v[128:131], v[144:147], v[124:127]
	v_mfma_f32_16x16x32_bf16 v[120:123], v[136:139], v[144:147], v[120:123]
	v_mfma_f32_16x16x32_bf16 v[108:111], v[128:131], v[152:155], v[108:111]
	v_mfma_f32_16x16x32_bf16 v[104:107], v[136:139], v[152:155], v[104:107]
	v_mfma_f32_16x16x32_bf16 v[92:95], v[128:131], v[194:197], v[92:95]
	v_mfma_f32_16x16x32_bf16 v[88:91], v[136:139], v[194:197], v[88:91]
	v_mfma_f32_16x16x32_bf16 v[76:79], v[128:131], v[202:205], v[76:79]
	v_mfma_f32_16x16x32_bf16 v[72:75], v[136:139], v[202:205], v[72:75]
	s_waitcnt lgkmcnt(3)
	v_mfma_f32_16x16x32_bf16 v[124:127], v[132:135], v[148:151], v[124:127]
	v_mfma_f32_16x16x32_bf16 v[120:123], v[140:143], v[148:151], v[120:123]
	s_waitcnt lgkmcnt(2)
	v_mfma_f32_16x16x32_bf16 v[108:111], v[132:135], v[184:187], v[108:111]
	v_mfma_f32_16x16x32_bf16 v[104:107], v[140:143], v[184:187], v[104:107]
	s_waitcnt lgkmcnt(1)
	v_mfma_f32_16x16x32_bf16 v[92:95], v[132:135], v[198:201], v[92:95]
	v_mfma_f32_16x16x32_bf16 v[88:91], v[140:143], v[198:201], v[88:91]
	s_waitcnt lgkmcnt(0)
	s_setprio 2
	s_barrier
	v_mfma_f32_16x16x32_bf16 v[76:79], v[132:135], v[206:209], v[76:79]
	v_mfma_f32_16x16x32_bf16 v[72:75], v[140:143], v[206:209], v[72:75]
	s_setprio 0
	s_add_i32 s14, 0, 0x1c000
	s_add_i32 s15, s41, s48
	v_add_u32_e32 v176, s14, v179
	v_lshl_add_u64 v[190:191], v[190:191], 0, s[22:23]
	s_mov_b32 m0, s15
	ds_read_b128 v[210:213], v176
	ds_read_b128 v[214:217], v176 offset:1024
	ds_read_b128 v[218:221], v176 offset:2048
	ds_read_b128 v[224:227], v176 offset:3072
	global_load_lds_dwordx4 v[190:191], off
	v_lshl_add_u64 v[190:191], v[228:229], 0, s[22:23]
	s_add_i32 m0, s15, 0x2000
	s_nop 0
	global_load_lds_dwordx4 v[190:191], off
	s_setprio 1
	s_barrier
	s_waitcnt lgkmcnt(0)
	v_mfma_f32_16x16x32_bf16 v[116:119], v[210:213], v[144:147], v[116:119]
	v_mfma_f32_16x16x32_bf16 v[112:115], v[218:221], v[144:147], v[112:115]
	v_mfma_f32_16x16x32_bf16 v[100:103], v[210:213], v[152:155], v[100:103]
	v_mfma_f32_16x16x32_bf16 v[96:99], v[218:221], v[152:155], v[96:99]
	v_mfma_f32_16x16x32_bf16 v[84:87], v[210:213], v[194:197], v[84:87]
	v_mfma_f32_16x16x32_bf16 v[80:83], v[218:221], v[194:197], v[80:83]
	v_mfma_f32_16x16x32_bf16 v[68:71], v[210:213], v[202:205], v[68:71]
	v_mfma_f32_16x16x32_bf16 v[64:67], v[218:221], v[202:205], v[64:67]
	v_mfma_f32_16x16x32_bf16 v[116:119], v[214:217], v[148:151], v[116:119]
	v_mfma_f32_16x16x32_bf16 v[112:115], v[224:227], v[148:151], v[112:115]
	v_mfma_f32_16x16x32_bf16 v[100:103], v[214:217], v[184:187], v[100:103]
	v_mfma_f32_16x16x32_bf16 v[96:99], v[224:227], v[184:187], v[96:99]
	v_mfma_f32_16x16x32_bf16 v[84:87], v[214:217], v[198:201], v[84:87]
	s_setprio 2
	s_barrier
	v_mfma_f32_16x16x32_bf16 v[80:83], v[224:227], v[198:201], v[80:83]
	v_mfma_f32_16x16x32_bf16 v[68:71], v[214:217], v[206:209], v[68:71]
	v_mfma_f32_16x16x32_bf16 v[64:67], v[224:227], v[206:209], v[64:67]
	s_setprio 0
	s_mov_b32 m0, s76
	v_lshl_add_u64 v[190:191], v[230:231], 0, s[22:23]
	ds_read_b128 v[144:147], v183 offset:49152
	ds_read_b128 v[152:155], v183 offset:51200
	ds_read_b128 v[194:197], v183 offset:53248
	ds_read_b128 v[202:205], v183 offset:55296
	global_load_lds_dwordx4 v[190:191], off
	v_lshl_add_u64 v[190:191], v[232:233], 0, s[22:23]
	s_mov_b32 m0, s77
	s_nop 0
	global_load_lds_dwordx4 v[190:191], off
	s_setprio 1
	s_barrier
; #define PG8_STAGE(bufoff, gbase, voff) do { _Pragma("unroll") for (int _i = 0; _i < 2; ++_i) \
;         __builtin_amdgcn_global_load_lds((const unsigned*)((const char*)(gbase) + (voff)[_i]), (LAS unsigned*)(lds + (bufoff) + ldsw + _i * 8192), 16, 0, 0); } while (0)
; #define PG8_LDA(dst, b, h) do { _Pragma("unroll") for (int m = 0; m < 4; ++m) _Pragma("unroll") for (int k = 0; k < 2; ++k) dst[m][k] = *(const LAS bf16x8*)(lds + PG8_SA(b, h) + aoff + m * 2048 + k * 1024); } while (0)
; #define PG8_MMA(ai, bj, At, Bt) do { __builtin_amdgcn_s_setprio(1); _Pragma("unroll") for (int m = 0; m < 4; ++m) _Pragma("unroll") for (int n = 0; n < 2; ++n) _Pragma("unroll") for (int k = 0; k < 2; ++k) \
;         acc[ai][bj][m][n] = __builtin_amdgcn_mfma_f32_16x16x32_bf16(Bt[n][k], At[m][k], acc[ai][bj][m][n], 0, 0, 0); __builtin_amdgcn_s_setprio(0); } while (0)
; #define PG8_WAIT_V(n) asm volatile("s_waitcnt vmcnt(" #n ")" ::: "memory")
; #define PG8_WAIT_L(n) asm volatile("s_waitcnt lgkmcnt(" #n ")" ::: "memory")
; #define PG8_BAR __builtin_amdgcn_s_barrier()
; #define PG8_SCHED __builtin_amdgcn_sched_barrier(0)
; #define PG8_LDA(dst, b, h) do { _Pragma("unroll") for (int m = 0; m < 4; ++m) _Pragma("unroll") for (int k = 0; k < 2; ++k) dst[m][k] = *(const LAS bf16x8*)(lds + PG8_SA(b, h) + aoff + m * 2048 + k * 1024); } while (0)
; DI RowScales load_rowscales(const float* ss, int row0) {
;     RowScales t;
; #pragma unroll
;     for (int ai = 0; ai < 2; ++ai)
; #pragma unroll
;         for (int m = 0; m < 4; ++m) t.r[ai][m] = ss[row0 + ai * 128 + m * 16];
; #pragma unroll
;     for (int ai = 0; ai < 2; ++ai)
; #pragma unroll
;         for (int m = 0; m < 4; ++m) t.r[ai][m] = rsqrtf(t.r[ai][m] * (1.0f / 1024.0f) + 1e-6f);
; template <class Epi0, class Epi1>
; DI void gemm_phase_dual(LAS unsigned char* lds, const Gemm g, const Gemm g1, const StaticOrder S, const Epi0 E0, const Epi1 E1) {
;     ...
;             PG8_BAR; PG8_WAIT_L(0); PG8_MMA(0, 1, At, B1); PG8_BAR;
;             PG8_LDA(At, 1, 1); PG8_STAGE(PG8_SA(1, 0), a3, voffA);
;             PG8_BAR; PG8_WAIT_L(0); PG8_MMA(1, 0, At, B0); PG8_BAR; PG8_SCHED;
;             PG8_STAGE(PG8_SB(1, 1), b3 + hstep, voffB);
;             PG8_WAIT_V(6); PG8_BAR; PG8_MMA(1, 1, At, B1); PG8_BAR;
;         }
;         if (ui & 1) E1(acc, cur, wr, wc, fr, fq); else E0(acc, cur, wr, wc, fr, fq);
	ds_read_b128 v[148:151], v183 offset:50176
	ds_read_b128 v[184:187], v183 offset:52224
	ds_read_b128 v[198:201], v183 offset:54272
	ds_read_b128 v[206:209], v183 offset:56320
	s_waitcnt lgkmcnt(4)
	v_mfma_f32_16x16x32_bf16 v[60:63], v[128:131], v[144:147], v[60:63]
	v_mfma_f32_16x16x32_bf16 v[56:59], v[136:139], v[144:147], v[56:59]
	v_mfma_f32_16x16x32_bf16 v[44:47], v[128:131], v[152:155], v[44:47]
	v_mfma_f32_16x16x32_bf16 v[40:43], v[136:139], v[152:155], v[40:43]
	v_mfma_f32_16x16x32_bf16 v[28:31], v[128:131], v[194:197], v[28:31]
	v_mfma_f32_16x16x32_bf16 v[24:27], v[136:139], v[194:197], v[24:27]
	v_mfma_f32_16x16x32_bf16 v[12:15], v[128:131], v[202:205], v[12:15]
	v_mfma_f32_16x16x32_bf16 v[8:11], v[136:139], v[202:205], v[8:11]
	s_waitcnt lgkmcnt(3)
	v_mfma_f32_16x16x32_bf16 v[60:63], v[132:135], v[148:151], v[60:63]
	v_mfma_f32_16x16x32_bf16 v[56:59], v[140:143], v[148:151], v[56:59]
	s_waitcnt lgkmcnt(2)
	v_mfma_f32_16x16x32_bf16 v[44:47], v[132:135], v[184:187], v[44:47]
	v_mfma_f32_16x16x32_bf16 v[40:43], v[140:143], v[184:187], v[40:43]
	s_waitcnt lgkmcnt(1)
	v_mfma_f32_16x16x32_bf16 v[28:31], v[132:135], v[198:201], v[28:31]
	v_mfma_f32_16x16x32_bf16 v[24:27], v[140:143], v[198:201], v[24:27]
	s_waitcnt lgkmcnt(0)
	s_setprio 2
	s_barrier
	v_mfma_f32_16x16x32_bf16 v[12:15], v[132:135], v[206:209], v[12:15]
	v_mfma_f32_16x16x32_bf16 v[8:11], v[140:143], v[206:209], v[8:11]
	s_setprio 0
	s_add_u32 s12, s12, 0x40080
	s_addc_u32 s13, s13, 0
	s_add_i32 s14, s14, s48
	v_lshl_add_u64 v[128:129], s[12:13], 0, v[158:159]
	s_mov_b32 m0, s14
	s_nop 0
	global_load_lds_dwordx4 v[128:129], off
	v_lshl_add_u64 v[128:129], s[12:13], 0, v[162:163]
	s_add_i32 m0, s14, 0x2000
	s_nop 0
	global_load_lds_dwordx4 v[128:129], off
	s_waitcnt vmcnt(6)
	s_setprio 1
	s_barrier
	v_mfma_f32_16x16x32_bf16 v[52:55], v[210:213], v[144:147], v[52:55]
	v_mfma_f32_16x16x32_bf16 v[48:51], v[218:221], v[144:147], v[48:51]
	v_mfma_f32_16x16x32_bf16 v[36:39], v[210:213], v[152:155], v[36:39]
	v_mfma_f32_16x16x32_bf16 v[32:35], v[218:221], v[152:155], v[32:35]
	v_mfma_f32_16x16x32_bf16 v[20:23], v[210:213], v[194:197], v[20:23]
	v_mfma_f32_16x16x32_bf16 v[16:19], v[218:221], v[194:197], v[16:19]
	v_mfma_f32_16x16x32_bf16 v[4:7], v[210:213], v[202:205], v[4:7]
	v_mfma_f32_16x16x32_bf16 v[0:3], v[218:221], v[202:205], v[0:3]
	v_mfma_f32_16x16x32_bf16 v[52:55], v[214:217], v[148:151], v[52:55]
	v_mfma_f32_16x16x32_bf16 v[48:51], v[224:227], v[148:151], v[48:51]
	v_mfma_f32_16x16x32_bf16 v[36:39], v[214:217], v[184:187], v[36:39]
	v_mfma_f32_16x16x32_bf16 v[32:35], v[224:227], v[184:187], v[32:35]
	v_mfma_f32_16x16x32_bf16 v[20:23], v[214:217], v[198:201], v[20:23]
	s_setprio 2
	s_barrier
	v_mfma_f32_16x16x32_bf16 v[16:19], v[224:227], v[198:201], v[16:19]
	v_mfma_f32_16x16x32_bf16 v[4:7], v[214:217], v[206:209], v[4:7]
	v_mfma_f32_16x16x32_bf16 v[0:3], v[224:227], v[206:209], v[0:3]
	s_setprio 0
	s_add_i32 s19, s19, 2
	s_add_u32 s10, s10, 0x100
	s_addc_u32 s11, s11, 0
	s_add_u32 s17, s17, 0x100
	s_addc_u32 s18, s18, 0
	s_cmp_gt_u32 s19, 13
	s_cbranch_scc0 .LBB0_632
	v_lshl_add_u32 v128, s0, 8, v177
	s_mov_b64 s[6:7], -1
	s_and_b64 vcc, exec, s[8:9]
	v_ashrrev_i32_e32 v129, 31, v128
	s_cbranch_vccz .LBB0_635
	v_lshl_add_u64 v[130:131], v[128:129], 2, s[60:61]
	global_load_dword v132, v[130:131], off
	global_load_dword v133, v[130:131], off offset:64
	global_load_dword v134, v[130:131], off offset:128
	global_load_dword v135, v[130:131], off offset:192
	global_load_dword v136, v[130:131], off offset:512
	global_load_dword v137, v[130:131], off offset:576
	global_load_dword v138, v[130:131], off offset:640
	global_load_dword v139, v[130:131], off offset:704
	s_lshl_b32 s0, s0, 3
	s_add_i32 s0, s0, s87
	s_ashr_i32 s1, s0, 31
	s_lshl_b64 s[0:1], s[0:1], 17
	v_lshl_add_u64 v[130:131], v[166:167], 0, s[0:1]
	s_mov_b64 s[6:7], 0
	s_waitcnt vmcnt(0)
	v_fmamk_f32 v132, v132, 0x3a800000, v193
	v_mul_f32_e32 v140, 0x4b800000, v132
	v_cmp_gt_f32_e32 vcc, s80, v132
	v_fmamk_f32 v134, v134, 0x3a800000, v193
	v_fmamk_f32 v136, v136, 0x3a800000, v193
	v_fmamk_f32 v137, v137, 0x3a800000, v193
	v_fmamk_f32 v138, v138, 0x3a800000, v193
	v_fmamk_f32 v139, v139, 0x3a800000, v193
	v_mul_f32_e32 v144, 0x4b800000, v136
	v_mul_f32_e32 v145, 0x4b800000, v137
	v_cndmask_b32_e32 v132, v132, v140, vcc
	v_cmp_gt_f32_e64 s[12:13], s80, v136
	v_cmp_gt_f32_e64 s[14:15], s80, v137
	v_fmamk_f32 v133, v133, 0x3a800000, v193
	v_fmamk_f32 v135, v135, 0x3a800000, v193
	v_mul_f32_e32 v142, 0x4b800000, v134
	v_mul_f32_e32 v146, 0x4b800000, v138
	v_mul_f32_e32 v147, 0x4b800000, v139
	v_cmp_gt_f32_e64 s[8:9], s80, v134
	v_cndmask_b32_e64 v136, v136, v144, s[12:13]
	v_cndmask_b32_e64 v137, v137, v145, s[14:15]
	v_cmp_gt_f32_e64 s[16:17], s80, v138
	v_cmp_gt_f32_e64 s[18:19], s80, v139
	v_rsq_f32_e32 v132, v132
	v_mul_f32_e32 v141, 0x4b800000, v133
	v_mul_f32_e32 v143, 0x4b800000, v135
	v_cmp_gt_f32_e64 s[0:1], s80, v133
	v_cndmask_b32_e64 v134, v134, v142, s[8:9]
	v_cmp_gt_f32_e64 s[10:11], s80, v135
	v_cndmask_b32_e64 v138, v138, v146, s[16:17]
	v_cndmask_b32_e64 v139, v139, v147, s[18:19]
	v_rsq_f32_e32 v136, v136
	v_rsq_f32_e32 v137, v137
	v_cndmask_b32_e64 v133, v133, v141, s[0:1]
	v_cndmask_b32_e64 v135, v135, v143, s[10:11]
	v_rsq_f32_e32 v134, v134
	v_rsq_f32_e32 v141, v138
	v_rsq_f32_e32 v139, v139
	v_rsq_f32_e32 v133, v133
	v_rsq_f32_e32 v135, v135
	v_mul_f32_e32 v138, 0x45800000, v132
	v_mul_f32_e32 v144, 0x45800000, v136
	v_mul_f32_e32 v145, 0x45800000, v137
	v_cndmask_b32_e32 v148, v132, v138, vcc
	v_mul_f32_e32 v142, 0x45800000, v134
	v_mul_f32_e32 v146, 0x45800000, v141
	v_mul_f32_e32 v147, 0x45800000, v139
; DI unsigned pk_bf16(float lo, float hi) { f32x2 v = {lo, hi}; return __builtin_bit_cast(unsigned, __builtin_convertvector(v, bf16v2)); }
; DI float fast_sigmoid(float x) { return __builtin_amdgcn_rcpf(1.0f + __expf(-x)); }
;     DI void operator()(AccRef acc, const Unit& u, int wr, int wc, int fr, int fq) const {
;         const int row0 = u.pm * 256 + wr * 64 + fr;
;         bf16_t* Gp = gab + (size_t)(u.pm * 8 + u.pn) * 65536 + (wr * 64 + fr) * 256 + wc * 32 + 8 * fq;
;         const RowScales rsc = load_rowscales(ss, row0);
; #pragma unroll
;         for (int ai = 0; ai < 2; ++ai)
; #pragma unroll
;             for (int m = 0; m < 4; ++m)
; #pragma unroll
;                 for (int bj = 0; bj < 2; ++bj) {
;                     const float rs = rsc.r[ai][m];
;                     const f32x4 r0 = acc[ai][bj][m][0] * rs, r1 = acc[ai][bj][m][1] * rs;
;                     u32x4 w;
;                     w.x = pk_bf16(fast_sigmoid(r0[0]), fast_sigmoid(r0[1])); w.y = pk_bf16(fast_sigmoid(r0[2]), fast_sigmoid(r0[3]));
;                     w.z = pk_bf16(fast_sigmoid(r1[0]), fast_sigmoid(r1[1])); w.w = pk_bf16(fast_sigmoid(r1[2]), fast_sigmoid(r1[3]));
;                     *(u32x4*)(Gp + (ai * 128 + m * 16) * 256 + bj * 128) = w;
;                 }
;     }
	v_cndmask_b32_e64 v138, v136, v144, s[12:13]
	v_cndmask_b32_e64 v136, v137, v145, s[14:15]
	v_pk_mul_f32 v[144:145], v[126:127], v[148:149] op_sel_hi:[1,0]
	v_pk_mul_f32 v[152:153], v[122:123], v[148:149] op_sel_hi:[1,0]
	v_mul_f32_e32 v140, 0x45800000, v133
	v_mul_f32_e32 v143, 0x45800000, v135
	v_cndmask_b32_e64 v142, v134, v142, s[8:9]
	v_cndmask_b32_e64 v134, v141, v146, s[16:17]
	v_cndmask_b32_e64 v132, v139, v147, s[18:19]
	v_pk_mul_f32 v[146:147], v[124:125], v[148:149] op_sel_hi:[1,0]
	v_pk_mul_f32 v[154:155], v[120:121], v[148:149] op_sel_hi:[1,0]
	v_mul_f32_e32 v137, 0xbfb8aa3b, v144
	v_mul_f32_e32 v144, 0xbfb8aa3b, v152
	v_cndmask_b32_e64 v150, v133, v140, s[0:1]
	v_cndmask_b32_e64 v140, v135, v143, s[10:11]
	v_mul_f32_e32 v133, 0xbfb8aa3b, v146
	v_mul_f32_e32 v135, 0xbfb8aa3b, v147
	v_mul_f32_e32 v139, 0xbfb8aa3b, v145
	v_mul_f32_e32 v141, 0xbfb8aa3b, v154
	v_mul_f32_e32 v143, 0xbfb8aa3b, v155
	v_exp_f32_e32 v144, v144
	v_mul_f32_e32 v145, 0xbfb8aa3b, v153
	v_exp_f32_e32 v133, v133
	v_exp_f32_e32 v135, v135
	v_exp_f32_e32 v137, v137
	v_exp_f32_e32 v139, v139
	v_exp_f32_e32 v141, v141
	v_exp_f32_e32 v143, v143
	v_exp_f32_e32 v145, v145
	v_add_f32_e32 v144, 1.0, v144
	v_add_f32_e32 v133, 1.0, v133
	v_add_f32_e32 v135, 1.0, v135
	v_add_f32_e32 v137, 1.0, v137
	v_add_f32_e32 v139, 1.0, v139
	v_add_f32_e32 v141, 1.0, v141
	v_add_f32_e32 v143, 1.0, v143
	v_rcp_f32_e32 v147, v144
	v_add_f32_e32 v144, 1.0, v145
	v_rcp_f32_e32 v133, v133
	v_rcp_f32_e32 v135, v135
	v_rcp_f32_e32 v137, v137
	v_rcp_f32_e32 v139, v139
	v_rcp_f32_e32 v141, v141
	v_rcp_f32_e32 v143, v143
	v_rcp_f32_e32 v149, v144
	v_cvt_pk_bf16_f32 v144, v133, v135
	v_cvt_pk_bf16_f32 v145, v137, v139
	v_cvt_pk_bf16_f32 v146, v141, v143
	v_cvt_pk_bf16_f32 v147, v147, v149
	global_store_dwordx4 v[130:131], v[144:147], off
	v_pk_mul_f32 v[152:153], v[114:115], v[148:149] op_sel_hi:[1,0]
	s_nop 0
	v_pk_mul_f32 v[144:145], v[118:119], v[148:149] op_sel_hi:[1,0]
	v_pk_mul_f32 v[146:147], v[116:117], v[148:149] op_sel_hi:[1,0]
	v_mul_f32_e32 v137, 0xbfb8aa3b, v144
	v_mul_f32_e32 v133, 0xbfb8aa3b, v146
	v_mul_f32_e32 v135, 0xbfb8aa3b, v147
	v_pk_mul_f32 v[146:147], v[112:113], v[148:149] op_sel_hi:[1,0]
	v_mul_f32_e32 v144, 0xbfb8aa3b, v152
	v_mul_f32_e32 v139, 0xbfb8aa3b, v145
	v_mul_f32_e32 v141, 0xbfb8aa3b, v146
	v_mul_f32_e32 v143, 0xbfb8aa3b, v147
	v_exp_f32_e32 v144, v144
	v_mul_f32_e32 v145, 0xbfb8aa3b, v153
	v_exp_f32_e32 v133, v133
	v_exp_f32_e32 v135, v135
	v_exp_f32_e32 v137, v137
	v_exp_f32_e32 v139, v139
	v_exp_f32_e32 v141, v141
	v_exp_f32_e32 v143, v143
	v_exp_f32_e32 v145, v145
	v_add_f32_e32 v144, 1.0, v144
	v_add_f32_e32 v133, 1.0, v133
	v_add_f32_e32 v135, 1.0, v135
	v_add_f32_e32 v137, 1.0, v137
	v_add_f32_e32 v139, 1.0, v139
	v_add_f32_e32 v141, 1.0, v141
	v_add_f32_e32 v143, 1.0, v143
	v_rcp_f32_e32 v147, v144
	v_add_f32_e32 v144, 1.0, v145
	v_rcp_f32_e32 v133, v133
	v_rcp_f32_e32 v135, v135
	v_rcp_f32_e32 v137, v137
	v_rcp_f32_e32 v139, v139
	v_rcp_f32_e32 v141, v141
	v_rcp_f32_e32 v143, v143
	v_rcp_f32_e32 v148, v144
	v_cvt_pk_bf16_f32 v144, v133, v135
	v_cvt_pk_bf16_f32 v145, v137, v139
	v_cvt_pk_bf16_f32 v146, v141, v143
	v_cvt_pk_bf16_f32 v147, v147, v148
	global_store_dwordx4 v[130:131], v[144:147], off offset:256
	v_pk_mul_f32 v[148:149], v[106:107], v[150:151] op_sel_hi:[1,0]
	v_pk_mul_f32 v[152:153], v[98:99], v[150:151] op_sel_hi:[1,0]
	v_pk_mul_f32 v[144:145], v[110:111], v[150:151] op_sel_hi:[1,0]
	v_pk_mul_f32 v[146:147], v[108:109], v[150:151] op_sel_hi:[1,0]
	v_mul_f32_e32 v137, 0xbfb8aa3b, v144
	v_mul_f32_e32 v144, 0xbfb8aa3b, v148
	v_mul_f32_e32 v133, 0xbfb8aa3b, v146
	v_mul_f32_e32 v135, 0xbfb8aa3b, v147
	v_pk_mul_f32 v[146:147], v[104:105], v[150:151] op_sel_hi:[1,0]
	v_mul_f32_e32 v139, 0xbfb8aa3b, v145
	v_exp_f32_e32 v144, v144
	v_mul_f32_e32 v145, 0xbfb8aa3b, v149
	v_mul_f32_e32 v141, 0xbfb8aa3b, v146
	v_mul_f32_e32 v143, 0xbfb8aa3b, v147
	v_exp_f32_e32 v145, v145
	v_exp_f32_e32 v133, v133
	v_exp_f32_e32 v135, v135
	v_exp_f32_e32 v137, v137
	v_exp_f32_e32 v139, v139
	v_exp_f32_e32 v141, v141
	v_exp_f32_e32 v143, v143
	v_add_f32_e32 v144, 1.0, v144
	v_rcp_f32_e32 v147, v144
	v_add_f32_e32 v144, 1.0, v145
	v_add_f32_e32 v133, 1.0, v133
	v_add_f32_e32 v135, 1.0, v135
	v_add_f32_e32 v137, 1.0, v137
	v_add_f32_e32 v139, 1.0, v139
	v_add_f32_e32 v141, 1.0, v141
	v_add_f32_e32 v143, 1.0, v143
	v_rcp_f32_e32 v148, v144
	v_rcp_f32_e32 v133, v133
	v_rcp_f32_e32 v135, v135
	v_rcp_f32_e32 v137, v137
	v_rcp_f32_e32 v139, v139
	v_rcp_f32_e32 v141, v141
	v_rcp_f32_e32 v143, v143
	v_cvt_pk_bf16_f32 v147, v147, v148
	v_add_co_u32_e32 v148, vcc, s59, v130
	v_cvt_pk_bf16_f32 v144, v133, v135
	v_cvt_pk_bf16_f32 v145, v137, v139
	v_cvt_pk_bf16_f32 v146, v141, v143
	v_addc_co_u32_e32 v149, vcc, 0, v131, vcc
	global_store_dwordx4 v[148:149], v[144:147], off
	s_nop 1
	v_pk_mul_f32 v[144:145], v[102:103], v[150:151] op_sel_hi:[1,0]
	v_pk_mul_f32 v[146:147], v[100:101], v[150:151] op_sel_hi:[1,0]
	v_mul_f32_e32 v137, 0xbfb8aa3b, v144
	v_mul_f32_e32 v133, 0xbfb8aa3b, v146
	v_mul_f32_e32 v135, 0xbfb8aa3b, v147
	v_pk_mul_f32 v[146:147], v[96:97], v[150:151] op_sel_hi:[1,0]
	v_mul_f32_e32 v144, 0xbfb8aa3b, v152
	v_mul_f32_e32 v139, 0xbfb8aa3b, v145
	v_mul_f32_e32 v141, 0xbfb8aa3b, v146
	v_mul_f32_e32 v143, 0xbfb8aa3b, v147
	v_exp_f32_e32 v144, v144
	v_mul_f32_e32 v145, 0xbfb8aa3b, v153
	v_exp_f32_e32 v133, v133
	v_exp_f32_e32 v135, v135
	v_exp_f32_e32 v137, v137
	v_exp_f32_e32 v139, v139
	v_exp_f32_e32 v141, v141
	v_exp_f32_e32 v143, v143
	v_exp_f32_e32 v145, v145
	v_add_f32_e32 v144, 1.0, v144
	v_add_f32_e32 v133, 1.0, v133
	v_add_f32_e32 v135, 1.0, v135
; DI unsigned pk_bf16(float lo, float hi) { f32x2 v = {lo, hi}; return __builtin_bit_cast(unsigned, __builtin_convertvector(v, bf16v2)); }
; DI float fast_sigmoid(float x) { return __builtin_amdgcn_rcpf(1.0f + __expf(-x)); }
;     DI void operator()(AccRef acc, const Unit& u, int wr, int wc, int fr, int fq) const {
;     ...
;         for (int ai = 0; ai < 2; ++ai)
; #pragma unroll
;             for (int m = 0; m < 4; ++m)
; #pragma unroll
;                 for (int bj = 0; bj < 2; ++bj) {
;                     const float rs = rsc.r[ai][m];
;                     const f32x4 r0 = acc[ai][bj][m][0] * rs, r1 = acc[ai][bj][m][1] * rs;
;                     u32x4 w;
;                     w.x = pk_bf16(fast_sigmoid(r0[0]), fast_sigmoid(r0[1])); w.y = pk_bf16(fast_sigmoid(r0[2]), fast_sigmoid(r0[3]));
;                     w.z = pk_bf16(fast_sigmoid(r1[0]), fast_sigmoid(r1[1])); w.w = pk_bf16(fast_sigmoid(r1[2]), fast_sigmoid(r1[3]));
;                     *(u32x4*)(Gp + (ai * 128 + m * 16) * 256 + bj * 128) = w;
	v_add_f32_e32 v137, 1.0, v137
	v_add_f32_e32 v139, 1.0, v139
	v_add_f32_e32 v141, 1.0, v141
	v_add_f32_e32 v143, 1.0, v143
	v_rcp_f32_e32 v147, v144
	v_add_f32_e32 v144, 1.0, v145
	v_rcp_f32_e32 v133, v133
	v_rcp_f32_e32 v135, v135
	v_rcp_f32_e32 v137, v137
	v_rcp_f32_e32 v139, v139
	v_rcp_f32_e32 v141, v141
	v_rcp_f32_e32 v143, v143
	v_rcp_f32_e32 v150, v144
	v_cvt_pk_bf16_f32 v144, v133, v135
	v_cvt_pk_bf16_f32 v145, v137, v139
	v_cvt_pk_bf16_f32 v146, v141, v143
	v_cvt_pk_bf16_f32 v147, v147, v150
	global_store_dwordx4 v[148:149], v[144:147], off offset:256
	v_pk_mul_f32 v[148:149], v[90:91], v[142:143] op_sel_hi:[1,0]
	s_nop 0
	v_pk_mul_f32 v[144:145], v[94:95], v[142:143] op_sel_hi:[1,0]
	v_pk_mul_f32 v[146:147], v[92:93], v[142:143] op_sel_hi:[1,0]
	v_mul_f32_e32 v137, 0xbfb8aa3b, v144
	v_mul_f32_e32 v144, 0xbfb8aa3b, v148
	v_mul_f32_e32 v133, 0xbfb8aa3b, v146
	v_mul_f32_e32 v135, 0xbfb8aa3b, v147
	v_pk_mul_f32 v[146:147], v[88:89], v[142:143] op_sel_hi:[1,0]
	v_mul_f32_e32 v139, 0xbfb8aa3b, v145
	v_exp_f32_e32 v144, v144
	v_mul_f32_e32 v145, 0xbfb8aa3b, v149
	v_mul_f32_e32 v141, 0xbfb8aa3b, v146
	v_mul_f32_e32 v143, 0xbfb8aa3b, v147
	v_exp_f32_e32 v145, v145
	v_exp_f32_e32 v133, v133
	v_exp_f32_e32 v135, v135
	v_exp_f32_e32 v137, v137
	v_exp_f32_e32 v139, v139
	v_exp_f32_e32 v141, v141
	v_exp_f32_e32 v143, v143
	v_add_f32_e32 v144, 1.0, v144
	v_rcp_f32_e32 v147, v144
	v_add_f32_e32 v144, 1.0, v145
	v_add_f32_e32 v133, 1.0, v133
	v_add_f32_e32 v135, 1.0, v135
	v_add_f32_e32 v137, 1.0, v137
	v_add_f32_e32 v139, 1.0, v139
	v_add_f32_e32 v141, 1.0, v141
	v_add_f32_e32 v143, 1.0, v143
	v_rcp_f32_e32 v148, v144
	v_rcp_f32_e32 v133, v133
	v_rcp_f32_e32 v135, v135
	v_rcp_f32_e32 v137, v137
	v_rcp_f32_e32 v139, v139
	v_rcp_f32_e32 v141, v141
	v_rcp_f32_e32 v143, v143
	v_cvt_pk_bf16_f32 v147, v147, v148
	v_add_co_u32_e32 v148, vcc, s66, v130
	v_cvt_pk_bf16_f32 v144, v133, v135
	v_cvt_pk_bf16_f32 v145, v137, v139
	v_cvt_pk_bf16_f32 v146, v141, v143
	v_addc_co_u32_e32 v149, vcc, 0, v131, vcc
	global_store_dwordx4 v[148:149], v[144:147], off
	v_pk_mul_f32 v[150:151], v[82:83], v[142:143] op_sel_hi:[1,0]
	s_nop 0
	v_pk_mul_f32 v[144:145], v[86:87], v[142:143] op_sel_hi:[1,0]
	v_pk_mul_f32 v[146:147], v[84:85], v[142:143] op_sel_hi:[1,0]
	v_pk_mul_f32 v[142:143], v[80:81], v[142:143] op_sel_hi:[1,0]
	v_mul_f32_e32 v133, 0xbfb8aa3b, v146
	v_mul_f32_e32 v141, 0xbfb8aa3b, v142
	v_mul_f32_e32 v142, 0xbfb8aa3b, v143
	v_exp_f32_e32 v142, v142
	v_mul_f32_e32 v143, 0xbfb8aa3b, v150
	v_mul_f32_e32 v135, 0xbfb8aa3b, v147
	v_mul_f32_e32 v137, 0xbfb8aa3b, v144
	v_mul_f32_e32 v139, 0xbfb8aa3b, v145
	v_exp_f32_e32 v143, v143
	v_mul_f32_e32 v144, 0xbfb8aa3b, v151
	v_exp_f32_e32 v133, v133
	v_exp_f32_e32 v135, v135
	v_exp_f32_e32 v137, v137
	v_exp_f32_e32 v139, v139
	v_exp_f32_e32 v141, v141
	v_exp_f32_e32 v144, v144
	v_add_f32_e32 v142, 1.0, v142
	v_rcp_f32_e32 v145, v142
	v_add_f32_e32 v142, 1.0, v143
	v_add_f32_e32 v133, 1.0, v133
	v_add_f32_e32 v135, 1.0, v135
	v_add_f32_e32 v137, 1.0, v137
	v_add_f32_e32 v139, 1.0, v139
	v_add_f32_e32 v141, 1.0, v141
	v_rcp_f32_e32 v146, v142
	v_add_f32_e32 v142, 1.0, v144
	v_rcp_f32_e32 v133, v133
	v_rcp_f32_e32 v135, v135
	v_rcp_f32_e32 v137, v137
	v_rcp_f32_e32 v139, v139
	v_rcp_f32_e32 v141, v141
	v_rcp_f32_e32 v147, v142
	v_cvt_pk_bf16_f32 v142, v133, v135
	v_cvt_pk_bf16_f32 v143, v137, v139
	v_cvt_pk_bf16_f32 v144, v141, v145
	v_cvt_pk_bf16_f32 v145, v146, v147
	global_store_dwordx4 v[148:149], v[142:145], off offset:256
	v_pk_mul_f32 v[146:147], v[74:75], v[140:141] op_sel_hi:[1,0]
	s_nop 0
	v_pk_mul_f32 v[144:145], v[76:77], v[140:141] op_sel_hi:[1,0]
	v_pk_mul_f32 v[142:143], v[78:79], v[140:141] op_sel_hi:[1,0]
	v_mul_f32_e32 v133, 0xbfb8aa3b, v144
	v_mul_f32_e32 v135, 0xbfb8aa3b, v145
	v_pk_mul_f32 v[144:145], v[72:73], v[140:141] op_sel_hi:[1,0]
	v_mul_f32_e32 v137, 0xbfb8aa3b, v142
	v_mul_f32_e32 v142, 0xbfb8aa3b, v145
	v_mul_f32_e32 v139, 0xbfb8aa3b, v143
	v_exp_f32_e32 v142, v142
	v_mul_f32_e32 v143, 0xbfb8aa3b, v146
	v_mul_f32_e32 v141, 0xbfb8aa3b, v144
	v_exp_f32_e32 v143, v143
	v_mul_f32_e32 v144, 0xbfb8aa3b, v147
	v_exp_f32_e32 v141, v141
	v_exp_f32_e32 v144, v144
	v_exp_f32_e32 v133, v133
	v_exp_f32_e32 v135, v135
	v_exp_f32_e32 v137, v137
	v_exp_f32_e32 v139, v139
	v_add_f32_e32 v142, 1.0, v142
	v_rcp_f32_e32 v145, v142
	v_add_f32_e32 v142, 1.0, v143
	v_add_f32_e32 v141, 1.0, v141
	v_rcp_f32_e32 v146, v142
	v_add_f32_e32 v142, 1.0, v144
	v_add_f32_e32 v133, 1.0, v133
	v_add_f32_e32 v135, 1.0, v135
	v_add_f32_e32 v137, 1.0, v137
	v_add_f32_e32 v139, 1.0, v139
	v_rcp_f32_e32 v141, v141
	v_rcp_f32_e32 v147, v142
	v_rcp_f32_e32 v133, v133
	v_rcp_f32_e32 v135, v135
	v_rcp_f32_e32 v137, v137
	v_rcp_f32_e32 v139, v139
	v_cvt_pk_bf16_f32 v144, v141, v145
	v_cvt_pk_bf16_f32 v145, v146, v147
	v_add_co_u32_e32 v146, vcc, s67, v130
	v_cvt_pk_bf16_f32 v142, v133, v135
	v_cvt_pk_bf16_f32 v143, v137, v139
	v_addc_co_u32_e32 v147, vcc, 0, v131, vcc
	global_store_dwordx4 v[146:147], v[142:145], off
	v_pk_mul_f32 v[148:149], v[66:67], v[140:141] op_sel_hi:[1,0]
	s_nop 0
	v_pk_mul_f32 v[142:143], v[70:71], v[140:141] op_sel_hi:[1,0]
	v_pk_mul_f32 v[144:145], v[68:69], v[140:141] op_sel_hi:[1,0]
	v_pk_mul_f32 v[140:141], v[64:65], v[140:141] op_sel_hi:[1,0]
	v_mul_f32_e32 v137, 0xbfb8aa3b, v142
	v_mul_f32_e32 v140, 0xbfb8aa3b, v140
	v_exp_f32_e32 v140, v140
	v_mul_f32_e32 v141, 0xbfb8aa3b, v141
	v_exp_f32_e32 v141, v141
	v_mul_f32_e32 v133, 0xbfb8aa3b, v144
	v_add_f32_e32 v140, 1.0, v140
	v_rcp_f32_e32 v142, v140
	v_add_f32_e32 v140, 1.0, v141
	v_mul_f32_e32 v141, 0xbfb8aa3b, v148
	v_mul_f32_e32 v135, 0xbfb8aa3b, v145
; DI unsigned pk_bf16(float lo, float hi) { f32x2 v = {lo, hi}; return __builtin_bit_cast(unsigned, __builtin_convertvector(v, bf16v2)); }
; DI float fast_sigmoid(float x) { return __builtin_amdgcn_rcpf(1.0f + __expf(-x)); }
;     DI void operator()(AccRef acc, const Unit& u, int wr, int wc, int fr, int fq) const {
;     ...
;         for (int ai = 0; ai < 2; ++ai)
; #pragma unroll
;             for (int m = 0; m < 4; ++m)
; #pragma unroll
;                 for (int bj = 0; bj < 2; ++bj) {
;                     const float rs = rsc.r[ai][m];
;                     const f32x4 r0 = acc[ai][bj][m][0] * rs, r1 = acc[ai][bj][m][1] * rs;
;                     u32x4 w;
;                     w.x = pk_bf16(fast_sigmoid(r0[0]), fast_sigmoid(r0[1])); w.y = pk_bf16(fast_sigmoid(r0[2]), fast_sigmoid(r0[3]));
;                     w.z = pk_bf16(fast_sigmoid(r1[0]), fast_sigmoid(r1[1])); w.w = pk_bf16(fast_sigmoid(r1[2]), fast_sigmoid(r1[3]));
;                     *(u32x4*)(Gp + (ai * 128 + m * 16) * 256 + bj * 128) = w;
	v_mul_f32_e32 v139, 0xbfb8aa3b, v143
	v_exp_f32_e32 v141, v141
	v_mul_f32_e32 v143, 0xbfb8aa3b, v149
	v_exp_f32_e32 v133, v133
	v_exp_f32_e32 v135, v135
	v_exp_f32_e32 v137, v137
	v_exp_f32_e32 v139, v139
	v_exp_f32_e32 v143, v143
	v_rcp_f32_e32 v144, v140
	v_add_f32_e32 v140, 1.0, v141
	v_add_f32_e32 v133, 1.0, v133
	v_add_f32_e32 v135, 1.0, v135
	v_add_f32_e32 v137, 1.0, v137
	v_add_f32_e32 v139, 1.0, v139
	v_rcp_f32_e32 v145, v140
	v_add_f32_e32 v140, 1.0, v143
	v_rcp_f32_e32 v133, v133
	v_rcp_f32_e32 v135, v135
	v_rcp_f32_e32 v137, v137
	v_rcp_f32_e32 v139, v139
	v_rcp_f32_e32 v143, v140
	v_cvt_pk_bf16_f32 v140, v133, v135
	v_cvt_pk_bf16_f32 v142, v142, v144
	v_cvt_pk_bf16_f32 v141, v137, v139
	v_cvt_pk_bf16_f32 v143, v145, v143
	global_store_dwordx4 v[146:147], v[140:143], off offset:256
	v_pk_mul_f32 v[144:145], v[58:59], v[138:139] op_sel_hi:[1,0]
	s_nop 0
	v_pk_mul_f32 v[142:143], v[60:61], v[138:139] op_sel_hi:[1,0]
	v_pk_mul_f32 v[140:141], v[62:63], v[138:139] op_sel_hi:[1,0]
	v_mul_f32_e32 v133, 0xbfb8aa3b, v142
	v_mul_f32_e32 v135, 0xbfb8aa3b, v143
	v_pk_mul_f32 v[142:143], v[56:57], v[138:139] op_sel_hi:[1,0]
	v_mul_f32_e32 v137, 0xbfb8aa3b, v140
	v_mul_f32_e32 v140, 0xbfb8aa3b, v142
	v_mul_f32_e32 v139, 0xbfb8aa3b, v141
	v_exp_f32_e32 v140, v140
	v_mul_f32_e32 v141, 0xbfb8aa3b, v143
	v_exp_f32_e32 v141, v141
	v_mul_f32_e32 v143, 0xbfb8aa3b, v145
	v_add_f32_e32 v140, 1.0, v140
	v_rcp_f32_e32 v142, v140
	v_add_f32_e32 v140, 1.0, v141
	v_mul_f32_e32 v141, 0xbfb8aa3b, v144
	v_exp_f32_e32 v141, v141
	v_exp_f32_e32 v133, v133
	v_exp_f32_e32 v135, v135
	v_exp_f32_e32 v137, v137
	v_exp_f32_e32 v139, v139
	v_exp_f32_e32 v143, v143
	v_rcp_f32_e32 v144, v140
	v_add_f32_e32 v140, 1.0, v141
	v_add_f32_e32 v133, 1.0, v133
	v_add_f32_e32 v135, 1.0, v135
	v_add_f32_e32 v137, 1.0, v137
	v_add_f32_e32 v139, 1.0, v139
	v_rcp_f32_e32 v145, v140
	v_add_f32_e32 v140, 1.0, v143
	v_rcp_f32_e32 v133, v133
	v_rcp_f32_e32 v135, v135
	v_rcp_f32_e32 v137, v137
	v_rcp_f32_e32 v139, v139
	v_rcp_f32_e32 v143, v140
	v_cvt_pk_bf16_f32 v142, v142, v144
	v_add_co_u32_e32 v144, vcc, s62, v130
	v_cvt_pk_bf16_f32 v140, v133, v135
	v_cvt_pk_bf16_f32 v141, v137, v139
	v_cvt_pk_bf16_f32 v143, v145, v143
	v_addc_co_u32_e32 v145, vcc, 0, v131, vcc
	global_store_dwordx4 v[144:145], v[140:143], off
	v_pk_mul_f32 v[146:147], v[50:51], v[138:139] op_sel_hi:[1,0]
	s_nop 0
	v_pk_mul_f32 v[140:141], v[54:55], v[138:139] op_sel_hi:[1,0]
	v_pk_mul_f32 v[142:143], v[52:53], v[138:139] op_sel_hi:[1,0]
	v_pk_mul_f32 v[138:139], v[48:49], v[138:139] op_sel_hi:[1,0]
	v_mul_f32_e32 v137, 0xbfb8aa3b, v140
	v_mul_f32_e32 v138, 0xbfb8aa3b, v138
	v_exp_f32_e32 v138, v138
	v_mul_f32_e32 v139, 0xbfb8aa3b, v139
	v_exp_f32_e32 v139, v139
	v_mul_f32_e32 v140, 0xbfb8aa3b, v141
	v_add_f32_e32 v138, 1.0, v138
	v_rcp_f32_e32 v141, v138
	v_add_f32_e32 v138, 1.0, v139
	v_mul_f32_e32 v139, 0xbfb8aa3b, v146
	v_mul_f32_e32 v133, 0xbfb8aa3b, v142
	v_mul_f32_e32 v135, 0xbfb8aa3b, v143
	v_exp_f32_e32 v139, v139
	v_mul_f32_e32 v142, 0xbfb8aa3b, v147
	v_exp_f32_e32 v133, v133
	v_exp_f32_e32 v135, v135
	v_exp_f32_e32 v137, v137
	v_exp_f32_e32 v140, v140
	v_exp_f32_e32 v142, v142
	v_rcp_f32_e32 v143, v138
	v_add_f32_e32 v138, 1.0, v139
	v_add_f32_e32 v133, 1.0, v133
	v_add_f32_e32 v135, 1.0, v135
	v_add_f32_e32 v137, 1.0, v137
	v_add_f32_e32 v140, 1.0, v140
	v_rcp_f32_e32 v146, v138
	v_add_f32_e32 v138, 1.0, v142
	v_rcp_f32_e32 v133, v133
	v_rcp_f32_e32 v135, v135
	v_rcp_f32_e32 v137, v137
	v_rcp_f32_e32 v140, v140
	v_rcp_f32_e32 v142, v138
	v_cvt_pk_bf16_f32 v138, v133, v135
	v_cvt_pk_bf16_f32 v139, v137, v140
	v_cvt_pk_bf16_f32 v140, v141, v143
	v_cvt_pk_bf16_f32 v141, v146, v142
	global_store_dwordx4 v[144:145], v[138:141], off offset:256
	v_pk_mul_f32 v[142:143], v[42:43], v[136:137] op_sel_hi:[1,0]
	s_nop 0
	v_pk_mul_f32 v[138:139], v[46:47], v[136:137] op_sel_hi:[1,0]
	v_pk_mul_f32 v[140:141], v[44:45], v[136:137] op_sel_hi:[1,0]
	s_nop 0
	v_mul_f32_e32 v133, 0xbfb8aa3b, v140
	v_mul_f32_e32 v135, 0xbfb8aa3b, v141
	v_pk_mul_f32 v[140:141], v[40:41], v[136:137] op_sel_hi:[1,0]
	v_mul_f32_e32 v137, 0xbfb8aa3b, v138
	v_mul_f32_e32 v138, 0xbfb8aa3b, v139
	v_exp_f32_e32 v138, v138
	v_mul_f32_e32 v139, 0xbfb8aa3b, v140
	v_exp_f32_e32 v139, v139
	v_mul_f32_e32 v140, 0xbfb8aa3b, v141
	v_exp_f32_e32 v140, v140
	v_add_f32_e32 v138, 1.0, v138
	v_rcp_f32_e32 v141, v138
	v_add_f32_e32 v138, 1.0, v139
	v_mul_f32_e32 v139, 0xbfb8aa3b, v142
	v_rcp_f32_e32 v144, v138
	v_add_f32_e32 v138, 1.0, v140
	v_exp_f32_e32 v139, v139
	v_mul_f32_e32 v140, 0xbfb8aa3b, v143
	v_exp_f32_e32 v133, v133
	v_exp_f32_e32 v135, v135
	v_exp_f32_e32 v137, v137
	v_exp_f32_e32 v140, v140
	v_rcp_f32_e32 v142, v138
	v_add_f32_e32 v138, 1.0, v139
	v_add_f32_e32 v133, 1.0, v133
	v_add_f32_e32 v135, 1.0, v135
	v_add_f32_e32 v137, 1.0, v137
	v_rcp_f32_e32 v143, v138
	v_add_f32_e32 v138, 1.0, v140
	v_rcp_f32_e32 v133, v133
	v_rcp_f32_e32 v135, v135
	v_rcp_f32_e32 v137, v137
	v_rcp_f32_e32 v145, v138
	v_cvt_pk_bf16_f32 v140, v144, v142
	v_add_co_u32_e32 v142, vcc, s63, v130
	v_cvt_pk_bf16_f32 v138, v133, v135
	v_cvt_pk_bf16_f32 v139, v137, v141
	v_cvt_pk_bf16_f32 v141, v143, v145
	v_addc_co_u32_e32 v143, vcc, 0, v131, vcc
	global_store_dwordx4 v[142:143], v[138:141], off
	v_pk_mul_f32 v[144:145], v[34:35], v[136:137] op_sel_hi:[1,0]
	s_nop 0
	v_pk_mul_f32 v[138:139], v[38:39], v[136:137] op_sel_hi:[1,0]
	v_pk_mul_f32 v[140:141], v[36:37], v[136:137] op_sel_hi:[1,0]
	v_pk_mul_f32 v[136:137], v[32:33], v[136:137] op_sel_hi:[1,0]
	v_mul_f32_e32 v133, 0xbfb8aa3b, v140
	v_mul_f32_e32 v136, 0xbfb8aa3b, v136
	v_exp_f32_e32 v136, v136
; DI unsigned pk_bf16(float lo, float hi) { f32x2 v = {lo, hi}; return __builtin_bit_cast(unsigned, __builtin_convertvector(v, bf16v2)); }
; DI float fast_sigmoid(float x) { return __builtin_amdgcn_rcpf(1.0f + __expf(-x)); }
;     DI void operator()(AccRef acc, const Unit& u, int wr, int wc, int fr, int fq) const {
;     ...
;         for (int ai = 0; ai < 2; ++ai)
; #pragma unroll
;             for (int m = 0; m < 4; ++m)
; #pragma unroll
;                 for (int bj = 0; bj < 2; ++bj) {
;                     const float rs = rsc.r[ai][m];
;                     const f32x4 r0 = acc[ai][bj][m][0] * rs, r1 = acc[ai][bj][m][1] * rs;
;                     u32x4 w;
;                     w.x = pk_bf16(fast_sigmoid(r0[0]), fast_sigmoid(r0[1])); w.y = pk_bf16(fast_sigmoid(r0[2]), fast_sigmoid(r0[3]));
;                     w.z = pk_bf16(fast_sigmoid(r1[0]), fast_sigmoid(r1[1])); w.w = pk_bf16(fast_sigmoid(r1[2]), fast_sigmoid(r1[3]));
;                     *(u32x4*)(Gp + (ai * 128 + m * 16) * 256 + bj * 128) = w;
	v_mul_f32_e32 v137, 0xbfb8aa3b, v137
	v_exp_f32_e32 v137, v137
	v_mul_f32_e32 v135, 0xbfb8aa3b, v141
	v_add_f32_e32 v136, 1.0, v136
	v_rcp_f32_e32 v140, v136
	v_add_f32_e32 v136, 1.0, v137
	v_mul_f32_e32 v137, 0xbfb8aa3b, v144
	v_mul_f32_e32 v138, 0xbfb8aa3b, v138
	v_mul_f32_e32 v139, 0xbfb8aa3b, v139
	v_exp_f32_e32 v137, v137
	v_mul_f32_e32 v141, 0xbfb8aa3b, v145
	v_exp_f32_e32 v133, v133
	v_exp_f32_e32 v135, v135
	v_exp_f32_e32 v138, v138
	v_exp_f32_e32 v139, v139
	v_exp_f32_e32 v141, v141
	v_rcp_f32_e32 v144, v136
	v_add_f32_e32 v136, 1.0, v137
	v_add_f32_e32 v133, 1.0, v133
	v_add_f32_e32 v135, 1.0, v135
	v_add_f32_e32 v138, 1.0, v138
	v_add_f32_e32 v139, 1.0, v139
	v_rcp_f32_e32 v145, v136
	v_add_f32_e32 v136, 1.0, v141
	v_rcp_f32_e32 v133, v133
	v_rcp_f32_e32 v135, v135
	v_rcp_f32_e32 v138, v138
	v_rcp_f32_e32 v139, v139
	v_rcp_f32_e32 v141, v136
	v_cvt_pk_bf16_f32 v136, v133, v135
	v_cvt_pk_bf16_f32 v137, v138, v139
	v_cvt_pk_bf16_f32 v138, v140, v144
	v_cvt_pk_bf16_f32 v139, v145, v141
	global_store_dwordx4 v[142:143], v[136:139], off offset:256
	v_pk_mul_f32 v[140:141], v[26:27], v[134:135] op_sel_hi:[1,0]
	s_nop 0
	v_pk_mul_f32 v[136:137], v[30:31], v[134:135] op_sel_hi:[1,0]
	v_pk_mul_f32 v[138:139], v[28:29], v[134:135] op_sel_hi:[1,0]
	v_mul_f32_e32 v136, 0xbfb8aa3b, v136
	v_mul_f32_e32 v135, 0xbfb8aa3b, v139
	v_exp_f32_e32 v135, v135
	v_exp_f32_e32 v136, v136
	v_mul_f32_e32 v137, 0xbfb8aa3b, v137
	v_exp_f32_e32 v137, v137
	v_mul_f32_e32 v133, 0xbfb8aa3b, v138
	v_pk_mul_f32 v[138:139], v[24:25], v[134:135] op_sel_hi:[1,0]
	v_add_f32_e32 v136, 1.0, v136
	v_rcp_f32_e32 v142, v136
	v_add_f32_e32 v136, 1.0, v137
	v_mul_f32_e32 v137, 0xbfb8aa3b, v138
	v_exp_f32_e32 v137, v137
	v_mul_f32_e32 v138, 0xbfb8aa3b, v139
	v_exp_f32_e32 v138, v138
	v_rcp_f32_e32 v139, v136
	v_add_f32_e32 v136, 1.0, v137
	v_mul_f32_e32 v137, 0xbfb8aa3b, v140
	v_rcp_f32_e32 v143, v136
	v_add_f32_e32 v136, 1.0, v138
	v_exp_f32_e32 v137, v137
	v_mul_f32_e32 v138, 0xbfb8aa3b, v141
	v_exp_f32_e32 v133, v133
	v_exp_f32_e32 v138, v138
	v_rcp_f32_e32 v140, v136
	v_add_f32_e32 v136, 1.0, v137
	v_add_f32_e32 v133, 1.0, v133
	v_add_f32_e32 v135, 1.0, v135
	v_rcp_f32_e32 v141, v136
	v_add_f32_e32 v136, 1.0, v138
	v_rcp_f32_e32 v133, v133
	v_rcp_f32_e32 v135, v135
	v_rcp_f32_e32 v144, v136
	v_cvt_pk_bf16_f32 v138, v143, v140
	v_add_co_u32_e32 v140, vcc, s64, v130
	v_cvt_pk_bf16_f32 v136, v133, v135
	v_cvt_pk_bf16_f32 v137, v142, v139
	v_cvt_pk_bf16_f32 v139, v141, v144
	v_addc_co_u32_e32 v141, vcc, 0, v131, vcc
	global_store_dwordx4 v[140:141], v[136:139], off
	v_pk_mul_f32 v[142:143], v[18:19], v[134:135] op_sel_hi:[1,0]
	s_nop 0
	v_pk_mul_f32 v[138:139], v[20:21], v[134:135] op_sel_hi:[1,0]
	v_pk_mul_f32 v[136:137], v[22:23], v[134:135] op_sel_hi:[1,0]
	v_mul_f32_e32 v135, 0xbfb8aa3b, v139
	v_mul_f32_e32 v133, 0xbfb8aa3b, v138
	v_exp_f32_e32 v138, v135
	v_pk_mul_f32 v[134:135], v[16:17], v[134:135] op_sel_hi:[1,0]
	v_mul_f32_e32 v136, 0xbfb8aa3b, v136
	v_mul_f32_e32 v134, 0xbfb8aa3b, v134
	v_exp_f32_e32 v134, v134
	v_mul_f32_e32 v135, 0xbfb8aa3b, v135
	v_exp_f32_e32 v135, v135
	v_mul_f32_e32 v137, 0xbfb8aa3b, v137
	v_add_f32_e32 v134, 1.0, v134
	v_rcp_f32_e32 v139, v134
	v_add_f32_e32 v134, 1.0, v135
	v_mul_f32_e32 v135, 0xbfb8aa3b, v142
	v_exp_f32_e32 v135, v135
	v_mul_f32_e32 v142, 0xbfb8aa3b, v143
	v_exp_f32_e32 v133, v133
	v_exp_f32_e32 v136, v136
	v_exp_f32_e32 v137, v137
	v_exp_f32_e32 v142, v142
	v_rcp_f32_e32 v143, v134
	v_add_f32_e32 v134, 1.0, v135
	v_add_f32_e32 v133, 1.0, v133
	v_add_f32_e32 v138, 1.0, v138
	v_add_f32_e32 v136, 1.0, v136
	v_add_f32_e32 v137, 1.0, v137
	v_rcp_f32_e32 v144, v134
	v_add_f32_e32 v134, 1.0, v142
	v_rcp_f32_e32 v133, v133
	v_rcp_f32_e32 v138, v138
	v_rcp_f32_e32 v136, v136
	v_rcp_f32_e32 v137, v137
	v_rcp_f32_e32 v142, v134
	v_cvt_pk_bf16_f32 v134, v133, v138
	v_cvt_pk_bf16_f32 v135, v136, v137
	v_cvt_pk_bf16_f32 v136, v139, v143
	v_cvt_pk_bf16_f32 v137, v144, v142
	global_store_dwordx4 v[140:141], v[134:137], off offset:256
	v_pk_mul_f32 v[138:139], v[10:11], v[132:133] op_sel_hi:[1,0]
	s_nop 0
	v_pk_mul_f32 v[134:135], v[14:15], v[132:133] op_sel_hi:[1,0]
	v_pk_mul_f32 v[136:137], v[12:13], v[132:133] op_sel_hi:[1,0]
	v_mul_f32_e32 v134, 0xbfb8aa3b, v134
	v_mul_f32_e32 v133, 0xbfb8aa3b, v136
	v_exp_f32_e32 v133, v133
	v_exp_f32_e32 v134, v134
	v_mul_f32_e32 v135, 0xbfb8aa3b, v135
	v_exp_f32_e32 v135, v135
	v_mul_f32_e32 v136, 0xbfb8aa3b, v137
	v_exp_f32_e32 v140, v136
	v_pk_mul_f32 v[136:137], v[8:9], v[132:133] op_sel_hi:[1,0]
	v_add_f32_e32 v134, 1.0, v134
	v_rcp_f32_e32 v141, v134
	v_add_f32_e32 v134, 1.0, v135
	v_mul_f32_e32 v135, 0xbfb8aa3b, v136
	v_exp_f32_e32 v135, v135
	v_mul_f32_e32 v136, 0xbfb8aa3b, v137
	v_exp_f32_e32 v136, v136
	v_rcp_f32_e32 v137, v134
	v_add_f32_e32 v134, 1.0, v135
	v_mul_f32_e32 v135, 0xbfb8aa3b, v138
	v_rcp_f32_e32 v142, v134
	v_add_f32_e32 v134, 1.0, v136
	v_exp_f32_e32 v135, v135
	v_mul_f32_e32 v136, 0xbfb8aa3b, v139
	v_exp_f32_e32 v136, v136
	v_rcp_f32_e32 v138, v134
	v_add_f32_e32 v134, 1.0, v135
	v_add_f32_e32 v133, 1.0, v133
	v_rcp_f32_e32 v139, v134
	v_add_f32_e32 v134, 1.0, v136
	v_rcp_f32_e32 v133, v133
	v_rcp_f32_e32 v143, v134
	v_add_f32_e32 v140, 1.0, v140
	v_rcp_f32_e32 v140, v140
	v_cvt_pk_bf16_f32 v136, v142, v138
	v_add_co_u32_e32 v138, vcc, s65, v130
	v_cvt_pk_bf16_f32 v135, v141, v137
	v_cvt_pk_bf16_f32 v137, v139, v143
	v_addc_co_u32_e32 v139, vcc, 0, v131, vcc
	v_pk_mul_f32 v[130:131], v[6:7], v[132:133] op_sel_hi:[1,0]
	v_cvt_pk_bf16_f32 v134, v133, v140
	v_mul_f32_e32 v130, 0xbfb8aa3b, v130
	v_exp_f32_e32 v130, v130
	v_mul_f32_e32 v131, 0xbfb8aa3b, v131
	global_store_dwordx4 v[138:139], v[134:137], off
	v_exp_f32_e32 v131, v131
	v_add_f32_e32 v130, 1.0, v130
	v_pk_mul_f32 v[134:135], v[4:5], v[132:133] op_sel_hi:[1,0]
	v_pk_mul_f32 v[136:137], v[2:3], v[132:133] op_sel_hi:[1,0]
	v_mul_f32_e32 v133, 0xbfb8aa3b, v134
	v_exp_f32_e32 v134, v133
	v_mul_f32_e32 v133, 0xbfb8aa3b, v135
	v_exp_f32_e32 v135, v133
	v_pk_mul_f32 v[132:133], v[0:1], v[132:133] op_sel_hi:[1,0]
	v_rcp_f32_e32 v140, v130
	v_add_f32_e32 v130, 1.0, v131
	v_mul_f32_e32 v131, 0xbfb8aa3b, v132
	v_exp_f32_e32 v131, v131
	v_mul_f32_e32 v132, 0xbfb8aa3b, v133
	v_exp_f32_e32 v132, v132
	v_rcp_f32_e32 v133, v130
	v_add_f32_e32 v130, 1.0, v131
	v_mul_f32_e32 v131, 0xbfb8aa3b, v136
	v_rcp_f32_e32 v141, v130
	v_add_f32_e32 v130, 1.0, v132
	v_exp_f32_e32 v131, v131
	v_mul_f32_e32 v132, 0xbfb8aa3b, v137
	v_exp_f32_e32 v132, v132
	v_rcp_f32_e32 v136, v130
	v_add_f32_e32 v130, 1.0, v131
	v_add_f32_e32 v134, 1.0, v134
	v_add_f32_e32 v135, 1.0, v135
	v_rcp_f32_e32 v137, v130
	v_add_f32_e32 v130, 1.0, v132
	v_rcp_f32_e32 v134, v134
	v_rcp_f32_e32 v135, v135
	v_rcp_f32_e32 v142, v130
	v_cvt_pk_bf16_f32 v131, v140, v133
	v_cvt_pk_bf16_f32 v132, v141, v136
	v_cvt_pk_bf16_f32 v130, v134, v135
	v_cvt_pk_bf16_f32 v133, v137, v142
	global_store_dwordx4 v[138:139], v[130:133], off offset:256

; #define PG8_STAGE(bufoff, gbase, voff) do { _Pragma("unroll") for (int _i = 0; _i < 2; ++_i) \
;         __builtin_amdgcn_global_load_lds((const unsigned*)((const char*)(gbase) + (voff)[_i]), (LAS unsigned*)(lds + (bufoff) + ldsw + _i * 8192), 16, 0, 0); } while (0)
; #define PG8_LDA(dst, b, h) do { _Pragma("unroll") for (int m = 0; m < 4; ++m) _Pragma("unroll") for (int k = 0; k < 2; ++k) dst[m][k] = *(const LAS bf16x8*)(lds + PG8_SA(b, h) + aoff + m * 2048 + k * 1024); } while (0)
; #define PG8_LDB(dst, b, h) do { _Pragma("unroll") for (int n = 0; n < 2; ++n) _Pragma("unroll") for (int k = 0; k < 2; ++k) dst[n][k] = *(const LAS bf16x8*)(lds + PG8_SB(b, h) + boff + n * 2048 + k * 1024); } while (0)
; #define PG8_MMA(ai, bj, At, Bt) do { __builtin_amdgcn_s_setprio(1); _Pragma("unroll") for (int m = 0; m < 4; ++m) _Pragma("unroll") for (int n = 0; n < 2; ++n) _Pragma("unroll") for (int k = 0; k < 2; ++k) \
;         acc[ai][bj][m][n] = __builtin_amdgcn_mfma_f32_16x16x32_bf16(Bt[n][k], At[m][k], acc[ai][bj][m][n], 0, 0, 0); __builtin_amdgcn_s_setprio(0); } while (0)
; #define PG8_WAIT_V(n) asm volatile("s_waitcnt vmcnt(" #n ")" ::: "memory")
; #define PG8_WAIT_L(n) asm volatile("s_waitcnt lgkmcnt(" #n ")" ::: "memory")
; template <class Epi0, class Epi1>
; DI void gemm_phase_dual(LAS unsigned char* lds, const Gemm g, const Gemm g1, const StaticOrder S, const Epi0 E0, const Epi1 E1) {
;     ...
;         for (int t = 0; t < nt; t += 2) {
;             const bool last = (t == nt - 2);
;             const char* a1 = cA + (size_t)(t + 1) * kstep;
;             const char* a2 = last ? nA : cA + (size_t)(t + 2) * kstep; const char* b2 = last ? nB : cB + (size_t)(t + 2) * kstep;
;             const char* a3 = a2 + kstep; const char* b3 = b2 + kstep;
;             PG8_LDB(B0, 0, 0); PG8_SCHED; PG8_LDA(At, 0, 0); PG8_STAGE(PG8_SA(1, 1), a1 + hstep, voffA);
;             PG8_WAIT_L(8); PG8_BAR; PG8_WAIT_L(0); PG8_MMA(0, 0, At, B0); PG8_BAR; PG8_SCHED;
;             PG8_LDB(B1, 0, 1); PG8_STAGE(PG8_SB(0, 0), b2, voffB);
;             PG8_BAR; PG8_WAIT_L(0); PG8_MMA(0, 1, At, B1); PG8_BAR;
;             PG8_LDA(At, 0, 1); PG8_STAGE(PG8_SA(0, 0), a2, voffA);
;             PG8_BAR; PG8_WAIT_L(0); PG8_MMA(1, 0, At, B0); PG8_BAR; PG8_SCHED;
;             PG8_STAGE(PG8_SB(0, 1), b2 + hstep, voffB);
;             PG8_WAIT_V(6); PG8_BAR; PG8_MMA(1, 1, At, B1); PG8_BAR;
.LBB0_708:
	ds_read_b128 v[156:159], v179
	ds_read_b128 v[160:163], v179 offset:1024
	ds_read_b128 v[164:167], v179 offset:2048
	ds_read_b128 v[168:171], v179 offset:3072
	s_add_u32 s40, s38, 0xfffc0080
	s_addc_u32 s41, s39, -1
	s_cmp_eq_u32 s69, 12
	s_cselect_b32 s43, s6, s41
	s_cselect_b32 s42, s7, s40
	s_cselect_b32 s41, s17, s68
	s_cselect_b32 s40, s19, s67
	v_lshl_add_u64 v[210:211], s[38:39], 0, v[148:149]
	s_add_i32 m0, s25, 0xc000
	ds_read_b128 v[172:175], v180
	ds_read_b128 v[186:189], v180 offset:2048
	ds_read_b128 v[194:197], v180 offset:4096
	ds_read_b128 v[202:205], v180 offset:6144
	global_load_lds_dwordx4 v[210:211], off
	v_lshl_add_u64 v[210:211], s[38:39], 0, v[150:151]
	s_add_i32 m0, s25, 0xe000
	s_nop 0
	global_load_lds_dwordx4 v[210:211], off
	s_waitcnt lgkmcnt(4)
	s_setprio 1
	s_barrier
	ds_read_b128 v[182:185], v180 offset:1024
	ds_read_b128 v[190:193], v180 offset:3072
	ds_read_b128 v[198:201], v180 offset:5120
	ds_read_b128 v[206:209], v180 offset:7168
	s_waitcnt lgkmcnt(4)
	v_mfma_f32_16x16x32_bf16 v[124:127], v[156:159], v[172:175], v[124:127]
	v_mfma_f32_16x16x32_bf16 v[120:123], v[164:167], v[172:175], v[120:123]
	v_mfma_f32_16x16x32_bf16 v[108:111], v[156:159], v[186:189], v[108:111]
	v_mfma_f32_16x16x32_bf16 v[104:107], v[164:167], v[186:189], v[104:107]
	v_mfma_f32_16x16x32_bf16 v[92:95], v[156:159], v[194:197], v[92:95]
	v_mfma_f32_16x16x32_bf16 v[88:91], v[164:167], v[194:197], v[88:91]
	v_mfma_f32_16x16x32_bf16 v[84:87], v[156:159], v[202:205], v[84:87]
	v_mfma_f32_16x16x32_bf16 v[80:83], v[164:167], v[202:205], v[80:83]
	s_waitcnt lgkmcnt(3)
	v_mfma_f32_16x16x32_bf16 v[124:127], v[160:163], v[182:185], v[124:127]
	v_mfma_f32_16x16x32_bf16 v[120:123], v[168:171], v[182:185], v[120:123]
	s_waitcnt lgkmcnt(2)
	v_mfma_f32_16x16x32_bf16 v[108:111], v[160:163], v[190:193], v[108:111]
	v_mfma_f32_16x16x32_bf16 v[104:107], v[168:171], v[190:193], v[104:107]
	s_waitcnt lgkmcnt(1)
	v_mfma_f32_16x16x32_bf16 v[92:95], v[160:163], v[198:201], v[92:95]
	v_mfma_f32_16x16x32_bf16 v[88:91], v[168:171], v[198:201], v[88:91]
	s_waitcnt lgkmcnt(0)
	s_setprio 2
	s_barrier
	v_mfma_f32_16x16x32_bf16 v[84:87], v[160:163], v[206:209], v[84:87]
	v_mfma_f32_16x16x32_bf16 v[80:83], v[168:171], v[206:209], v[80:83]
	s_setprio 0
	s_add_i32 s76, s52, s44
	v_lshl_add_u64 v[228:229], s[40:41], 0, v[130:131]
	s_mov_b32 m0, s76
	ds_read_b128 v[210:213], v181
	ds_read_b128 v[214:217], v181 offset:1024
	ds_read_b128 v[218:221], v181 offset:2048
	ds_read_b128 v[224:227], v181 offset:3072
	global_load_lds_dwordx4 v[228:229], off
	v_lshl_add_u64 v[230:231], s[40:41], 0, v[134:135]
	s_add_i32 m0, s76, 0x2000
	s_nop 0
	global_load_lds_dwordx4 v[230:231], off
	s_setprio 1
	s_barrier
	s_waitcnt lgkmcnt(0)
	v_mfma_f32_16x16x32_bf16 v[116:119], v[210:213], v[172:175], v[116:119]
	v_mfma_f32_16x16x32_bf16 v[112:115], v[218:221], v[172:175], v[112:115]
	v_mfma_f32_16x16x32_bf16 v[100:103], v[210:213], v[186:189], v[100:103]
	v_mfma_f32_16x16x32_bf16 v[96:99], v[218:221], v[186:189], v[96:99]
	v_mfma_f32_16x16x32_bf16 v[76:79], v[210:213], v[194:197], v[76:79]
	v_mfma_f32_16x16x32_bf16 v[72:75], v[218:221], v[194:197], v[72:75]
	v_mfma_f32_16x16x32_bf16 v[68:71], v[210:213], v[202:205], v[68:71]
	v_mfma_f32_16x16x32_bf16 v[64:67], v[218:221], v[202:205], v[64:67]
	v_mfma_f32_16x16x32_bf16 v[116:119], v[214:217], v[182:185], v[116:119]
	v_mfma_f32_16x16x32_bf16 v[112:115], v[224:227], v[182:185], v[112:115]
	v_mfma_f32_16x16x32_bf16 v[100:103], v[214:217], v[190:193], v[100:103]
	v_mfma_f32_16x16x32_bf16 v[96:99], v[224:227], v[190:193], v[96:99]
	v_mfma_f32_16x16x32_bf16 v[76:79], v[214:217], v[198:201], v[76:79]
	s_setprio 2
	s_barrier
	v_mfma_f32_16x16x32_bf16 v[72:75], v[224:227], v[198:201], v[72:75]
	v_mfma_f32_16x16x32_bf16 v[68:71], v[214:217], v[206:209], v[68:71]
	v_mfma_f32_16x16x32_bf16 v[64:67], v[224:227], v[206:209], v[64:67]
	s_setprio 0
	s_mov_b32 m0, s25
	v_lshl_add_u64 v[232:233], s[42:43], 0, v[128:129]
	ds_read_b128 v[172:175], v180 offset:16384
	ds_read_b128 v[186:189], v180 offset:18432
	ds_read_b128 v[194:197], v180 offset:20480
	ds_read_b128 v[202:205], v180 offset:22528
	global_load_lds_dwordx4 v[232:233], off
	v_lshl_add_u64 v[234:235], s[42:43], 0, v[132:133]
	s_mov_b32 m0, s45
	s_nop 0
	global_load_lds_dwordx4 v[234:235], off
	s_setprio 1
	s_barrier
	ds_read_b128 v[182:185], v180 offset:17408
	ds_read_b128 v[190:193], v180 offset:19456
	ds_read_b128 v[198:201], v180 offset:21504
	ds_read_b128 v[206:209], v180 offset:23552
	s_waitcnt lgkmcnt(4)
	v_mfma_f32_16x16x32_bf16 v[60:63], v[156:159], v[172:175], v[60:63]
	v_mfma_f32_16x16x32_bf16 v[56:59], v[164:167], v[172:175], v[56:59]
	v_mfma_f32_16x16x32_bf16 v[52:55], v[156:159], v[186:189], v[52:55]
	v_mfma_f32_16x16x32_bf16 v[48:51], v[164:167], v[186:189], v[48:51]
	v_mfma_f32_16x16x32_bf16 v[28:31], v[156:159], v[194:197], v[28:31]
	v_mfma_f32_16x16x32_bf16 v[24:27], v[164:167], v[194:197], v[24:27]
	v_mfma_f32_16x16x32_bf16 v[20:23], v[156:159], v[202:205], v[20:23]
	v_mfma_f32_16x16x32_bf16 v[16:19], v[164:167], v[202:205], v[16:19]
	s_waitcnt lgkmcnt(3)
	v_mfma_f32_16x16x32_bf16 v[60:63], v[160:163], v[182:185], v[60:63]
	v_mfma_f32_16x16x32_bf16 v[56:59], v[168:171], v[182:185], v[56:59]
	s_waitcnt lgkmcnt(2)
	v_mfma_f32_16x16x32_bf16 v[52:55], v[160:163], v[190:193], v[52:55]
	v_mfma_f32_16x16x32_bf16 v[48:51], v[168:171], v[190:193], v[48:51]
	s_waitcnt lgkmcnt(1)
	v_mfma_f32_16x16x32_bf16 v[28:31], v[160:163], v[198:201], v[28:31]
	v_mfma_f32_16x16x32_bf16 v[24:27], v[168:171], v[198:201], v[24:27]
	s_waitcnt lgkmcnt(0)
	s_setprio 2
	s_barrier
; #define PG8_STAGE(bufoff, gbase, voff) do { _Pragma("unroll") for (int _i = 0; _i < 2; ++_i) \
;         __builtin_amdgcn_global_load_lds((const unsigned*)((const char*)(gbase) + (voff)[_i]), (LAS unsigned*)(lds + (bufoff) + ldsw + _i * 8192), 16, 0, 0); } while (0)
; #define PG8_LDA(dst, b, h) do { _Pragma("unroll") for (int m = 0; m < 4; ++m) _Pragma("unroll") for (int k = 0; k < 2; ++k) dst[m][k] = *(const LAS bf16x8*)(lds + PG8_SA(b, h) + aoff + m * 2048 + k * 1024); } while (0)
; #define PG8_LDB(dst, b, h) do { _Pragma("unroll") for (int n = 0; n < 2; ++n) _Pragma("unroll") for (int k = 0; k < 2; ++k) dst[n][k] = *(const LAS bf16x8*)(lds + PG8_SB(b, h) + boff + n * 2048 + k * 1024); } while (0)
; #define PG8_MMA(ai, bj, At, Bt) do { __builtin_amdgcn_s_setprio(1); _Pragma("unroll") for (int m = 0; m < 4; ++m) _Pragma("unroll") for (int n = 0; n < 2; ++n) _Pragma("unroll") for (int k = 0; k < 2; ++k) \
;         acc[ai][bj][m][n] = __builtin_amdgcn_mfma_f32_16x16x32_bf16(Bt[n][k], At[m][k], acc[ai][bj][m][n], 0, 0, 0); __builtin_amdgcn_s_setprio(0); } while (0)
; #define PG8_WAIT_V(n) asm volatile("s_waitcnt vmcnt(" #n ")" ::: "memory")
; #define PG8_WAIT_L(n) asm volatile("s_waitcnt lgkmcnt(" #n ")" ::: "memory")
; #define PG8_BAR __builtin_amdgcn_s_barrier()
; #define PG8_SCHED __builtin_amdgcn_sched_barrier(0)
; #define PG8_WAIT_V(n) asm volatile("s_waitcnt vmcnt(" #n ")" ::: "memory")
; #define PG8_WAIT_L(n) asm volatile("s_waitcnt lgkmcnt(" #n ")" ::: "memory")
; template <class Epi0, class Epi1>
; DI void gemm_phase_dual(LAS unsigned char* lds, const Gemm g, const Gemm g1, const StaticOrder S, const Epi0 E0, const Epi1 E1) {
;     ...
;             PG8_WAIT_V(6); PG8_BAR; PG8_MMA(1, 1, At, B1); PG8_BAR;
;             PG8_LDB(B0, 1, 0); PG8_SCHED; PG8_LDA(At, 1, 0); PG8_STAGE(PG8_SA(0, 1), a2 + hstep, voffA);
;             PG8_WAIT_L(8); PG8_BAR; PG8_WAIT_L(0); PG8_MMA(0, 0, At, B0); PG8_BAR; PG8_SCHED;
;             PG8_LDB(B1, 1, 1); PG8_STAGE(PG8_SB(1, 0), b3, voffB);
;             PG8_BAR; PG8_WAIT_L(0); PG8_MMA(0, 1, At, B1); PG8_BAR;
;             PG8_LDA(At, 1, 1); PG8_STAGE(PG8_SA(1, 0), a3, voffA);
;             PG8_BAR; PG8_WAIT_L(0); PG8_MMA(1, 0, At, B0); PG8_BAR; PG8_SCHED;
;             PG8_STAGE(PG8_SB(1, 1), b3 + hstep, voffB);
;             PG8_WAIT_V(6); PG8_BAR; PG8_MMA(1, 1, At, B1); PG8_BAR;
	v_mfma_f32_16x16x32_bf16 v[20:23], v[160:163], v[206:209], v[20:23]
	v_mfma_f32_16x16x32_bf16 v[16:19], v[168:171], v[206:209], v[16:19]
	s_setprio 0
	s_add_u32 s76, s40, 0x40000
	s_addc_u32 s77, s41, 0
	s_add_i32 s78, s53, s44
	v_lshl_add_u64 v[156:157], s[76:77], 0, v[130:131]
	s_mov_b32 m0, s78
	s_nop 0
	global_load_lds_dwordx4 v[156:157], off
	v_lshl_add_u64 v[156:157], s[76:77], 0, v[134:135]
	s_add_i32 m0, s78, 0x2000
	s_nop 0
	global_load_lds_dwordx4 v[156:157], off
	s_waitcnt vmcnt(6)
	s_setprio 1
	s_barrier
	v_mfma_f32_16x16x32_bf16 v[44:47], v[210:213], v[172:175], v[44:47]
	v_mfma_f32_16x16x32_bf16 v[40:43], v[218:221], v[172:175], v[40:43]
	v_mfma_f32_16x16x32_bf16 v[36:39], v[210:213], v[186:189], v[36:39]
	v_mfma_f32_16x16x32_bf16 v[32:35], v[218:221], v[186:189], v[32:35]
	v_mfma_f32_16x16x32_bf16 v[12:15], v[210:213], v[194:197], v[12:15]
	v_mfma_f32_16x16x32_bf16 v[8:11], v[218:221], v[194:197], v[8:11]
	v_mfma_f32_16x16x32_bf16 v[4:7], v[210:213], v[202:205], v[4:7]
	v_mfma_f32_16x16x32_bf16 v[0:3], v[218:221], v[202:205], v[0:3]
	v_mfma_f32_16x16x32_bf16 v[44:47], v[214:217], v[182:185], v[44:47]
	v_mfma_f32_16x16x32_bf16 v[40:43], v[224:227], v[182:185], v[40:43]
	v_mfma_f32_16x16x32_bf16 v[36:39], v[214:217], v[190:193], v[36:39]
	v_mfma_f32_16x16x32_bf16 v[32:35], v[224:227], v[190:193], v[32:35]
	v_mfma_f32_16x16x32_bf16 v[12:15], v[214:217], v[198:201], v[12:15]
	s_setprio 2
	s_barrier
	v_mfma_f32_16x16x32_bf16 v[8:11], v[224:227], v[198:201], v[8:11]
	v_mfma_f32_16x16x32_bf16 v[4:7], v[214:217], v[206:209], v[4:7]
	v_mfma_f32_16x16x32_bf16 v[0:3], v[224:227], v[206:209], v[0:3]
	s_setprio 0
	s_add_i32 s76, 0, 0x18000
	v_add_u32_e32 v168, s76, v177
	ds_read_b128 v[156:159], v168
	ds_read_b128 v[160:163], v168 offset:1024
	ds_read_b128 v[164:167], v168 offset:2048
	ds_read_b128 v[168:171], v168 offset:3072
	s_add_u32 s42, s42, 0x40000
	s_addc_u32 s43, s43, 0
	s_mov_b32 m0, s46
	v_lshl_add_u64 v[210:211], s[42:43], 0, v[128:129]
	ds_read_b128 v[172:175], v180 offset:32768
	ds_read_b128 v[186:189], v180 offset:34816
	ds_read_b128 v[194:197], v180 offset:36864
	ds_read_b128 v[202:205], v180 offset:38912
	global_load_lds_dwordx4 v[210:211], off
	v_lshl_add_u64 v[210:211], s[42:43], 0, v[132:133]
	s_mov_b32 m0, s47
	s_nop 0
	global_load_lds_dwordx4 v[210:211], off
	s_waitcnt lgkmcnt(4)
	s_setprio 1
	s_barrier
	ds_read_b128 v[182:185], v180 offset:33792
	ds_read_b128 v[190:193], v180 offset:35840
	ds_read_b128 v[198:201], v180 offset:37888
	ds_read_b128 v[206:209], v180 offset:39936
	s_waitcnt lgkmcnt(4)
	v_mfma_f32_16x16x32_bf16 v[124:127], v[156:159], v[172:175], v[124:127]
	v_mfma_f32_16x16x32_bf16 v[120:123], v[164:167], v[172:175], v[120:123]
	v_mfma_f32_16x16x32_bf16 v[108:111], v[156:159], v[186:189], v[108:111]
	v_mfma_f32_16x16x32_bf16 v[104:107], v[164:167], v[186:189], v[104:107]
	v_mfma_f32_16x16x32_bf16 v[92:95], v[156:159], v[194:197], v[92:95]
	v_mfma_f32_16x16x32_bf16 v[88:91], v[164:167], v[194:197], v[88:91]
	v_mfma_f32_16x16x32_bf16 v[84:87], v[156:159], v[202:205], v[84:87]
	v_mfma_f32_16x16x32_bf16 v[80:83], v[164:167], v[202:205], v[80:83]
	s_waitcnt lgkmcnt(3)
	v_mfma_f32_16x16x32_bf16 v[124:127], v[160:163], v[182:185], v[124:127]
	v_mfma_f32_16x16x32_bf16 v[120:123], v[168:171], v[182:185], v[120:123]
	s_waitcnt lgkmcnt(2)
	v_mfma_f32_16x16x32_bf16 v[108:111], v[160:163], v[190:193], v[108:111]
	v_mfma_f32_16x16x32_bf16 v[104:107], v[168:171], v[190:193], v[104:107]
	s_waitcnt lgkmcnt(1)
	v_mfma_f32_16x16x32_bf16 v[92:95], v[160:163], v[198:201], v[92:95]
	v_mfma_f32_16x16x32_bf16 v[88:91], v[168:171], v[198:201], v[88:91]
	s_waitcnt lgkmcnt(0)
	s_setprio 2
	s_barrier
	v_mfma_f32_16x16x32_bf16 v[84:87], v[160:163], v[206:209], v[84:87]
	v_mfma_f32_16x16x32_bf16 v[80:83], v[168:171], v[206:209], v[80:83]
	s_setprio 0
	s_add_i32 s42, 0, 0x1c000
	s_add_i32 s43, s76, s44
	v_add_u32_e32 v224, s42, v177
	v_lshl_add_u64 v[228:229], v[228:229], 0, s[8:9]
	s_mov_b32 m0, s43
	ds_read_b128 v[210:213], v224
	ds_read_b128 v[214:217], v224 offset:1024
	ds_read_b128 v[218:221], v224 offset:2048
	ds_read_b128 v[224:227], v224 offset:3072
	global_load_lds_dwordx4 v[228:229], off
	v_lshl_add_u64 v[228:229], v[230:231], 0, s[8:9]
	s_add_i32 m0, s43, 0x2000
	s_nop 0
	global_load_lds_dwordx4 v[228:229], off
	s_setprio 1
	s_barrier
	s_waitcnt lgkmcnt(0)
	v_mfma_f32_16x16x32_bf16 v[116:119], v[210:213], v[172:175], v[116:119]
	v_mfma_f32_16x16x32_bf16 v[112:115], v[218:221], v[172:175], v[112:115]
	v_mfma_f32_16x16x32_bf16 v[100:103], v[210:213], v[186:189], v[100:103]
	v_mfma_f32_16x16x32_bf16 v[96:99], v[218:221], v[186:189], v[96:99]
	v_mfma_f32_16x16x32_bf16 v[76:79], v[210:213], v[194:197], v[76:79]
	v_mfma_f32_16x16x32_bf16 v[72:75], v[218:221], v[194:197], v[72:75]
	v_mfma_f32_16x16x32_bf16 v[68:71], v[210:213], v[202:205], v[68:71]
	v_mfma_f32_16x16x32_bf16 v[64:67], v[218:221], v[202:205], v[64:67]
	v_mfma_f32_16x16x32_bf16 v[116:119], v[214:217], v[182:185], v[116:119]
	v_mfma_f32_16x16x32_bf16 v[112:115], v[224:227], v[182:185], v[112:115]
	v_mfma_f32_16x16x32_bf16 v[100:103], v[214:217], v[190:193], v[100:103]
	v_mfma_f32_16x16x32_bf16 v[96:99], v[224:227], v[190:193], v[96:99]
	v_mfma_f32_16x16x32_bf16 v[76:79], v[214:217], v[198:201], v[76:79]
	s_setprio 2
	s_barrier
	v_mfma_f32_16x16x32_bf16 v[72:75], v[224:227], v[198:201], v[72:75]
	v_mfma_f32_16x16x32_bf16 v[68:71], v[214:217], v[206:209], v[68:71]
	v_mfma_f32_16x16x32_bf16 v[64:67], v[224:227], v[206:209], v[64:67]
	s_setprio 0
	s_mov_b32 m0, s59
	v_lshl_add_u64 v[228:229], v[232:233], 0, s[8:9]
	ds_read_b128 v[172:175], v180 offset:49152
	ds_read_b128 v[186:189], v180 offset:51200
	ds_read_b128 v[194:197], v180 offset:53248
	ds_read_b128 v[202:205], v180 offset:55296
	global_load_lds_dwordx4 v[228:229], off
	v_lshl_add_u64 v[228:229], v[234:235], 0, s[8:9]
	s_mov_b32 m0, s60
	s_nop 0
	global_load_lds_dwordx4 v[228:229], off
	s_setprio 1
	s_barrier
; #define PG8_STAGE(bufoff, gbase, voff) do { _Pragma("unroll") for (int _i = 0; _i < 2; ++_i) \
;         __builtin_amdgcn_global_load_lds((const unsigned*)((const char*)(gbase) + (voff)[_i]), (LAS unsigned*)(lds + (bufoff) + ldsw + _i * 8192), 16, 0, 0); } while (0)
; #define PG8_LDA(dst, b, h) do { _Pragma("unroll") for (int m = 0; m < 4; ++m) _Pragma("unroll") for (int k = 0; k < 2; ++k) dst[m][k] = *(const LAS bf16x8*)(lds + PG8_SA(b, h) + aoff + m * 2048 + k * 1024); } while (0)
; #define PG8_WAIT_V(n) asm volatile("s_waitcnt vmcnt(" #n ")" ::: "memory")
; #define PG8_WAIT_L(n) asm volatile("s_waitcnt lgkmcnt(" #n ")" ::: "memory")
; #define PG8_BAR __builtin_amdgcn_s_barrier()
; #define PG8_SCHED __builtin_amdgcn_sched_barrier(0)
; #define PG8_WAIT_V(n) asm volatile("s_waitcnt vmcnt(" #n ")" ::: "memory")
; template <class Epi0, class Epi1>
; DI void gemm_phase_dual(LAS unsigned char* lds, const Gemm g, const Gemm g1, const StaticOrder S, const Epi0 E0, const Epi1 E1) {
;     ...
;             PG8_BAR; PG8_WAIT_L(0); PG8_MMA(0, 1, At, B1); PG8_BAR;
;             PG8_LDA(At, 1, 1); PG8_STAGE(PG8_SA(1, 0), a3, voffA);
;             PG8_BAR; PG8_WAIT_L(0); PG8_MMA(1, 0, At, B0); PG8_BAR; PG8_SCHED;
;             PG8_STAGE(PG8_SB(1, 1), b3 + hstep, voffB);
;             PG8_WAIT_V(6); PG8_BAR; PG8_MMA(1, 1, At, B1); PG8_BAR;
;         }
;         if (ui & 1) E1(acc, cur, wr, wc, fr, fq); else E0(acc, cur, wr, wc, fr, fq);
;     DI void operator()(AccRef acc, const Unit& u, int wr, int wc, int fr, int fq) const {
;         const int row0 = u.pm * 256 + wr * 64 + fr, col0 = u.pn * 256 + wc * 32 + 8 * fq;
; #pragma unroll
;         for (int ai = 0; ai < 2; ++ai)
; #pragma unroll
;             for (int mh = 0; mh < 2; ++mh) {
;                 u32x4 gv[2][2], mv[2][2];
; #pragma unroll
;                 for (int mm = 0; mm < 2; ++mm)
; #pragma unroll
;                     for (int bj = 0; bj < 2; ++bj) {
;                         const size_t row = (size_t)(row0 + ai * 128 + (mh * 2 + mm) * 16); const int col = col0 + bj * 128;
;                         gv[mm][bj] = *(const u32x4*)(gab + (size_t)(u.pm * 8 + SECOND * 4 + u.pn) * 65536 + (wr * 64 + fr + ai * 128 + (mh * 2 + mm) * 16) * 256 + wc * 32 + 8 * fq + bj * 128);
;                         if (SECOND) mv[mm][bj] = *(const u32x4*)(mrg + row * 1024 + col);
;                     }
	ds_read_b128 v[182:185], v180 offset:50176
	ds_read_b128 v[190:193], v180 offset:52224
	ds_read_b128 v[198:201], v180 offset:54272
	ds_read_b128 v[206:209], v180 offset:56320
	s_waitcnt lgkmcnt(4)
	v_mfma_f32_16x16x32_bf16 v[60:63], v[156:159], v[172:175], v[60:63]
	v_mfma_f32_16x16x32_bf16 v[56:59], v[164:167], v[172:175], v[56:59]
	v_mfma_f32_16x16x32_bf16 v[52:55], v[156:159], v[186:189], v[52:55]
	v_mfma_f32_16x16x32_bf16 v[48:51], v[164:167], v[186:189], v[48:51]
	v_mfma_f32_16x16x32_bf16 v[28:31], v[156:159], v[194:197], v[28:31]
	v_mfma_f32_16x16x32_bf16 v[24:27], v[164:167], v[194:197], v[24:27]
	v_mfma_f32_16x16x32_bf16 v[20:23], v[156:159], v[202:205], v[20:23]
	v_mfma_f32_16x16x32_bf16 v[16:19], v[164:167], v[202:205], v[16:19]
	s_waitcnt lgkmcnt(3)
	v_mfma_f32_16x16x32_bf16 v[60:63], v[160:163], v[182:185], v[60:63]
	v_mfma_f32_16x16x32_bf16 v[56:59], v[168:171], v[182:185], v[56:59]
	s_waitcnt lgkmcnt(2)
	v_mfma_f32_16x16x32_bf16 v[52:55], v[160:163], v[190:193], v[52:55]
	v_mfma_f32_16x16x32_bf16 v[48:51], v[168:171], v[190:193], v[48:51]
	s_waitcnt lgkmcnt(1)
	v_mfma_f32_16x16x32_bf16 v[28:31], v[160:163], v[198:201], v[28:31]
	v_mfma_f32_16x16x32_bf16 v[24:27], v[168:171], v[198:201], v[24:27]
	s_waitcnt lgkmcnt(0)
	s_setprio 2
	s_barrier
	v_mfma_f32_16x16x32_bf16 v[20:23], v[160:163], v[206:209], v[20:23]
	v_mfma_f32_16x16x32_bf16 v[16:19], v[168:171], v[206:209], v[16:19]
	s_setprio 0
	s_add_u32 s40, s40, 0x40080
	s_addc_u32 s41, s41, 0
	s_add_i32 s42, s42, s44
	v_lshl_add_u64 v[156:157], s[40:41], 0, v[130:131]
	s_mov_b32 m0, s42
	s_nop 0
	global_load_lds_dwordx4 v[156:157], off
	v_lshl_add_u64 v[156:157], s[40:41], 0, v[134:135]
	s_add_i32 m0, s42, 0x2000
	s_nop 0
	global_load_lds_dwordx4 v[156:157], off
	s_waitcnt vmcnt(6)
	s_setprio 1
	s_barrier
	v_mfma_f32_16x16x32_bf16 v[44:47], v[210:213], v[172:175], v[44:47]
	v_mfma_f32_16x16x32_bf16 v[40:43], v[218:221], v[172:175], v[40:43]
	v_mfma_f32_16x16x32_bf16 v[36:39], v[210:213], v[186:189], v[36:39]
	v_mfma_f32_16x16x32_bf16 v[32:35], v[218:221], v[186:189], v[32:35]
	v_mfma_f32_16x16x32_bf16 v[12:15], v[210:213], v[194:197], v[12:15]
	v_mfma_f32_16x16x32_bf16 v[8:11], v[218:221], v[194:197], v[8:11]
	v_mfma_f32_16x16x32_bf16 v[4:7], v[210:213], v[202:205], v[4:7]
	v_mfma_f32_16x16x32_bf16 v[0:3], v[218:221], v[202:205], v[0:3]
	v_mfma_f32_16x16x32_bf16 v[44:47], v[214:217], v[182:185], v[44:47]
	v_mfma_f32_16x16x32_bf16 v[40:43], v[224:227], v[182:185], v[40:43]
	v_mfma_f32_16x16x32_bf16 v[36:39], v[214:217], v[190:193], v[36:39]
	v_mfma_f32_16x16x32_bf16 v[32:35], v[224:227], v[190:193], v[32:35]
	v_mfma_f32_16x16x32_bf16 v[12:15], v[214:217], v[198:201], v[12:15]
	s_setprio 2
	s_barrier
	v_mfma_f32_16x16x32_bf16 v[8:11], v[224:227], v[198:201], v[8:11]
	v_mfma_f32_16x16x32_bf16 v[4:7], v[214:217], v[206:209], v[4:7]
	v_mfma_f32_16x16x32_bf16 v[0:3], v[224:227], v[206:209], v[0:3]
	s_setprio 0
	s_add_i32 s69, s69, 2
	s_add_u32 s38, s38, 0x100
	s_addc_u32 s39, s39, 0
	s_add_u32 s67, s67, 0x100
	s_addc_u32 s68, s68, 0
	s_cmp_gt_u32 s69, 13
	s_cbranch_scc0 .LBB0_708
	v_lshl_add_u32 v164, s24, 8, v176
	s_lshl_b32 s17, s66, 8
	v_or_b32_e32 v162, s17, v178
	v_or_b32_e32 v160, 16, v164
	s_mov_b64 s[6:7], -1
	s_and_b64 vcc, exec, s[28:29]
	v_ashrrev_i32_e32 v165, 31, v164
	v_ashrrev_i32_e32 v163, 31, v162
	v_ashrrev_i32_e32 v161, 31, v160
	v_or_b32_e32 v158, 32, v164
	v_or_b32_e32 v156, 48, v164
	s_cbranch_vccz .LBB0_711
	s_lshl_b32 s6, s24, 3
	s_add_i32 s6, s66, s6
	s_add_i32 s6, s6, 4
	v_lshlrev_b64 v[168:169], 11, v[160:161]
	s_ashr_i32 s7, s6, 31
	v_lshlrev_b64 v[166:167], 11, v[164:165]
	v_lshlrev_b64 v[170:171], 1, v[162:163]
	v_lshl_add_u64 v[168:169], s[36:37], 0, v[168:169]
	s_lshl_b64 s[6:7], s[6:7], 17
	v_lshl_add_u64 v[166:167], s[36:37], 0, v[166:167]
	v_lshl_add_u64 v[174:175], v[168:169], 0, v[170:171]
	v_lshl_add_u64 v[168:169], v[136:137], 0, s[6:7]
	v_lshl_add_u64 v[166:167], v[166:167], 0, v[170:171]
	v_lshl_add_u64 v[172:173], v[138:139], 1, v[168:169]
	global_load_dwordx4 v[182:185], v[166:167], off
	global_load_dwordx4 v[186:189], v[166:167], off offset:256
	global_load_dwordx4 v[190:193], v[174:175], off
	global_load_dwordx4 v[194:197], v[172:173], off
	global_load_dwordx4 v[198:201], v[172:173], off offset:256
	v_add_co_u32_e32 v206, vcc, s48, v172
	v_ashrrev_i32_e32 v159, 31, v158
	s_nop 0
	v_addc_co_u32_e32 v207, vcc, 0, v173, vcc
	global_load_dwordx4 v[202:205], v[206:207], off
	s_nop 0
	global_load_dwordx4 v[206:209], v[206:207], off offset:256
	s_nop 0
	global_load_dwordx4 v[210:213], v[174:175], off offset:256
	v_ashrrev_i32_e32 v157, 31, v156
	s_mov_b64 s[6:7], 0
	s_waitcnt vmcnt(0)
; DI unsigned pk_bf16(float lo, float hi) { f32x2 v = {lo, hi}; return __builtin_bit_cast(unsigned, __builtin_convertvector(v, bf16v2)); }
; DI float bf_lo(unsigned w) { return __uint_as_float(w << 16); }
; DI float bf_hi(unsigned w) { return __uint_as_float(w & 0xffff0000u); }
;     DI void operator()(AccRef acc, const Unit& u, int wr, int wc, int fr, int fq) const {
;     ...
;                         const size_t row = (size_t)(row0 + ai * 128 + (mh * 2 + mm) * 16); const int col = col0 + bj * 128;
;                         gv[mm][bj] = *(const u32x4*)(gab + (size_t)(u.pm * 8 + SECOND * 4 + u.pn) * 65536 + (wr * 64 + fr + ai * 128 + (mh * 2 + mm) * 16) * 256 + wc * 32 + 8 * fq + bj * 128);
;                         if (SECOND) mv[mm][bj] = *(const u32x4*)(mrg + row * 1024 + col);
;                     }
; #pragma unroll
;                 for (int mm = 0; mm < 2; ++mm)
; #pragma unroll
;                     for (int bj = 0; bj < 2; ++bj) {
;                         const int m = mh * 2 + mm;
;                         const size_t row = (size_t)(row0 + ai * 128 + m * 16); const int col = col0 + bj * 128;
;                         const u32x4 gt = gv[mm][bj];
;                         const f32x4 r0 = acc[ai][bj][m][0], r1 = acc[ai][bj][m][1];
;                         float v[8] = {bf_lo(gt.x) * r0[0], bf_hi(gt.x) * r0[1], bf_lo(gt.y) * r0[2], bf_hi(gt.y) * r0[3], bf_lo(gt.z) * r1[0], bf_hi(gt.z) * r1[1], bf_lo(gt.w) * r1[2], bf_hi(gt.w) * r1[3]};
;                         if (SECOND) { const u32x4 o = mv[mm][bj]; v[0] += bf_lo(o.x); v[1] += bf_hi(o.x); v[2] += bf_lo(o.y); v[3] += bf_hi(o.y); v[4] += bf_lo(o.z); v[5] += bf_hi(o.z); v[6] += bf_lo(o.w); v[7] += bf_hi(o.w); }
;                         u32x4 w; w.x = pk_bf16(v[0], v[1]); w.y = pk_bf16(v[2], v[3]); w.z = pk_bf16(v[4], v[5]); w.w = pk_bf16(v[6], v[7]);
;                         *(u32x4*)(mrg + row * 1024 + col) = w;
;                     }
	v_lshlrev_b32_e32 v214, 16, v182
	v_and_b32_e32 v215, 0xffff0000, v182
	v_lshlrev_b32_e32 v182, 16, v183
	v_and_b32_e32 v183, 0xffff0000, v183
	v_lshlrev_b32_e32 v216, 16, v184
	v_and_b32_e32 v217, 0xffff0000, v184
	v_lshlrev_b32_e32 v184, 16, v185
	v_and_b32_e32 v185, 0xffff0000, v185
	v_lshlrev_b32_e32 v228, 16, v194
	v_and_b32_e32 v229, 0xffff0000, v194
	v_lshlrev_b32_e32 v194, 16, v195
	v_and_b32_e32 v195, 0xffff0000, v195
	v_lshlrev_b32_e32 v230, 16, v196
	v_and_b32_e32 v231, 0xffff0000, v196
	v_lshlrev_b32_e32 v196, 16, v197
	v_and_b32_e32 v197, 0xffff0000, v197
	v_lshlrev_b32_e32 v218, 16, v186
	v_and_b32_e32 v219, 0xffff0000, v186
	v_lshlrev_b32_e32 v186, 16, v187
	v_and_b32_e32 v187, 0xffff0000, v187
	v_lshlrev_b32_e32 v220, 16, v188
	v_and_b32_e32 v221, 0xffff0000, v188
	v_lshlrev_b32_e32 v188, 16, v189
	v_and_b32_e32 v189, 0xffff0000, v189
	v_lshlrev_b32_e32 v232, 16, v198
	v_and_b32_e32 v233, 0xffff0000, v198
	v_lshlrev_b32_e32 v198, 16, v199
	v_and_b32_e32 v199, 0xffff0000, v199
	v_lshlrev_b32_e32 v234, 16, v200
	v_and_b32_e32 v235, 0xffff0000, v200
	v_lshlrev_b32_e32 v200, 16, v201
	v_and_b32_e32 v201, 0xffff0000, v201
	v_pk_fma_f32 v[214:215], v[124:125], v[228:229], v[214:215]
	v_pk_fma_f32 v[194:195], v[126:127], v[194:195], v[182:183]
	v_pk_fma_f32 v[216:217], v[120:121], v[230:231], v[216:217]
	v_pk_fma_f32 v[196:197], v[122:123], v[196:197], v[184:185]
	v_pk_fma_f32 v[218:219], v[116:117], v[232:233], v[218:219]
	v_pk_fma_f32 v[198:199], v[118:119], v[198:199], v[186:187]
	v_pk_fma_f32 v[220:221], v[112:113], v[234:235], v[220:221]
	v_pk_fma_f32 v[200:201], v[114:115], v[200:201], v[188:189]
	v_cvt_pk_bf16_f32 v182, v214, v215
	v_cvt_pk_bf16_f32 v183, v194, v195
	v_cvt_pk_bf16_f32 v184, v216, v217
	v_cvt_pk_bf16_f32 v185, v196, v197
	v_lshlrev_b32_e32 v224, 16, v190
	v_and_b32_e32 v225, 0xffff0000, v190
	v_lshlrev_b32_e32 v190, 16, v191
	v_and_b32_e32 v191, 0xffff0000, v191
	v_lshlrev_b32_e32 v226, 16, v192
	v_and_b32_e32 v227, 0xffff0000, v192
	v_lshlrev_b32_e32 v228, 16, v202
	v_and_b32_e32 v229, 0xffff0000, v202
	v_lshlrev_b32_e32 v202, 16, v203
	v_and_b32_e32 v203, 0xffff0000, v203
	v_lshlrev_b32_e32 v230, 16, v204
	v_and_b32_e32 v231, 0xffff0000, v204
	v_cvt_pk_bf16_f32 v186, v218, v219
	v_cvt_pk_bf16_f32 v187, v198, v199
	v_cvt_pk_bf16_f32 v188, v220, v221
	v_cvt_pk_bf16_f32 v189, v200, v201
	global_store_dwordx4 v[166:167], v[182:185], off
	global_store_dwordx4 v[166:167], v[186:189], off offset:256
	v_pk_fma_f32 v[194:195], v[108:109], v[228:229], v[224:225]
	v_lshlrev_b32_e32 v182, 16, v205
	v_and_b32_e32 v183, 0xffff0000, v205
	v_lshlrev_b32_e32 v184, 16, v193
	v_and_b32_e32 v185, 0xffff0000, v193
	v_pk_fma_f32 v[190:191], v[110:111], v[202:203], v[190:191]
	v_pk_fma_f32 v[196:197], v[104:105], v[230:231], v[226:227]
	v_pk_fma_f32 v[186:187], v[106:107], v[182:183], v[184:185]
	v_cvt_pk_bf16_f32 v182, v194, v195
	v_cvt_pk_bf16_f32 v183, v190, v191
	v_cvt_pk_bf16_f32 v184, v196, v197
	v_cvt_pk_bf16_f32 v185, v186, v187
	global_store_dwordx4 v[174:175], v[182:185], off
	v_lshlrev_b32_e32 v186, 16, v211
	v_and_b32_e32 v187, 0xffff0000, v211
	v_lshlrev_b32_e32 v182, 16, v206
	v_and_b32_e32 v183, 0xffff0000, v206
	v_lshlrev_b32_e32 v184, 16, v210
	v_and_b32_e32 v185, 0xffff0000, v210
	v_pk_fma_f32 v[182:183], v[100:101], v[182:183], v[184:185]
	v_lshlrev_b32_e32 v184, 16, v207
	v_and_b32_e32 v185, 0xffff0000, v207
	v_pk_fma_f32 v[184:185], v[102:103], v[184:185], v[186:187]
	v_lshlrev_b32_e32 v186, 16, v208
	v_and_b32_e32 v187, 0xffff0000, v208
	v_lshlrev_b32_e32 v188, 16, v212
	v_and_b32_e32 v189, 0xffff0000, v212
	v_pk_fma_f32 v[190:191], v[96:97], v[186:187], v[188:189]
	v_lshlrev_b32_e32 v186, 16, v209
	v_and_b32_e32 v187, 0xffff0000, v209
	v_lshlrev_b32_e32 v188, 16, v213
	v_and_b32_e32 v189, 0xffff0000, v213
	v_cvt_pk_bf16_f32 v182, v182, v183
	v_cvt_pk_bf16_f32 v183, v184, v185
	v_lshlrev_b64 v[184:185], 11, v[158:159]
	v_pk_fma_f32 v[192:193], v[98:99], v[186:187], v[188:189]
	v_lshl_add_u64 v[184:185], s[36:37], 0, v[184:185]
	v_lshl_add_u64 v[210:211], v[184:185], 0, v[170:171]
	v_cvt_pk_bf16_f32 v184, v190, v191
	v_cvt_pk_bf16_f32 v185, v192, v193
	global_load_dwordx4 v[186:189], v[210:211], off
	s_waitcnt vmcnt(0)
	v_lshlrev_b32_e32 v214, 16, v188
	global_store_dwordx4 v[174:175], v[182:185], off offset:256
	v_add_co_u32_e32 v174, vcc, s49, v172
	v_and_b32_e32 v215, 0xffff0000, v188
	s_nop 0
	v_addc_co_u32_e32 v175, vcc, 0, v173, vcc
	global_load_dwordx4 v[182:185], v[174:175], off
	global_load_dwordx4 v[190:193], v[174:175], off offset:256
	global_load_dwordx4 v[194:197], v[210:211], off offset:256
	v_add_co_u32_e32 v202, vcc, s50, v172
	v_lshlrev_b64 v[174:175], 11, v[156:157]
	s_nop 0
	v_addc_co_u32_e32 v203, vcc, 0, v173, vcc
	v_lshl_add_u64 v[198:199], s[36:37], 0, v[174:175]
	global_load_dwordx4 v[172:175], v[202:203], off
	v_lshl_add_u64 v[212:213], v[198:199], 0, v[170:171]
	global_load_dwordx4 v[198:201], v[212:213], off
	s_nop 0
	global_load_dwordx4 v[202:205], v[202:203], off offset:256
	s_nop 0
	global_load_dwordx4 v[206:209], v[212:213], off offset:256
	v_lshlrev_b32_e32 v170, 16, v186
	v_and_b32_e32 v171, 0xffff0000, v186
	v_lshlrev_b32_e32 v186, 16, v187
	v_and_b32_e32 v187, 0xffff0000, v187
	v_lshlrev_b32_e32 v188, 16, v189
	v_and_b32_e32 v189, 0xffff0000, v189
	s_waitcnt vmcnt(0)
; DI unsigned pk_bf16(float lo, float hi) { f32x2 v = {lo, hi}; return __builtin_bit_cast(unsigned, __builtin_convertvector(v, bf16v2)); }
; DI float bf_lo(unsigned w) { return __uint_as_float(w << 16); }
; DI float bf_hi(unsigned w) { return __uint_as_float(w & 0xffff0000u); }
;     DI void operator()(AccRef acc, const Unit& u, int wr, int wc, int fr, int fq) const {
;     ...
;                         const size_t row = (size_t)(row0 + ai * 128 + (mh * 2 + mm) * 16); const int col = col0 + bj * 128;
;                         gv[mm][bj] = *(const u32x4*)(gab + (size_t)(u.pm * 8 + SECOND * 4 + u.pn) * 65536 + (wr * 64 + fr + ai * 128 + (mh * 2 + mm) * 16) * 256 + wc * 32 + 8 * fq + bj * 128);
;                         if (SECOND) mv[mm][bj] = *(const u32x4*)(mrg + row * 1024 + col);
;                     }
; #pragma unroll
;                 for (int mm = 0; mm < 2; ++mm)
; #pragma unroll
;                     for (int bj = 0; bj < 2; ++bj) {
;                         const int m = mh * 2 + mm;
;                         const size_t row = (size_t)(row0 + ai * 128 + m * 16); const int col = col0 + bj * 128;
;                         const u32x4 gt = gv[mm][bj];
;                         const f32x4 r0 = acc[ai][bj][m][0], r1 = acc[ai][bj][m][1];
;                         float v[8] = {bf_lo(gt.x) * r0[0], bf_hi(gt.x) * r0[1], bf_lo(gt.y) * r0[2], bf_hi(gt.y) * r0[3], bf_lo(gt.z) * r1[0], bf_hi(gt.z) * r1[1], bf_lo(gt.w) * r1[2], bf_hi(gt.w) * r1[3]};
;                         if (SECOND) { const u32x4 o = mv[mm][bj]; v[0] += bf_lo(o.x); v[1] += bf_hi(o.x); v[2] += bf_lo(o.y); v[3] += bf_hi(o.y); v[4] += bf_lo(o.z); v[5] += bf_hi(o.z); v[6] += bf_lo(o.w); v[7] += bf_hi(o.w); }
;                         u32x4 w; w.x = pk_bf16(v[0], v[1]); w.y = pk_bf16(v[2], v[3]); w.z = pk_bf16(v[4], v[5]); w.w = pk_bf16(v[6], v[7]);
;                         *(u32x4*)(mrg + row * 1024 + col) = w;
;                     }
	v_lshlrev_b32_e32 v216, 16, v182
	v_and_b32_e32 v217, 0xffff0000, v182
	v_lshlrev_b32_e32 v182, 16, v183
	v_and_b32_e32 v183, 0xffff0000, v183
	v_lshlrev_b32_e32 v218, 16, v184
	v_and_b32_e32 v219, 0xffff0000, v184
	v_lshlrev_b32_e32 v184, 16, v185
	v_and_b32_e32 v185, 0xffff0000, v185
	v_pk_fma_f32 v[170:171], v[92:93], v[216:217], v[170:171]
	v_pk_fma_f32 v[186:187], v[94:95], v[182:183], v[186:187]
	v_pk_fma_f32 v[214:215], v[88:89], v[218:219], v[214:215]
	v_pk_fma_f32 v[188:189], v[90:91], v[184:185], v[188:189]
	v_cvt_pk_bf16_f32 v182, v170, v171
	v_cvt_pk_bf16_f32 v183, v186, v187
	v_cvt_pk_bf16_f32 v184, v214, v215
	v_cvt_pk_bf16_f32 v185, v188, v189
	global_store_dwordx4 v[210:211], v[182:185], off
	v_lshlrev_b32_e32 v186, 16, v196
	v_and_b32_e32 v187, 0xffff0000, v196
	v_lshlrev_b32_e32 v182, 16, v191
	v_and_b32_e32 v183, 0xffff0000, v191
	v_lshlrev_b32_e32 v184, 16, v195
	v_and_b32_e32 v185, 0xffff0000, v195
	v_pk_fma_f32 v[184:185], v[78:79], v[182:183], v[184:185]
	v_lshlrev_b32_e32 v182, 16, v192
	v_and_b32_e32 v183, 0xffff0000, v192
	v_lshlrev_b32_e32 v220, 16, v190
	v_and_b32_e32 v221, 0xffff0000, v190
	v_lshlrev_b32_e32 v170, 16, v194
	v_and_b32_e32 v171, 0xffff0000, v194
	v_pk_fma_f32 v[186:187], v[72:73], v[182:183], v[186:187]
	v_lshlrev_b32_e32 v182, 16, v193
	v_and_b32_e32 v183, 0xffff0000, v193
	v_lshlrev_b32_e32 v188, 16, v197
	v_and_b32_e32 v189, 0xffff0000, v197
	v_pk_fma_f32 v[170:171], v[76:77], v[220:221], v[170:171]
	v_pk_fma_f32 v[188:189], v[74:75], v[182:183], v[188:189]
	v_cvt_pk_bf16_f32 v182, v170, v171
	v_cvt_pk_bf16_f32 v183, v184, v185
	v_cvt_pk_bf16_f32 v184, v186, v187
	v_cvt_pk_bf16_f32 v185, v188, v189
	global_store_dwordx4 v[210:211], v[182:185], off offset:256
	v_lshlrev_b32_e32 v170, 16, v172
	v_and_b32_e32 v171, 0xffff0000, v172
	v_lshlrev_b32_e32 v182, 16, v198
	v_and_b32_e32 v183, 0xffff0000, v198
	v_pk_fma_f32 v[170:171], v[84:85], v[170:171], v[182:183]
	v_lshlrev_b32_e32 v172, 16, v173
	v_and_b32_e32 v173, 0xffff0000, v173
	v_lshlrev_b32_e32 v182, 16, v199
	v_and_b32_e32 v183, 0xffff0000, v199
	v_pk_fma_f32 v[172:173], v[86:87], v[172:173], v[182:183]
	v_lshlrev_b32_e32 v182, 16, v174
	v_and_b32_e32 v183, 0xffff0000, v174
	v_lshlrev_b32_e32 v184, 16, v200
	v_and_b32_e32 v185, 0xffff0000, v200
	v_pk_fma_f32 v[182:183], v[80:81], v[182:183], v[184:185]
	v_lshlrev_b32_e32 v174, 16, v175
	v_and_b32_e32 v175, 0xffff0000, v175
	v_lshlrev_b32_e32 v184, 16, v201
	v_and_b32_e32 v185, 0xffff0000, v201
	v_pk_fma_f32 v[174:175], v[82:83], v[174:175], v[184:185]
	v_cvt_pk_bf16_f32 v170, v170, v171
	v_cvt_pk_bf16_f32 v171, v172, v173
	v_cvt_pk_bf16_f32 v172, v182, v183
	v_cvt_pk_bf16_f32 v173, v174, v175
	global_store_dwordx4 v[212:213], v[170:173], off
	v_lshlrev_b32_e32 v174, 16, v207
	v_and_b32_e32 v175, 0xffff0000, v207
	v_lshlrev_b32_e32 v170, 16, v202
	v_and_b32_e32 v171, 0xffff0000, v202
	v_lshlrev_b32_e32 v172, 16, v206
	v_and_b32_e32 v173, 0xffff0000, v206
	v_pk_fma_f32 v[170:171], v[68:69], v[170:171], v[172:173]
	v_lshlrev_b32_e32 v172, 16, v203
	v_and_b32_e32 v173, 0xffff0000, v203
	v_pk_fma_f32 v[172:173], v[70:71], v[172:173], v[174:175]
	v_lshlrev_b32_e32 v174, 16, v204
	v_and_b32_e32 v175, 0xffff0000, v204
	v_lshlrev_b32_e32 v182, 16, v208
	v_and_b32_e32 v183, 0xffff0000, v208
	v_pk_fma_f32 v[174:175], v[64:65], v[174:175], v[182:183]
	v_lshlrev_b32_e32 v182, 16, v205
	v_and_b32_e32 v183, 0xffff0000, v205
	v_lshlrev_b32_e32 v184, 16, v209
	v_and_b32_e32 v185, 0xffff0000, v209
	v_pk_fma_f32 v[182:183], v[66:67], v[182:183], v[184:185]
	v_cvt_pk_bf16_f32 v170, v170, v171
	v_cvt_pk_bf16_f32 v171, v172, v173
	v_cvt_pk_bf16_f32 v172, v174, v175
	v_cvt_pk_bf16_f32 v173, v182, v183
	global_store_dwordx4 v[212:213], v[170:173], off offset:256
	v_lshl_add_u64 v[174:175], v[140:141], 1, v[168:169]
	v_add_co_u32_e32 v210, vcc, s61, v166
	global_load_dwordx4 v[170:173], v[174:175], off
	s_nop 0
	v_addc_co_u32_e32 v211, vcc, 0, v167, vcc
	global_load_dwordx4 v[182:185], v[210:211], off
	global_load_dwordx4 v[186:189], v[174:175], off offset:256
	v_lshl_add_u64 v[174:175], v[166:167], 0, s[0:1]
	global_load_dwordx4 v[190:193], v[174:175], off offset:256
	v_lshl_add_u64 v[202:203], v[142:143], 1, v[168:169]
	v_add_co_u32_e32 v212, vcc, s62, v166
	global_load_dwordx4 v[194:197], v[202:203], off
	s_nop 0
	v_addc_co_u32_e32 v213, vcc, 0, v167, vcc
	global_load_dwordx4 v[198:201], v[212:213], off
	s_nop 0
	global_load_dwordx4 v[202:205], v[202:203], off offset:256
	v_lshl_add_u64 v[214:215], v[166:167], 0, s[10:11]
	global_load_dwordx4 v[206:209], v[214:215], off offset:256
	s_waitcnt vmcnt(0)
; DI unsigned pk_bf16(float lo, float hi) { f32x2 v = {lo, hi}; return __builtin_bit_cast(unsigned, __builtin_convertvector(v, bf16v2)); }
; DI float bf_lo(unsigned w) { return __uint_as_float(w << 16); }
; DI float bf_hi(unsigned w) { return __uint_as_float(w & 0xffff0000u); }
;     DI void operator()(AccRef acc, const Unit& u, int wr, int wc, int fr, int fq) const {
;     ...
;                         const size_t row = (size_t)(row0 + ai * 128 + (mh * 2 + mm) * 16); const int col = col0 + bj * 128;
;                         gv[mm][bj] = *(const u32x4*)(gab + (size_t)(u.pm * 8 + SECOND * 4 + u.pn) * 65536 + (wr * 64 + fr + ai * 128 + (mh * 2 + mm) * 16) * 256 + wc * 32 + 8 * fq + bj * 128);
;                         if (SECOND) mv[mm][bj] = *(const u32x4*)(mrg + row * 1024 + col);
;                     }
; #pragma unroll
;                 for (int mm = 0; mm < 2; ++mm)
; #pragma unroll
;                     for (int bj = 0; bj < 2; ++bj) {
;                         const int m = mh * 2 + mm;
;                         const size_t row = (size_t)(row0 + ai * 128 + m * 16); const int col = col0 + bj * 128;
;                         const u32x4 gt = gv[mm][bj];
;                         const f32x4 r0 = acc[ai][bj][m][0], r1 = acc[ai][bj][m][1];
;                         float v[8] = {bf_lo(gt.x) * r0[0], bf_hi(gt.x) * r0[1], bf_lo(gt.y) * r0[2], bf_hi(gt.y) * r0[3], bf_lo(gt.z) * r1[0], bf_hi(gt.z) * r1[1], bf_lo(gt.w) * r1[2], bf_hi(gt.w) * r1[3]};
;                         if (SECOND) { const u32x4 o = mv[mm][bj]; v[0] += bf_lo(o.x); v[1] += bf_hi(o.x); v[2] += bf_lo(o.y); v[3] += bf_hi(o.y); v[4] += bf_lo(o.z); v[5] += bf_hi(o.z); v[6] += bf_lo(o.w); v[7] += bf_hi(o.w); }
;                         u32x4 w; w.x = pk_bf16(v[0], v[1]); w.y = pk_bf16(v[2], v[3]); w.z = pk_bf16(v[4], v[5]); w.w = pk_bf16(v[6], v[7]);
;                         *(u32x4*)(mrg + row * 1024 + col) = w;
	v_lshlrev_b32_e32 v216, 16, v170
	v_and_b32_e32 v217, 0xffff0000, v170
	v_lshlrev_b32_e32 v218, 16, v182
	v_and_b32_e32 v219, 0xffff0000, v182
	v_lshlrev_b32_e32 v170, 16, v171
	v_and_b32_e32 v171, 0xffff0000, v171
	v_lshlrev_b32_e32 v182, 16, v183
	v_and_b32_e32 v183, 0xffff0000, v183
	v_pk_fma_f32 v[216:217], v[60:61], v[216:217], v[218:219]
	v_pk_fma_f32 v[182:183], v[62:63], v[170:171], v[182:183]
	v_lshlrev_b32_e32 v170, 16, v172
	v_and_b32_e32 v171, 0xffff0000, v172
	v_lshlrev_b32_e32 v218, 16, v184
	v_and_b32_e32 v219, 0xffff0000, v184
	v_pk_fma_f32 v[218:219], v[56:57], v[170:171], v[218:219]
	v_lshlrev_b32_e32 v170, 16, v173
	v_and_b32_e32 v171, 0xffff0000, v173
	v_lshlrev_b32_e32 v172, 16, v185
	v_and_b32_e32 v173, 0xffff0000, v185
	v_pk_fma_f32 v[184:185], v[58:59], v[170:171], v[172:173]
	v_cvt_pk_bf16_f32 v170, v216, v217
	v_cvt_pk_bf16_f32 v171, v182, v183
	v_cvt_pk_bf16_f32 v172, v218, v219
	v_cvt_pk_bf16_f32 v173, v184, v185
	global_store_dwordx4 v[210:211], v[170:173], off
	v_lshlrev_b32_e32 v182, 16, v191
	v_and_b32_e32 v183, 0xffff0000, v191
	v_lshlrev_b32_e32 v170, 16, v186
	v_and_b32_e32 v171, 0xffff0000, v186
	v_lshlrev_b32_e32 v172, 16, v190
	v_and_b32_e32 v173, 0xffff0000, v190
	v_pk_fma_f32 v[170:171], v[44:45], v[170:171], v[172:173]
	v_lshlrev_b32_e32 v172, 16, v187
	v_and_b32_e32 v173, 0xffff0000, v187
	v_pk_fma_f32 v[172:173], v[46:47], v[172:173], v[182:183]
	v_lshlrev_b32_e32 v182, 16, v188
	v_and_b32_e32 v183, 0xffff0000, v188
	v_lshlrev_b32_e32 v184, 16, v192
	v_and_b32_e32 v185, 0xffff0000, v192
	v_pk_fma_f32 v[182:183], v[40:41], v[182:183], v[184:185]
	v_lshlrev_b32_e32 v184, 16, v189
	v_and_b32_e32 v185, 0xffff0000, v189
	v_lshlrev_b32_e32 v186, 16, v193
	v_and_b32_e32 v187, 0xffff0000, v193
	v_pk_fma_f32 v[184:185], v[42:43], v[184:185], v[186:187]
	v_cvt_pk_bf16_f32 v170, v170, v171
	v_cvt_pk_bf16_f32 v171, v172, v173
	v_cvt_pk_bf16_f32 v172, v182, v183
	v_cvt_pk_bf16_f32 v173, v184, v185
	global_store_dwordx4 v[174:175], v[170:173], off offset:256
	v_lshlrev_b32_e32 v174, 16, v199
	v_and_b32_e32 v175, 0xffff0000, v199
	v_lshlrev_b32_e32 v170, 16, v194
	v_and_b32_e32 v171, 0xffff0000, v194
	v_lshlrev_b32_e32 v172, 16, v198
	v_and_b32_e32 v173, 0xffff0000, v198
	v_pk_fma_f32 v[170:171], v[52:53], v[170:171], v[172:173]
	v_lshlrev_b32_e32 v172, 16, v195
	v_and_b32_e32 v173, 0xffff0000, v195
	v_pk_fma_f32 v[172:173], v[54:55], v[172:173], v[174:175]
	v_lshlrev_b32_e32 v174, 16, v196
	v_and_b32_e32 v175, 0xffff0000, v196
	v_lshlrev_b32_e32 v182, 16, v200
	v_and_b32_e32 v183, 0xffff0000, v200
	v_pk_fma_f32 v[174:175], v[48:49], v[174:175], v[182:183]
	v_lshlrev_b32_e32 v182, 16, v197
	v_and_b32_e32 v183, 0xffff0000, v197
	v_lshlrev_b32_e32 v184, 16, v201
	v_and_b32_e32 v185, 0xffff0000, v201
	v_pk_fma_f32 v[182:183], v[50:51], v[182:183], v[184:185]
	v_cvt_pk_bf16_f32 v170, v170, v171
	v_cvt_pk_bf16_f32 v171, v172, v173
	v_cvt_pk_bf16_f32 v172, v174, v175
	v_cvt_pk_bf16_f32 v173, v182, v183
	global_store_dwordx4 v[212:213], v[170:173], off
	v_lshlrev_b32_e32 v174, 16, v207
	v_and_b32_e32 v175, 0xffff0000, v207
	v_lshlrev_b32_e32 v170, 16, v202
	v_and_b32_e32 v171, 0xffff0000, v202
	v_lshlrev_b32_e32 v172, 16, v206
	v_and_b32_e32 v173, 0xffff0000, v206
	v_pk_fma_f32 v[170:171], v[36:37], v[170:171], v[172:173]
	v_lshlrev_b32_e32 v172, 16, v203
	v_and_b32_e32 v173, 0xffff0000, v203
	v_pk_fma_f32 v[172:173], v[38:39], v[172:173], v[174:175]
	v_lshlrev_b32_e32 v174, 16, v204
	v_and_b32_e32 v175, 0xffff0000, v204
	v_lshlrev_b32_e32 v182, 16, v208
	v_and_b32_e32 v183, 0xffff0000, v208
	v_pk_fma_f32 v[174:175], v[32:33], v[174:175], v[182:183]
	v_lshlrev_b32_e32 v182, 16, v205
	v_and_b32_e32 v183, 0xffff0000, v205
	v_lshlrev_b32_e32 v184, 16, v209
	v_and_b32_e32 v185, 0xffff0000, v209
	v_pk_fma_f32 v[182:183], v[34:35], v[182:183], v[184:185]
	v_cvt_pk_bf16_f32 v170, v170, v171
	v_cvt_pk_bf16_f32 v171, v172, v173
	v_cvt_pk_bf16_f32 v172, v174, v175
	v_cvt_pk_bf16_f32 v173, v182, v183
	global_store_dwordx4 v[214:215], v[170:173], off offset:256
	v_lshl_add_u64 v[174:175], v[144:145], 1, v[168:169]
	v_add_co_u32_e32 v206, vcc, s63, v166
	global_load_dwordx4 v[170:173], v[174:175], off
	s_nop 0
	v_addc_co_u32_e32 v207, vcc, 0, v167, vcc
	global_load_dwordx4 v[182:185], v[206:207], off
	global_load_dwordx4 v[186:189], v[174:175], off offset:256
	v_lshl_add_u64 v[174:175], v[166:167], 0, s[12:13]
	global_load_dwordx4 v[190:193], v[174:175], off offset:256
	v_lshl_add_u64 v[168:169], v[146:147], 1, v[168:169]
	v_add_co_u32_e32 v208, vcc, s64, v166
	global_load_dwordx4 v[194:197], v[168:169], off
	s_nop 0
	v_addc_co_u32_e32 v209, vcc, 0, v167, vcc
	global_load_dwordx4 v[198:201], v[208:209], off
	global_load_dwordx4 v[202:205], v[168:169], off offset:256
	v_lshl_add_u64 v[210:211], v[166:167], 0, s[14:15]
	global_load_dwordx4 v[166:169], v[210:211], off offset:256
	s_waitcnt vmcnt(0)
; DI unsigned pk_bf16(float lo, float hi) { f32x2 v = {lo, hi}; return __builtin_bit_cast(unsigned, __builtin_convertvector(v, bf16v2)); }
; DI float bf_lo(unsigned w) { return __uint_as_float(w << 16); }
; DI float bf_hi(unsigned w) { return __uint_as_float(w & 0xffff0000u); }
;     DI void operator()(AccRef acc, const Unit& u, int wr, int wc, int fr, int fq) const {
;     ...
;                         const size_t row = (size_t)(row0 + ai * 128 + (mh * 2 + mm) * 16); const int col = col0 + bj * 128;
;                         gv[mm][bj] = *(const u32x4*)(gab + (size_t)(u.pm * 8 + SECOND * 4 + u.pn) * 65536 + (wr * 64 + fr + ai * 128 + (mh * 2 + mm) * 16) * 256 + wc * 32 + 8 * fq + bj * 128);
;                         if (SECOND) mv[mm][bj] = *(const u32x4*)(mrg + row * 1024 + col);
;                     }
; #pragma unroll
;                 for (int mm = 0; mm < 2; ++mm)
; #pragma unroll
;                     for (int bj = 0; bj < 2; ++bj) {
;                         const int m = mh * 2 + mm;
;                         const size_t row = (size_t)(row0 + ai * 128 + m * 16); const int col = col0 + bj * 128;
;                         const u32x4 gt = gv[mm][bj];
;                         const f32x4 r0 = acc[ai][bj][m][0], r1 = acc[ai][bj][m][1];
;                         float v[8] = {bf_lo(gt.x) * r0[0], bf_hi(gt.x) * r0[1], bf_lo(gt.y) * r0[2], bf_hi(gt.y) * r0[3], bf_lo(gt.z) * r1[0], bf_hi(gt.z) * r1[1], bf_lo(gt.w) * r1[2], bf_hi(gt.w) * r1[3]};
;                         if (SECOND) { const u32x4 o = mv[mm][bj]; v[0] += bf_lo(o.x); v[1] += bf_hi(o.x); v[2] += bf_lo(o.y); v[3] += bf_hi(o.y); v[4] += bf_lo(o.z); v[5] += bf_hi(o.z); v[6] += bf_lo(o.w); v[7] += bf_hi(o.w); }
;                         u32x4 w; w.x = pk_bf16(v[0], v[1]); w.y = pk_bf16(v[2], v[3]); w.z = pk_bf16(v[4], v[5]); w.w = pk_bf16(v[6], v[7]);
;                         *(u32x4*)(mrg + row * 1024 + col) = w;
	v_lshlrev_b32_e32 v212, 16, v170
	v_and_b32_e32 v213, 0xffff0000, v170
	v_lshlrev_b32_e32 v214, 16, v182
	v_and_b32_e32 v215, 0xffff0000, v182
	v_lshlrev_b32_e32 v170, 16, v171
	v_and_b32_e32 v171, 0xffff0000, v171
	v_lshlrev_b32_e32 v182, 16, v183
	v_and_b32_e32 v183, 0xffff0000, v183
	v_pk_fma_f32 v[212:213], v[28:29], v[212:213], v[214:215]
	v_pk_fma_f32 v[182:183], v[30:31], v[170:171], v[182:183]
	v_lshlrev_b32_e32 v170, 16, v172
	v_and_b32_e32 v171, 0xffff0000, v172
	v_lshlrev_b32_e32 v214, 16, v184
	v_and_b32_e32 v215, 0xffff0000, v184
	v_pk_fma_f32 v[214:215], v[24:25], v[170:171], v[214:215]
	v_lshlrev_b32_e32 v170, 16, v173
	v_and_b32_e32 v171, 0xffff0000, v173
	v_lshlrev_b32_e32 v172, 16, v185
	v_and_b32_e32 v173, 0xffff0000, v185
	v_pk_fma_f32 v[184:185], v[26:27], v[170:171], v[172:173]
	v_cvt_pk_bf16_f32 v170, v212, v213
	v_cvt_pk_bf16_f32 v171, v182, v183
	v_cvt_pk_bf16_f32 v172, v214, v215
	v_cvt_pk_bf16_f32 v173, v184, v185
	global_store_dwordx4 v[206:207], v[170:173], off
	v_lshlrev_b32_e32 v182, 16, v191
	v_and_b32_e32 v183, 0xffff0000, v191
	v_lshlrev_b32_e32 v170, 16, v186
	v_and_b32_e32 v171, 0xffff0000, v186
	v_lshlrev_b32_e32 v172, 16, v190
	v_and_b32_e32 v173, 0xffff0000, v190
	v_pk_fma_f32 v[170:171], v[12:13], v[170:171], v[172:173]
	v_lshlrev_b32_e32 v172, 16, v187
	v_and_b32_e32 v173, 0xffff0000, v187
	v_pk_fma_f32 v[172:173], v[14:15], v[172:173], v[182:183]
	v_lshlrev_b32_e32 v182, 16, v188
	v_and_b32_e32 v183, 0xffff0000, v188
	v_lshlrev_b32_e32 v184, 16, v192
	v_and_b32_e32 v185, 0xffff0000, v192
	v_pk_fma_f32 v[182:183], v[8:9], v[182:183], v[184:185]
	v_lshlrev_b32_e32 v184, 16, v189
	v_and_b32_e32 v185, 0xffff0000, v189
	v_lshlrev_b32_e32 v186, 16, v193
	v_and_b32_e32 v187, 0xffff0000, v193
	v_pk_fma_f32 v[184:185], v[10:11], v[184:185], v[186:187]
	v_cvt_pk_bf16_f32 v170, v170, v171
	v_cvt_pk_bf16_f32 v171, v172, v173
	v_cvt_pk_bf16_f32 v172, v182, v183
	v_cvt_pk_bf16_f32 v173, v184, v185
	global_store_dwordx4 v[174:175], v[170:173], off offset:256
	v_lshlrev_b32_e32 v174, 16, v199
	v_and_b32_e32 v175, 0xffff0000, v199
	v_lshlrev_b32_e32 v170, 16, v194
	v_and_b32_e32 v171, 0xffff0000, v194
	v_lshlrev_b32_e32 v172, 16, v198
	v_and_b32_e32 v173, 0xffff0000, v198
	v_pk_fma_f32 v[170:171], v[20:21], v[170:171], v[172:173]
	v_lshlrev_b32_e32 v172, 16, v195
	v_and_b32_e32 v173, 0xffff0000, v195
	v_pk_fma_f32 v[172:173], v[22:23], v[172:173], v[174:175]
	v_lshlrev_b32_e32 v174, 16, v196
	v_and_b32_e32 v175, 0xffff0000, v196
	v_lshlrev_b32_e32 v182, 16, v200
	v_and_b32_e32 v183, 0xffff0000, v200
	v_pk_fma_f32 v[174:175], v[16:17], v[174:175], v[182:183]
	v_lshlrev_b32_e32 v182, 16, v197
	v_and_b32_e32 v183, 0xffff0000, v197
	v_lshlrev_b32_e32 v184, 16, v201
	v_and_b32_e32 v185, 0xffff0000, v201
	v_pk_fma_f32 v[182:183], v[18:19], v[182:183], v[184:185]
	v_cvt_pk_bf16_f32 v170, v170, v171
	v_cvt_pk_bf16_f32 v171, v172, v173
	v_cvt_pk_bf16_f32 v172, v174, v175
	v_cvt_pk_bf16_f32 v173, v182, v183
	global_store_dwordx4 v[208:209], v[170:173], off
	v_lshlrev_b32_e32 v174, 16, v168
	v_and_b32_e32 v175, 0xffff0000, v168
	v_lshlrev_b32_e32 v170, 16, v202
	v_and_b32_e32 v171, 0xffff0000, v202
	v_lshlrev_b32_e32 v172, 16, v166
	v_and_b32_e32 v173, 0xffff0000, v166
	v_pk_fma_f32 v[170:171], v[4:5], v[170:171], v[172:173]
	v_lshlrev_b32_e32 v172, 16, v203
	v_and_b32_e32 v173, 0xffff0000, v203
	v_lshlrev_b32_e32 v166, 16, v167
	v_and_b32_e32 v167, 0xffff0000, v167
	v_pk_fma_f32 v[172:173], v[6:7], v[172:173], v[166:167]
	v_lshlrev_b32_e32 v166, 16, v204
	v_and_b32_e32 v167, 0xffff0000, v204
	v_pk_fma_f32 v[174:175], v[0:1], v[166:167], v[174:175]
	v_lshlrev_b32_e32 v166, 16, v205
	v_and_b32_e32 v167, 0xffff0000, v205
	v_lshlrev_b32_e32 v168, 16, v169
	v_and_b32_e32 v169, 0xffff0000, v169
	v_pk_fma_f32 v[182:183], v[2:3], v[166:167], v[168:169]
	v_cvt_pk_bf16_f32 v166, v170, v171
	v_cvt_pk_bf16_f32 v167, v172, v173
	v_cvt_pk_bf16_f32 v168, v174, v175
	v_cvt_pk_bf16_f32 v169, v182, v183
	global_store_dwordx4 v[210:211], v[166:169], off offset:256

; #define PG8_STAGE(bufoff, gbase, voff) do { _Pragma("unroll") for (int _i = 0; _i < 2; ++_i) \
;         __builtin_amdgcn_global_load_lds((const unsigned*)((const char*)(gbase) + (voff)[_i]), (LAS unsigned*)(lds + (bufoff) + ldsw + _i * 8192), 16, 0, 0); } while (0)
; #define PG8_LDA(dst, b, h) do { _Pragma("unroll") for (int m = 0; m < 4; ++m) _Pragma("unroll") for (int k = 0; k < 2; ++k) dst[m][k] = *(const LAS bf16x8*)(lds + PG8_SA(b, h) + aoff + m * 2048 + k * 1024); } while (0)
; #define PG8_LDB(dst, b, h) do { _Pragma("unroll") for (int n = 0; n < 2; ++n) _Pragma("unroll") for (int k = 0; k < 2; ++k) dst[n][k] = *(const LAS bf16x8*)(lds + PG8_SB(b, h) + boff + n * 2048 + k * 1024); } while (0)
; #define PG8_MMA(ai, bj, At, Bt) do { __builtin_amdgcn_s_setprio(1); _Pragma("unroll") for (int m = 0; m < 4; ++m) _Pragma("unroll") for (int n = 0; n < 2; ++n) _Pragma("unroll") for (int k = 0; k < 2; ++k) \
;         acc[ai][bj][m][n] = __builtin_amdgcn_mfma_f32_16x16x32_bf16(Bt[n][k], At[m][k], acc[ai][bj][m][n], 0, 0, 0); __builtin_amdgcn_s_setprio(0); } while (0)
; #define PG8_WAIT_V(n) asm volatile("s_waitcnt vmcnt(" #n ")" ::: "memory")
; #define PG8_WAIT_L(n) asm volatile("s_waitcnt lgkmcnt(" #n ")" ::: "memory")
; #define PG8_BAR __builtin_amdgcn_s_barrier()
; #define PG8_SCHED __builtin_amdgcn_sched_barrier(0)
; template <class Epi>
; DI void gemm_phase(LAS unsigned char* lds, const Gemm g, const StaticOrder S, const Epi E) {
;     ...
;             const bool last = (t == nt - 2);
;             const char* a1 = cA + (size_t)(t + 1) * kstep;
;             const char* a2 = last ? nA : cA + (size_t)(t + 2) * kstep; const char* b2 = last ? nB : cB + (size_t)(t + 2) * kstep;
;             const char* a3 = a2 + kstep; const char* b3 = b2 + kstep;
;             PG8_LDB(B0, 0, 0); PG8_SCHED; PG8_LDA(At, 0, 0); PG8_STAGE(PG8_SA(1, 1), a1 + hstep, voffA);
;             PG8_WAIT_L(8); PG8_BAR; PG8_WAIT_L(0); PG8_MMA(0, 0, At, B0); PG8_BAR; PG8_SCHED;
;             PG8_LDB(B1, 0, 1); PG8_STAGE(PG8_SB(0, 0), b2, voffB);
;             PG8_BAR; PG8_WAIT_L(0); PG8_MMA(0, 1, At, B1); PG8_BAR;
;             PG8_LDA(At, 0, 1); PG8_STAGE(PG8_SA(0, 0), a2, voffA);
;             PG8_BAR; PG8_WAIT_L(0); PG8_MMA(1, 0, At, B0); PG8_BAR; PG8_SCHED;
;             PG8_STAGE(PG8_SB(0, 1), b2 + hstep, voffB);
;             PG8_WAIT_V(6); PG8_BAR; PG8_MMA(1, 1, At, B1); PG8_BAR;
.LBB0_786:
	ds_read_b128 v[128:131], v187
	ds_read_b128 v[132:135], v187 offset:1024
	ds_read_b128 v[136:139], v187 offset:2048
	ds_read_b128 v[140:143], v187 offset:3072
	s_add_u32 s28, s24, 0xfffc0080
	s_addc_u32 s29, s25, -1
	s_cmp_eq_u32 s52, 12
	s_cselect_b32 s39, s6, s29
	s_cselect_b32 s38, s7, s28
	s_cselect_b32 s29, s11, s51
	s_cselect_b32 s28, s13, s50
	v_lshl_add_u64 v[200:201], s[24:25], 0, v[160:161]
	s_add_i32 m0, s19, 0xc000
	ds_read_b128 v[144:147], v188
	ds_read_b128 v[168:171], v188 offset:2048
	ds_read_b128 v[176:179], v188 offset:4096
	ds_read_b128 v[192:195], v188 offset:6144
	global_load_lds_dwordx4 v[200:201], off
	v_lshl_add_u64 v[200:201], s[24:25], 0, v[162:163]
	s_add_i32 m0, s19, 0xe000
	s_nop 0
	global_load_lds_dwordx4 v[200:201], off
	s_waitcnt lgkmcnt(4)
	s_setprio 1
	s_barrier
	ds_read_b128 v[148:151], v188 offset:1024
	ds_read_b128 v[172:175], v188 offset:3072
	ds_read_b128 v[180:183], v188 offset:5120
	ds_read_b128 v[196:199], v188 offset:7168
	s_waitcnt lgkmcnt(4)
	v_mfma_f32_16x16x32_bf16 v[124:127], v[128:131], v[144:147], v[124:127]
	v_mfma_f32_16x16x32_bf16 v[120:123], v[136:139], v[144:147], v[120:123]
	v_mfma_f32_16x16x32_bf16 v[108:111], v[128:131], v[168:171], v[108:111]
	v_mfma_f32_16x16x32_bf16 v[104:107], v[136:139], v[168:171], v[104:107]
	v_mfma_f32_16x16x32_bf16 v[92:95], v[128:131], v[176:179], v[92:95]
	v_mfma_f32_16x16x32_bf16 v[88:91], v[136:139], v[176:179], v[88:91]
	v_mfma_f32_16x16x32_bf16 v[76:79], v[128:131], v[192:195], v[76:79]
	v_mfma_f32_16x16x32_bf16 v[72:75], v[136:139], v[192:195], v[72:75]
	s_waitcnt lgkmcnt(3)
	v_mfma_f32_16x16x32_bf16 v[124:127], v[132:135], v[148:151], v[124:127]
	v_mfma_f32_16x16x32_bf16 v[120:123], v[140:143], v[148:151], v[120:123]
	s_waitcnt lgkmcnt(2)
	v_mfma_f32_16x16x32_bf16 v[108:111], v[132:135], v[172:175], v[108:111]
	v_mfma_f32_16x16x32_bf16 v[104:107], v[140:143], v[172:175], v[104:107]
	s_waitcnt lgkmcnt(1)
	v_mfma_f32_16x16x32_bf16 v[92:95], v[132:135], v[180:183], v[92:95]
	v_mfma_f32_16x16x32_bf16 v[88:91], v[140:143], v[180:183], v[88:91]
	s_waitcnt lgkmcnt(0)
	s_setprio 2
	s_barrier
	v_mfma_f32_16x16x32_bf16 v[76:79], v[132:135], v[196:199], v[76:79]
	v_mfma_f32_16x16x32_bf16 v[72:75], v[140:143], v[196:199], v[72:75]
	s_setprio 0
	s_add_i32 s53, s48, s40
	v_lshl_add_u64 v[216:217], s[28:29], 0, v[154:155]
	s_mov_b32 m0, s53
	ds_read_b128 v[200:203], v189
	ds_read_b128 v[204:207], v189 offset:1024
	ds_read_b128 v[208:211], v189 offset:2048
	ds_read_b128 v[212:215], v189 offset:3072
	global_load_lds_dwordx4 v[216:217], off
	v_lshl_add_u64 v[218:219], s[28:29], 0, v[158:159]
	s_add_i32 m0, s53, 0x2000
	s_nop 0
	global_load_lds_dwordx4 v[218:219], off
	s_setprio 1
	s_barrier
	s_waitcnt lgkmcnt(0)
	v_mfma_f32_16x16x32_bf16 v[116:119], v[200:203], v[144:147], v[116:119]
	v_mfma_f32_16x16x32_bf16 v[112:115], v[208:211], v[144:147], v[112:115]
	v_mfma_f32_16x16x32_bf16 v[100:103], v[200:203], v[168:171], v[100:103]
	v_mfma_f32_16x16x32_bf16 v[96:99], v[208:211], v[168:171], v[96:99]
	v_mfma_f32_16x16x32_bf16 v[84:87], v[200:203], v[176:179], v[84:87]
	v_mfma_f32_16x16x32_bf16 v[80:83], v[208:211], v[176:179], v[80:83]
	v_mfma_f32_16x16x32_bf16 v[68:71], v[200:203], v[192:195], v[68:71]
	v_mfma_f32_16x16x32_bf16 v[64:67], v[208:211], v[192:195], v[64:67]
	v_mfma_f32_16x16x32_bf16 v[116:119], v[204:207], v[148:151], v[116:119]
	v_mfma_f32_16x16x32_bf16 v[112:115], v[212:215], v[148:151], v[112:115]
	v_mfma_f32_16x16x32_bf16 v[100:103], v[204:207], v[172:175], v[100:103]
	v_mfma_f32_16x16x32_bf16 v[96:99], v[212:215], v[172:175], v[96:99]
	v_mfma_f32_16x16x32_bf16 v[84:87], v[204:207], v[180:183], v[84:87]
	s_setprio 2
	s_barrier
	v_mfma_f32_16x16x32_bf16 v[80:83], v[212:215], v[180:183], v[80:83]
	v_mfma_f32_16x16x32_bf16 v[68:71], v[204:207], v[196:199], v[68:71]
	v_mfma_f32_16x16x32_bf16 v[64:67], v[212:215], v[196:199], v[64:67]
	s_setprio 0
	s_mov_b32 m0, s19
	v_lshl_add_u64 v[220:221], s[38:39], 0, v[152:153]
	ds_read_b128 v[144:147], v188 offset:16384
	ds_read_b128 v[168:171], v188 offset:18432
	ds_read_b128 v[176:179], v188 offset:20480
	ds_read_b128 v[192:195], v188 offset:22528
	global_load_lds_dwordx4 v[220:221], off
	v_lshl_add_u64 v[224:225], s[38:39], 0, v[156:157]
	s_mov_b32 m0, s23
	s_nop 0
	global_load_lds_dwordx4 v[224:225], off
	s_setprio 1
	s_barrier
	ds_read_b128 v[148:151], v188 offset:17408
	ds_read_b128 v[172:175], v188 offset:19456
	ds_read_b128 v[180:183], v188 offset:21504
	ds_read_b128 v[196:199], v188 offset:23552
	s_waitcnt lgkmcnt(4)
	v_mfma_f32_16x16x32_bf16 v[60:63], v[128:131], v[144:147], v[60:63]
	v_mfma_f32_16x16x32_bf16 v[56:59], v[136:139], v[144:147], v[56:59]
	v_mfma_f32_16x16x32_bf16 v[44:47], v[128:131], v[168:171], v[44:47]
	v_mfma_f32_16x16x32_bf16 v[40:43], v[136:139], v[168:171], v[40:43]
	v_mfma_f32_16x16x32_bf16 v[28:31], v[128:131], v[176:179], v[28:31]
	v_mfma_f32_16x16x32_bf16 v[24:27], v[136:139], v[176:179], v[24:27]
	v_mfma_f32_16x16x32_bf16 v[12:15], v[128:131], v[192:195], v[12:15]
	v_mfma_f32_16x16x32_bf16 v[8:11], v[136:139], v[192:195], v[8:11]
	s_waitcnt lgkmcnt(3)
	v_mfma_f32_16x16x32_bf16 v[60:63], v[132:135], v[148:151], v[60:63]
	v_mfma_f32_16x16x32_bf16 v[56:59], v[140:143], v[148:151], v[56:59]
	s_waitcnt lgkmcnt(2)
	v_mfma_f32_16x16x32_bf16 v[44:47], v[132:135], v[172:175], v[44:47]
	v_mfma_f32_16x16x32_bf16 v[40:43], v[140:143], v[172:175], v[40:43]
	s_waitcnt lgkmcnt(1)
	v_mfma_f32_16x16x32_bf16 v[28:31], v[132:135], v[180:183], v[28:31]
	v_mfma_f32_16x16x32_bf16 v[24:27], v[140:143], v[180:183], v[24:27]
	s_waitcnt lgkmcnt(0)
	s_setprio 2
	s_barrier
; #define PG8_STAGE(bufoff, gbase, voff) do { _Pragma("unroll") for (int _i = 0; _i < 2; ++_i) \
;         __builtin_amdgcn_global_load_lds((const unsigned*)((const char*)(gbase) + (voff)[_i]), (LAS unsigned*)(lds + (bufoff) + ldsw + _i * 8192), 16, 0, 0); } while (0)
; #define PG8_LDA(dst, b, h) do { _Pragma("unroll") for (int m = 0; m < 4; ++m) _Pragma("unroll") for (int k = 0; k < 2; ++k) dst[m][k] = *(const LAS bf16x8*)(lds + PG8_SA(b, h) + aoff + m * 2048 + k * 1024); } while (0)
; #define PG8_LDB(dst, b, h) do { _Pragma("unroll") for (int n = 0; n < 2; ++n) _Pragma("unroll") for (int k = 0; k < 2; ++k) dst[n][k] = *(const LAS bf16x8*)(lds + PG8_SB(b, h) + boff + n * 2048 + k * 1024); } while (0)
; #define PG8_MMA(ai, bj, At, Bt) do { __builtin_amdgcn_s_setprio(1); _Pragma("unroll") for (int m = 0; m < 4; ++m) _Pragma("unroll") for (int n = 0; n < 2; ++n) _Pragma("unroll") for (int k = 0; k < 2; ++k) \
;         acc[ai][bj][m][n] = __builtin_amdgcn_mfma_f32_16x16x32_bf16(Bt[n][k], At[m][k], acc[ai][bj][m][n], 0, 0, 0); __builtin_amdgcn_s_setprio(0); } while (0)
; #define PG8_WAIT_V(n) asm volatile("s_waitcnt vmcnt(" #n ")" ::: "memory")
; #define PG8_WAIT_L(n) asm volatile("s_waitcnt lgkmcnt(" #n ")" ::: "memory")
; #define PG8_BAR __builtin_amdgcn_s_barrier()
; #define PG8_SCHED __builtin_amdgcn_sched_barrier(0)
; #define PG8_LDA(dst, b, h) do { _Pragma("unroll") for (int m = 0; m < 4; ++m) _Pragma("unroll") for (int k = 0; k < 2; ++k) dst[m][k] = *(const LAS bf16x8*)(lds + PG8_SA(b, h) + aoff + m * 2048 + k * 1024); } while (0)
; template <class Epi>
; DI void gemm_phase(LAS unsigned char* lds, const Gemm g, const StaticOrder S, const Epi E) {
;     ...
;             PG8_BAR; PG8_WAIT_L(0); PG8_MMA(1, 0, At, B0); PG8_BAR; PG8_SCHED;
;             PG8_STAGE(PG8_SB(0, 1), b2 + hstep, voffB);
;             PG8_WAIT_V(6); PG8_BAR; PG8_MMA(1, 1, At, B1); PG8_BAR;
;             PG8_LDB(B0, 1, 0); PG8_SCHED; PG8_LDA(At, 1, 0); PG8_STAGE(PG8_SA(0, 1), a2 + hstep, voffA);
;             PG8_WAIT_L(8); PG8_BAR; PG8_WAIT_L(0); PG8_MMA(0, 0, At, B0); PG8_BAR; PG8_SCHED;
;             PG8_LDB(B1, 1, 1); PG8_STAGE(PG8_SB(1, 0), b3, voffB);
;             PG8_BAR; PG8_WAIT_L(0); PG8_MMA(0, 1, At, B1); PG8_BAR;
;             PG8_LDA(At, 1, 1); PG8_STAGE(PG8_SA(1, 0), a3, voffA);
;             PG8_BAR; PG8_WAIT_L(0); PG8_MMA(1, 0, At, B0); PG8_BAR; PG8_SCHED;
	v_mfma_f32_16x16x32_bf16 v[12:15], v[132:135], v[196:199], v[12:15]
	v_mfma_f32_16x16x32_bf16 v[8:11], v[140:143], v[196:199], v[8:11]
	s_setprio 0
	s_add_u32 s58, s28, 0x40000
	s_addc_u32 s59, s29, 0
	s_add_i32 s53, s49, s40
	v_lshl_add_u64 v[128:129], s[58:59], 0, v[154:155]
	s_mov_b32 m0, s53
	s_nop 0
	global_load_lds_dwordx4 v[128:129], off
	v_lshl_add_u64 v[128:129], s[58:59], 0, v[158:159]
	s_add_i32 m0, s53, 0x2000
	s_nop 0
	global_load_lds_dwordx4 v[128:129], off
	s_waitcnt vmcnt(6)
	s_setprio 1
	s_barrier
	v_mfma_f32_16x16x32_bf16 v[52:55], v[200:203], v[144:147], v[52:55]
	v_mfma_f32_16x16x32_bf16 v[48:51], v[208:211], v[144:147], v[48:51]
	v_mfma_f32_16x16x32_bf16 v[36:39], v[200:203], v[168:171], v[36:39]
	v_mfma_f32_16x16x32_bf16 v[32:35], v[208:211], v[168:171], v[32:35]
	v_mfma_f32_16x16x32_bf16 v[20:23], v[200:203], v[176:179], v[20:23]
	v_mfma_f32_16x16x32_bf16 v[16:19], v[208:211], v[176:179], v[16:19]
	v_mfma_f32_16x16x32_bf16 v[4:7], v[200:203], v[192:195], v[4:7]
	v_mfma_f32_16x16x32_bf16 v[0:3], v[208:211], v[192:195], v[0:3]
	v_mfma_f32_16x16x32_bf16 v[52:55], v[204:207], v[148:151], v[52:55]
	v_mfma_f32_16x16x32_bf16 v[48:51], v[212:215], v[148:151], v[48:51]
	v_mfma_f32_16x16x32_bf16 v[36:39], v[204:207], v[172:175], v[36:39]
	v_mfma_f32_16x16x32_bf16 v[32:35], v[212:215], v[172:175], v[32:35]
	v_mfma_f32_16x16x32_bf16 v[20:23], v[204:207], v[180:183], v[20:23]
	s_setprio 2
	s_barrier
	v_mfma_f32_16x16x32_bf16 v[16:19], v[212:215], v[180:183], v[16:19]
	v_mfma_f32_16x16x32_bf16 v[4:7], v[204:207], v[196:199], v[4:7]
	v_mfma_f32_16x16x32_bf16 v[0:3], v[212:215], v[196:199], v[0:3]
	s_setprio 0
	s_add_i32 s53, 0, 0x18000
	v_add_u32_e32 v140, s53, v185
	ds_read_b128 v[128:131], v140
	ds_read_b128 v[132:135], v140 offset:1024
	ds_read_b128 v[136:139], v140 offset:2048
	ds_read_b128 v[140:143], v140 offset:3072
	s_add_u32 s38, s38, 0x40000
	s_addc_u32 s39, s39, 0
	s_mov_b32 m0, s41
	v_lshl_add_u64 v[200:201], s[38:39], 0, v[152:153]
	ds_read_b128 v[144:147], v188 offset:32768
	ds_read_b128 v[168:171], v188 offset:34816
	ds_read_b128 v[176:179], v188 offset:36864
	ds_read_b128 v[192:195], v188 offset:38912
	global_load_lds_dwordx4 v[200:201], off
	v_lshl_add_u64 v[200:201], s[38:39], 0, v[156:157]
	s_mov_b32 m0, s42
	s_nop 0
	global_load_lds_dwordx4 v[200:201], off
	s_waitcnt lgkmcnt(4)
	s_setprio 1
	s_barrier
	ds_read_b128 v[148:151], v188 offset:33792
	ds_read_b128 v[172:175], v188 offset:35840
	ds_read_b128 v[180:183], v188 offset:37888
	ds_read_b128 v[196:199], v188 offset:39936
	s_waitcnt lgkmcnt(4)
	v_mfma_f32_16x16x32_bf16 v[124:127], v[128:131], v[144:147], v[124:127]
	v_mfma_f32_16x16x32_bf16 v[120:123], v[136:139], v[144:147], v[120:123]
	v_mfma_f32_16x16x32_bf16 v[108:111], v[128:131], v[168:171], v[108:111]
	v_mfma_f32_16x16x32_bf16 v[104:107], v[136:139], v[168:171], v[104:107]
	v_mfma_f32_16x16x32_bf16 v[92:95], v[128:131], v[176:179], v[92:95]
	v_mfma_f32_16x16x32_bf16 v[88:91], v[136:139], v[176:179], v[88:91]
	v_mfma_f32_16x16x32_bf16 v[76:79], v[128:131], v[192:195], v[76:79]
	v_mfma_f32_16x16x32_bf16 v[72:75], v[136:139], v[192:195], v[72:75]
	s_waitcnt lgkmcnt(3)
	v_mfma_f32_16x16x32_bf16 v[124:127], v[132:135], v[148:151], v[124:127]
	v_mfma_f32_16x16x32_bf16 v[120:123], v[140:143], v[148:151], v[120:123]
	s_waitcnt lgkmcnt(2)
	v_mfma_f32_16x16x32_bf16 v[108:111], v[132:135], v[172:175], v[108:111]
	v_mfma_f32_16x16x32_bf16 v[104:107], v[140:143], v[172:175], v[104:107]
	s_waitcnt lgkmcnt(1)
	v_mfma_f32_16x16x32_bf16 v[92:95], v[132:135], v[180:183], v[92:95]
	v_mfma_f32_16x16x32_bf16 v[88:91], v[140:143], v[180:183], v[88:91]
	s_waitcnt lgkmcnt(0)
	s_setprio 2
	s_barrier
	v_mfma_f32_16x16x32_bf16 v[76:79], v[132:135], v[196:199], v[76:79]
	v_mfma_f32_16x16x32_bf16 v[72:75], v[140:143], v[196:199], v[72:75]
	s_setprio 0
	s_add_i32 s38, 0, 0x1c000
	s_add_i32 s39, s53, s40
	v_add_u32_e32 v191, s38, v185
	v_lshl_add_u64 v[216:217], v[216:217], 0, s[8:9]
	s_mov_b32 m0, s39
	ds_read_b128 v[200:203], v191
	ds_read_b128 v[204:207], v191 offset:1024
	ds_read_b128 v[208:211], v191 offset:2048
	ds_read_b128 v[212:215], v191 offset:3072
	global_load_lds_dwordx4 v[216:217], off
	v_lshl_add_u64 v[216:217], v[218:219], 0, s[8:9]
	s_add_i32 m0, s39, 0x2000
	s_nop 0
	global_load_lds_dwordx4 v[216:217], off
	s_setprio 1
	s_barrier
	s_waitcnt lgkmcnt(0)
	v_mfma_f32_16x16x32_bf16 v[116:119], v[200:203], v[144:147], v[116:119]
	v_mfma_f32_16x16x32_bf16 v[112:115], v[208:211], v[144:147], v[112:115]
	v_mfma_f32_16x16x32_bf16 v[100:103], v[200:203], v[168:171], v[100:103]
	v_mfma_f32_16x16x32_bf16 v[96:99], v[208:211], v[168:171], v[96:99]
	v_mfma_f32_16x16x32_bf16 v[84:87], v[200:203], v[176:179], v[84:87]
	v_mfma_f32_16x16x32_bf16 v[80:83], v[208:211], v[176:179], v[80:83]
	v_mfma_f32_16x16x32_bf16 v[68:71], v[200:203], v[192:195], v[68:71]
	v_mfma_f32_16x16x32_bf16 v[64:67], v[208:211], v[192:195], v[64:67]
	v_mfma_f32_16x16x32_bf16 v[116:119], v[204:207], v[148:151], v[116:119]
	v_mfma_f32_16x16x32_bf16 v[112:115], v[212:215], v[148:151], v[112:115]
	v_mfma_f32_16x16x32_bf16 v[100:103], v[204:207], v[172:175], v[100:103]
	v_mfma_f32_16x16x32_bf16 v[96:99], v[212:215], v[172:175], v[96:99]
	v_mfma_f32_16x16x32_bf16 v[84:87], v[204:207], v[180:183], v[84:87]
	s_setprio 2
	s_barrier
	v_mfma_f32_16x16x32_bf16 v[80:83], v[212:215], v[180:183], v[80:83]
	v_mfma_f32_16x16x32_bf16 v[68:71], v[204:207], v[196:199], v[68:71]
	v_mfma_f32_16x16x32_bf16 v[64:67], v[212:215], v[196:199], v[64:67]
	s_setprio 0
	s_mov_b32 m0, s44
	v_lshl_add_u64 v[216:217], v[220:221], 0, s[8:9]
	ds_read_b128 v[144:147], v188 offset:49152
	ds_read_b128 v[168:171], v188 offset:51200
	ds_read_b128 v[176:179], v188 offset:53248
	ds_read_b128 v[192:195], v188 offset:55296
	global_load_lds_dwordx4 v[216:217], off
	v_lshl_add_u64 v[216:217], v[224:225], 0, s[8:9]
	s_mov_b32 m0, s45
	s_nop 0
	global_load_lds_dwordx4 v[216:217], off
	s_setprio 1
	s_barrier
; DI unsigned pk_bf16(float lo, float hi) { f32x2 v = {lo, hi}; return __builtin_bit_cast(unsigned, __builtin_convertvector(v, bf16v2)); }
; #define PG8_STAGE(bufoff, gbase, voff) do { _Pragma("unroll") for (int _i = 0; _i < 2; ++_i) \
;         __builtin_amdgcn_global_load_lds((const unsigned*)((const char*)(gbase) + (voff)[_i]), (LAS unsigned*)(lds + (bufoff) + ldsw + _i * 8192), 16, 0, 0); } while (0)
; #define PG8_LDA(dst, b, h) do { _Pragma("unroll") for (int m = 0; m < 4; ++m) _Pragma("unroll") for (int k = 0; k < 2; ++k) dst[m][k] = *(const LAS bf16x8*)(lds + PG8_SA(b, h) + aoff + m * 2048 + k * 1024); } while (0)
; #define PG8_MMA(ai, bj, At, Bt) do { __builtin_amdgcn_s_setprio(1); _Pragma("unroll") for (int m = 0; m < 4; ++m) _Pragma("unroll") for (int n = 0; n < 2; ++n) _Pragma("unroll") for (int k = 0; k < 2; ++k) \
;         acc[ai][bj][m][n] = __builtin_amdgcn_mfma_f32_16x16x32_bf16(Bt[n][k], At[m][k], acc[ai][bj][m][n], 0, 0, 0); __builtin_amdgcn_s_setprio(0); } while (0)
; template <class Epi>
; DI void gemm_phase(LAS unsigned char* lds, const Gemm g, const StaticOrder S, const Epi E) {
;     ...
;             PG8_LDA(At, 1, 1); PG8_STAGE(PG8_SA(1, 0), a3, voffA);
;             PG8_BAR; PG8_WAIT_L(0); PG8_MMA(1, 0, At, B0); PG8_BAR; PG8_SCHED;
;             PG8_STAGE(PG8_SB(1, 1), b3 + hstep, voffB);
;             PG8_WAIT_V(6); PG8_BAR; PG8_MMA(1, 1, At, B1); PG8_BAR;
;     DI void operator()(AccRef acc, const Unit& u, int wr, int wc, int fr, int fq) const {
;     ...
;             for (int m = 0; m < 4; ++m) {
;                 const int row = row0 + ai * 128 + m * 16;
;                 float q = 0.f;
; #pragma unroll
;                 for (int bj = 0; bj < 2; ++bj) {
;                     const size_t o = (size_t)row * DM + col0 + bj * 128;
;                     const f32x4 r0 = bv[m][bj][0] + scale * acc[ai][bj][m][0], r1 = bv[m][bj][1] + scale * acc[ai][bj][m][1];
;                     u32x4 w; w.x = pk_bf16(r0[0], r0[1]); w.y = pk_bf16(r0[2], r0[3]); w.z = pk_bf16(r1[0], r1[1]); w.w = pk_bf16(r1[2], r1[3]);
;                     *(u32x4*)(xnb + o) = w;
;                     if (STATS) q += r0[0] * r0[0] + r0[1] * r0[1] + r0[2] * r0[2] + r0[3] * r0[3] + r1[0] * r1[0] + r1[1] * r1[1] + r1[2] * r1[2] + r1[3] * r1[3];
;                 }
;                 if (STATS) { q += __shfl_xor(q, 16); q += __shfl_xor(q, 32); if (fq == 0) atomicAdd(ss + row, q); }
	ds_read_b128 v[148:151], v188 offset:50176
	ds_read_b128 v[172:175], v188 offset:52224
	ds_read_b128 v[180:183], v188 offset:54272
	ds_read_b128 v[196:199], v188 offset:56320
	s_waitcnt lgkmcnt(4)
	v_mfma_f32_16x16x32_bf16 v[60:63], v[128:131], v[144:147], v[60:63]
	v_mfma_f32_16x16x32_bf16 v[56:59], v[136:139], v[144:147], v[56:59]
	v_mfma_f32_16x16x32_bf16 v[44:47], v[128:131], v[168:171], v[44:47]
	v_mfma_f32_16x16x32_bf16 v[40:43], v[136:139], v[168:171], v[40:43]
	v_mfma_f32_16x16x32_bf16 v[28:31], v[128:131], v[176:179], v[28:31]
	v_mfma_f32_16x16x32_bf16 v[24:27], v[136:139], v[176:179], v[24:27]
	v_mfma_f32_16x16x32_bf16 v[12:15], v[128:131], v[192:195], v[12:15]
	v_mfma_f32_16x16x32_bf16 v[8:11], v[136:139], v[192:195], v[8:11]
	s_waitcnt lgkmcnt(3)
	v_mfma_f32_16x16x32_bf16 v[60:63], v[132:135], v[148:151], v[60:63]
	v_mfma_f32_16x16x32_bf16 v[56:59], v[140:143], v[148:151], v[56:59]
	s_waitcnt lgkmcnt(2)
	v_mfma_f32_16x16x32_bf16 v[44:47], v[132:135], v[172:175], v[44:47]
	v_mfma_f32_16x16x32_bf16 v[40:43], v[140:143], v[172:175], v[40:43]
	s_waitcnt lgkmcnt(1)
	v_mfma_f32_16x16x32_bf16 v[28:31], v[132:135], v[180:183], v[28:31]
	v_mfma_f32_16x16x32_bf16 v[24:27], v[140:143], v[180:183], v[24:27]
	s_waitcnt lgkmcnt(0)
	s_setprio 2
	s_barrier
	v_mfma_f32_16x16x32_bf16 v[12:15], v[132:135], v[196:199], v[12:15]
	v_mfma_f32_16x16x32_bf16 v[8:11], v[140:143], v[196:199], v[8:11]
	s_setprio 0
	s_add_u32 s28, s28, 0x40080
	s_addc_u32 s29, s29, 0
	s_add_i32 s38, s38, s40
	v_lshl_add_u64 v[128:129], s[28:29], 0, v[154:155]
	s_mov_b32 m0, s38
	s_nop 0
	global_load_lds_dwordx4 v[128:129], off
	v_lshl_add_u64 v[128:129], s[28:29], 0, v[158:159]
	s_add_i32 m0, s38, 0x2000
	s_nop 0
	global_load_lds_dwordx4 v[128:129], off
	s_waitcnt vmcnt(6)
	s_setprio 1
	s_barrier
	v_mfma_f32_16x16x32_bf16 v[52:55], v[200:203], v[144:147], v[52:55]
	v_mfma_f32_16x16x32_bf16 v[48:51], v[208:211], v[144:147], v[48:51]
	v_mfma_f32_16x16x32_bf16 v[36:39], v[200:203], v[168:171], v[36:39]
	v_mfma_f32_16x16x32_bf16 v[32:35], v[208:211], v[168:171], v[32:35]
	v_mfma_f32_16x16x32_bf16 v[20:23], v[200:203], v[176:179], v[20:23]
	v_mfma_f32_16x16x32_bf16 v[16:19], v[208:211], v[176:179], v[16:19]
	v_mfma_f32_16x16x32_bf16 v[4:7], v[200:203], v[192:195], v[4:7]
	v_mfma_f32_16x16x32_bf16 v[0:3], v[208:211], v[192:195], v[0:3]
	v_mfma_f32_16x16x32_bf16 v[52:55], v[204:207], v[148:151], v[52:55]
	v_mfma_f32_16x16x32_bf16 v[48:51], v[212:215], v[148:151], v[48:51]
	v_mfma_f32_16x16x32_bf16 v[36:39], v[204:207], v[172:175], v[36:39]
	v_mfma_f32_16x16x32_bf16 v[32:35], v[212:215], v[172:175], v[32:35]
	v_mfma_f32_16x16x32_bf16 v[20:23], v[204:207], v[180:183], v[20:23]
	s_setprio 2
	s_barrier
	v_mfma_f32_16x16x32_bf16 v[16:19], v[212:215], v[180:183], v[16:19]
	v_mfma_f32_16x16x32_bf16 v[4:7], v[204:207], v[196:199], v[4:7]
	v_mfma_f32_16x16x32_bf16 v[0:3], v[212:215], v[196:199], v[0:3]
	s_setprio 0
	s_add_i32 s52, s52, 2
	s_add_u32 s24, s24, 0x100
	s_addc_u32 s25, s25, 0
	s_add_u32 s50, s50, 0x100
	s_addc_u32 s51, s51, 0
	s_cmp_gt_u32 s52, 13
	s_cbranch_scc0 .LBB0_786
	v_lshl_add_u32 v170, s18, 8, v184
	v_lshl_or_b32 v128, s22, 8, v186
	v_ashrrev_i32_e32 v129, 31, v128
	v_ashrrev_i32_e32 v171, 31, v170
	v_lshl_add_u64 v[168:169], v[128:129], 1, s[56:57]
	v_lshlrev_b64 v[128:129], 11, v[170:171]
	v_lshl_add_u64 v[202:203], v[168:169], 0, v[128:129]
	global_load_dwordx4 v[194:197], v[202:203], off
	global_load_dwordx4 v[198:201], v[202:203], off offset:256
	v_or_b32_e32 v180, 16, v170
	v_or_b32_e32 v176, 32, v170
	v_or_b32_e32 v172, 48, v170
	v_ashrrev_i32_e32 v181, 31, v180
	v_ashrrev_i32_e32 v177, 31, v176
	v_ashrrev_i32_e32 v173, 31, v172
	v_lshlrev_b64 v[128:129], 11, v[180:181]
	v_lshlrev_b64 v[130:131], 11, v[176:177]
	v_lshlrev_b64 v[132:133], 11, v[172:173]
	v_lshl_add_u64 v[182:183], v[168:169], 0, v[128:129]
	v_lshl_add_u64 v[178:179], v[168:169], 0, v[130:131]
	v_lshl_add_u64 v[174:175], v[168:169], 0, v[132:133]
	global_load_dwordx4 v[148:151], v[182:183], off
	global_load_dwordx4 v[144:147], v[182:183], off offset:256
	global_load_dwordx4 v[140:143], v[178:179], off
	global_load_dwordx4 v[136:139], v[178:179], off offset:256
	global_load_dwordx4 v[132:135], v[174:175], off
	global_load_dwordx4 v[128:131], v[174:175], off offset:256
	v_and_b32_e32 v192, 64, v190
	v_xor_b32_e32 v191, 16, v190
	v_add_u32_e32 v192, 64, v192
	v_cmp_lt_i32_e32 vcc, v191, v192
	v_xor_b32_e32 v193, 32, v190
	s_waitcnt vmcnt(0)
	v_lshlrev_b32_e32 v204, 16, v194
	v_and_b32_e32 v205, 0xffff0000, v194
	v_lshlrev_b32_e32 v208, 16, v198
	v_and_b32_e32 v209, 0xffff0000, v198
	v_lshlrev_b32_e32 v194, 16, v195
	v_and_b32_e32 v195, 0xffff0000, v195
	v_lshlrev_b32_e32 v210, 16, v200
	v_and_b32_e32 v211, 0xffff0000, v200
	v_lshlrev_b32_e32 v200, 16, v201
	v_and_b32_e32 v201, 0xffff0000, v201
	v_pk_add_f32 v[124:125], v[124:125], v[204:205]
	v_pk_add_f32 v[116:117], v[116:117], v[208:209]
	v_lshlrev_b32_e32 v198, 16, v199
	v_and_b32_e32 v199, 0xffff0000, v199
	v_pk_add_f32 v[126:127], v[126:127], v[194:195]
	v_pk_add_f32 v[194:195], v[114:115], v[200:201]
	v_mul_f32_e32 v114, v125, v125
	v_mul_f32_e32 v115, v117, v117
	v_pk_add_f32 v[118:119], v[118:119], v[198:199]
	v_fmac_f32_e32 v114, v124, v124
	v_fmac_f32_e32 v115, v116, v116
	v_lshlrev_b32_e32 v206, 16, v196
	v_and_b32_e32 v207, 0xffff0000, v196
	v_lshlrev_b32_e32 v196, 16, v197
	v_and_b32_e32 v197, 0xffff0000, v197
	v_fmac_f32_e32 v114, v126, v126
	v_fmac_f32_e32 v115, v118, v118
	v_pk_add_f32 v[122:123], v[122:123], v[196:197]
	v_pk_add_f32 v[120:121], v[120:121], v[206:207]
	v_pk_add_f32 v[196:197], v[112:113], v[210:211]
	v_fmac_f32_e32 v114, v127, v127
	v_fmac_f32_e32 v115, v119, v119
	v_fmac_f32_e32 v114, v120, v120
	v_fmac_f32_e32 v115, v196, v196
	v_fmac_f32_e32 v114, v121, v121
	v_fmac_f32_e32 v115, v197, v197
	v_fmac_f32_e32 v114, v122, v122
	v_fmac_f32_e32 v115, v194, v194
	v_cndmask_b32_e32 v191, v190, v191, vcc
	v_fmac_f32_e32 v114, v123, v123
	v_fmac_f32_e32 v115, v195, v195
	v_cmp_lt_i32_e32 vcc, v193, v192
	v_lshlrev_b32_e32 v192, 2, v191
	v_cvt_pk_bf16_f32 v112, v124, v125
	v_add_f32_e32 v124, v114, v115
	ds_bpermute_b32 v125, v192, v124
	v_cndmask_b32_e32 v193, v190, v193, vcc
	v_cvt_pk_bf16_f32 v113, v126, v127
	v_cvt_pk_bf16_f32 v114, v120, v121
	v_cvt_pk_bf16_f32 v115, v122, v123
	v_lshlrev_b32_e32 v191, 2, v193
	global_store_dwordx4 v[202:203], v[112:115], off
	s_waitcnt lgkmcnt(0)
	s_nop 0
	v_add_f32_e32 v112, v124, v125
	ds_bpermute_b32 v113, v191, v112
	v_cvt_pk_bf16_f32 v114, v116, v117
	v_cvt_pk_bf16_f32 v115, v118, v119
	v_cvt_pk_bf16_f32 v116, v196, v197
	v_cvt_pk_bf16_f32 v117, v194, v195
	global_store_dwordx4 v[202:203], v[114:117], off offset:256
	s_and_saveexec_b64 s[6:7], s[0:1]
	s_cbranch_execz .LBB0_789
	s_waitcnt lgkmcnt(0)
	v_add_f32_e32 v114, v112, v113
	v_lshl_add_u64 v[112:113], v[170:171], 2, s[20:21]
	global_atomic_add_f32 v[112:113], v114, off

; #define PG8_STAGE(bufoff, gbase, voff) do { _Pragma("unroll") for (int _i = 0; _i < 2; ++_i) \
;         __builtin_amdgcn_global_load_lds((const unsigned*)((const char*)(gbase) + (voff)[_i]), (LAS unsigned*)(lds + (bufoff) + ldsw + _i * 8192), 16, 0, 0); } while (0)
; #define PG8_LDA(dst, b, h) do { _Pragma("unroll") for (int m = 0; m < 4; ++m) _Pragma("unroll") for (int k = 0; k < 2; ++k) dst[m][k] = *(const LAS bf16x8*)(lds + PG8_SA(b, h) + aoff + m * 2048 + k * 1024); } while (0)
; #define PG8_LDB(dst, b, h) do { _Pragma("unroll") for (int n = 0; n < 2; ++n) _Pragma("unroll") for (int k = 0; k < 2; ++k) dst[n][k] = *(const LAS bf16x8*)(lds + PG8_SB(b, h) + boff + n * 2048 + k * 1024); } while (0)
; #define PG8_MMA(ai, bj, At, Bt) do { __builtin_amdgcn_s_setprio(1); _Pragma("unroll") for (int m = 0; m < 4; ++m) _Pragma("unroll") for (int n = 0; n < 2; ++n) _Pragma("unroll") for (int k = 0; k < 2; ++k) \
;         acc[ai][bj][m][n] = __builtin_amdgcn_mfma_f32_16x16x32_bf16(Bt[n][k], At[m][k], acc[ai][bj][m][n], 0, 0, 0); __builtin_amdgcn_s_setprio(0); } while (0)
; #define PG8_WAIT_V(n) asm volatile("s_waitcnt vmcnt(" #n ")" ::: "memory")
; #define PG8_WAIT_L(n) asm volatile("s_waitcnt lgkmcnt(" #n ")" ::: "memory")
; #define PG8_BAR __builtin_amdgcn_s_barrier()
; #define PG8_SCHED __builtin_amdgcn_sched_barrier(0)
; template <class Epi>
; DI void gemm_phase(LAS unsigned char* lds, const Gemm g, const StaticOrder S, const Epi E) {
;     ...
;             const bool last = (t == nt - 2);
;             const char* a1 = cA + (size_t)(t + 1) * kstep;
;             const char* a2 = last ? nA : cA + (size_t)(t + 2) * kstep; const char* b2 = last ? nB : cB + (size_t)(t + 2) * kstep;
;             const char* a3 = a2 + kstep; const char* b3 = b2 + kstep;
;             PG8_LDB(B0, 0, 0); PG8_SCHED; PG8_LDA(At, 0, 0); PG8_STAGE(PG8_SA(1, 1), a1 + hstep, voffA);
;             PG8_WAIT_L(8); PG8_BAR; PG8_WAIT_L(0); PG8_MMA(0, 0, At, B0); PG8_BAR; PG8_SCHED;
;             PG8_LDB(B1, 0, 1); PG8_STAGE(PG8_SB(0, 0), b2, voffB);
;             PG8_BAR; PG8_WAIT_L(0); PG8_MMA(0, 1, At, B1); PG8_BAR;
;             PG8_LDA(At, 0, 1); PG8_STAGE(PG8_SA(0, 0), a2, voffA);
;             PG8_BAR; PG8_WAIT_L(0); PG8_MMA(1, 0, At, B0); PG8_BAR; PG8_SCHED;
;             PG8_STAGE(PG8_SB(0, 1), b2 + hstep, voffB);
;             PG8_WAIT_V(6); PG8_BAR; PG8_MMA(1, 1, At, B1); PG8_BAR;
.LBB0_865:
	ds_read_b128 v[144:147], v155
	ds_read_b128 v[160:163], v155 offset:1024
	ds_read_b128 v[164:167], v155 offset:2048
	ds_read_b128 v[168:171], v155 offset:3072
	s_add_u32 s10, s8, 0xfffc0080
	s_addc_u32 s11, s9, -1
	s_cmp_eq_u32 s25, 12
	s_cselect_b32 s13, s14, s11
	s_cselect_b32 s12, s15, s10
	s_cselect_b32 s11, s16, s19
	s_cselect_b32 s10, s17, s18
	v_lshl_add_u64 v[204:205], s[8:9], 0, v[136:137]
	s_add_i32 m0, s40, 0xc000
	ds_read_b128 v[172:175], v157
	ds_read_b128 v[180:183], v157 offset:2048
	ds_read_b128 v[188:191], v157 offset:4096
	ds_read_b128 v[196:199], v157 offset:6144
	global_load_lds_dwordx4 v[204:205], off
	v_lshl_add_u64 v[204:205], s[8:9], 0, v[138:139]
	s_add_i32 m0, s40, 0xe000
	s_nop 0
	global_load_lds_dwordx4 v[204:205], off
	s_waitcnt lgkmcnt(4)
	s_setprio 1
	s_barrier
	ds_read_b128 v[176:179], v157 offset:1024
	ds_read_b128 v[184:187], v157 offset:3072
	ds_read_b128 v[192:195], v157 offset:5120
	ds_read_b128 v[200:203], v157 offset:7168
	s_waitcnt lgkmcnt(4)
	v_mfma_f32_16x16x32_bf16 v[124:127], v[144:147], v[172:175], v[124:127]
	v_mfma_f32_16x16x32_bf16 v[120:123], v[164:167], v[172:175], v[120:123]
	v_mfma_f32_16x16x32_bf16 v[108:111], v[144:147], v[180:183], v[108:111]
	v_mfma_f32_16x16x32_bf16 v[104:107], v[164:167], v[180:183], v[104:107]
	v_mfma_f32_16x16x32_bf16 v[92:95], v[144:147], v[188:191], v[92:95]
	v_mfma_f32_16x16x32_bf16 v[88:91], v[164:167], v[188:191], v[88:91]
	v_mfma_f32_16x16x32_bf16 v[76:79], v[144:147], v[196:199], v[76:79]
	v_mfma_f32_16x16x32_bf16 v[72:75], v[164:167], v[196:199], v[72:75]
	s_waitcnt lgkmcnt(3)
	v_mfma_f32_16x16x32_bf16 v[124:127], v[160:163], v[176:179], v[124:127]
	v_mfma_f32_16x16x32_bf16 v[120:123], v[168:171], v[176:179], v[120:123]
	s_waitcnt lgkmcnt(2)
	v_mfma_f32_16x16x32_bf16 v[108:111], v[160:163], v[184:187], v[108:111]
	v_mfma_f32_16x16x32_bf16 v[104:107], v[168:171], v[184:187], v[104:107]
	s_waitcnt lgkmcnt(1)
	v_mfma_f32_16x16x32_bf16 v[92:95], v[160:163], v[192:195], v[92:95]
	v_mfma_f32_16x16x32_bf16 v[88:91], v[168:171], v[192:195], v[88:91]
	s_waitcnt lgkmcnt(0)
	s_setprio 2
	s_barrier
	v_mfma_f32_16x16x32_bf16 v[76:79], v[160:163], v[200:203], v[76:79]
	v_mfma_f32_16x16x32_bf16 v[72:75], v[168:171], v[200:203], v[72:75]
	s_setprio 0
	s_add_i32 s29, s49, s34
	v_lshl_add_u64 v[220:221], s[10:11], 0, v[132:133]
	s_mov_b32 m0, s29
	ds_read_b128 v[204:207], v158
	ds_read_b128 v[208:211], v158 offset:1024
	ds_read_b128 v[212:215], v158 offset:2048
	ds_read_b128 v[216:219], v158 offset:3072
	global_load_lds_dwordx4 v[220:221], off
	v_lshl_add_u64 v[224:225], s[10:11], 0, v[128:129]
	s_add_i32 m0, s29, 0x2000
	s_nop 0
	global_load_lds_dwordx4 v[224:225], off
	s_setprio 1
	s_barrier
	s_waitcnt lgkmcnt(0)
	v_mfma_f32_16x16x32_bf16 v[116:119], v[204:207], v[172:175], v[116:119]
	v_mfma_f32_16x16x32_bf16 v[112:115], v[212:215], v[172:175], v[112:115]
	v_mfma_f32_16x16x32_bf16 v[100:103], v[204:207], v[180:183], v[100:103]
	v_mfma_f32_16x16x32_bf16 v[96:99], v[212:215], v[180:183], v[96:99]
	v_mfma_f32_16x16x32_bf16 v[84:87], v[204:207], v[188:191], v[84:87]
	v_mfma_f32_16x16x32_bf16 v[80:83], v[212:215], v[188:191], v[80:83]
	v_mfma_f32_16x16x32_bf16 v[68:71], v[204:207], v[196:199], v[68:71]
	v_mfma_f32_16x16x32_bf16 v[64:67], v[212:215], v[196:199], v[64:67]
	v_mfma_f32_16x16x32_bf16 v[116:119], v[208:211], v[176:179], v[116:119]
	v_mfma_f32_16x16x32_bf16 v[112:115], v[216:219], v[176:179], v[112:115]
	v_mfma_f32_16x16x32_bf16 v[100:103], v[208:211], v[184:187], v[100:103]
	v_mfma_f32_16x16x32_bf16 v[96:99], v[216:219], v[184:187], v[96:99]
	v_mfma_f32_16x16x32_bf16 v[84:87], v[208:211], v[192:195], v[84:87]
	s_setprio 2
	s_barrier
	v_mfma_f32_16x16x32_bf16 v[80:83], v[216:219], v[192:195], v[80:83]
	v_mfma_f32_16x16x32_bf16 v[68:71], v[208:211], v[200:203], v[68:71]
	v_mfma_f32_16x16x32_bf16 v[64:67], v[216:219], v[200:203], v[64:67]
	s_setprio 0
	s_mov_b32 m0, s40
	v_lshl_add_u64 v[226:227], s[12:13], 0, v[134:135]
	ds_read_b128 v[172:175], v157 offset:16384
	ds_read_b128 v[180:183], v157 offset:18432
	ds_read_b128 v[188:191], v157 offset:20480
	ds_read_b128 v[196:199], v157 offset:22528
	global_load_lds_dwordx4 v[226:227], off
	v_lshl_add_u64 v[228:229], s[12:13], 0, v[130:131]
	s_mov_b32 m0, s41
	s_nop 0
	global_load_lds_dwordx4 v[228:229], off
	s_setprio 1
	s_barrier
	ds_read_b128 v[176:179], v157 offset:17408
	ds_read_b128 v[184:187], v157 offset:19456
	ds_read_b128 v[192:195], v157 offset:21504
	ds_read_b128 v[200:203], v157 offset:23552
	s_waitcnt lgkmcnt(4)
	v_mfma_f32_16x16x32_bf16 v[60:63], v[144:147], v[172:175], v[60:63]
	v_mfma_f32_16x16x32_bf16 v[56:59], v[164:167], v[172:175], v[56:59]
	v_mfma_f32_16x16x32_bf16 v[44:47], v[144:147], v[180:183], v[44:47]
	v_mfma_f32_16x16x32_bf16 v[40:43], v[164:167], v[180:183], v[40:43]
	v_mfma_f32_16x16x32_bf16 v[28:31], v[144:147], v[188:191], v[28:31]
	v_mfma_f32_16x16x32_bf16 v[24:27], v[164:167], v[188:191], v[24:27]
	v_mfma_f32_16x16x32_bf16 v[12:15], v[144:147], v[196:199], v[12:15]
	v_mfma_f32_16x16x32_bf16 v[8:11], v[164:167], v[196:199], v[8:11]
	s_waitcnt lgkmcnt(3)
	v_mfma_f32_16x16x32_bf16 v[60:63], v[160:163], v[176:179], v[60:63]
	v_mfma_f32_16x16x32_bf16 v[56:59], v[168:171], v[176:179], v[56:59]
	s_waitcnt lgkmcnt(2)
	v_mfma_f32_16x16x32_bf16 v[44:47], v[160:163], v[184:187], v[44:47]
	v_mfma_f32_16x16x32_bf16 v[40:43], v[168:171], v[184:187], v[40:43]
	s_waitcnt lgkmcnt(1)
	v_mfma_f32_16x16x32_bf16 v[28:31], v[160:163], v[192:195], v[28:31]
	v_mfma_f32_16x16x32_bf16 v[24:27], v[168:171], v[192:195], v[24:27]
	s_waitcnt lgkmcnt(0)
	s_setprio 2
	s_barrier
; #define PG8_STAGE(bufoff, gbase, voff) do { _Pragma("unroll") for (int _i = 0; _i < 2; ++_i) \
;         __builtin_amdgcn_global_load_lds((const unsigned*)((const char*)(gbase) + (voff)[_i]), (LAS unsigned*)(lds + (bufoff) + ldsw + _i * 8192), 16, 0, 0); } while (0)
; #define PG8_LDA(dst, b, h) do { _Pragma("unroll") for (int m = 0; m < 4; ++m) _Pragma("unroll") for (int k = 0; k < 2; ++k) dst[m][k] = *(const LAS bf16x8*)(lds + PG8_SA(b, h) + aoff + m * 2048 + k * 1024); } while (0)
; #define PG8_LDB(dst, b, h) do { _Pragma("unroll") for (int n = 0; n < 2; ++n) _Pragma("unroll") for (int k = 0; k < 2; ++k) dst[n][k] = *(const LAS bf16x8*)(lds + PG8_SB(b, h) + boff + n * 2048 + k * 1024); } while (0)
; #define PG8_MMA(ai, bj, At, Bt) do { __builtin_amdgcn_s_setprio(1); _Pragma("unroll") for (int m = 0; m < 4; ++m) _Pragma("unroll") for (int n = 0; n < 2; ++n) _Pragma("unroll") for (int k = 0; k < 2; ++k) \
;         acc[ai][bj][m][n] = __builtin_amdgcn_mfma_f32_16x16x32_bf16(Bt[n][k], At[m][k], acc[ai][bj][m][n], 0, 0, 0); __builtin_amdgcn_s_setprio(0); } while (0)
; #define PG8_WAIT_V(n) asm volatile("s_waitcnt vmcnt(" #n ")" ::: "memory")
; #define PG8_WAIT_L(n) asm volatile("s_waitcnt lgkmcnt(" #n ")" ::: "memory")
; #define PG8_BAR __builtin_amdgcn_s_barrier()
; #define PG8_SCHED __builtin_amdgcn_sched_barrier(0)
; #define PG8_LDA(dst, b, h) do { _Pragma("unroll") for (int m = 0; m < 4; ++m) _Pragma("unroll") for (int k = 0; k < 2; ++k) dst[m][k] = *(const LAS bf16x8*)(lds + PG8_SA(b, h) + aoff + m * 2048 + k * 1024); } while (0)
; template <class Epi>
; DI void gemm_phase(LAS unsigned char* lds, const Gemm g, const StaticOrder S, const Epi E) {
;     ...
;             PG8_BAR; PG8_WAIT_L(0); PG8_MMA(1, 0, At, B0); PG8_BAR; PG8_SCHED;
;             PG8_STAGE(PG8_SB(0, 1), b2 + hstep, voffB);
;             PG8_WAIT_V(6); PG8_BAR; PG8_MMA(1, 1, At, B1); PG8_BAR;
;             PG8_LDB(B0, 1, 0); PG8_SCHED; PG8_LDA(At, 1, 0); PG8_STAGE(PG8_SA(0, 1), a2 + hstep, voffA);
;             PG8_WAIT_L(8); PG8_BAR; PG8_WAIT_L(0); PG8_MMA(0, 0, At, B0); PG8_BAR; PG8_SCHED;
;             PG8_LDB(B1, 1, 1); PG8_STAGE(PG8_SB(1, 0), b3, voffB);
;             PG8_BAR; PG8_WAIT_L(0); PG8_MMA(0, 1, At, B1); PG8_BAR;
;             PG8_LDA(At, 1, 1); PG8_STAGE(PG8_SA(1, 0), a3, voffA);
;             PG8_BAR; PG8_WAIT_L(0); PG8_MMA(1, 0, At, B0); PG8_BAR; PG8_SCHED;
	v_mfma_f32_16x16x32_bf16 v[12:15], v[160:163], v[200:203], v[12:15]
	v_mfma_f32_16x16x32_bf16 v[8:11], v[168:171], v[200:203], v[8:11]
	s_setprio 0
	s_add_u32 s58, s10, 0x40000
	s_addc_u32 s59, s11, 0
	s_add_i32 s29, s50, s34
	v_lshl_add_u64 v[144:145], s[58:59], 0, v[132:133]
	s_mov_b32 m0, s29
	s_nop 0
	global_load_lds_dwordx4 v[144:145], off
	v_lshl_add_u64 v[144:145], s[58:59], 0, v[128:129]
	s_add_i32 m0, s29, 0x2000
	s_nop 0
	global_load_lds_dwordx4 v[144:145], off
	s_waitcnt vmcnt(6)
	s_setprio 1
	s_barrier
	v_mfma_f32_16x16x32_bf16 v[52:55], v[204:207], v[172:175], v[52:55]
	v_mfma_f32_16x16x32_bf16 v[48:51], v[212:215], v[172:175], v[48:51]
	v_mfma_f32_16x16x32_bf16 v[36:39], v[204:207], v[180:183], v[36:39]
	v_mfma_f32_16x16x32_bf16 v[32:35], v[212:215], v[180:183], v[32:35]
	v_mfma_f32_16x16x32_bf16 v[20:23], v[204:207], v[188:191], v[20:23]
	v_mfma_f32_16x16x32_bf16 v[16:19], v[212:215], v[188:191], v[16:19]
	v_mfma_f32_16x16x32_bf16 v[4:7], v[204:207], v[196:199], v[4:7]
	v_mfma_f32_16x16x32_bf16 v[0:3], v[212:215], v[196:199], v[0:3]
	v_mfma_f32_16x16x32_bf16 v[52:55], v[208:211], v[176:179], v[52:55]
	v_mfma_f32_16x16x32_bf16 v[48:51], v[216:219], v[176:179], v[48:51]
	v_mfma_f32_16x16x32_bf16 v[36:39], v[208:211], v[184:187], v[36:39]
	v_mfma_f32_16x16x32_bf16 v[32:35], v[216:219], v[184:187], v[32:35]
	v_mfma_f32_16x16x32_bf16 v[20:23], v[208:211], v[192:195], v[20:23]
	s_setprio 2
	s_barrier
	v_mfma_f32_16x16x32_bf16 v[16:19], v[216:219], v[192:195], v[16:19]
	v_mfma_f32_16x16x32_bf16 v[4:7], v[208:211], v[200:203], v[4:7]
	v_mfma_f32_16x16x32_bf16 v[0:3], v[216:219], v[200:203], v[0:3]
	s_setprio 0
	s_add_i32 s29, 0, 0x18000
	v_add_u32_e32 v148, s29, v151
	ds_read_b128 v[144:147], v148
	ds_read_b128 v[160:163], v148 offset:1024
	ds_read_b128 v[164:167], v148 offset:2048
	ds_read_b128 v[168:171], v148 offset:3072
	s_add_u32 s12, s12, 0x40000
	s_addc_u32 s13, s13, 0
	s_mov_b32 m0, s42
	v_lshl_add_u64 v[204:205], s[12:13], 0, v[134:135]
	ds_read_b128 v[172:175], v157 offset:32768
	ds_read_b128 v[180:183], v157 offset:34816
	ds_read_b128 v[188:191], v157 offset:36864
	ds_read_b128 v[196:199], v157 offset:38912
	global_load_lds_dwordx4 v[204:205], off
	v_lshl_add_u64 v[204:205], s[12:13], 0, v[130:131]
	s_mov_b32 m0, s43
	s_nop 0
	global_load_lds_dwordx4 v[204:205], off
	s_waitcnt lgkmcnt(4)
	s_setprio 1
	s_barrier
	ds_read_b128 v[176:179], v157 offset:33792
	ds_read_b128 v[184:187], v157 offset:35840
	ds_read_b128 v[192:195], v157 offset:37888
	ds_read_b128 v[200:203], v157 offset:39936
	s_waitcnt lgkmcnt(4)
	v_mfma_f32_16x16x32_bf16 v[124:127], v[144:147], v[172:175], v[124:127]
	v_mfma_f32_16x16x32_bf16 v[120:123], v[164:167], v[172:175], v[120:123]
	v_mfma_f32_16x16x32_bf16 v[108:111], v[144:147], v[180:183], v[108:111]
	v_mfma_f32_16x16x32_bf16 v[104:107], v[164:167], v[180:183], v[104:107]
	v_mfma_f32_16x16x32_bf16 v[92:95], v[144:147], v[188:191], v[92:95]
	v_mfma_f32_16x16x32_bf16 v[88:91], v[164:167], v[188:191], v[88:91]
	v_mfma_f32_16x16x32_bf16 v[76:79], v[144:147], v[196:199], v[76:79]
	v_mfma_f32_16x16x32_bf16 v[72:75], v[164:167], v[196:199], v[72:75]
	s_waitcnt lgkmcnt(3)
	v_mfma_f32_16x16x32_bf16 v[124:127], v[160:163], v[176:179], v[124:127]
	v_mfma_f32_16x16x32_bf16 v[120:123], v[168:171], v[176:179], v[120:123]
	s_waitcnt lgkmcnt(2)
	v_mfma_f32_16x16x32_bf16 v[108:111], v[160:163], v[184:187], v[108:111]
	v_mfma_f32_16x16x32_bf16 v[104:107], v[168:171], v[184:187], v[104:107]
	s_waitcnt lgkmcnt(1)
	v_mfma_f32_16x16x32_bf16 v[92:95], v[160:163], v[192:195], v[92:95]
	v_mfma_f32_16x16x32_bf16 v[88:91], v[168:171], v[192:195], v[88:91]
	s_waitcnt lgkmcnt(0)
	s_setprio 2
	s_barrier
	v_mfma_f32_16x16x32_bf16 v[76:79], v[160:163], v[200:203], v[76:79]
	v_mfma_f32_16x16x32_bf16 v[72:75], v[168:171], v[200:203], v[72:75]
	s_setprio 0
	s_add_i32 s12, 0, 0x1c000
	s_add_i32 s13, s29, s34
	v_add_u32_e32 v148, s12, v151
	v_lshl_add_u64 v[220:221], v[220:221], 0, s[22:23]
	s_mov_b32 m0, s13
	ds_read_b128 v[204:207], v148
	ds_read_b128 v[208:211], v148 offset:1024
	ds_read_b128 v[212:215], v148 offset:2048
	ds_read_b128 v[216:219], v148 offset:3072
	global_load_lds_dwordx4 v[220:221], off
	v_lshl_add_u64 v[220:221], v[224:225], 0, s[22:23]
	s_add_i32 m0, s13, 0x2000
	s_nop 0
	global_load_lds_dwordx4 v[220:221], off
	s_setprio 1
	s_barrier
	s_waitcnt lgkmcnt(0)
	v_mfma_f32_16x16x32_bf16 v[116:119], v[204:207], v[172:175], v[116:119]
	v_mfma_f32_16x16x32_bf16 v[112:115], v[212:215], v[172:175], v[112:115]
	v_mfma_f32_16x16x32_bf16 v[100:103], v[204:207], v[180:183], v[100:103]
	v_mfma_f32_16x16x32_bf16 v[96:99], v[212:215], v[180:183], v[96:99]
	v_mfma_f32_16x16x32_bf16 v[84:87], v[204:207], v[188:191], v[84:87]
	v_mfma_f32_16x16x32_bf16 v[80:83], v[212:215], v[188:191], v[80:83]
	v_mfma_f32_16x16x32_bf16 v[68:71], v[204:207], v[196:199], v[68:71]
	v_mfma_f32_16x16x32_bf16 v[64:67], v[212:215], v[196:199], v[64:67]
	v_mfma_f32_16x16x32_bf16 v[116:119], v[208:211], v[176:179], v[116:119]
	v_mfma_f32_16x16x32_bf16 v[112:115], v[216:219], v[176:179], v[112:115]
	v_mfma_f32_16x16x32_bf16 v[100:103], v[208:211], v[184:187], v[100:103]
	v_mfma_f32_16x16x32_bf16 v[96:99], v[216:219], v[184:187], v[96:99]
	v_mfma_f32_16x16x32_bf16 v[84:87], v[208:211], v[192:195], v[84:87]
	s_setprio 2
	s_barrier
	v_mfma_f32_16x16x32_bf16 v[80:83], v[216:219], v[192:195], v[80:83]
	v_mfma_f32_16x16x32_bf16 v[68:71], v[208:211], v[200:203], v[68:71]
	v_mfma_f32_16x16x32_bf16 v[64:67], v[216:219], v[200:203], v[64:67]
	s_setprio 0
	s_mov_b32 m0, s45
	v_lshl_add_u64 v[220:221], v[226:227], 0, s[22:23]
	ds_read_b128 v[172:175], v157 offset:49152
	ds_read_b128 v[180:183], v157 offset:51200
	ds_read_b128 v[188:191], v157 offset:53248
	ds_read_b128 v[196:199], v157 offset:55296
	global_load_lds_dwordx4 v[220:221], off
	v_lshl_add_u64 v[220:221], v[228:229], 0, s[22:23]
	s_mov_b32 m0, s46
	s_nop 0
	global_load_lds_dwordx4 v[220:221], off
	s_setprio 1
	s_barrier
; #define PG8_STAGE(bufoff, gbase, voff) do { _Pragma("unroll") for (int _i = 0; _i < 2; ++_i) \
;         __builtin_amdgcn_global_load_lds((const unsigned*)((const char*)(gbase) + (voff)[_i]), (LAS unsigned*)(lds + (bufoff) + ldsw + _i * 8192), 16, 0, 0); } while (0)
; #define PG8_LDA(dst, b, h) do { _Pragma("unroll") for (int m = 0; m < 4; ++m) _Pragma("unroll") for (int k = 0; k < 2; ++k) dst[m][k] = *(const LAS bf16x8*)(lds + PG8_SA(b, h) + aoff + m * 2048 + k * 1024); } while (0)
; #define PG8_MMA(ai, bj, At, Bt) do { __builtin_amdgcn_s_setprio(1); _Pragma("unroll") for (int m = 0; m < 4; ++m) _Pragma("unroll") for (int n = 0; n < 2; ++n) _Pragma("unroll") for (int k = 0; k < 2; ++k) \
;         acc[ai][bj][m][n] = __builtin_amdgcn_mfma_f32_16x16x32_bf16(Bt[n][k], At[m][k], acc[ai][bj][m][n], 0, 0, 0); __builtin_amdgcn_s_setprio(0); } while (0)
; #define PG8_WAIT_V(n) asm volatile("s_waitcnt vmcnt(" #n ")" ::: "memory")
; #define PG8_WAIT_L(n) asm volatile("s_waitcnt lgkmcnt(" #n ")" ::: "memory")
; #define PG8_BAR __builtin_amdgcn_s_barrier()
; #define PG8_SCHED __builtin_amdgcn_sched_barrier(0)
; #define PG8_STAGE(bufoff, gbase, voff) do { _Pragma("unroll") for (int _i = 0; _i < 2; ++_i) \
;         __builtin_amdgcn_global_load_lds((const unsigned*)((const char*)(gbase) + (voff)[_i]), (LAS unsigned*)(lds + (bufoff) + ldsw + _i * 8192), 16, 0, 0); } while (0)
; #define PG8_WAIT_V(n) asm volatile("s_waitcnt vmcnt(" #n ")" ::: "memory")
; #define PG8_WAIT_L(n) asm volatile("s_waitcnt lgkmcnt(" #n ")" ::: "memory")
; #define PG8_BAR __builtin_amdgcn_s_barrier()
; DI RowScales load_rowscales(const float* ss, int row0) {
;     RowScales t;
; #pragma unroll
;     for (int ai = 0; ai < 2; ++ai)
; #pragma unroll
;         for (int m = 0; m < 4; ++m) t.r[ai][m] = ss[row0 + ai * 128 + m * 16];
; #pragma unroll
;     for (int ai = 0; ai < 2; ++ai)
; #pragma unroll
;         for (int m = 0; m < 4; ++m) t.r[ai][m] = rsqrtf(t.r[ai][m] * (1.0f / 1024.0f) + 1e-6f);
; template <class Epi>
; DI void gemm_phase(LAS unsigned char* lds, const Gemm g, const StaticOrder S, const Epi E) {
;     ...
;             PG8_LDA(At, 1, 1); PG8_STAGE(PG8_SA(1, 0), a3, voffA);
;             PG8_BAR; PG8_WAIT_L(0); PG8_MMA(1, 0, At, B0); PG8_BAR; PG8_SCHED;
;             PG8_STAGE(PG8_SB(1, 1), b3 + hstep, voffB);
;             PG8_WAIT_V(6); PG8_BAR; PG8_MMA(1, 1, At, B1); PG8_BAR;
	ds_read_b128 v[176:179], v157 offset:50176
	ds_read_b128 v[184:187], v157 offset:52224
	ds_read_b128 v[192:195], v157 offset:54272
	ds_read_b128 v[200:203], v157 offset:56320
	s_waitcnt lgkmcnt(4)
	v_mfma_f32_16x16x32_bf16 v[60:63], v[144:147], v[172:175], v[60:63]
	v_mfma_f32_16x16x32_bf16 v[56:59], v[164:167], v[172:175], v[56:59]
	v_mfma_f32_16x16x32_bf16 v[44:47], v[144:147], v[180:183], v[44:47]
	v_mfma_f32_16x16x32_bf16 v[40:43], v[164:167], v[180:183], v[40:43]
	v_mfma_f32_16x16x32_bf16 v[28:31], v[144:147], v[188:191], v[28:31]
	v_mfma_f32_16x16x32_bf16 v[24:27], v[164:167], v[188:191], v[24:27]
	v_mfma_f32_16x16x32_bf16 v[12:15], v[144:147], v[196:199], v[12:15]
	v_mfma_f32_16x16x32_bf16 v[8:11], v[164:167], v[196:199], v[8:11]
	s_waitcnt lgkmcnt(3)
	v_mfma_f32_16x16x32_bf16 v[60:63], v[160:163], v[176:179], v[60:63]
	v_mfma_f32_16x16x32_bf16 v[56:59], v[168:171], v[176:179], v[56:59]
	s_waitcnt lgkmcnt(2)
	v_mfma_f32_16x16x32_bf16 v[44:47], v[160:163], v[184:187], v[44:47]
	v_mfma_f32_16x16x32_bf16 v[40:43], v[168:171], v[184:187], v[40:43]
	s_waitcnt lgkmcnt(1)
	v_mfma_f32_16x16x32_bf16 v[28:31], v[160:163], v[192:195], v[28:31]
	v_mfma_f32_16x16x32_bf16 v[24:27], v[168:171], v[192:195], v[24:27]
	s_waitcnt lgkmcnt(0)
	s_setprio 2
	s_barrier
	v_mfma_f32_16x16x32_bf16 v[12:15], v[160:163], v[200:203], v[12:15]
	v_mfma_f32_16x16x32_bf16 v[8:11], v[168:171], v[200:203], v[8:11]
	s_setprio 0
	s_add_u32 s10, s10, 0x40080
	s_addc_u32 s11, s11, 0
	s_add_i32 s12, s12, s34
	v_lshl_add_u64 v[144:145], s[10:11], 0, v[132:133]
	s_mov_b32 m0, s12
	s_nop 0
	global_load_lds_dwordx4 v[144:145], off
	v_lshl_add_u64 v[144:145], s[10:11], 0, v[128:129]
	s_add_i32 m0, s12, 0x2000
	s_nop 0
	global_load_lds_dwordx4 v[144:145], off
	s_waitcnt vmcnt(6)
	s_setprio 1
	s_barrier
	v_mfma_f32_16x16x32_bf16 v[52:55], v[204:207], v[172:175], v[52:55]
	v_mfma_f32_16x16x32_bf16 v[48:51], v[212:215], v[172:175], v[48:51]
	v_mfma_f32_16x16x32_bf16 v[36:39], v[204:207], v[180:183], v[36:39]
	v_mfma_f32_16x16x32_bf16 v[32:35], v[212:215], v[180:183], v[32:35]
	v_mfma_f32_16x16x32_bf16 v[20:23], v[204:207], v[188:191], v[20:23]
	v_mfma_f32_16x16x32_bf16 v[16:19], v[212:215], v[188:191], v[16:19]
	v_mfma_f32_16x16x32_bf16 v[4:7], v[204:207], v[196:199], v[4:7]
	v_mfma_f32_16x16x32_bf16 v[0:3], v[212:215], v[196:199], v[0:3]
	v_mfma_f32_16x16x32_bf16 v[52:55], v[208:211], v[176:179], v[52:55]
	v_mfma_f32_16x16x32_bf16 v[48:51], v[216:219], v[176:179], v[48:51]
	v_mfma_f32_16x16x32_bf16 v[36:39], v[208:211], v[184:187], v[36:39]
	v_mfma_f32_16x16x32_bf16 v[32:35], v[216:219], v[184:187], v[32:35]
	v_mfma_f32_16x16x32_bf16 v[20:23], v[208:211], v[192:195], v[20:23]
	s_setprio 2
	s_barrier
	v_mfma_f32_16x16x32_bf16 v[16:19], v[216:219], v[192:195], v[16:19]
	v_mfma_f32_16x16x32_bf16 v[4:7], v[208:211], v[200:203], v[4:7]
	v_mfma_f32_16x16x32_bf16 v[0:3], v[216:219], v[200:203], v[0:3]
	s_setprio 0
	s_add_i32 s25, s25, 2
	s_add_u32 s8, s8, 0x100
	s_addc_u32 s9, s9, 0
	s_add_u32 s18, s18, 0x100
	s_addc_u32 s19, s19, 0
	s_cmp_gt_u32 s25, 13
	s_cbranch_scc0 .LBB0_865
	v_lshl_add_u32 v146, s4, 8, v149
	v_ashrrev_i32_e32 v147, 31, v146
	v_lshl_add_u64 v[144:145], v[146:147], 2, s[20:21]
	global_load_dword v147, v[144:145], off
	global_load_dword v148, v[144:145], off offset:64
	global_load_dword v150, v[144:145], off offset:128
	global_load_dword v152, v[144:145], off offset:192
	global_load_dword v154, v[144:145], off offset:512
	global_load_dword v156, v[144:145], off offset:576
	global_load_dword v160, v[144:145], off offset:640
	global_load_dword v161, v[144:145], off offset:704
	v_lshl_or_b32 v144, s5, 7, v153
	v_ashrrev_i32_e32 v145, 31, v144
	v_lshl_add_u64 v[144:145], v[144:145], 1, s[54:55]
	s_waitcnt vmcnt(0)
	v_fmamk_f32 v147, v147, 0x3a800000, v159
	v_mul_f32_e32 v162, 0x4b800000, v147
	v_cmp_gt_f32_e32 vcc, s51, v147
	v_fmamk_f32 v152, v152, 0x3a800000, v159
	v_fmamk_f32 v154, v154, 0x3a800000, v159
	v_cndmask_b32_e32 v147, v147, v162, vcc
	v_mul_f32_e32 v165, 0x4b800000, v152
	v_fmamk_f32 v161, v161, 0x3a800000, v159
	v_mul_f32_e32 v166, 0x4b800000, v154
	v_mul_f32_e32 v169, 0x4b800000, v161
	v_cmp_gt_f32_e64 s[10:11], s51, v152
	v_cmp_gt_f32_e64 s[12:13], s51, v154
	v_cmp_gt_f32_e64 s[18:19], s51, v161
	v_rsq_f32_e32 v147, v147
	v_fmamk_f32 v156, v156, 0x3a800000, v159
	v_cndmask_b32_e64 v152, v152, v165, s[10:11]
	v_cndmask_b32_e64 v154, v154, v166, s[12:13]
	v_cndmask_b32_e64 v161, v161, v169, s[18:19]
	v_fmamk_f32 v148, v148, 0x3a800000, v159
	v_fmamk_f32 v160, v160, 0x3a800000, v159
	v_mul_f32_e32 v167, 0x4b800000, v156
	v_cmp_gt_f32_e64 s[14:15], s51, v156
	v_rsq_f32_e32 v152, v152
	v_rsq_f32_e32 v154, v154
	v_rsq_f32_e32 v161, v161
	v_mul_f32_e32 v163, 0x4b800000, v148
	v_mul_f32_e32 v168, 0x4b800000, v160
	v_cmp_gt_f32_e64 s[4:5], s51, v148
	v_cndmask_b32_e64 v156, v156, v167, s[14:15]
	v_cmp_gt_f32_e64 s[16:17], s51, v160
	v_fmamk_f32 v150, v150, 0x3a800000, v159
	v_cndmask_b32_e64 v148, v148, v163, s[4:5]
	v_cndmask_b32_e64 v160, v160, v168, s[16:17]
	v_rsq_f32_e32 v163, v156
	v_mul_f32_e32 v156, 0x45800000, v147
	v_mul_f32_e32 v164, 0x4b800000, v150
	v_cmp_gt_f32_e64 s[8:9], s51, v150
	v_rsq_f32_e32 v165, v160
	v_cndmask_b32_e32 v160, v147, v156, vcc
	v_cndmask_b32_e64 v150, v150, v164, s[8:9]
	v_rsq_f32_e32 v148, v148
	v_mul_f32_e32 v166, 0x45800000, v152
	v_mul_f32_e32 v167, 0x45800000, v154
	v_pk_mul_f32 v[126:127], v[126:127], v[160:161] op_sel_hi:[1,0]
	v_pk_mul_f32 v[124:125], v[124:125], v[160:161] op_sel_hi:[1,0]
	v_rsq_f32_e32 v150, v150
	v_cndmask_b32_e64 v156, v152, v166, s[10:11]
	v_cndmask_b32_e64 v154, v154, v167, s[12:13]
; DI unsigned pk_bf16(float lo, float hi) { f32x2 v = {lo, hi}; return __builtin_bit_cast(unsigned, __builtin_convertvector(v, bf16v2)); }
; DI float fast_silu(float x) { return x * fast_sigmoid(x); }
;     DI void operator()(AccRef acc, const Unit& u, int wr, int wc, int fr, int fq) const {
;     ...
; #pragma unroll
;         for (int ai = 0; ai < 2; ++ai)
; #pragma unroll
;             for (int m = 0; m < 4; ++m) {
;                 const int row = row0 + ai * 128 + m * 16;
;                 const float r = RS ? rsc.r[ai][m] : 1.0f;
;                 const f32x4 a0 = acc[ai][0][m][0] * r, a1 = acc[ai][0][m][1] * r, b0 = acc[ai][1][m][0] * r, b1 = acc[ai][1][m][1] * r;
;                 u32x4 w;
;                 w.x = pk_bf16(fast_silu(a0[0]) * b0[0], fast_silu(a0[1]) * b0[1]); w.y = pk_bf16(fast_silu(a0[2]) * b0[2], fast_silu(a0[3]) * b0[3]);
;                 w.z = pk_bf16(fast_silu(a1[0]) * b1[0], fast_silu(a1[1]) * b1[1]); w.w = pk_bf16(fast_silu(a1[2]) * b1[2], fast_silu(a1[3]) * b1[3]);
;                 *(u32x4*)(G + (size_t)row * DFF + col) = w;
	v_pk_mul_f32 v[122:123], v[122:123], v[160:161] op_sel_hi:[1,0]
	v_pk_mul_f32 v[120:121], v[120:121], v[160:161] op_sel_hi:[1,0]
	v_pk_mul_f32 v[118:119], v[118:119], v[160:161] op_sel_hi:[1,0]
	v_pk_mul_f32 v[116:117], v[116:117], v[160:161] op_sel_hi:[1,0]
	v_pk_mul_f32 v[166:167], v[114:115], v[160:161] op_sel_hi:[1,0]
	v_pk_mul_f32 v[114:115], v[112:113], v[160:161] op_sel_hi:[1,0]
	v_mul_f32_e32 v112, 0xbfb8aa3b, v124
	v_mul_f32_e32 v113, 0xbfb8aa3b, v125
	v_mul_f32_e32 v147, 0xbfb8aa3b, v126
	v_mul_f32_e32 v160, 0xbfb8aa3b, v127
	v_exp_f32_e32 v112, v112
	v_exp_f32_e32 v113, v113
	v_exp_f32_e32 v147, v147
	v_exp_f32_e32 v160, v160
	v_mul_f32_e32 v162, 0x45800000, v148
	v_mul_f32_e32 v170, 0x45800000, v161
	v_mul_f32_e32 v164, 0x45800000, v150
	v_mul_f32_e32 v169, 0x45800000, v165
	v_cndmask_b32_e64 v162, v148, v162, s[4:5]
	v_cndmask_b32_e64 v148, v161, v170, s[18:19]
	v_mul_f32_e32 v161, 0xbfb8aa3b, v120
	v_cndmask_b32_e64 v164, v150, v164, s[8:9]
	v_cndmask_b32_e64 v150, v165, v169, s[16:17]
	v_exp_f32_e32 v165, v161
	v_add_f32_e32 v112, 1.0, v112
	v_add_f32_e32 v113, 1.0, v113
	v_add_f32_e32 v147, 1.0, v147
	v_add_f32_e32 v161, 1.0, v160
	v_rcp_f32_e32 v112, v112
	v_rcp_f32_e32 v113, v113
	v_rcp_f32_e32 v160, v147
	v_rcp_f32_e32 v161, v161
	v_mul_f32_e32 v168, 0x45800000, v163
	v_pk_mul_f32 v[112:113], v[124:125], v[112:113]
	v_cndmask_b32_e64 v152, v163, v168, s[14:15]
	v_pk_mul_f32 v[124:125], v[126:127], v[160:161]
	v_mul_f32_e32 v163, 0xbfb8aa3b, v121
	v_pk_mul_f32 v[112:113], v[116:117], v[112:113]
	v_pk_mul_f32 v[116:117], v[118:119], v[124:125]
	v_exp_f32_e32 v163, v163
	v_cvt_pk_bf16_f32 v112, v112, v113
	v_cvt_pk_bf16_f32 v113, v116, v117
	v_mul_f32_e32 v117, 0xbfb8aa3b, v122
	v_mul_f32_e32 v118, 0xbfb8aa3b, v123
	v_exp_f32_e32 v117, v117
	v_exp_f32_e32 v118, v118
	v_add_f32_e32 v116, 1.0, v163
	v_add_f32_e32 v147, 1.0, v165
	v_rcp_f32_e32 v169, v116
	v_add_f32_e32 v116, 1.0, v117
	v_add_f32_e32 v117, 1.0, v118
	v_rcp_f32_e32 v168, v147
	v_rcp_f32_e32 v116, v116
	v_rcp_f32_e32 v117, v117
	v_pk_mul_f32 v[108:109], v[108:109], v[162:163] op_sel_hi:[1,0]
	v_pk_mul_f32 v[118:119], v[120:121], v[168:169]
	v_pk_mul_f32 v[110:111], v[110:111], v[162:163] op_sel_hi:[1,0]
	v_pk_mul_f32 v[116:117], v[122:123], v[116:117]
	v_pk_mul_f32 v[114:115], v[114:115], v[118:119]
	v_pk_mul_f32 v[116:117], v[166:167], v[116:117]
	v_cvt_pk_bf16_f32 v114, v114, v115
	v_cvt_pk_bf16_f32 v115, v116, v117
	v_mad_i64_i32 v[116:117], s[4:5], v146, s52, v[144:145]
	global_store_dwordx4 v[116:117], v[112:115], off
	v_pk_mul_f32 v[100:101], v[100:101], v[162:163] op_sel_hi:[1,0]
	v_pk_mul_f32 v[104:105], v[104:105], v[162:163] op_sel_hi:[1,0]
	v_pk_mul_f32 v[112:113], v[98:99], v[162:163] op_sel_hi:[1,0]
	v_mul_f32_e32 v98, 0xbfb8aa3b, v108
	v_exp_f32_e32 v114, v98
	v_mul_f32_e32 v98, 0xbfb8aa3b, v109
	v_exp_f32_e32 v115, v98
	v_pk_mul_f32 v[98:99], v[96:97], v[162:163] op_sel_hi:[1,0]
	v_add_f32_e32 v96, 1.0, v114
	v_mul_f32_e32 v114, 0xbfb8aa3b, v110
	v_add_f32_e32 v97, 1.0, v115
	v_mul_f32_e32 v115, 0xbfb8aa3b, v111
	v_exp_f32_e32 v114, v114
	v_exp_f32_e32 v115, v115
	v_rcp_f32_e32 v96, v96
	v_rcp_f32_e32 v97, v97
	v_add_f32_e32 v114, 1.0, v114
	v_add_f32_e32 v115, 1.0, v115
	v_rcp_f32_e32 v114, v114
	v_rcp_f32_e32 v115, v115
	v_pk_mul_f32 v[96:97], v[108:109], v[96:97]
	v_pk_mul_f32 v[102:103], v[102:103], v[162:163] op_sel_hi:[1,0]
	v_pk_mul_f32 v[96:97], v[100:101], v[96:97]
	v_pk_mul_f32 v[100:101], v[110:111], v[114:115]
	v_cvt_pk_bf16_f32 v96, v96, v97
	v_mul_f32_e32 v97, 0xbfb8aa3b, v104
	v_pk_mul_f32 v[100:101], v[102:103], v[100:101]
	v_exp_f32_e32 v102, v97
	v_mul_f32_e32 v97, 0xbfb8aa3b, v105
	v_exp_f32_e32 v103, v97
	v_pk_mul_f32 v[106:107], v[106:107], v[162:163] op_sel_hi:[1,0]
	v_cvt_pk_bf16_f32 v97, v100, v101
	v_add_f32_e32 v100, 1.0, v102
	v_add_f32_e32 v101, 1.0, v103
	v_mul_f32_e32 v102, 0xbfb8aa3b, v106
	v_mul_f32_e32 v103, 0xbfb8aa3b, v107
	v_exp_f32_e32 v102, v102
	v_exp_f32_e32 v103, v103
	v_rcp_f32_e32 v100, v100
	v_rcp_f32_e32 v101, v101
	v_add_f32_e32 v102, 1.0, v102
	v_add_f32_e32 v103, 1.0, v103
	v_rcp_f32_e32 v102, v102
	v_rcp_f32_e32 v103, v103
	v_pk_mul_f32 v[100:101], v[104:105], v[100:101]
	v_or_b32_e32 v116, 16, v146
	v_pk_mul_f32 v[98:99], v[98:99], v[100:101]
	v_pk_mul_f32 v[100:101], v[106:107], v[102:103]
	v_cvt_pk_bf16_f32 v98, v98, v99
	v_pk_mul_f32 v[100:101], v[112:113], v[100:101]
	v_pk_mul_f32 v[92:93], v[92:93], v[164:165] op_sel_hi:[1,0]
	v_cvt_pk_bf16_f32 v99, v100, v101
	v_mad_i64_i32 v[100:101], s[4:5], v116, s52, v[144:145]
	global_store_dwordx4 v[100:101], v[96:99], off
	v_pk_mul_f32 v[94:95], v[94:95], v[164:165] op_sel_hi:[1,0]
	v_pk_mul_f32 v[84:85], v[84:85], v[164:165] op_sel_hi:[1,0]
	v_pk_mul_f32 v[96:97], v[82:83], v[164:165] op_sel_hi:[1,0]
	v_mul_f32_e32 v82, 0xbfb8aa3b, v92
	v_exp_f32_e32 v98, v82
	v_mul_f32_e32 v82, 0xbfb8aa3b, v93
	v_exp_f32_e32 v99, v82
	v_pk_mul_f32 v[82:83], v[80:81], v[164:165] op_sel_hi:[1,0]
	v_add_f32_e32 v80, 1.0, v98
	v_mul_f32_e32 v98, 0xbfb8aa3b, v94
	v_add_f32_e32 v81, 1.0, v99
	v_mul_f32_e32 v99, 0xbfb8aa3b, v95
	v_exp_f32_e32 v98, v98
	v_exp_f32_e32 v99, v99
	v_rcp_f32_e32 v80, v80
	v_rcp_f32_e32 v81, v81
	v_add_f32_e32 v98, 1.0, v98
	v_add_f32_e32 v99, 1.0, v99
	v_rcp_f32_e32 v98, v98
	v_rcp_f32_e32 v99, v99
	v_pk_mul_f32 v[80:81], v[92:93], v[80:81]
	v_pk_mul_f32 v[88:89], v[88:89], v[164:165] op_sel_hi:[1,0]
	v_pk_mul_f32 v[80:81], v[84:85], v[80:81]
	v_pk_mul_f32 v[86:87], v[86:87], v[164:165] op_sel_hi:[1,0]
	v_cvt_pk_bf16_f32 v80, v80, v81
	v_pk_mul_f32 v[84:85], v[94:95], v[98:99]
	v_mul_f32_e32 v81, 0xbfb8aa3b, v88
	v_pk_mul_f32 v[84:85], v[86:87], v[84:85]
; DI unsigned pk_bf16(float lo, float hi) { f32x2 v = {lo, hi}; return __builtin_bit_cast(unsigned, __builtin_convertvector(v, bf16v2)); }
; DI float fast_silu(float x) { return x * fast_sigmoid(x); }
;     DI void operator()(AccRef acc, const Unit& u, int wr, int wc, int fr, int fq) const {
;     ...
; #pragma unroll
;         for (int ai = 0; ai < 2; ++ai)
; #pragma unroll
;             for (int m = 0; m < 4; ++m) {
;                 const int row = row0 + ai * 128 + m * 16;
;                 const float r = RS ? rsc.r[ai][m] : 1.0f;
;                 const f32x4 a0 = acc[ai][0][m][0] * r, a1 = acc[ai][0][m][1] * r, b0 = acc[ai][1][m][0] * r, b1 = acc[ai][1][m][1] * r;
;                 u32x4 w;
;                 w.x = pk_bf16(fast_silu(a0[0]) * b0[0], fast_silu(a0[1]) * b0[1]); w.y = pk_bf16(fast_silu(a0[2]) * b0[2], fast_silu(a0[3]) * b0[3]);
;                 w.z = pk_bf16(fast_silu(a1[0]) * b1[0], fast_silu(a1[1]) * b1[1]); w.w = pk_bf16(fast_silu(a1[2]) * b1[2], fast_silu(a1[3]) * b1[3]);
;                 *(u32x4*)(G + (size_t)row * DFF + col) = w;
	v_exp_f32_e32 v86, v81
	v_mul_f32_e32 v81, 0xbfb8aa3b, v89
	v_exp_f32_e32 v87, v81
	v_pk_mul_f32 v[90:91], v[90:91], v[164:165] op_sel_hi:[1,0]
	v_cvt_pk_bf16_f32 v81, v84, v85
	v_add_f32_e32 v84, 1.0, v86
	v_add_f32_e32 v85, 1.0, v87
	v_mul_f32_e32 v86, 0xbfb8aa3b, v90
	v_mul_f32_e32 v87, 0xbfb8aa3b, v91
	v_exp_f32_e32 v86, v86
	v_exp_f32_e32 v87, v87
	v_rcp_f32_e32 v84, v84
	v_rcp_f32_e32 v85, v85
	v_add_f32_e32 v86, 1.0, v86
	v_add_f32_e32 v87, 1.0, v87
	v_rcp_f32_e32 v86, v86
	v_rcp_f32_e32 v87, v87
	v_pk_mul_f32 v[84:85], v[88:89], v[84:85]
	v_or_b32_e32 v100, 32, v146
	v_pk_mul_f32 v[82:83], v[82:83], v[84:85]
	v_pk_mul_f32 v[84:85], v[90:91], v[86:87]
	v_cvt_pk_bf16_f32 v82, v82, v83
	v_pk_mul_f32 v[84:85], v[96:97], v[84:85]
	v_pk_mul_f32 v[76:77], v[76:77], v[156:157] op_sel_hi:[1,0]
	v_cvt_pk_bf16_f32 v83, v84, v85
	v_mad_i64_i32 v[84:85], s[4:5], v100, s52, v[144:145]
	global_store_dwordx4 v[84:85], v[80:83], off
	v_pk_mul_f32 v[78:79], v[78:79], v[156:157] op_sel_hi:[1,0]
	v_pk_mul_f32 v[68:69], v[68:69], v[156:157] op_sel_hi:[1,0]
	v_pk_mul_f32 v[80:81], v[66:67], v[156:157] op_sel_hi:[1,0]
	v_mul_f32_e32 v66, 0xbfb8aa3b, v76
	v_exp_f32_e32 v82, v66
	v_mul_f32_e32 v66, 0xbfb8aa3b, v77
	v_exp_f32_e32 v83, v66
	v_pk_mul_f32 v[66:67], v[64:65], v[156:157] op_sel_hi:[1,0]
	v_add_f32_e32 v64, 1.0, v82
	v_mul_f32_e32 v82, 0xbfb8aa3b, v78
	v_add_f32_e32 v65, 1.0, v83
	v_mul_f32_e32 v83, 0xbfb8aa3b, v79
	v_exp_f32_e32 v82, v82
	v_exp_f32_e32 v83, v83
	v_rcp_f32_e32 v64, v64
	v_rcp_f32_e32 v65, v65
	v_add_f32_e32 v82, 1.0, v82
	v_add_f32_e32 v83, 1.0, v83
	v_rcp_f32_e32 v82, v82
	v_rcp_f32_e32 v83, v83
	v_pk_mul_f32 v[64:65], v[76:77], v[64:65]
	v_pk_mul_f32 v[72:73], v[72:73], v[156:157] op_sel_hi:[1,0]
	v_pk_mul_f32 v[64:65], v[68:69], v[64:65]
	v_pk_mul_f32 v[70:71], v[70:71], v[156:157] op_sel_hi:[1,0]
	v_cvt_pk_bf16_f32 v64, v64, v65
	v_pk_mul_f32 v[68:69], v[78:79], v[82:83]
	v_mul_f32_e32 v65, 0xbfb8aa3b, v72
	v_pk_mul_f32 v[68:69], v[70:71], v[68:69]
	v_exp_f32_e32 v70, v65
	v_mul_f32_e32 v65, 0xbfb8aa3b, v73
	v_exp_f32_e32 v71, v65
	v_pk_mul_f32 v[74:75], v[74:75], v[156:157] op_sel_hi:[1,0]
	v_cvt_pk_bf16_f32 v65, v68, v69
	v_add_f32_e32 v68, 1.0, v70
	v_add_f32_e32 v69, 1.0, v71
	v_mul_f32_e32 v70, 0xbfb8aa3b, v74
	v_mul_f32_e32 v71, 0xbfb8aa3b, v75
	v_exp_f32_e32 v70, v70
	v_exp_f32_e32 v71, v71
	v_rcp_f32_e32 v68, v68
	v_rcp_f32_e32 v69, v69
	v_add_f32_e32 v70, 1.0, v70
	v_add_f32_e32 v71, 1.0, v71
	v_rcp_f32_e32 v70, v70
	v_rcp_f32_e32 v71, v71
	v_pk_mul_f32 v[68:69], v[72:73], v[68:69]
	v_or_b32_e32 v84, 48, v146
	v_pk_mul_f32 v[66:67], v[66:67], v[68:69]
	v_pk_mul_f32 v[68:69], v[74:75], v[70:71]
	v_cvt_pk_bf16_f32 v66, v66, v67
	v_pk_mul_f32 v[68:69], v[80:81], v[68:69]
	v_pk_mul_f32 v[60:61], v[60:61], v[154:155] op_sel_hi:[1,0]
	v_cvt_pk_bf16_f32 v67, v68, v69
	v_mad_i64_i32 v[68:69], s[4:5], v84, s52, v[144:145]
	global_store_dwordx4 v[68:69], v[64:67], off
	v_pk_mul_f32 v[62:63], v[62:63], v[154:155] op_sel_hi:[1,0]
	v_pk_mul_f32 v[52:53], v[52:53], v[154:155] op_sel_hi:[1,0]
	v_pk_mul_f32 v[64:65], v[50:51], v[154:155] op_sel_hi:[1,0]
	v_mul_f32_e32 v50, 0xbfb8aa3b, v60
	v_exp_f32_e32 v66, v50
	v_mul_f32_e32 v50, 0xbfb8aa3b, v61
	v_exp_f32_e32 v67, v50
	v_pk_mul_f32 v[50:51], v[48:49], v[154:155] op_sel_hi:[1,0]
	v_add_f32_e32 v48, 1.0, v66
	v_mul_f32_e32 v66, 0xbfb8aa3b, v62
	v_add_f32_e32 v49, 1.0, v67
	v_mul_f32_e32 v67, 0xbfb8aa3b, v63
	v_exp_f32_e32 v66, v66
	v_exp_f32_e32 v67, v67
	v_rcp_f32_e32 v48, v48
	v_rcp_f32_e32 v49, v49
	v_add_f32_e32 v66, 1.0, v66
	v_add_f32_e32 v67, 1.0, v67
	v_rcp_f32_e32 v66, v66
	v_rcp_f32_e32 v67, v67
	v_pk_mul_f32 v[48:49], v[60:61], v[48:49]
	v_pk_mul_f32 v[56:57], v[56:57], v[154:155] op_sel_hi:[1,0]
	v_pk_mul_f32 v[48:49], v[52:53], v[48:49]
	v_pk_mul_f32 v[54:55], v[54:55], v[154:155] op_sel_hi:[1,0]
	v_cvt_pk_bf16_f32 v48, v48, v49
	v_pk_mul_f32 v[52:53], v[62:63], v[66:67]
	v_mul_f32_e32 v49, 0xbfb8aa3b, v56
	v_pk_mul_f32 v[52:53], v[54:55], v[52:53]
	v_exp_f32_e32 v54, v49
	v_mul_f32_e32 v49, 0xbfb8aa3b, v57
	v_exp_f32_e32 v55, v49
	v_pk_mul_f32 v[58:59], v[58:59], v[154:155] op_sel_hi:[1,0]
	v_cvt_pk_bf16_f32 v49, v52, v53
	v_add_f32_e32 v52, 1.0, v54
	v_add_f32_e32 v53, 1.0, v55
	v_mul_f32_e32 v54, 0xbfb8aa3b, v58
	v_mul_f32_e32 v55, 0xbfb8aa3b, v59
	v_exp_f32_e32 v54, v54
	v_exp_f32_e32 v55, v55
	v_rcp_f32_e32 v52, v52
	v_rcp_f32_e32 v53, v53
	v_add_f32_e32 v54, 1.0, v54
	v_add_f32_e32 v55, 1.0, v55
	v_rcp_f32_e32 v54, v54
	v_rcp_f32_e32 v55, v55
	v_pk_mul_f32 v[52:53], v[56:57], v[52:53]
	v_add_u32_e32 v68, 0x80, v146
	v_pk_mul_f32 v[50:51], v[50:51], v[52:53]
	v_pk_mul_f32 v[52:53], v[58:59], v[54:55]
	v_cvt_pk_bf16_f32 v50, v50, v51
	v_pk_mul_f32 v[52:53], v[64:65], v[52:53]
	v_pk_mul_f32 v[44:45], v[44:45], v[152:153] op_sel_hi:[1,0]
	v_cvt_pk_bf16_f32 v51, v52, v53
	v_mad_i64_i32 v[52:53], s[4:5], v68, s52, v[144:145]
	global_store_dwordx4 v[52:53], v[48:51], off
	v_pk_mul_f32 v[46:47], v[46:47], v[152:153] op_sel_hi:[1,0]
	v_pk_mul_f32 v[36:37], v[36:37], v[152:153] op_sel_hi:[1,0]
	v_pk_mul_f32 v[48:49], v[34:35], v[152:153] op_sel_hi:[1,0]
	v_mul_f32_e32 v34, 0xbfb8aa3b, v44
	v_exp_f32_e32 v50, v34
	v_mul_f32_e32 v34, 0xbfb8aa3b, v45
	v_exp_f32_e32 v51, v34
	v_pk_mul_f32 v[34:35], v[32:33], v[152:153] op_sel_hi:[1,0]
	v_add_f32_e32 v32, 1.0, v50
	v_mul_f32_e32 v50, 0xbfb8aa3b, v46
	v_add_f32_e32 v33, 1.0, v51
	v_mul_f32_e32 v51, 0xbfb8aa3b, v47
	v_exp_f32_e32 v50, v50
	v_exp_f32_e32 v51, v51
	v_rcp_f32_e32 v32, v32
; DI unsigned pk_bf16(float lo, float hi) { f32x2 v = {lo, hi}; return __builtin_bit_cast(unsigned, __builtin_convertvector(v, bf16v2)); }
; DI float fast_silu(float x) { return x * fast_sigmoid(x); }
; #define PG8_WAIT_V(n) asm volatile("s_waitcnt vmcnt(" #n ")" ::: "memory")
; #define PG8_BAR __builtin_amdgcn_s_barrier()
; #define PG8_WAIT_V(n) asm volatile("s_waitcnt vmcnt(" #n ")" ::: "memory")
; #define PG8_BAR __builtin_amdgcn_s_barrier()
; template <class Epi>
; DI void gemm_phase(LAS unsigned char* lds, const Gemm g, const StaticOrder S, const Epi E) {
;     ...
;         E(acc, cur, wr, wc, fr, fq);
;         if (!has_next) break;
; #pragma unroll
;         for (int a = 0; a < 2; ++a)
; #pragma unroll
;             for (int b = 0; b < 2; ++b)
; #pragma unroll
;                 for (int m = 0; m < 4; ++m)
; #pragma unroll
;                     for (int n = 0; n < 2; ++n) acc[a][b][m][n] = (f32x4){0.f, 0.f, 0.f, 0.f};
;         cur = nxt; cA = nA; cB = nB; ++ui;
;     }
;     PG8_WAIT_V(0);
;     if (wr == 0) PG8_BAR;
;     PG8_BAR;
;     DI void operator()(AccRef acc, const Unit& u, int wr, int wc, int fr, int fq) const {
;     ...
;             for (int m = 0; m < 4; ++m) {
;                 const int row = row0 + ai * 128 + m * 16;
;                 const float r = RS ? rsc.r[ai][m] : 1.0f;
;                 const f32x4 a0 = acc[ai][0][m][0] * r, a1 = acc[ai][0][m][1] * r, b0 = acc[ai][1][m][0] * r, b1 = acc[ai][1][m][1] * r;
;                 u32x4 w;
;                 w.x = pk_bf16(fast_silu(a0[0]) * b0[0], fast_silu(a0[1]) * b0[1]); w.y = pk_bf16(fast_silu(a0[2]) * b0[2], fast_silu(a0[3]) * b0[3]);
;                 w.z = pk_bf16(fast_silu(a1[0]) * b1[0], fast_silu(a1[1]) * b1[1]); w.w = pk_bf16(fast_silu(a1[2]) * b1[2], fast_silu(a1[3]) * b1[3]);
;                 *(u32x4*)(G + (size_t)row * DFF + col) = w;
	v_rcp_f32_e32 v33, v33
	v_add_f32_e32 v50, 1.0, v50
	v_add_f32_e32 v51, 1.0, v51
	v_rcp_f32_e32 v50, v50
	v_rcp_f32_e32 v51, v51
	v_pk_mul_f32 v[32:33], v[44:45], v[32:33]
	v_pk_mul_f32 v[40:41], v[40:41], v[152:153] op_sel_hi:[1,0]
	v_pk_mul_f32 v[32:33], v[36:37], v[32:33]
	v_pk_mul_f32 v[38:39], v[38:39], v[152:153] op_sel_hi:[1,0]
	v_cvt_pk_bf16_f32 v32, v32, v33
	v_pk_mul_f32 v[36:37], v[46:47], v[50:51]
	v_mul_f32_e32 v33, 0xbfb8aa3b, v40
	v_pk_mul_f32 v[36:37], v[38:39], v[36:37]
	v_exp_f32_e32 v38, v33
	v_mul_f32_e32 v33, 0xbfb8aa3b, v41
	v_exp_f32_e32 v39, v33
	v_pk_mul_f32 v[42:43], v[42:43], v[152:153] op_sel_hi:[1,0]
	v_cvt_pk_bf16_f32 v33, v36, v37
	v_add_f32_e32 v36, 1.0, v38
	v_add_f32_e32 v37, 1.0, v39
	v_mul_f32_e32 v38, 0xbfb8aa3b, v42
	v_mul_f32_e32 v39, 0xbfb8aa3b, v43
	v_exp_f32_e32 v38, v38
	v_exp_f32_e32 v39, v39
	v_rcp_f32_e32 v36, v36
	v_rcp_f32_e32 v37, v37
	v_add_f32_e32 v38, 1.0, v38
	v_add_f32_e32 v39, 1.0, v39
	v_rcp_f32_e32 v38, v38
	v_rcp_f32_e32 v39, v39
	v_pk_mul_f32 v[36:37], v[40:41], v[36:37]
	v_add_u32_e32 v52, 0x90, v146
	v_pk_mul_f32 v[34:35], v[34:35], v[36:37]
	v_pk_mul_f32 v[36:37], v[42:43], v[38:39]
	v_cvt_pk_bf16_f32 v34, v34, v35
	v_pk_mul_f32 v[36:37], v[48:49], v[36:37]
	v_pk_mul_f32 v[28:29], v[28:29], v[150:151] op_sel_hi:[1,0]
	v_cvt_pk_bf16_f32 v35, v36, v37
	v_mad_i64_i32 v[36:37], s[4:5], v52, s52, v[144:145]
	global_store_dwordx4 v[36:37], v[32:35], off
	v_pk_mul_f32 v[30:31], v[30:31], v[150:151] op_sel_hi:[1,0]
	v_pk_mul_f32 v[20:21], v[20:21], v[150:151] op_sel_hi:[1,0]
	v_pk_mul_f32 v[32:33], v[18:19], v[150:151] op_sel_hi:[1,0]
	v_mul_f32_e32 v18, 0xbfb8aa3b, v28
	v_exp_f32_e32 v34, v18
	v_mul_f32_e32 v18, 0xbfb8aa3b, v29
	v_exp_f32_e32 v35, v18
	v_pk_mul_f32 v[18:19], v[16:17], v[150:151] op_sel_hi:[1,0]
	v_add_f32_e32 v16, 1.0, v34
	v_mul_f32_e32 v34, 0xbfb8aa3b, v30
	v_add_f32_e32 v17, 1.0, v35
	v_mul_f32_e32 v35, 0xbfb8aa3b, v31
	v_exp_f32_e32 v34, v34
	v_exp_f32_e32 v35, v35
	v_rcp_f32_e32 v16, v16
	v_rcp_f32_e32 v17, v17
	v_add_f32_e32 v34, 1.0, v34
	v_add_f32_e32 v35, 1.0, v35
	v_rcp_f32_e32 v34, v34
	v_rcp_f32_e32 v35, v35
	v_pk_mul_f32 v[16:17], v[28:29], v[16:17]
	v_pk_mul_f32 v[24:25], v[24:25], v[150:151] op_sel_hi:[1,0]
	v_pk_mul_f32 v[16:17], v[20:21], v[16:17]
	v_pk_mul_f32 v[22:23], v[22:23], v[150:151] op_sel_hi:[1,0]
	v_cvt_pk_bf16_f32 v16, v16, v17
	v_pk_mul_f32 v[20:21], v[30:31], v[34:35]
	v_mul_f32_e32 v17, 0xbfb8aa3b, v24
	v_pk_mul_f32 v[20:21], v[22:23], v[20:21]
	v_exp_f32_e32 v22, v17
	v_mul_f32_e32 v17, 0xbfb8aa3b, v25
	v_exp_f32_e32 v23, v17
	v_pk_mul_f32 v[26:27], v[26:27], v[150:151] op_sel_hi:[1,0]
	v_cvt_pk_bf16_f32 v17, v20, v21
	v_add_f32_e32 v20, 1.0, v22
	v_add_f32_e32 v21, 1.0, v23
	v_mul_f32_e32 v22, 0xbfb8aa3b, v26
	v_mul_f32_e32 v23, 0xbfb8aa3b, v27
	v_exp_f32_e32 v22, v22
	v_exp_f32_e32 v23, v23
	v_rcp_f32_e32 v20, v20
	v_rcp_f32_e32 v21, v21
	v_add_f32_e32 v22, 1.0, v22
	v_add_f32_e32 v23, 1.0, v23
	v_rcp_f32_e32 v22, v22
	v_rcp_f32_e32 v23, v23
	v_pk_mul_f32 v[20:21], v[24:25], v[20:21]
	v_add_u32_e32 v36, 0xa0, v146
	v_pk_mul_f32 v[18:19], v[18:19], v[20:21]
	v_pk_mul_f32 v[20:21], v[26:27], v[22:23]
	v_cvt_pk_bf16_f32 v18, v18, v19
	v_pk_mul_f32 v[20:21], v[32:33], v[20:21]
	v_pk_mul_f32 v[12:13], v[12:13], v[148:149] op_sel_hi:[1,0]
	v_cvt_pk_bf16_f32 v19, v20, v21
	v_mad_i64_i32 v[20:21], s[4:5], v36, s52, v[144:145]
	global_store_dwordx4 v[20:21], v[16:19], off
	v_pk_mul_f32 v[14:15], v[14:15], v[148:149] op_sel_hi:[1,0]
	v_pk_mul_f32 v[4:5], v[4:5], v[148:149] op_sel_hi:[1,0]
	v_pk_mul_f32 v[16:17], v[2:3], v[148:149] op_sel_hi:[1,0]
	v_mul_f32_e32 v2, 0xbfb8aa3b, v12
	v_exp_f32_e32 v18, v2
	v_mul_f32_e32 v2, 0xbfb8aa3b, v13
	v_exp_f32_e32 v19, v2
	v_pk_mul_f32 v[2:3], v[0:1], v[148:149] op_sel_hi:[1,0]
	v_add_f32_e32 v0, 1.0, v18
	v_mul_f32_e32 v18, 0xbfb8aa3b, v14
	v_add_f32_e32 v1, 1.0, v19
	v_mul_f32_e32 v19, 0xbfb8aa3b, v15
	v_exp_f32_e32 v18, v18
	v_exp_f32_e32 v19, v19
	v_rcp_f32_e32 v0, v0
	v_rcp_f32_e32 v1, v1
	v_add_f32_e32 v18, 1.0, v18
	v_add_f32_e32 v19, 1.0, v19
	v_rcp_f32_e32 v18, v18
	v_rcp_f32_e32 v19, v19
	v_pk_mul_f32 v[0:1], v[12:13], v[0:1]
	v_pk_mul_f32 v[8:9], v[8:9], v[148:149] op_sel_hi:[1,0]
	v_pk_mul_f32 v[0:1], v[4:5], v[0:1]
	v_pk_mul_f32 v[6:7], v[6:7], v[148:149] op_sel_hi:[1,0]
	v_cvt_pk_bf16_f32 v0, v0, v1
	v_pk_mul_f32 v[4:5], v[14:15], v[18:19]
	v_mul_f32_e32 v1, 0xbfb8aa3b, v8
	v_pk_mul_f32 v[4:5], v[6:7], v[4:5]
	v_exp_f32_e32 v6, v1
	v_mul_f32_e32 v1, 0xbfb8aa3b, v9
	v_exp_f32_e32 v7, v1
	v_pk_mul_f32 v[10:11], v[10:11], v[148:149] op_sel_hi:[1,0]
	v_cvt_pk_bf16_f32 v1, v4, v5
	v_add_f32_e32 v4, 1.0, v6
	v_add_f32_e32 v5, 1.0, v7
	v_mul_f32_e32 v6, 0xbfb8aa3b, v10
	v_mul_f32_e32 v7, 0xbfb8aa3b, v11
	v_exp_f32_e32 v6, v6
	v_exp_f32_e32 v7, v7
	v_rcp_f32_e32 v4, v4
	v_rcp_f32_e32 v5, v5
	v_add_f32_e32 v6, 1.0, v6
	v_add_f32_e32 v7, 1.0, v7
	v_rcp_f32_e32 v6, v6
	v_rcp_f32_e32 v7, v7
	v_pk_mul_f32 v[4:5], v[8:9], v[4:5]
	v_add_u32_e32 v20, 0xb0, v146
	v_pk_mul_f32 v[2:3], v[2:3], v[4:5]
	v_pk_mul_f32 v[4:5], v[10:11], v[6:7]
	v_cvt_pk_bf16_f32 v2, v2, v3
	v_pk_mul_f32 v[4:5], v[16:17], v[4:5]
	s_and_b64 vcc, exec, s[0:1]
	v_cvt_pk_bf16_f32 v3, v4, v5
	v_mad_i64_i32 v[4:5], s[4:5], v20, s52, v[144:145]
	s_mov_b32 s5, s24
	s_mov_b32 s4, s28
	s_mov_b64 s[10:11], s[38:39]
	s_mov_b64 s[8:9], s[36:37]
	global_store_dwordx4 v[4:5], v[0:3], off
	s_cbranch_vccz .LBB0_862
	s_waitcnt vmcnt(0)
	s_cmpk_gt_u32 s6, 0xff
	s_cbranch_scc1 .LBB0_869
	s_barrier

; #define PG8_STAGE(bufoff, gbase, voff) do { _Pragma("unroll") for (int _i = 0; _i < 2; ++_i) \
;         __builtin_amdgcn_global_load_lds((const unsigned*)((const char*)(gbase) + (voff)[_i]), (LAS unsigned*)(lds + (bufoff) + ldsw + _i * 8192), 16, 0, 0); } while (0)
; #define PG8_LDA(dst, b, h) do { _Pragma("unroll") for (int m = 0; m < 4; ++m) _Pragma("unroll") for (int k = 0; k < 2; ++k) dst[m][k] = *(const LAS bf16x8*)(lds + PG8_SA(b, h) + aoff + m * 2048 + k * 1024); } while (0)
; #define PG8_LDB(dst, b, h) do { _Pragma("unroll") for (int n = 0; n < 2; ++n) _Pragma("unroll") for (int k = 0; k < 2; ++k) dst[n][k] = *(const LAS bf16x8*)(lds + PG8_SB(b, h) + boff + n * 2048 + k * 1024); } while (0)
; #define PG8_MMA(ai, bj, At, Bt) do { __builtin_amdgcn_s_setprio(1); _Pragma("unroll") for (int m = 0; m < 4; ++m) _Pragma("unroll") for (int n = 0; n < 2; ++n) _Pragma("unroll") for (int k = 0; k < 2; ++k) \
;         acc[ai][bj][m][n] = __builtin_amdgcn_mfma_f32_16x16x32_bf16(Bt[n][k], At[m][k], acc[ai][bj][m][n], 0, 0, 0); __builtin_amdgcn_s_setprio(0); } while (0)
; #define PG8_WAIT_V(n) asm volatile("s_waitcnt vmcnt(" #n ")" ::: "memory")
; #define PG8_WAIT_L(n) asm volatile("s_waitcnt lgkmcnt(" #n ")" ::: "memory")
; #define PG8_BAR __builtin_amdgcn_s_barrier()
; #define PG8_SCHED __builtin_amdgcn_sched_barrier(0)
; template <class Epi>
; DI void gemm_phase(LAS unsigned char* lds, const Gemm g, const StaticOrder S, const Epi E) {
;     ...
;             const bool last = (t == nt - 2);
;             const char* a1 = cA + (size_t)(t + 1) * kstep;
;             const char* a2 = last ? nA : cA + (size_t)(t + 2) * kstep; const char* b2 = last ? nB : cB + (size_t)(t + 2) * kstep;
;             const char* a3 = a2 + kstep; const char* b3 = b2 + kstep;
;             PG8_LDB(B0, 0, 0); PG8_SCHED; PG8_LDA(At, 0, 0); PG8_STAGE(PG8_SA(1, 1), a1 + hstep, voffA);
;             PG8_WAIT_L(8); PG8_BAR; PG8_WAIT_L(0); PG8_MMA(0, 0, At, B0); PG8_BAR; PG8_SCHED;
;             PG8_LDB(B1, 0, 1); PG8_STAGE(PG8_SB(0, 0), b2, voffB);
;             PG8_BAR; PG8_WAIT_L(0); PG8_MMA(0, 1, At, B1); PG8_BAR;
;             PG8_LDA(At, 0, 1); PG8_STAGE(PG8_SA(0, 0), a2, voffA);
;             PG8_BAR; PG8_WAIT_L(0); PG8_MMA(1, 0, At, B0); PG8_BAR; PG8_SCHED;
;             PG8_STAGE(PG8_SB(0, 1), b2 + hstep, voffB);
;             PG8_WAIT_V(6); PG8_BAR; PG8_MMA(1, 1, At, B1); PG8_BAR;
.LBB0_941:
	ds_read_b128 v[144:147], v199
	ds_read_b128 v[148:151], v199 offset:1024
	ds_read_b128 v[152:155], v199 offset:2048
	ds_read_b128 v[156:159], v199 offset:3072
	s_add_u32 s22, s20, 0x100
	s_addc_u32 s23, s21, 0
	s_cmp_eq_u32 s58, 40
	s_cselect_b32 s27, s9, s23
	s_cselect_b32 s26, s8, s22
	s_cselect_b32 s25, s5, s53
	s_cselect_b32 s24, s4, s52
	v_lshl_add_u64 v[192:193], s[20:21], 0, v[136:137]
	s_add_i32 m0, s33, 0xc000
	ds_read_b128 v[160:163], v200
	ds_read_b128 v[168:171], v200 offset:2048
	ds_read_b128 v[176:179], v200 offset:4096
	ds_read_b128 v[184:187], v200 offset:6144
	global_load_lds_dwordx4 v[192:193], off
	v_lshl_add_u64 v[192:193], s[20:21], 0, v[138:139]
	s_add_i32 m0, s33, 0xe000
	s_nop 0
	global_load_lds_dwordx4 v[192:193], off
	s_waitcnt lgkmcnt(4)
	s_setprio 1
	s_barrier
	ds_read_b128 v[164:167], v200 offset:1024
	ds_read_b128 v[172:175], v200 offset:3072
	ds_read_b128 v[180:183], v200 offset:5120
	ds_read_b128 v[188:191], v200 offset:7168
	s_waitcnt lgkmcnt(4)
	v_mfma_f32_16x16x32_bf16 v[124:127], v[144:147], v[160:163], v[124:127]
	v_mfma_f32_16x16x32_bf16 v[120:123], v[152:155], v[160:163], v[120:123]
	v_mfma_f32_16x16x32_bf16 v[108:111], v[144:147], v[168:171], v[108:111]
	v_mfma_f32_16x16x32_bf16 v[104:107], v[152:155], v[168:171], v[104:107]
	v_mfma_f32_16x16x32_bf16 v[92:95], v[144:147], v[176:179], v[92:95]
	v_mfma_f32_16x16x32_bf16 v[88:91], v[152:155], v[176:179], v[88:91]
	v_mfma_f32_16x16x32_bf16 v[84:87], v[144:147], v[184:187], v[84:87]
	v_mfma_f32_16x16x32_bf16 v[76:79], v[152:155], v[184:187], v[76:79]
	s_waitcnt lgkmcnt(3)
	v_mfma_f32_16x16x32_bf16 v[124:127], v[148:151], v[164:167], v[124:127]
	v_mfma_f32_16x16x32_bf16 v[120:123], v[156:159], v[164:167], v[120:123]
	s_waitcnt lgkmcnt(2)
	v_mfma_f32_16x16x32_bf16 v[108:111], v[148:151], v[172:175], v[108:111]
	v_mfma_f32_16x16x32_bf16 v[104:107], v[156:159], v[172:175], v[104:107]
	s_waitcnt lgkmcnt(1)
	v_mfma_f32_16x16x32_bf16 v[92:95], v[148:151], v[180:183], v[92:95]
	v_mfma_f32_16x16x32_bf16 v[88:91], v[156:159], v[180:183], v[88:91]
	s_waitcnt lgkmcnt(0)
	s_setprio 2
	s_barrier
	v_mfma_f32_16x16x32_bf16 v[84:87], v[148:151], v[188:191], v[84:87]
	v_mfma_f32_16x16x32_bf16 v[76:79], v[156:159], v[188:191], v[76:79]
	s_setprio 0
	s_add_i32 s20, s42, s29
	v_lshl_add_u64 v[214:215], s[24:25], 0, v[130:131]
	s_mov_b32 m0, s20
	ds_read_b128 v[192:195], v201
	ds_read_b128 v[202:205], v201 offset:1024
	ds_read_b128 v[206:209], v201 offset:2048
	ds_read_b128 v[210:213], v201 offset:3072
	global_load_lds_dwordx4 v[214:215], off
	v_lshl_add_u64 v[216:217], s[24:25], 0, v[134:135]
	s_add_i32 m0, s20, 0x2000
	s_nop 0
	global_load_lds_dwordx4 v[216:217], off
	s_setprio 1
	s_barrier
	s_waitcnt lgkmcnt(0)
	v_mfma_f32_16x16x32_bf16 v[116:119], v[192:195], v[160:163], v[116:119]
	v_mfma_f32_16x16x32_bf16 v[112:115], v[206:209], v[160:163], v[112:115]
	v_mfma_f32_16x16x32_bf16 v[100:103], v[192:195], v[168:171], v[100:103]
	v_mfma_f32_16x16x32_bf16 v[96:99], v[206:209], v[168:171], v[96:99]
	v_mfma_f32_16x16x32_bf16 v[80:83], v[192:195], v[176:179], v[80:83]
	v_mfma_f32_16x16x32_bf16 v[72:75], v[206:209], v[176:179], v[72:75]
	v_mfma_f32_16x16x32_bf16 v[68:71], v[192:195], v[184:187], v[68:71]
	v_mfma_f32_16x16x32_bf16 v[64:67], v[206:209], v[184:187], v[64:67]
	v_mfma_f32_16x16x32_bf16 v[116:119], v[202:205], v[164:167], v[116:119]
	v_mfma_f32_16x16x32_bf16 v[112:115], v[210:213], v[164:167], v[112:115]
	v_mfma_f32_16x16x32_bf16 v[100:103], v[202:205], v[172:175], v[100:103]
	v_mfma_f32_16x16x32_bf16 v[96:99], v[210:213], v[172:175], v[96:99]
	v_mfma_f32_16x16x32_bf16 v[80:83], v[202:205], v[180:183], v[80:83]
	s_setprio 2
	s_barrier
	v_mfma_f32_16x16x32_bf16 v[72:75], v[210:213], v[180:183], v[72:75]
	v_mfma_f32_16x16x32_bf16 v[68:71], v[202:205], v[188:191], v[68:71]
	v_mfma_f32_16x16x32_bf16 v[64:67], v[210:213], v[188:191], v[64:67]
	s_setprio 0
	s_mov_b32 m0, s33
	v_lshl_add_u64 v[218:219], s[26:27], 0, v[128:129]
	ds_read_b128 v[160:163], v200 offset:16384
	ds_read_b128 v[168:171], v200 offset:18432
	ds_read_b128 v[176:179], v200 offset:20480
	ds_read_b128 v[184:187], v200 offset:22528
	global_load_lds_dwordx4 v[218:219], off
	v_lshl_add_u64 v[220:221], s[26:27], 0, v[132:133]
	s_mov_b32 m0, s34
	s_nop 0
	global_load_lds_dwordx4 v[220:221], off
	s_setprio 1
	s_barrier
	ds_read_b128 v[164:167], v200 offset:17408
	ds_read_b128 v[172:175], v200 offset:19456
	ds_read_b128 v[180:183], v200 offset:21504
	ds_read_b128 v[188:191], v200 offset:23552
	s_waitcnt lgkmcnt(4)
	v_mfma_f32_16x16x32_bf16 v[60:63], v[144:147], v[160:163], v[60:63]
	v_mfma_f32_16x16x32_bf16 v[56:59], v[152:155], v[160:163], v[56:59]
	v_mfma_f32_16x16x32_bf16 v[48:51], v[144:147], v[168:171], v[48:51]
	v_mfma_f32_16x16x32_bf16 v[40:43], v[152:155], v[168:171], v[40:43]
	v_mfma_f32_16x16x32_bf16 v[32:35], v[144:147], v[176:179], v[32:35]
	v_mfma_f32_16x16x32_bf16 v[24:27], v[152:155], v[176:179], v[24:27]
	v_mfma_f32_16x16x32_bf16 v[16:19], v[144:147], v[184:187], v[16:19]
	v_mfma_f32_16x16x32_bf16 v[8:11], v[152:155], v[184:187], v[8:11]
	s_waitcnt lgkmcnt(3)
	v_mfma_f32_16x16x32_bf16 v[60:63], v[148:151], v[164:167], v[60:63]
	v_mfma_f32_16x16x32_bf16 v[56:59], v[156:159], v[164:167], v[56:59]
	s_waitcnt lgkmcnt(2)
	v_mfma_f32_16x16x32_bf16 v[48:51], v[148:151], v[172:175], v[48:51]
	v_mfma_f32_16x16x32_bf16 v[40:43], v[156:159], v[172:175], v[40:43]
	s_waitcnt lgkmcnt(1)
	v_mfma_f32_16x16x32_bf16 v[32:35], v[148:151], v[180:183], v[32:35]
	v_mfma_f32_16x16x32_bf16 v[24:27], v[156:159], v[180:183], v[24:27]
	s_waitcnt lgkmcnt(0)
	s_setprio 2
	s_barrier
; #define PG8_STAGE(bufoff, gbase, voff) do { _Pragma("unroll") for (int _i = 0; _i < 2; ++_i) \
;         __builtin_amdgcn_global_load_lds((const unsigned*)((const char*)(gbase) + (voff)[_i]), (LAS unsigned*)(lds + (bufoff) + ldsw + _i * 8192), 16, 0, 0); } while (0)
; #define PG8_LDA(dst, b, h) do { _Pragma("unroll") for (int m = 0; m < 4; ++m) _Pragma("unroll") for (int k = 0; k < 2; ++k) dst[m][k] = *(const LAS bf16x8*)(lds + PG8_SA(b, h) + aoff + m * 2048 + k * 1024); } while (0)
; #define PG8_LDB(dst, b, h) do { _Pragma("unroll") for (int n = 0; n < 2; ++n) _Pragma("unroll") for (int k = 0; k < 2; ++k) dst[n][k] = *(const LAS bf16x8*)(lds + PG8_SB(b, h) + boff + n * 2048 + k * 1024); } while (0)
; #define PG8_MMA(ai, bj, At, Bt) do { __builtin_amdgcn_s_setprio(1); _Pragma("unroll") for (int m = 0; m < 4; ++m) _Pragma("unroll") for (int n = 0; n < 2; ++n) _Pragma("unroll") for (int k = 0; k < 2; ++k) \
;         acc[ai][bj][m][n] = __builtin_amdgcn_mfma_f32_16x16x32_bf16(Bt[n][k], At[m][k], acc[ai][bj][m][n], 0, 0, 0); __builtin_amdgcn_s_setprio(0); } while (0)
; #define PG8_WAIT_V(n) asm volatile("s_waitcnt vmcnt(" #n ")" ::: "memory")
; #define PG8_WAIT_L(n) asm volatile("s_waitcnt lgkmcnt(" #n ")" ::: "memory")
; #define PG8_BAR __builtin_amdgcn_s_barrier()
; #define PG8_SCHED __builtin_amdgcn_sched_barrier(0)
; #define PG8_LDA(dst, b, h) do { _Pragma("unroll") for (int m = 0; m < 4; ++m) _Pragma("unroll") for (int k = 0; k < 2; ++k) dst[m][k] = *(const LAS bf16x8*)(lds + PG8_SA(b, h) + aoff + m * 2048 + k * 1024); } while (0)
; template <class Epi>
; DI void gemm_phase(LAS unsigned char* lds, const Gemm g, const StaticOrder S, const Epi E) {
;     ...
;             PG8_BAR; PG8_WAIT_L(0); PG8_MMA(1, 0, At, B0); PG8_BAR; PG8_SCHED;
;             PG8_STAGE(PG8_SB(0, 1), b2 + hstep, voffB);
;             PG8_WAIT_V(6); PG8_BAR; PG8_MMA(1, 1, At, B1); PG8_BAR;
;             PG8_LDB(B0, 1, 0); PG8_SCHED; PG8_LDA(At, 1, 0); PG8_STAGE(PG8_SA(0, 1), a2 + hstep, voffA);
;             PG8_WAIT_L(8); PG8_BAR; PG8_WAIT_L(0); PG8_MMA(0, 0, At, B0); PG8_BAR; PG8_SCHED;
;             PG8_LDB(B1, 1, 1); PG8_STAGE(PG8_SB(1, 0), b3, voffB);
;             PG8_BAR; PG8_WAIT_L(0); PG8_MMA(0, 1, At, B1); PG8_BAR;
;             PG8_LDA(At, 1, 1); PG8_STAGE(PG8_SA(1, 0), a3, voffA);
;             PG8_BAR; PG8_WAIT_L(0); PG8_MMA(1, 0, At, B0); PG8_BAR; PG8_SCHED;
	v_mfma_f32_16x16x32_bf16 v[16:19], v[148:151], v[188:191], v[16:19]
	v_mfma_f32_16x16x32_bf16 v[8:11], v[156:159], v[188:191], v[8:11]
	s_setprio 0
	s_add_u32 s20, s24, 0xb0000
	s_addc_u32 s21, s25, 0
	s_add_i32 s59, s43, s29
	v_lshl_add_u64 v[144:145], s[20:21], 0, v[130:131]
	s_mov_b32 m0, s59
	s_nop 0
	global_load_lds_dwordx4 v[144:145], off
	v_lshl_add_u64 v[144:145], s[20:21], 0, v[134:135]
	s_add_i32 m0, s59, 0x2000
	s_nop 0
	global_load_lds_dwordx4 v[144:145], off
	s_waitcnt vmcnt(6)
	s_setprio 1
	s_barrier
	v_mfma_f32_16x16x32_bf16 v[52:55], v[192:195], v[160:163], v[52:55]
	v_mfma_f32_16x16x32_bf16 v[44:47], v[206:209], v[160:163], v[44:47]
	v_mfma_f32_16x16x32_bf16 v[36:39], v[192:195], v[168:171], v[36:39]
	v_mfma_f32_16x16x32_bf16 v[28:31], v[206:209], v[168:171], v[28:31]
	v_mfma_f32_16x16x32_bf16 v[20:23], v[192:195], v[176:179], v[20:23]
	v_mfma_f32_16x16x32_bf16 v[12:15], v[206:209], v[176:179], v[12:15]
	v_mfma_f32_16x16x32_bf16 v[4:7], v[192:195], v[184:187], v[4:7]
	v_mfma_f32_16x16x32_bf16 v[0:3], v[206:209], v[184:187], v[0:3]
	v_mfma_f32_16x16x32_bf16 v[52:55], v[202:205], v[164:167], v[52:55]
	v_mfma_f32_16x16x32_bf16 v[44:47], v[210:213], v[164:167], v[44:47]
	v_mfma_f32_16x16x32_bf16 v[36:39], v[202:205], v[172:175], v[36:39]
	v_mfma_f32_16x16x32_bf16 v[28:31], v[210:213], v[172:175], v[28:31]
	v_mfma_f32_16x16x32_bf16 v[20:23], v[202:205], v[180:183], v[20:23]
	s_setprio 2
	s_barrier
	v_mfma_f32_16x16x32_bf16 v[12:15], v[210:213], v[180:183], v[12:15]
	v_mfma_f32_16x16x32_bf16 v[4:7], v[202:205], v[188:191], v[4:7]
	v_mfma_f32_16x16x32_bf16 v[0:3], v[210:213], v[188:191], v[0:3]
	s_setprio 0
	s_add_i32 s59, 0, 0x18000
	v_add_u32_e32 v156, s59, v197
	ds_read_b128 v[144:147], v156
	ds_read_b128 v[148:151], v156 offset:1024
	ds_read_b128 v[152:155], v156 offset:2048
	ds_read_b128 v[156:159], v156 offset:3072
	s_add_u32 s20, s26, 0xb0000
	s_addc_u32 s21, s27, 0
	s_mov_b32 m0, s35
	v_lshl_add_u64 v[192:193], s[20:21], 0, v[128:129]
	ds_read_b128 v[160:163], v200 offset:32768
	ds_read_b128 v[168:171], v200 offset:34816
	ds_read_b128 v[176:179], v200 offset:36864
	ds_read_b128 v[184:187], v200 offset:38912
	global_load_lds_dwordx4 v[192:193], off
	v_lshl_add_u64 v[192:193], s[20:21], 0, v[132:133]
	s_mov_b32 m0, s36
	s_nop 0
	global_load_lds_dwordx4 v[192:193], off
	s_waitcnt lgkmcnt(4)
	s_setprio 1
	s_barrier
	ds_read_b128 v[164:167], v200 offset:33792
	ds_read_b128 v[172:175], v200 offset:35840
	ds_read_b128 v[180:183], v200 offset:37888
	ds_read_b128 v[188:191], v200 offset:39936
	s_waitcnt lgkmcnt(4)
	v_mfma_f32_16x16x32_bf16 v[124:127], v[144:147], v[160:163], v[124:127]
	v_mfma_f32_16x16x32_bf16 v[120:123], v[152:155], v[160:163], v[120:123]
	v_mfma_f32_16x16x32_bf16 v[108:111], v[144:147], v[168:171], v[108:111]
	v_mfma_f32_16x16x32_bf16 v[104:107], v[152:155], v[168:171], v[104:107]
	v_mfma_f32_16x16x32_bf16 v[92:95], v[144:147], v[176:179], v[92:95]
	v_mfma_f32_16x16x32_bf16 v[88:91], v[152:155], v[176:179], v[88:91]
	v_mfma_f32_16x16x32_bf16 v[84:87], v[144:147], v[184:187], v[84:87]
	v_mfma_f32_16x16x32_bf16 v[76:79], v[152:155], v[184:187], v[76:79]
	s_waitcnt lgkmcnt(3)
	v_mfma_f32_16x16x32_bf16 v[124:127], v[148:151], v[164:167], v[124:127]
	v_mfma_f32_16x16x32_bf16 v[120:123], v[156:159], v[164:167], v[120:123]
	s_waitcnt lgkmcnt(2)
	v_mfma_f32_16x16x32_bf16 v[108:111], v[148:151], v[172:175], v[108:111]
	v_mfma_f32_16x16x32_bf16 v[104:107], v[156:159], v[172:175], v[104:107]
	s_waitcnt lgkmcnt(1)
	v_mfma_f32_16x16x32_bf16 v[92:95], v[148:151], v[180:183], v[92:95]
	v_mfma_f32_16x16x32_bf16 v[88:91], v[156:159], v[180:183], v[88:91]
	s_waitcnt lgkmcnt(0)
	s_setprio 2
	s_barrier
	v_mfma_f32_16x16x32_bf16 v[84:87], v[148:151], v[188:191], v[84:87]
	v_mfma_f32_16x16x32_bf16 v[76:79], v[156:159], v[188:191], v[76:79]
	s_setprio 0
	s_add_i32 s26, 0, 0x1c000
	s_add_i32 s20, s59, s29
	v_add_u32_e32 v210, s26, v197
	v_lshl_add_u64 v[214:215], v[214:215], 0, s[10:11]
	s_mov_b32 m0, s20
	ds_read_b128 v[192:195], v210
	ds_read_b128 v[202:205], v210 offset:1024
	ds_read_b128 v[206:209], v210 offset:2048
	ds_read_b128 v[210:213], v210 offset:3072
	global_load_lds_dwordx4 v[214:215], off
	v_lshl_add_u64 v[214:215], v[216:217], 0, s[10:11]
	s_add_i32 m0, s20, 0x2000
	s_nop 0
	global_load_lds_dwordx4 v[214:215], off
	s_setprio 1
	s_barrier
	s_waitcnt lgkmcnt(0)
	v_mfma_f32_16x16x32_bf16 v[116:119], v[192:195], v[160:163], v[116:119]
	v_mfma_f32_16x16x32_bf16 v[112:115], v[206:209], v[160:163], v[112:115]
	v_mfma_f32_16x16x32_bf16 v[100:103], v[192:195], v[168:171], v[100:103]
	v_mfma_f32_16x16x32_bf16 v[96:99], v[206:209], v[168:171], v[96:99]
	v_mfma_f32_16x16x32_bf16 v[80:83], v[192:195], v[176:179], v[80:83]
	v_mfma_f32_16x16x32_bf16 v[72:75], v[206:209], v[176:179], v[72:75]
	v_mfma_f32_16x16x32_bf16 v[68:71], v[192:195], v[184:187], v[68:71]
	v_mfma_f32_16x16x32_bf16 v[64:67], v[206:209], v[184:187], v[64:67]
	v_mfma_f32_16x16x32_bf16 v[116:119], v[202:205], v[164:167], v[116:119]
	v_mfma_f32_16x16x32_bf16 v[112:115], v[210:213], v[164:167], v[112:115]
	v_mfma_f32_16x16x32_bf16 v[100:103], v[202:205], v[172:175], v[100:103]
	v_mfma_f32_16x16x32_bf16 v[96:99], v[210:213], v[172:175], v[96:99]
	v_mfma_f32_16x16x32_bf16 v[80:83], v[202:205], v[180:183], v[80:83]
	s_setprio 2
	s_barrier
	v_mfma_f32_16x16x32_bf16 v[72:75], v[210:213], v[180:183], v[72:75]
	v_mfma_f32_16x16x32_bf16 v[68:71], v[202:205], v[188:191], v[68:71]
	v_mfma_f32_16x16x32_bf16 v[64:67], v[210:213], v[188:191], v[64:67]
	s_setprio 0
	s_mov_b32 m0, s38
	v_lshl_add_u64 v[214:215], v[218:219], 0, s[10:11]
	ds_read_b128 v[160:163], v200 offset:49152
	ds_read_b128 v[168:171], v200 offset:51200
	ds_read_b128 v[176:179], v200 offset:53248
	ds_read_b128 v[184:187], v200 offset:55296
	global_load_lds_dwordx4 v[214:215], off
	v_lshl_add_u64 v[214:215], v[220:221], 0, s[10:11]
	s_mov_b32 m0, s39
	s_nop 0
	global_load_lds_dwordx4 v[214:215], off
	s_setprio 1
	s_barrier
; DI f32x4 bf_lo4(u32x4 w) { f32x4 r; r[0] = bf_lo(w.x); r[1] = bf_hi(w.x); r[2] = bf_lo(w.y); r[3] = bf_hi(w.y); return r; }
; DI f32x4 bf_hi4(u32x4 w) { f32x4 r; r[0] = bf_lo(w.z); r[1] = bf_hi(w.z); r[2] = bf_lo(w.w); r[3] = bf_hi(w.w); return r; }
; #define PG8_STAGE(bufoff, gbase, voff) do { _Pragma("unroll") for (int _i = 0; _i < 2; ++_i) \
;         __builtin_amdgcn_global_load_lds((const unsigned*)((const char*)(gbase) + (voff)[_i]), (LAS unsigned*)(lds + (bufoff) + ldsw + _i * 8192), 16, 0, 0); } while (0)
; #define PG8_LDA(dst, b, h) do { _Pragma("unroll") for (int m = 0; m < 4; ++m) _Pragma("unroll") for (int k = 0; k < 2; ++k) dst[m][k] = *(const LAS bf16x8*)(lds + PG8_SA(b, h) + aoff + m * 2048 + k * 1024); } while (0)
; #define PG8_MMA(ai, bj, At, Bt) do { __builtin_amdgcn_s_setprio(1); _Pragma("unroll") for (int m = 0; m < 4; ++m) _Pragma("unroll") for (int n = 0; n < 2; ++n) _Pragma("unroll") for (int k = 0; k < 2; ++k) \
;         acc[ai][bj][m][n] = __builtin_amdgcn_mfma_f32_16x16x32_bf16(Bt[n][k], At[m][k], acc[ai][bj][m][n], 0, 0, 0); __builtin_amdgcn_s_setprio(0); } while (0)
; #define PG8_WAIT_V(n) asm volatile("s_waitcnt vmcnt(" #n ")" ::: "memory")
; #define PG8_WAIT_L(n) asm volatile("s_waitcnt lgkmcnt(" #n ")" ::: "memory")
; #define PG8_BAR __builtin_amdgcn_s_barrier()
; template <class Epi>
; DI void gemm_phase(LAS unsigned char* lds, const Gemm g, const StaticOrder S, const Epi E) {
;     ...
;             PG8_LDA(At, 1, 1); PG8_STAGE(PG8_SA(1, 0), a3, voffA);
;             PG8_BAR; PG8_WAIT_L(0); PG8_MMA(1, 0, At, B0); PG8_BAR; PG8_SCHED;
;             PG8_STAGE(PG8_SB(1, 1), b3 + hstep, voffB);
;             PG8_WAIT_V(6); PG8_BAR; PG8_MMA(1, 1, At, B1); PG8_BAR;
;     DI void operator()(AccRef acc, const Unit& u, int wr, int wc, int fr, int fq) const {
;     ...
;         for (int ai = 0; ai < 2; ++ai) {
;             f32x4 bv[4][2][2];
; #pragma unroll
;             for (int m = 0; m < 4; ++m)
; #pragma unroll
;                 for (int bj = 0; bj < 2; ++bj) {
;                     const size_t o = (size_t)(row0 + ai * 128 + m * 16) * DM + col0 + bj * 128;
;                     if (BASEF32) { bv[m][bj][0] = *(const f32x4*)(basef + o); bv[m][bj][1] = *(const f32x4*)(basef + o + 4); }
;                     else { const u32x4 h = *(const u32x4*)(xnb + o); bv[m][bj][0] = bf_lo4(h); bv[m][bj][1] = bf_hi4(h); }
;                 }
	ds_read_b128 v[164:167], v200 offset:50176
	ds_read_b128 v[172:175], v200 offset:52224
	ds_read_b128 v[180:183], v200 offset:54272
	ds_read_b128 v[188:191], v200 offset:56320
	s_waitcnt lgkmcnt(4)
	v_mfma_f32_16x16x32_bf16 v[60:63], v[144:147], v[160:163], v[60:63]
	v_mfma_f32_16x16x32_bf16 v[56:59], v[152:155], v[160:163], v[56:59]
	v_mfma_f32_16x16x32_bf16 v[48:51], v[144:147], v[168:171], v[48:51]
	v_mfma_f32_16x16x32_bf16 v[40:43], v[152:155], v[168:171], v[40:43]
	v_mfma_f32_16x16x32_bf16 v[32:35], v[144:147], v[176:179], v[32:35]
	v_mfma_f32_16x16x32_bf16 v[24:27], v[152:155], v[176:179], v[24:27]
	v_mfma_f32_16x16x32_bf16 v[16:19], v[144:147], v[184:187], v[16:19]
	v_mfma_f32_16x16x32_bf16 v[8:11], v[152:155], v[184:187], v[8:11]
	s_waitcnt lgkmcnt(3)
	v_mfma_f32_16x16x32_bf16 v[60:63], v[148:151], v[164:167], v[60:63]
	v_mfma_f32_16x16x32_bf16 v[56:59], v[156:159], v[164:167], v[56:59]
	s_waitcnt lgkmcnt(2)
	v_mfma_f32_16x16x32_bf16 v[48:51], v[148:151], v[172:175], v[48:51]
	v_mfma_f32_16x16x32_bf16 v[40:43], v[156:159], v[172:175], v[40:43]
	s_waitcnt lgkmcnt(1)
	v_mfma_f32_16x16x32_bf16 v[32:35], v[148:151], v[180:183], v[32:35]
	v_mfma_f32_16x16x32_bf16 v[24:27], v[156:159], v[180:183], v[24:27]
	s_waitcnt lgkmcnt(0)
	s_setprio 2
	s_barrier
	v_mfma_f32_16x16x32_bf16 v[16:19], v[148:151], v[188:191], v[16:19]
	v_mfma_f32_16x16x32_bf16 v[8:11], v[156:159], v[188:191], v[8:11]
	s_setprio 0
	s_add_u32 s20, s24, 0xb0080
	s_addc_u32 s21, s25, 0
	s_add_i32 s24, s26, s29
	v_lshl_add_u64 v[144:145], s[20:21], 0, v[130:131]
	s_mov_b32 m0, s24
	s_nop 0
	global_load_lds_dwordx4 v[144:145], off
	v_lshl_add_u64 v[144:145], s[20:21], 0, v[134:135]
	s_add_i32 m0, s24, 0x2000
	s_nop 0
	global_load_lds_dwordx4 v[144:145], off
	s_waitcnt vmcnt(6)
	s_setprio 1
	s_barrier
	v_mfma_f32_16x16x32_bf16 v[52:55], v[192:195], v[160:163], v[52:55]
	v_mfma_f32_16x16x32_bf16 v[44:47], v[206:209], v[160:163], v[44:47]
	v_mfma_f32_16x16x32_bf16 v[36:39], v[192:195], v[168:171], v[36:39]
	v_mfma_f32_16x16x32_bf16 v[28:31], v[206:209], v[168:171], v[28:31]
	v_mfma_f32_16x16x32_bf16 v[20:23], v[192:195], v[176:179], v[20:23]
	v_mfma_f32_16x16x32_bf16 v[12:15], v[206:209], v[176:179], v[12:15]
	v_mfma_f32_16x16x32_bf16 v[4:7], v[192:195], v[184:187], v[4:7]
	v_mfma_f32_16x16x32_bf16 v[0:3], v[206:209], v[184:187], v[0:3]
	v_mfma_f32_16x16x32_bf16 v[52:55], v[202:205], v[164:167], v[52:55]
	v_mfma_f32_16x16x32_bf16 v[44:47], v[210:213], v[164:167], v[44:47]
	v_mfma_f32_16x16x32_bf16 v[36:39], v[202:205], v[172:175], v[36:39]
	v_mfma_f32_16x16x32_bf16 v[28:31], v[210:213], v[172:175], v[28:31]
	v_mfma_f32_16x16x32_bf16 v[20:23], v[202:205], v[180:183], v[20:23]
	s_setprio 2
	s_barrier
	v_mfma_f32_16x16x32_bf16 v[12:15], v[210:213], v[180:183], v[12:15]
	v_mfma_f32_16x16x32_bf16 v[4:7], v[202:205], v[188:191], v[4:7]
	v_mfma_f32_16x16x32_bf16 v[0:3], v[210:213], v[188:191], v[0:3]
	s_setprio 0
	s_add_i32 s58, s58, 2
	s_add_u32 s52, s52, 0x100
	s_addc_u32 s53, s53, 0
	s_cmp_gt_u32 s58, 41
	s_mov_b64 s[20:21], s[22:23]
	s_cbranch_scc0 .LBB0_941
	v_lshl_add_u32 v148, s50, 8, v196
	v_lshl_or_b32 v144, s51, 8, v198
	v_or_b32_e32 v146, 16, v148
	v_ashrrev_i32_e32 v145, 31, v144
	v_ashrrev_i32_e32 v147, 31, v146
	v_lshl_add_u64 v[176:177], v[144:145], 1, s[56:57]
	v_ashrrev_i32_e32 v149, 31, v148
	v_lshlrev_b64 v[146:147], 11, v[146:147]
	v_lshlrev_b64 v[144:145], 11, v[148:149]
	v_lshl_add_u64 v[150:151], v[176:177], 0, v[146:147]
	v_or_b32_e32 v146, 32, v148
	v_or_b32_e32 v148, 48, v148
	v_ashrrev_i32_e32 v147, 31, v146
	v_ashrrev_i32_e32 v149, 31, v148
	v_lshl_add_u64 v[144:145], v[176:177], 0, v[144:145]
	v_lshlrev_b64 v[146:147], 11, v[146:147]
	v_lshlrev_b64 v[148:149], 11, v[148:149]
	global_load_dwordx4 v[152:155], v[144:145], off
	global_load_dwordx4 v[156:159], v[144:145], off offset:256
	v_lshl_add_u64 v[146:147], v[176:177], 0, v[146:147]
	v_lshl_add_u64 v[148:149], v[176:177], 0, v[148:149]
	global_load_dwordx4 v[160:163], v[150:151], off
	global_load_dwordx4 v[164:167], v[150:151], off offset:256
	global_load_dwordx4 v[168:171], v[146:147], off
	global_load_dwordx4 v[172:175], v[146:147], off offset:256
	global_load_dwordx4 v[202:205], v[148:149], off
	global_load_dwordx4 v[206:209], v[148:149], off offset:256
	s_mov_b32 s51, s48
	s_mov_b32 s50, s49
	s_mov_b64 s[22:23], s[4:5]
	s_mov_b64 s[20:21], s[8:9]
	s_waitcnt vmcnt(0)
; DI unsigned pk_bf16(float lo, float hi) { f32x2 v = {lo, hi}; return __builtin_bit_cast(unsigned, __builtin_convertvector(v, bf16v2)); }
;     DI void operator()(AccRef acc, const Unit& u, int wr, int wc, int fr, int fq) const {
;     ...
;             for (int m = 0; m < 4; ++m) {
;                 const int row = row0 + ai * 128 + m * 16;
;                 float q = 0.f;
; #pragma unroll
;                 for (int bj = 0; bj < 2; ++bj) {
;                     const size_t o = (size_t)row * DM + col0 + bj * 128;
;                     const f32x4 r0 = bv[m][bj][0] + scale * acc[ai][bj][m][0], r1 = bv[m][bj][1] + scale * acc[ai][bj][m][1];
;                     u32x4 w; w.x = pk_bf16(r0[0], r0[1]); w.y = pk_bf16(r0[2], r0[3]); w.z = pk_bf16(r1[0], r1[1]); w.w = pk_bf16(r1[2], r1[3]);
;                     *(u32x4*)(xnb + o) = w;
	v_lshlrev_b32_e32 v214, 16, v154
	v_and_b32_e32 v215, 0xffff0000, v154
	v_lshlrev_b32_e32 v216, 16, v155
	v_and_b32_e32 v217, 0xffff0000, v155
	v_lshlrev_b32_e32 v210, 16, v152
	v_and_b32_e32 v211, 0xffff0000, v152
	v_lshlrev_b32_e32 v212, 16, v153
	v_and_b32_e32 v213, 0xffff0000, v153
	v_lshlrev_b32_e32 v194, 16, v162
	v_and_b32_e32 v195, 0xffff0000, v162
	v_lshlrev_b32_e32 v230, 16, v163
	v_and_b32_e32 v231, 0xffff0000, v163
	v_lshlrev_b32_e32 v154, 16, v202
	v_and_b32_e32 v155, 0xffff0000, v202
	v_lshlrev_b32_e32 v162, 16, v203
	v_and_b32_e32 v163, 0xffff0000, v203
	v_pk_fma_f32 v[202:203], v[122:123], 0.5, v[216:217] op_sel_hi:[1,0,1]
	v_pk_fma_f32 v[122:123], v[120:121], 0.5, v[214:215] op_sel_hi:[1,0,1]
	v_lshlrev_b32_e32 v218, 16, v156
	v_and_b32_e32 v219, 0xffff0000, v156
	v_lshlrev_b32_e32 v220, 16, v157
	v_and_b32_e32 v221, 0xffff0000, v157
	v_pk_fma_f32 v[126:127], v[126:127], 0.5, v[212:213] op_sel_hi:[1,0,1]
	v_pk_fma_f32 v[124:125], v[124:125], 0.5, v[210:211] op_sel_hi:[1,0,1]
	v_cvt_pk_bf16_f32 v122, v122, v123
	v_cvt_pk_bf16_f32 v123, v202, v203
	v_add_co_u32_e32 v202, vcc, s44, v144
	v_lshlrev_b32_e32 v224, 16, v158
	v_and_b32_e32 v225, 0xffff0000, v158
	v_lshlrev_b32_e32 v226, 16, v159
	v_and_b32_e32 v227, 0xffff0000, v159
	v_cvt_pk_bf16_f32 v120, v124, v125
	v_cvt_pk_bf16_f32 v121, v126, v127
	v_pk_fma_f32 v[118:119], v[118:119], 0.5, v[220:221] op_sel_hi:[1,0,1]
	v_pk_fma_f32 v[116:117], v[116:117], 0.5, v[218:219] op_sel_hi:[1,0,1]
	v_addc_co_u32_e32 v203, vcc, 0, v145, vcc
	v_lshlrev_b32_e32 v192, 16, v160
	v_and_b32_e32 v193, 0xffff0000, v160
	global_store_dwordx4 v[144:145], v[120:123], off
	v_pk_fma_f32 v[108:109], v[108:109], 0.5, v[192:193] op_sel_hi:[1,0,1]
	v_lshl_add_u64 v[192:193], v[144:145], 0, s[12:13]
	v_pk_fma_f32 v[120:121], v[114:115], 0.5, v[226:227] op_sel_hi:[1,0,1]
	v_pk_fma_f32 v[114:115], v[112:113], 0.5, v[224:225] op_sel_hi:[1,0,1]
	v_cvt_pk_bf16_f32 v112, v116, v117
	v_cvt_pk_bf16_f32 v113, v118, v119
	global_load_dwordx4 v[116:119], v[202:203], off
	v_cvt_pk_bf16_f32 v114, v114, v115
	v_cvt_pk_bf16_f32 v115, v120, v121
	v_lshlrev_b32_e32 v228, 16, v161
	v_and_b32_e32 v229, 0xffff0000, v161
	global_store_dwordx4 v[144:145], v[112:115], off offset:256
	v_pk_fma_f32 v[120:121], v[106:107], 0.5, v[230:231] op_sel_hi:[1,0,1]
	v_pk_fma_f32 v[110:111], v[110:111], 0.5, v[228:229] op_sel_hi:[1,0,1]
	v_pk_fma_f32 v[112:113], v[104:105], 0.5, v[194:195] op_sel_hi:[1,0,1]
	global_load_dwordx4 v[104:107], v[192:193], off offset:256
	v_add_co_u32_e32 v194, vcc, s45, v144
	v_lshlrev_b32_e32 v184, 16, v164
	s_nop 0
	v_addc_co_u32_e32 v195, vcc, 0, v145, vcc
	v_and_b32_e32 v185, 0xffff0000, v164
	v_lshlrev_b32_e32 v188, 16, v165
	v_and_b32_e32 v189, 0xffff0000, v165
	v_lshlrev_b32_e32 v186, 16, v166
	v_and_b32_e32 v187, 0xffff0000, v166
	v_lshlrev_b32_e32 v190, 16, v167
	v_and_b32_e32 v191, 0xffff0000, v167
	v_cvt_pk_bf16_f32 v108, v108, v109
	v_cvt_pk_bf16_f32 v109, v110, v111
	v_cvt_pk_bf16_f32 v110, v112, v113
	global_load_dwordx4 v[112:115], v[194:195], off
	v_cvt_pk_bf16_f32 v111, v120, v121
	global_store_dwordx4 v[150:151], v[108:111], off
	v_pk_fma_f32 v[124:125], v[98:99], 0.5, v[190:191] op_sel_hi:[1,0,1]
	v_pk_fma_f32 v[96:97], v[96:97], 0.5, v[186:187] op_sel_hi:[1,0,1]
	v_pk_fma_f32 v[110:111], v[102:103], 0.5, v[188:189] op_sel_hi:[1,0,1]
	v_pk_fma_f32 v[108:109], v[100:101], 0.5, v[184:185] op_sel_hi:[1,0,1]
	v_lshl_add_u64 v[98:99], v[144:145], 0, s[14:15]
	global_load_dwordx4 v[100:103], v[98:99], off offset:256
	v_cvt_pk_bf16_f32 v108, v108, v109
	v_cvt_pk_bf16_f32 v109, v110, v111
	v_cvt_pk_bf16_f32 v110, v96, v97
	v_add_co_u32_e32 v96, vcc, s46, v144
	v_lshlrev_b32_e32 v176, 16, v168
	s_nop 0
	v_addc_co_u32_e32 v97, vcc, 0, v145, vcc
	v_and_b32_e32 v177, 0xffff0000, v168
	v_lshlrev_b32_e32 v180, 16, v169
	v_and_b32_e32 v181, 0xffff0000, v169
	v_lshlrev_b32_e32 v178, 16, v170
	v_and_b32_e32 v179, 0xffff0000, v170
	v_lshlrev_b32_e32 v182, 16, v171
	v_and_b32_e32 v183, 0xffff0000, v171
	global_load_dwordx4 v[120:123], v[96:97], off
	v_cvt_pk_bf16_f32 v111, v124, v125
	global_store_dwordx4 v[150:151], v[108:111], off offset:256
	v_pk_fma_f32 v[150:151], v[90:91], 0.5, v[182:183] op_sel_hi:[1,0,1]
	v_pk_fma_f32 v[88:89], v[88:89], 0.5, v[178:179] op_sel_hi:[1,0,1]
	v_pk_fma_f32 v[110:111], v[94:95], 0.5, v[180:181] op_sel_hi:[1,0,1]
	v_pk_fma_f32 v[108:109], v[92:93], 0.5, v[176:177] op_sel_hi:[1,0,1]
	v_lshl_add_u64 v[90:91], v[144:145], 0, s[16:17]
	global_load_dwordx4 v[92:95], v[90:91], off offset:256
	v_cvt_pk_bf16_f32 v108, v108, v109
	v_cvt_pk_bf16_f32 v109, v110, v111
	v_cvt_pk_bf16_f32 v110, v88, v89
	v_add_co_u32_e32 v88, vcc, s47, v144
	v_lshlrev_b32_e32 v170, 16, v174
	s_nop 0
	v_addc_co_u32_e32 v89, vcc, 0, v145, vcc
	v_and_b32_e32 v171, 0xffff0000, v174
	global_load_dwordx4 v[124:127], v[88:89], off
	v_lshlrev_b32_e32 v168, 16, v172
	v_and_b32_e32 v169, 0xffff0000, v172
	v_lshlrev_b32_e32 v172, 16, v173
	v_and_b32_e32 v173, 0xffff0000, v173
	v_cvt_pk_bf16_f32 v111, v150, v151
	v_pk_fma_f32 v[150:151], v[72:73], 0.5, v[170:171] op_sel_hi:[1,0,1]
	v_lshl_add_u64 v[72:73], v[144:145], 0, s[18:19]
	global_store_dwordx4 v[146:147], v[108:111], off
	v_lshlrev_b32_e32 v174, 16, v175
	v_and_b32_e32 v175, 0xffff0000, v175
	v_pk_fma_f32 v[110:111], v[82:83], 0.5, v[172:173] op_sel_hi:[1,0,1]
	v_pk_fma_f32 v[108:109], v[80:81], 0.5, v[168:169] op_sel_hi:[1,0,1]
	global_load_dwordx4 v[80:83], v[72:73], off offset:256
	v_lshlrev_b32_e32 v160, 16, v204
	v_and_b32_e32 v161, 0xffff0000, v204
	v_lshlrev_b32_e32 v166, 16, v205
	v_and_b32_e32 v167, 0xffff0000, v205
	v_pk_fma_f32 v[74:75], v[74:75], 0.5, v[174:175] op_sel_hi:[1,0,1]
	v_cvt_pk_bf16_f32 v108, v108, v109
	v_cvt_pk_bf16_f32 v109, v110, v111
	v_cvt_pk_bf16_f32 v111, v74, v75
	v_pk_fma_f32 v[86:87], v[86:87], 0.5, v[162:163] op_sel_hi:[1,0,1]
	v_pk_fma_f32 v[74:75], v[84:85], 0.5, v[154:155] op_sel_hi:[1,0,1]
	v_pk_fma_f32 v[78:79], v[78:79], 0.5, v[166:167] op_sel_hi:[1,0,1]
	v_pk_fma_f32 v[76:77], v[76:77], 0.5, v[160:161] op_sel_hi:[1,0,1]
	v_lshlrev_b32_e32 v152, 16, v206
	v_and_b32_e32 v153, 0xffff0000, v206
	v_lshlrev_b32_e32 v158, 16, v207
	v_and_b32_e32 v159, 0xffff0000, v207
	v_lshlrev_b32_e32 v156, 16, v208
	v_and_b32_e32 v157, 0xffff0000, v208
	v_lshlrev_b32_e32 v164, 16, v209
	v_and_b32_e32 v165, 0xffff0000, v209
	v_cvt_pk_bf16_f32 v74, v74, v75
	v_cvt_pk_bf16_f32 v75, v86, v87
	v_cvt_pk_bf16_f32 v76, v76, v77
	v_cvt_pk_bf16_f32 v77, v78, v79
	global_store_dwordx4 v[148:149], v[74:77], off
	v_pk_fma_f32 v[70:71], v[70:71], 0.5, v[158:159] op_sel_hi:[1,0,1]
	v_pk_fma_f32 v[68:69], v[68:69], 0.5, v[152:153] op_sel_hi:[1,0,1]
	v_pk_fma_f32 v[74:75], v[66:67], 0.5, v[164:165] op_sel_hi:[1,0,1]
	v_pk_fma_f32 v[66:67], v[64:65], 0.5, v[156:157] op_sel_hi:[1,0,1]
	v_cvt_pk_bf16_f32 v64, v68, v69
	v_cvt_pk_bf16_f32 v65, v70, v71
	v_cvt_pk_bf16_f32 v66, v66, v67
	v_cvt_pk_bf16_f32 v67, v74, v75
	global_store_dwordx4 v[148:149], v[64:67], off offset:256
	s_waitcnt vmcnt(0)
; DI unsigned pk_bf16(float lo, float hi) { f32x2 v = {lo, hi}; return __builtin_bit_cast(unsigned, __builtin_convertvector(v, bf16v2)); }
; #define PG8_WAIT_V(n) asm volatile("s_waitcnt vmcnt(" #n ")" ::: "memory")
; #define PG8_BAR __builtin_amdgcn_s_barrier()
; #define PG8_WAIT_V(n) asm volatile("s_waitcnt vmcnt(" #n ")" ::: "memory")
; #define PG8_BAR __builtin_amdgcn_s_barrier()
; template <class Epi>
; DI void gemm_phase(LAS unsigned char* lds, const Gemm g, const StaticOrder S, const Epi E) {
;     ...
;         if (!has_next) break;
; #pragma unroll
;         for (int a = 0; a < 2; ++a)
; #pragma unroll
;             for (int b = 0; b < 2; ++b)
; #pragma unroll
;                 for (int m = 0; m < 4; ++m)
; #pragma unroll
;                     for (int n = 0; n < 2; ++n) acc[a][b][m][n] = (f32x4){0.f, 0.f, 0.f, 0.f};
;         cur = nxt; cA = nA; cB = nB; ++ui;
;     }
;     PG8_WAIT_V(0);
;     if (wr == 0) PG8_BAR;
;     PG8_BAR;
;     DI void operator()(AccRef acc, const Unit& u, int wr, int wc, int fr, int fq) const {
;     ...
;             for (int m = 0; m < 4; ++m) {
;                 const int row = row0 + ai * 128 + m * 16;
;                 float q = 0.f;
; #pragma unroll
;                 for (int bj = 0; bj < 2; ++bj) {
;                     const size_t o = (size_t)row * DM + col0 + bj * 128;
;                     const f32x4 r0 = bv[m][bj][0] + scale * acc[ai][bj][m][0], r1 = bv[m][bj][1] + scale * acc[ai][bj][m][1];
;                     u32x4 w; w.x = pk_bf16(r0[0], r0[1]); w.y = pk_bf16(r0[2], r0[3]); w.z = pk_bf16(r1[0], r1[1]); w.w = pk_bf16(r1[2], r1[3]);
;                     *(u32x4*)(xnb + o) = w;
	v_lshlrev_b32_e32 v68, 16, v118
	v_and_b32_e32 v69, 0xffff0000, v118
	v_lshlrev_b32_e32 v64, 16, v116
	v_and_b32_e32 v65, 0xffff0000, v116
	v_lshlrev_b32_e32 v66, 16, v117
	v_and_b32_e32 v67, 0xffff0000, v117
	v_lshlrev_b32_e32 v70, 16, v119
	v_and_b32_e32 v71, 0xffff0000, v119
	v_pk_fma_f32 v[62:63], v[62:63], 0.5, v[66:67] op_sel_hi:[1,0,1]
	v_pk_fma_f32 v[60:61], v[60:61], 0.5, v[64:65] op_sel_hi:[1,0,1]
	v_pk_fma_f32 v[64:65], v[58:59], 0.5, v[70:71] op_sel_hi:[1,0,1]
	v_pk_fma_f32 v[58:59], v[56:57], 0.5, v[68:69] op_sel_hi:[1,0,1]
	v_lshlrev_b32_e32 v74, 16, v104
	v_and_b32_e32 v75, 0xffff0000, v104
	v_lshlrev_b32_e32 v76, 16, v105
	v_and_b32_e32 v77, 0xffff0000, v105
	v_lshlrev_b32_e32 v78, 16, v106
	v_and_b32_e32 v79, 0xffff0000, v106
	v_lshlrev_b32_e32 v84, 16, v107
	v_and_b32_e32 v85, 0xffff0000, v107
	v_cvt_pk_bf16_f32 v56, v60, v61
	v_cvt_pk_bf16_f32 v57, v62, v63
	v_cvt_pk_bf16_f32 v58, v58, v59
	v_cvt_pk_bf16_f32 v59, v64, v65
	v_cvt_pk_bf16_f32 v110, v150, v151
	global_store_dwordx4 v[202:203], v[56:59], off
	v_pk_fma_f32 v[54:55], v[54:55], 0.5, v[76:77] op_sel_hi:[1,0,1]
	v_pk_fma_f32 v[52:53], v[52:53], 0.5, v[74:75] op_sel_hi:[1,0,1]
	v_pk_fma_f32 v[56:57], v[46:47], 0.5, v[84:85] op_sel_hi:[1,0,1]
	v_pk_fma_f32 v[46:47], v[44:45], 0.5, v[78:79] op_sel_hi:[1,0,1]
	global_store_dwordx4 v[146:147], v[108:111], off offset:256
	v_lshlrev_b32_e32 v86, 16, v112
	v_and_b32_e32 v87, 0xffff0000, v112
	v_lshlrev_b32_e32 v104, 16, v113
	v_and_b32_e32 v105, 0xffff0000, v113
	v_lshlrev_b32_e32 v106, 16, v114
	v_and_b32_e32 v107, 0xffff0000, v114
	v_lshlrev_b32_e32 v108, 16, v115
	v_and_b32_e32 v109, 0xffff0000, v115
	v_cvt_pk_bf16_f32 v44, v52, v53
	v_cvt_pk_bf16_f32 v45, v54, v55
	v_cvt_pk_bf16_f32 v46, v46, v47
	v_cvt_pk_bf16_f32 v47, v56, v57
	global_store_dwordx4 v[192:193], v[44:47], off offset:256
	v_lshlrev_b32_e32 v110, 16, v100
	v_and_b32_e32 v111, 0xffff0000, v100
	v_pk_fma_f32 v[44:45], v[50:51], 0.5, v[104:105] op_sel_hi:[1,0,1]
	v_pk_fma_f32 v[46:47], v[48:49], 0.5, v[86:87] op_sel_hi:[1,0,1]
	v_pk_fma_f32 v[48:49], v[42:43], 0.5, v[108:109] op_sel_hi:[1,0,1]
	v_pk_fma_f32 v[42:43], v[40:41], 0.5, v[106:107] op_sel_hi:[1,0,1]
	v_lshlrev_b32_e32 v100, 16, v101
	v_and_b32_e32 v101, 0xffff0000, v101
	v_lshlrev_b32_e32 v112, 16, v102
	v_and_b32_e32 v113, 0xffff0000, v102
	v_lshlrev_b32_e32 v102, 16, v103
	v_and_b32_e32 v103, 0xffff0000, v103
	v_cvt_pk_bf16_f32 v40, v46, v47
	v_cvt_pk_bf16_f32 v41, v44, v45
	v_cvt_pk_bf16_f32 v42, v42, v43
	v_cvt_pk_bf16_f32 v43, v48, v49
	global_store_dwordx4 v[194:195], v[40:43], off
	v_pk_fma_f32 v[38:39], v[38:39], 0.5, v[100:101] op_sel_hi:[1,0,1]
	v_pk_fma_f32 v[36:37], v[36:37], 0.5, v[110:111] op_sel_hi:[1,0,1]
	v_pk_fma_f32 v[40:41], v[30:31], 0.5, v[102:103] op_sel_hi:[1,0,1]
	v_pk_fma_f32 v[30:31], v[28:29], 0.5, v[112:113] op_sel_hi:[1,0,1]
	v_lshlrev_b32_e32 v114, 16, v120
	v_and_b32_e32 v115, 0xffff0000, v120
	v_lshlrev_b32_e32 v116, 16, v121
	v_and_b32_e32 v117, 0xffff0000, v121
	v_lshlrev_b32_e32 v118, 16, v122
	v_and_b32_e32 v119, 0xffff0000, v122
	v_lshlrev_b32_e32 v120, 16, v123
	v_and_b32_e32 v121, 0xffff0000, v123
	v_cvt_pk_bf16_f32 v28, v36, v37
	v_cvt_pk_bf16_f32 v29, v38, v39
	v_cvt_pk_bf16_f32 v30, v30, v31
	v_cvt_pk_bf16_f32 v31, v40, v41
	global_store_dwordx4 v[98:99], v[28:31], off offset:256
	v_lshlrev_b32_e32 v122, 16, v92
	v_and_b32_e32 v123, 0xffff0000, v92
	v_pk_fma_f32 v[28:29], v[34:35], 0.5, v[116:117] op_sel_hi:[1,0,1]
	v_pk_fma_f32 v[30:31], v[32:33], 0.5, v[114:115] op_sel_hi:[1,0,1]
	v_pk_fma_f32 v[32:33], v[26:27], 0.5, v[120:121] op_sel_hi:[1,0,1]
	v_pk_fma_f32 v[26:27], v[24:25], 0.5, v[118:119] op_sel_hi:[1,0,1]
	v_lshlrev_b32_e32 v92, 16, v93
	v_and_b32_e32 v93, 0xffff0000, v93
	v_lshlrev_b32_e32 v144, 16, v94
	v_and_b32_e32 v145, 0xffff0000, v94
	v_lshlrev_b32_e32 v94, 16, v95
	v_and_b32_e32 v95, 0xffff0000, v95
	v_cvt_pk_bf16_f32 v24, v30, v31
	v_cvt_pk_bf16_f32 v25, v28, v29
	v_cvt_pk_bf16_f32 v26, v26, v27
	v_cvt_pk_bf16_f32 v27, v32, v33
	global_store_dwordx4 v[96:97], v[24:27], off
	v_pk_fma_f32 v[22:23], v[22:23], 0.5, v[92:93] op_sel_hi:[1,0,1]
	v_pk_fma_f32 v[20:21], v[20:21], 0.5, v[122:123] op_sel_hi:[1,0,1]
	v_pk_fma_f32 v[24:25], v[14:15], 0.5, v[94:95] op_sel_hi:[1,0,1]
	v_pk_fma_f32 v[14:15], v[12:13], 0.5, v[144:145] op_sel_hi:[1,0,1]
	v_lshlrev_b32_e32 v146, 16, v124
	v_and_b32_e32 v147, 0xffff0000, v124
	v_lshlrev_b32_e32 v124, 16, v125
	v_and_b32_e32 v125, 0xffff0000, v125
	v_lshlrev_b32_e32 v148, 16, v126
	v_and_b32_e32 v149, 0xffff0000, v126
	v_lshlrev_b32_e32 v126, 16, v127
	v_and_b32_e32 v127, 0xffff0000, v127
	v_cvt_pk_bf16_f32 v12, v20, v21
	v_cvt_pk_bf16_f32 v13, v22, v23
	v_cvt_pk_bf16_f32 v14, v14, v15
	v_cvt_pk_bf16_f32 v15, v24, v25
	global_store_dwordx4 v[90:91], v[12:15], off offset:256
	v_lshlrev_b32_e32 v150, 16, v80
	v_and_b32_e32 v151, 0xffff0000, v80
	v_pk_fma_f32 v[12:13], v[18:19], 0.5, v[124:125] op_sel_hi:[1,0,1]
	v_pk_fma_f32 v[14:15], v[16:17], 0.5, v[146:147] op_sel_hi:[1,0,1]
	v_pk_fma_f32 v[16:17], v[10:11], 0.5, v[126:127] op_sel_hi:[1,0,1]
	v_pk_fma_f32 v[10:11], v[8:9], 0.5, v[148:149] op_sel_hi:[1,0,1]
	v_lshlrev_b32_e32 v80, 16, v81
	v_and_b32_e32 v81, 0xffff0000, v81
	v_lshlrev_b32_e32 v152, 16, v82
	v_and_b32_e32 v153, 0xffff0000, v82
	v_lshlrev_b32_e32 v82, 16, v83
	v_and_b32_e32 v83, 0xffff0000, v83
	v_cvt_pk_bf16_f32 v8, v14, v15
	v_cvt_pk_bf16_f32 v9, v12, v13
	v_cvt_pk_bf16_f32 v10, v10, v11
	v_cvt_pk_bf16_f32 v11, v16, v17
	global_store_dwordx4 v[88:89], v[8:11], off
	v_pk_fma_f32 v[6:7], v[6:7], 0.5, v[80:81] op_sel_hi:[1,0,1]
	v_pk_fma_f32 v[4:5], v[4:5], 0.5, v[150:151] op_sel_hi:[1,0,1]
	v_pk_fma_f32 v[8:9], v[2:3], 0.5, v[82:83] op_sel_hi:[1,0,1]
	v_pk_fma_f32 v[2:3], v[0:1], 0.5, v[152:153] op_sel_hi:[1,0,1]
	v_cvt_pk_bf16_f32 v0, v4, v5
	v_cvt_pk_bf16_f32 v1, v6, v7
	v_cvt_pk_bf16_f32 v2, v2, v3
	v_cvt_pk_bf16_f32 v3, v8, v9
	s_and_b64 vcc, exec, s[0:1]
	global_store_dwordx4 v[72:73], v[0:3], off offset:256
	s_cbranch_vccz .LBB0_930
	s_waitcnt vmcnt(0)
	s_cmpk_gt_u32 s6, 0xff
	s_cbranch_scc1 .LBB0_945
	s_barrier
